# baseline (speedup 1.0000x reference)
; #define PG8_STAGE(bufoff, gbase, voff) do { _Pragma("unroll") for (int _i = 0; _i < 2; ++_i) \
;         __builtin_amdgcn_global_load_lds((const unsigned*)((const char*)(gbase) + (voff)[_i]), (PG8_LAS unsigned*)(lds + (bufoff) + ldsw + _i * 8192), 16, 0, 0); } while (0)
; #define PG8_LDA(dst, b, h) do { _Pragma("unroll") for (int m = 0; m < 4; ++m) _Pragma("unroll") for (int k = 0; k < 2; ++k) dst[m][k] = *(const PG8_LAS bf16x8*)(lds + PG8_SA(b, h) + aoff + m * 2048 + k * 1024); } while (0)
; #define PG8_LDB(dst, b, h) do { _Pragma("unroll") for (int n = 0; n < 2; ++n) _Pragma("unroll") for (int k = 0; k < 2; ++k) dst[n][k] = *(const PG8_LAS bf16x8*)(lds + PG8_SB(b, h) + boff + n * 2048 + k * 1024); } while (0)
; #define PG8_MMA(ai, bj, At, Bt) do { __builtin_amdgcn_s_setprio(1); _Pragma("unroll") for (int m = 0; m < 4; ++m) _Pragma("unroll") for (int n = 0; n < 2; ++n) _Pragma("unroll") for (int k = 0; k < 2; ++k) \
;         acc[ai][bj][m][n] = __builtin_amdgcn_mfma_f32_16x16x32_bf16(Bt[n][k], At[m][k], acc[ai][bj][m][n], 0, 0, 0); __builtin_amdgcn_s_setprio(0); } while (0)
; #define PG8_WAIT_V(n) asm volatile("s_waitcnt vmcnt(" #n ")" ::: "memory")
; #define PG8_WAIT_L(n) asm volatile("s_waitcnt lgkmcnt(" #n ")" ::: "memory")
; #define PG8_BAR __builtin_amdgcn_s_barrier()
; #define PG8_SCHED __builtin_amdgcn_sched_barrier(0)
; template <class Epi, class Sched, bool ALIGN_EPI = false, bool SP2 = false>
; __device__ __forceinline__ void gemm_phase(PG8_LAS unsigned char* lds, const Gemm g, const Sched& S, const Epi& E) {
;     ...
;             const bool last = (t == nt - 2);
;             const char* a1 = cA + (size_t)(t + 1) * kstep;
;             const char* a2 = last ? nA : cA + (size_t)(t + 2) * kstep; const char* b2 = last ? nB : cB + (size_t)(t + 2) * kstep;
;             const char* a3 = a2 + kstep; const char* b3 = b2 + kstep;
;             if (last && has_next) S.a_ready(nxt);
;             if constexpr (SP2) {
;             PG8_LDB(B0, 0, 0); PG8_LDB(B1, 0, 1); PG8_SCHED; PG8_LDA(At, 0, 0); PG8_STAGE(PG8_SA(1, 1), a1 + hstep, voffA);
;             PG8_WAIT_V(8); PG8_WAIT_L(0); PG8_BAR; PG8_MMA(0, 0, At, B0); PG8_MMA(0, 1, At, B1); PG8_BAR; PG8_SCHED;
;             PG8_LDA(At, 0, 1); PG8_STAGE(PG8_SB(0, 0), b2, voffB); PG8_STAGE(PG8_SB(0, 1), b2 + hstep, voffB); PG8_STAGE(PG8_SA(0, 0), a2, voffA);
.LBB0_121:
	ds_read_b128 v[148:151], v159
	ds_read_b128 v[168:171], v159 offset:1024
	ds_read_b128 v[172:175], v159 offset:2048
	ds_read_b128 v[176:179], v159 offset:3072
	ds_read_b128 v[180:183], v160
	ds_read_b128 v[184:187], v160 offset:1024
	ds_read_b128 v[188:191], v160 offset:2048
	ds_read_b128 v[192:195], v160 offset:3072
	s_add_i32 s46, s42, 2
	s_add_u32 s47, s6, 0x80
	s_addc_u32 s43, s7, 0
	s_cmp_eq_u32 s93, s42
	s_cselect_b32 s42, s38, s47
	s_cselect_b32 s43, s39, s43
	s_cselect_b32 s69, s41, vcc_lo
	s_cselect_b32 s68, s40, s0
	v_lshl_add_u64 v[152:153], s[6:7], 0, v[142:143]
	s_add_i32 m0, s64, 0xc000
	ds_read_b128 v[196:199], v161
	ds_read_b128 v[200:203], v161 offset:1024
	ds_read_b128 v[204:207], v161 offset:2048
	ds_read_b128 v[208:211], v161 offset:3072
	ds_read_b128 v[212:215], v161 offset:4096
	ds_read_b128 v[216:219], v161 offset:5120
	ds_read_b128 v[220:223], v161 offset:6144
	ds_read_b128 v[224:227], v161 offset:7168
	global_load_lds_dwordx4 v[152:153], off
	s_add_i32 m0, s64, 0xe000
	v_lshl_add_u64 v[152:153], s[6:7], 0, v[140:141]
	global_load_lds_dwordx4 v[152:153], off
	s_waitcnt vmcnt(8) lgkmcnt(0)
	s_barrier
	s_setprio 1
	v_mfma_f32_16x16x32_bf16 v[126:129], v[148:151], v[196:199], v[126:129]
	v_mfma_f32_16x16x32_bf16 v[122:125], v[172:175], v[196:199], v[122:125]
	v_mfma_f32_16x16x32_bf16 v[110:113], v[148:151], v[204:207], v[110:113]
	v_mfma_f32_16x16x32_bf16 v[106:109], v[172:175], v[204:207], v[106:109]
	v_mfma_f32_16x16x32_bf16 v[94:97], v[148:151], v[212:215], v[94:97]
	v_mfma_f32_16x16x32_bf16 v[90:93], v[172:175], v[212:215], v[90:93]
	v_mfma_f32_16x16x32_bf16 v[78:81], v[148:151], v[220:223], v[78:81]
	v_mfma_f32_16x16x32_bf16 v[74:77], v[172:175], v[220:223], v[74:77]
	v_mfma_f32_16x16x32_bf16 v[126:129], v[168:171], v[200:203], v[126:129]
	v_mfma_f32_16x16x32_bf16 v[122:125], v[176:179], v[200:203], v[122:125]
	v_mfma_f32_16x16x32_bf16 v[110:113], v[168:171], v[208:211], v[110:113]
	v_mfma_f32_16x16x32_bf16 v[106:109], v[176:179], v[208:211], v[106:109]
	v_mfma_f32_16x16x32_bf16 v[94:97], v[168:171], v[216:219], v[94:97]
	v_mfma_f32_16x16x32_bf16 v[90:93], v[176:179], v[216:219], v[90:93]
	v_mfma_f32_16x16x32_bf16 v[78:81], v[168:171], v[224:227], v[78:81]
	v_mfma_f32_16x16x32_bf16 v[74:77], v[176:179], v[224:227], v[74:77]
	v_mfma_f32_16x16x32_bf16 v[118:121], v[180:183], v[196:199], v[118:121]
	v_mfma_f32_16x16x32_bf16 v[114:117], v[188:191], v[196:199], v[114:117]
	v_mfma_f32_16x16x32_bf16 v[102:105], v[180:183], v[204:207], v[102:105]
	v_mfma_f32_16x16x32_bf16 v[98:101], v[188:191], v[204:207], v[98:101]
	v_mfma_f32_16x16x32_bf16 v[86:89], v[180:183], v[212:215], v[86:89]
	v_mfma_f32_16x16x32_bf16 v[82:85], v[188:191], v[212:215], v[82:85]
	v_mfma_f32_16x16x32_bf16 v[70:73], v[180:183], v[220:223], v[70:73]
	v_mfma_f32_16x16x32_bf16 v[66:69], v[188:191], v[220:223], v[66:69]
	v_mfma_f32_16x16x32_bf16 v[118:121], v[184:187], v[200:203], v[118:121]
	v_mfma_f32_16x16x32_bf16 v[114:117], v[192:195], v[200:203], v[114:117]
	v_mfma_f32_16x16x32_bf16 v[102:105], v[184:187], v[208:211], v[102:105]
	v_mfma_f32_16x16x32_bf16 v[98:101], v[192:195], v[208:211], v[98:101]
	v_mfma_f32_16x16x32_bf16 v[86:89], v[184:187], v[216:219], v[86:89]
	v_mfma_f32_16x16x32_bf16 v[82:85], v[192:195], v[216:219], v[82:85]
	v_mfma_f32_16x16x32_bf16 v[70:73], v[184:187], v[224:227], v[70:73]
	v_mfma_f32_16x16x32_bf16 v[66:69], v[192:195], v[224:227], v[66:69]
	s_setprio 0
	s_barrier
	s_add_i32 s47, s97, s55
	v_lshl_add_u64 v[152:153], s[68:69], 0, v[132:133]
	s_mov_b32 m0, s47
	ds_read_b128 v[196:199], v161 offset:16384
	ds_read_b128 v[200:203], v161 offset:17408
	ds_read_b128 v[204:207], v161 offset:18432
	ds_read_b128 v[208:211], v161 offset:19456
	ds_read_b128 v[212:215], v161 offset:20480
	ds_read_b128 v[216:219], v161 offset:21504
	ds_read_b128 v[220:223], v161 offset:22528
	ds_read_b128 v[224:227], v161 offset:23552
	global_load_lds_dwordx4 v[152:153], off
	s_add_i32 m0, s47, 0x2000
	v_lshl_add_u64 v[228:229], s[68:69], 0, v[136:137]
	s_add_u32 s68, s68, s10
	s_addc_u32 s69, s69, s11
	s_add_i32 s47, s80, s55
	global_load_lds_dwordx4 v[228:229], off
	v_lshl_add_u64 v[230:231], s[68:69], 0, v[132:133]
	s_mov_b32 m0, s47
	v_lshl_add_u64 v[232:233], s[68:69], 0, v[136:137]
	global_load_lds_dwordx4 v[230:231], off
	s_add_i32 m0, s47, 0x2000
	v_lshl_add_u64 v[234:235], s[42:43], 0, v[130:131]
	global_load_lds_dwordx4 v[232:233], off
	s_mov_b32 m0, s64
	v_lshl_add_u64 v[236:237], s[42:43], 0, v[134:135]
	global_load_lds_dwordx4 v[234:235], off
	s_mov_b32 m0, s65
	s_nop 0
	global_load_lds_dwordx4 v[236:237], off
	s_waitcnt vmcnt(8) lgkmcnt(0)
	s_barrier
; #define PG8_STAGE(bufoff, gbase, voff) do { _Pragma("unroll") for (int _i = 0; _i < 2; ++_i) \
;         __builtin_amdgcn_global_load_lds((const unsigned*)((const char*)(gbase) + (voff)[_i]), (PG8_LAS unsigned*)(lds + (bufoff) + ldsw + _i * 8192), 16, 0, 0); } while (0)
; #define PG8_LDA(dst, b, h) do { _Pragma("unroll") for (int m = 0; m < 4; ++m) _Pragma("unroll") for (int k = 0; k < 2; ++k) dst[m][k] = *(const PG8_LAS bf16x8*)(lds + PG8_SA(b, h) + aoff + m * 2048 + k * 1024); } while (0)
; #define PG8_LDB(dst, b, h) do { _Pragma("unroll") for (int n = 0; n < 2; ++n) _Pragma("unroll") for (int k = 0; k < 2; ++k) dst[n][k] = *(const PG8_LAS bf16x8*)(lds + PG8_SB(b, h) + boff + n * 2048 + k * 1024); } while (0)
; #define PG8_MMA(ai, bj, At, Bt) do { __builtin_amdgcn_s_setprio(1); _Pragma("unroll") for (int m = 0; m < 4; ++m) _Pragma("unroll") for (int n = 0; n < 2; ++n) _Pragma("unroll") for (int k = 0; k < 2; ++k) \
;         acc[ai][bj][m][n] = __builtin_amdgcn_mfma_f32_16x16x32_bf16(Bt[n][k], At[m][k], acc[ai][bj][m][n], 0, 0, 0); __builtin_amdgcn_s_setprio(0); } while (0)
; #define PG8_WAIT_V(n) asm volatile("s_waitcnt vmcnt(" #n ")" ::: "memory")
; #define PG8_WAIT_L(n) asm volatile("s_waitcnt lgkmcnt(" #n ")" ::: "memory")
; #define PG8_BAR __builtin_amdgcn_s_barrier()
; #define PG8_SCHED __builtin_amdgcn_sched_barrier(0)
; template <class Epi, class Sched, bool ALIGN_EPI = false, bool SP2 = false>
; __device__ __forceinline__ void gemm_phase(PG8_LAS unsigned char* lds, const Gemm g, const Sched& S, const Epi& E) {
;     ...
;             PG8_WAIT_V(8); PG8_WAIT_L(0); PG8_BAR; PG8_MMA(1, 0, At, B0); PG8_MMA(1, 1, At, B1); PG8_BAR; PG8_SCHED;
;             PG8_LDB(B0, 1, 0); PG8_LDB(B1, 1, 1); PG8_SCHED; PG8_LDA(At, 1, 0); PG8_STAGE(PG8_SA(0, 1), a2 + hstep, voffA);
;             PG8_WAIT_V(8); PG8_WAIT_L(0); PG8_BAR; PG8_MMA(0, 0, At, B0); PG8_MMA(0, 1, At, B1); PG8_BAR; PG8_SCHED;
	s_setprio 1
	v_mfma_f32_16x16x32_bf16 v[62:65], v[148:151], v[196:199], v[62:65]
	v_mfma_f32_16x16x32_bf16 v[58:61], v[172:175], v[196:199], v[58:61]
	v_mfma_f32_16x16x32_bf16 v[46:49], v[148:151], v[204:207], v[46:49]
	v_mfma_f32_16x16x32_bf16 v[42:45], v[172:175], v[204:207], v[42:45]
	v_mfma_f32_16x16x32_bf16 v[30:33], v[148:151], v[212:215], v[30:33]
	v_mfma_f32_16x16x32_bf16 v[26:29], v[172:175], v[212:215], v[26:29]
	v_mfma_f32_16x16x32_bf16 v[14:17], v[148:151], v[220:223], v[14:17]
	v_mfma_f32_16x16x32_bf16 v[10:13], v[172:175], v[220:223], v[10:13]
	v_mfma_f32_16x16x32_bf16 v[62:65], v[168:171], v[200:203], v[62:65]
	v_mfma_f32_16x16x32_bf16 v[58:61], v[176:179], v[200:203], v[58:61]
	v_mfma_f32_16x16x32_bf16 v[46:49], v[168:171], v[208:211], v[46:49]
	v_mfma_f32_16x16x32_bf16 v[42:45], v[176:179], v[208:211], v[42:45]
	v_mfma_f32_16x16x32_bf16 v[30:33], v[168:171], v[216:219], v[30:33]
	v_mfma_f32_16x16x32_bf16 v[26:29], v[176:179], v[216:219], v[26:29]
	v_mfma_f32_16x16x32_bf16 v[14:17], v[168:171], v[224:227], v[14:17]
	v_mfma_f32_16x16x32_bf16 v[10:13], v[176:179], v[224:227], v[10:13]
	v_mfma_f32_16x16x32_bf16 v[54:57], v[180:183], v[196:199], v[54:57]
	v_mfma_f32_16x16x32_bf16 v[50:53], v[188:191], v[196:199], v[50:53]
	v_mfma_f32_16x16x32_bf16 v[38:41], v[180:183], v[204:207], v[38:41]
	v_mfma_f32_16x16x32_bf16 v[34:37], v[188:191], v[204:207], v[34:37]
	v_mfma_f32_16x16x32_bf16 v[22:25], v[180:183], v[212:215], v[22:25]
	v_mfma_f32_16x16x32_bf16 v[18:21], v[188:191], v[212:215], v[18:21]
	v_mfma_f32_16x16x32_bf16 v[6:9], v[180:183], v[220:223], v[6:9]
	v_mfma_f32_16x16x32_bf16 v[2:5], v[188:191], v[220:223], v[2:5]
	v_mfma_f32_16x16x32_bf16 v[54:57], v[184:187], v[200:203], v[54:57]
	v_mfma_f32_16x16x32_bf16 v[50:53], v[192:195], v[200:203], v[50:53]
	v_mfma_f32_16x16x32_bf16 v[38:41], v[184:187], v[208:211], v[38:41]
	v_mfma_f32_16x16x32_bf16 v[34:37], v[192:195], v[208:211], v[34:37]
	v_mfma_f32_16x16x32_bf16 v[22:25], v[184:187], v[216:219], v[22:25]
	v_mfma_f32_16x16x32_bf16 v[18:21], v[192:195], v[216:219], v[18:21]
	v_mfma_f32_16x16x32_bf16 v[6:9], v[184:187], v[224:227], v[6:9]
	v_mfma_f32_16x16x32_bf16 v[2:5], v[192:195], v[224:227], v[2:5]
	s_setprio 0
	s_barrier
	s_add_i32 s47, 0, 0x18000
	v_add_u32_e32 v138, s47, v154
	s_add_i32 s68, 0, 0x1c000
	ds_read_b128 v[148:151], v138
	ds_read_b128 v[168:171], v138 offset:1024
	ds_read_b128 v[172:175], v138 offset:2048
	ds_read_b128 v[176:179], v138 offset:3072
	v_add_u32_e32 v138, s68, v154
	ds_read_b128 v[180:183], v138
	ds_read_b128 v[184:187], v138 offset:1024
	ds_read_b128 v[188:191], v138 offset:2048
	ds_read_b128 v[192:195], v138 offset:3072
	s_add_u32 s42, s42, s10
	s_addc_u32 s43, s43, s11
	s_mov_b32 m0, s66
	v_lshl_add_u64 v[238:239], s[42:43], 0, v[130:131]
	ds_read_b128 v[196:199], v161 offset:32768
	ds_read_b128 v[200:203], v161 offset:33792
	ds_read_b128 v[204:207], v161 offset:34816
	ds_read_b128 v[208:211], v161 offset:35840
	ds_read_b128 v[212:215], v161 offset:36864
	ds_read_b128 v[216:219], v161 offset:37888
	ds_read_b128 v[220:223], v161 offset:38912
	ds_read_b128 v[224:227], v161 offset:39936
	global_load_lds_dwordx4 v[238:239], off
	s_mov_b32 m0, s67
	v_lshl_add_u64 v[238:239], s[42:43], 0, v[134:135]
	global_load_lds_dwordx4 v[238:239], off
	s_waitcnt vmcnt(8) lgkmcnt(0)
	s_barrier
	s_setprio 1
	v_mfma_f32_16x16x32_bf16 v[126:129], v[148:151], v[196:199], v[126:129]
	v_mfma_f32_16x16x32_bf16 v[122:125], v[172:175], v[196:199], v[122:125]
	v_mfma_f32_16x16x32_bf16 v[110:113], v[148:151], v[204:207], v[110:113]
	v_mfma_f32_16x16x32_bf16 v[106:109], v[172:175], v[204:207], v[106:109]
	v_mfma_f32_16x16x32_bf16 v[94:97], v[148:151], v[212:215], v[94:97]
	v_mfma_f32_16x16x32_bf16 v[90:93], v[172:175], v[212:215], v[90:93]
	v_mfma_f32_16x16x32_bf16 v[78:81], v[148:151], v[220:223], v[78:81]
	v_mfma_f32_16x16x32_bf16 v[74:77], v[172:175], v[220:223], v[74:77]
	v_mfma_f32_16x16x32_bf16 v[126:129], v[168:171], v[200:203], v[126:129]
	v_mfma_f32_16x16x32_bf16 v[122:125], v[176:179], v[200:203], v[122:125]
	v_mfma_f32_16x16x32_bf16 v[110:113], v[168:171], v[208:211], v[110:113]
	v_mfma_f32_16x16x32_bf16 v[106:109], v[176:179], v[208:211], v[106:109]
	v_mfma_f32_16x16x32_bf16 v[94:97], v[168:171], v[216:219], v[94:97]
	v_mfma_f32_16x16x32_bf16 v[90:93], v[176:179], v[216:219], v[90:93]
	v_mfma_f32_16x16x32_bf16 v[78:81], v[168:171], v[224:227], v[78:81]
	v_mfma_f32_16x16x32_bf16 v[74:77], v[176:179], v[224:227], v[74:77]
	v_mfma_f32_16x16x32_bf16 v[118:121], v[180:183], v[196:199], v[118:121]
	v_mfma_f32_16x16x32_bf16 v[114:117], v[188:191], v[196:199], v[114:117]
	v_mfma_f32_16x16x32_bf16 v[102:105], v[180:183], v[204:207], v[102:105]
	v_mfma_f32_16x16x32_bf16 v[98:101], v[188:191], v[204:207], v[98:101]
	v_mfma_f32_16x16x32_bf16 v[86:89], v[180:183], v[212:215], v[86:89]
	v_mfma_f32_16x16x32_bf16 v[82:85], v[188:191], v[212:215], v[82:85]
	v_mfma_f32_16x16x32_bf16 v[70:73], v[180:183], v[220:223], v[70:73]
	v_mfma_f32_16x16x32_bf16 v[66:69], v[188:191], v[220:223], v[66:69]
	v_mfma_f32_16x16x32_bf16 v[118:121], v[184:187], v[200:203], v[118:121]
	v_mfma_f32_16x16x32_bf16 v[114:117], v[192:195], v[200:203], v[114:117]
	v_mfma_f32_16x16x32_bf16 v[102:105], v[184:187], v[208:211], v[102:105]
	v_mfma_f32_16x16x32_bf16 v[98:101], v[192:195], v[208:211], v[98:101]
	v_mfma_f32_16x16x32_bf16 v[86:89], v[184:187], v[216:219], v[86:89]
	v_mfma_f32_16x16x32_bf16 v[82:85], v[192:195], v[216:219], v[82:85]
	v_mfma_f32_16x16x32_bf16 v[70:73], v[184:187], v[224:227], v[70:73]
	v_mfma_f32_16x16x32_bf16 v[66:69], v[192:195], v[224:227], v[66:69]
	s_setprio 0
	s_barrier
; #define PG8_STAGE(bufoff, gbase, voff) do { _Pragma("unroll") for (int _i = 0; _i < 2; ++_i) \
;         __builtin_amdgcn_global_load_lds((const unsigned*)((const char*)(gbase) + (voff)[_i]), (PG8_LAS unsigned*)(lds + (bufoff) + ldsw + _i * 8192), 16, 0, 0); } while (0)
; #define PG8_LDA(dst, b, h) do { _Pragma("unroll") for (int m = 0; m < 4; ++m) _Pragma("unroll") for (int k = 0; k < 2; ++k) dst[m][k] = *(const PG8_LAS bf16x8*)(lds + PG8_SA(b, h) + aoff + m * 2048 + k * 1024); } while (0)
; #define PG8_MMA(ai, bj, At, Bt) do { __builtin_amdgcn_s_setprio(1); _Pragma("unroll") for (int m = 0; m < 4; ++m) _Pragma("unroll") for (int n = 0; n < 2; ++n) _Pragma("unroll") for (int k = 0; k < 2; ++k) \
;         acc[ai][bj][m][n] = __builtin_amdgcn_mfma_f32_16x16x32_bf16(Bt[n][k], At[m][k], acc[ai][bj][m][n], 0, 0, 0); __builtin_amdgcn_s_setprio(0); } while (0)
; #define PG8_WAIT_V(n) asm volatile("s_waitcnt vmcnt(" #n ")" ::: "memory")
; #define PG8_WAIT_L(n) asm volatile("s_waitcnt lgkmcnt(" #n ")" ::: "memory")
; #define PG8_BAR __builtin_amdgcn_s_barrier()
; #define PG8_SCHED __builtin_amdgcn_sched_barrier(0)
; template <class Epi, class Sched, bool ALIGN_EPI = false, bool SP2 = false>
; __device__ __forceinline__ void gemm_phase(PG8_LAS unsigned char* lds, const Gemm g, const Sched& S, const Epi& E) {
;     ...
;             PG8_LDA(At, 1, 1); PG8_STAGE(PG8_SB(1, 0), b3, voffB); PG8_STAGE(PG8_SB(1, 1), b3 + hstep, voffB); PG8_STAGE(PG8_SA(1, 0), a3, voffA);
;             PG8_WAIT_V(8); PG8_WAIT_L(0); PG8_BAR; PG8_MMA(1, 0, At, B0); PG8_MMA(1, 1, At, B1); PG8_BAR; PG8_SCHED;
	s_add_i32 s42, s47, s55
	v_lshl_add_u64 v[152:153], v[152:153], 0, s[30:31]
	s_mov_b32 m0, s42
	ds_read_b128 v[196:199], v161 offset:49152
	ds_read_b128 v[200:203], v161 offset:50176
	ds_read_b128 v[204:207], v161 offset:51200
	ds_read_b128 v[208:211], v161 offset:52224
	ds_read_b128 v[212:215], v161 offset:53248
	ds_read_b128 v[216:219], v161 offset:54272
	ds_read_b128 v[220:223], v161 offset:55296
	ds_read_b128 v[224:227], v161 offset:56320
	global_load_lds_dwordx4 v[152:153], off
	v_lshl_add_u64 v[152:153], v[228:229], 0, s[30:31]
	s_add_i32 m0, s42, 0x2000
	s_add_i32 s42, s68, s55
	global_load_lds_dwordx4 v[152:153], off
	s_mov_b32 m0, s42
	v_lshl_add_u64 v[152:153], v[230:231], 0, s[30:31]
	global_load_lds_dwordx4 v[152:153], off
	s_add_i32 m0, s42, 0x2000
	v_lshl_add_u64 v[152:153], v[232:233], 0, s[30:31]
	global_load_lds_dwordx4 v[152:153], off
	s_mov_b32 m0, s89
	v_lshl_add_u64 v[152:153], v[234:235], 0, s[30:31]
	global_load_lds_dwordx4 v[152:153], off
	s_mov_b32 m0, s90
	v_lshl_add_u64 v[152:153], v[236:237], 0, s[30:31]
	global_load_lds_dwordx4 v[152:153], off
	s_waitcnt vmcnt(8) lgkmcnt(0)
	s_barrier
	s_setprio 1
	v_mfma_f32_16x16x32_bf16 v[62:65], v[148:151], v[196:199], v[62:65]
	v_mfma_f32_16x16x32_bf16 v[58:61], v[172:175], v[196:199], v[58:61]
	v_mfma_f32_16x16x32_bf16 v[46:49], v[148:151], v[204:207], v[46:49]
	v_mfma_f32_16x16x32_bf16 v[42:45], v[172:175], v[204:207], v[42:45]
	v_mfma_f32_16x16x32_bf16 v[30:33], v[148:151], v[212:215], v[30:33]
	v_mfma_f32_16x16x32_bf16 v[26:29], v[172:175], v[212:215], v[26:29]
	v_mfma_f32_16x16x32_bf16 v[14:17], v[148:151], v[220:223], v[14:17]
	v_mfma_f32_16x16x32_bf16 v[10:13], v[172:175], v[220:223], v[10:13]
	v_mfma_f32_16x16x32_bf16 v[62:65], v[168:171], v[200:203], v[62:65]
	v_mfma_f32_16x16x32_bf16 v[58:61], v[176:179], v[200:203], v[58:61]
	v_mfma_f32_16x16x32_bf16 v[46:49], v[168:171], v[208:211], v[46:49]
	v_mfma_f32_16x16x32_bf16 v[42:45], v[176:179], v[208:211], v[42:45]
	v_mfma_f32_16x16x32_bf16 v[30:33], v[168:171], v[216:219], v[30:33]
	v_mfma_f32_16x16x32_bf16 v[26:29], v[176:179], v[216:219], v[26:29]
	v_mfma_f32_16x16x32_bf16 v[14:17], v[168:171], v[224:227], v[14:17]
	v_mfma_f32_16x16x32_bf16 v[10:13], v[176:179], v[224:227], v[10:13]
	v_mfma_f32_16x16x32_bf16 v[54:57], v[180:183], v[196:199], v[54:57]
	v_mfma_f32_16x16x32_bf16 v[50:53], v[188:191], v[196:199], v[50:53]
	v_mfma_f32_16x16x32_bf16 v[38:41], v[180:183], v[204:207], v[38:41]
	v_mfma_f32_16x16x32_bf16 v[34:37], v[188:191], v[204:207], v[34:37]
	v_mfma_f32_16x16x32_bf16 v[22:25], v[180:183], v[212:215], v[22:25]
	v_mfma_f32_16x16x32_bf16 v[18:21], v[188:191], v[212:215], v[18:21]
	v_mfma_f32_16x16x32_bf16 v[6:9], v[180:183], v[220:223], v[6:9]
	v_mfma_f32_16x16x32_bf16 v[2:5], v[188:191], v[220:223], v[2:5]
	v_mfma_f32_16x16x32_bf16 v[54:57], v[184:187], v[200:203], v[54:57]
	v_mfma_f32_16x16x32_bf16 v[50:53], v[192:195], v[200:203], v[50:53]
	v_mfma_f32_16x16x32_bf16 v[38:41], v[184:187], v[208:211], v[38:41]
	v_mfma_f32_16x16x32_bf16 v[34:37], v[192:195], v[208:211], v[34:37]
	v_mfma_f32_16x16x32_bf16 v[22:25], v[184:187], v[216:219], v[22:25]
	v_mfma_f32_16x16x32_bf16 v[18:21], v[192:195], v[216:219], v[18:21]
	v_mfma_f32_16x16x32_bf16 v[6:9], v[184:187], v[224:227], v[6:9]
	v_mfma_f32_16x16x32_bf16 v[2:5], v[192:195], v[224:227], v[2:5]
	s_setprio 0
	s_barrier
	s_add_u32 s0, s0, 0x100
	s_addc_u32 vcc_lo, vcc_lo, 0
	s_add_u32 s6, s6, 0x100
	s_addc_u32 s7, s7, 0
	s_cmp_ge_i32 s46, s91
	s_mov_b32 s42, s46
	s_cbranch_scc0 .LBB0_121

; #define PG8_STAGE(bufoff, gbase, voff) do { _Pragma("unroll") for (int _i = 0; _i < 2; ++_i) \
;         __builtin_amdgcn_global_load_lds((const unsigned*)((const char*)(gbase) + (voff)[_i]), (PG8_LAS unsigned*)(lds + (bufoff) + ldsw + _i * 8192), 16, 0, 0); } while (0)
; #define PG8_LDA(dst, b, h) do { _Pragma("unroll") for (int m = 0; m < 4; ++m) _Pragma("unroll") for (int k = 0; k < 2; ++k) dst[m][k] = *(const PG8_LAS bf16x8*)(lds + PG8_SA(b, h) + aoff + m * 2048 + k * 1024); } while (0)
; #define PG8_LDB(dst, b, h) do { _Pragma("unroll") for (int n = 0; n < 2; ++n) _Pragma("unroll") for (int k = 0; k < 2; ++k) dst[n][k] = *(const PG8_LAS bf16x8*)(lds + PG8_SB(b, h) + boff + n * 2048 + k * 1024); } while (0)
; #define PG8_MMA(ai, bj, At, Bt) do { __builtin_amdgcn_s_setprio(1); _Pragma("unroll") for (int m = 0; m < 4; ++m) _Pragma("unroll") for (int n = 0; n < 2; ++n) _Pragma("unroll") for (int k = 0; k < 2; ++k) \
;         acc[ai][bj][m][n] = __builtin_amdgcn_mfma_f32_16x16x32_bf16(Bt[n][k], At[m][k], acc[ai][bj][m][n], 0, 0, 0); __builtin_amdgcn_s_setprio(0); } while (0)
; #define PG8_WAIT_V(n) asm volatile("s_waitcnt vmcnt(" #n ")" ::: "memory")
; #define PG8_WAIT_L(n) asm volatile("s_waitcnt lgkmcnt(" #n ")" ::: "memory")
; #define PG8_BAR __builtin_amdgcn_s_barrier()
; #define PG8_SCHED __builtin_amdgcn_sched_barrier(0)
; template <class Epi, class Sched, bool ALIGN_EPI = false, bool SP2 = false>
; __device__ __forceinline__ void gemm_phase(PG8_LAS unsigned char* lds, const Gemm g, const Sched& S, const Epi& E) {
;     ...
;             const bool last = (t == nt - 2);
;             const char* a1 = cA + (size_t)(t + 1) * kstep;
;             const char* a2 = last ? nA : cA + (size_t)(t + 2) * kstep; const char* b2 = last ? nB : cB + (size_t)(t + 2) * kstep;
;             const char* a3 = a2 + kstep; const char* b3 = b2 + kstep;
;             if (last && has_next) S.a_ready(nxt);
;             if constexpr (SP2) {
;             PG8_LDB(B0, 0, 0); PG8_LDB(B1, 0, 1); PG8_SCHED; PG8_LDA(At, 0, 0); PG8_STAGE(PG8_SA(1, 1), a1 + hstep, voffA);
;             PG8_WAIT_V(8); PG8_WAIT_L(0); PG8_BAR; PG8_MMA(0, 0, At, B0); PG8_MMA(0, 1, At, B1); PG8_BAR; PG8_SCHED;
;             PG8_LDA(At, 0, 1); PG8_STAGE(PG8_SB(0, 0), b2, voffB); PG8_STAGE(PG8_SB(0, 1), b2 + hstep, voffB); PG8_STAGE(PG8_SA(0, 0), a2, voffA);
.LBB0_497:
	ds_read_b128 v[146:149], v152
	ds_read_b128 v[156:159], v152 offset:1024
	ds_read_b128 v[160:163], v152 offset:2048
	ds_read_b128 v[164:167], v152 offset:3072
	ds_read_b128 v[168:171], v153
	ds_read_b128 v[172:175], v153 offset:1024
	ds_read_b128 v[176:179], v153 offset:2048
	ds_read_b128 v[180:183], v153 offset:3072
	s_add_i32 s60, s34, 2
	s_add_u32 s61, s30, 0x80
	s_addc_u32 s35, s31, 0
	s_cmp_eq_u32 s44, s34
	s_cselect_b32 s34, s6, s61
	s_cselect_b32 s35, s7, s35
	s_cselect_b32 s63, s29, s59
	s_cselect_b32 s62, s28, s58
	v_lshl_add_u64 v[216:217], s[30:31], 0, v[140:141]
	s_add_i32 m0, s39, 0xc000
	ds_read_b128 v[184:187], v154
	ds_read_b128 v[188:191], v154 offset:1024
	ds_read_b128 v[192:195], v154 offset:2048
	ds_read_b128 v[196:199], v154 offset:3072
	ds_read_b128 v[200:203], v154 offset:4096
	ds_read_b128 v[204:207], v154 offset:5120
	ds_read_b128 v[208:211], v154 offset:6144
	ds_read_b128 v[212:215], v154 offset:7168
	global_load_lds_dwordx4 v[216:217], off
	s_add_i32 m0, s39, 0xe000
	v_lshl_add_u64 v[216:217], s[30:31], 0, v[138:139]
	global_load_lds_dwordx4 v[216:217], off
	s_waitcnt vmcnt(8) lgkmcnt(0)
	s_barrier
	s_setprio 1
	v_mfma_f32_16x16x32_bf16 v[126:129], v[146:149], v[184:187], v[126:129]
	v_mfma_f32_16x16x32_bf16 v[122:125], v[160:163], v[184:187], v[122:125]
	v_mfma_f32_16x16x32_bf16 v[110:113], v[146:149], v[192:195], v[110:113]
	v_mfma_f32_16x16x32_bf16 v[106:109], v[160:163], v[192:195], v[106:109]
	v_mfma_f32_16x16x32_bf16 v[94:97], v[146:149], v[200:203], v[94:97]
	v_mfma_f32_16x16x32_bf16 v[90:93], v[160:163], v[200:203], v[90:93]
	v_mfma_f32_16x16x32_bf16 v[78:81], v[146:149], v[208:211], v[78:81]
	v_mfma_f32_16x16x32_bf16 v[74:77], v[160:163], v[208:211], v[74:77]
	v_mfma_f32_16x16x32_bf16 v[126:129], v[156:159], v[188:191], v[126:129]
	v_mfma_f32_16x16x32_bf16 v[122:125], v[164:167], v[188:191], v[122:125]
	v_mfma_f32_16x16x32_bf16 v[110:113], v[156:159], v[196:199], v[110:113]
	v_mfma_f32_16x16x32_bf16 v[106:109], v[164:167], v[196:199], v[106:109]
	v_mfma_f32_16x16x32_bf16 v[94:97], v[156:159], v[204:207], v[94:97]
	v_mfma_f32_16x16x32_bf16 v[90:93], v[164:167], v[204:207], v[90:93]
	v_mfma_f32_16x16x32_bf16 v[78:81], v[156:159], v[212:215], v[78:81]
	v_mfma_f32_16x16x32_bf16 v[74:77], v[164:167], v[212:215], v[74:77]
	v_mfma_f32_16x16x32_bf16 v[118:121], v[168:171], v[184:187], v[118:121]
	v_mfma_f32_16x16x32_bf16 v[114:117], v[176:179], v[184:187], v[114:117]
	v_mfma_f32_16x16x32_bf16 v[102:105], v[168:171], v[192:195], v[102:105]
	v_mfma_f32_16x16x32_bf16 v[98:101], v[176:179], v[192:195], v[98:101]
	v_mfma_f32_16x16x32_bf16 v[86:89], v[168:171], v[200:203], v[86:89]
	v_mfma_f32_16x16x32_bf16 v[82:85], v[176:179], v[200:203], v[82:85]
	v_mfma_f32_16x16x32_bf16 v[70:73], v[168:171], v[208:211], v[70:73]
	v_mfma_f32_16x16x32_bf16 v[66:69], v[176:179], v[208:211], v[66:69]
	v_mfma_f32_16x16x32_bf16 v[118:121], v[172:175], v[188:191], v[118:121]
	v_mfma_f32_16x16x32_bf16 v[114:117], v[180:183], v[188:191], v[114:117]
	v_mfma_f32_16x16x32_bf16 v[102:105], v[172:175], v[196:199], v[102:105]
	v_mfma_f32_16x16x32_bf16 v[98:101], v[180:183], v[196:199], v[98:101]
	v_mfma_f32_16x16x32_bf16 v[86:89], v[172:175], v[204:207], v[86:89]
	v_mfma_f32_16x16x32_bf16 v[82:85], v[180:183], v[204:207], v[82:85]
	v_mfma_f32_16x16x32_bf16 v[70:73], v[172:175], v[212:215], v[70:73]
	v_mfma_f32_16x16x32_bf16 v[66:69], v[180:183], v[212:215], v[66:69]
	s_setprio 0
	s_barrier
	s_add_i32 s61, s54, s38
	v_lshl_add_u64 v[216:217], s[62:63], 0, v[132:133]
	s_mov_b32 m0, s61
	ds_read_b128 v[184:187], v154 offset:16384
	ds_read_b128 v[188:191], v154 offset:17408
	ds_read_b128 v[192:195], v154 offset:18432
	ds_read_b128 v[196:199], v154 offset:19456
	ds_read_b128 v[200:203], v154 offset:20480
	ds_read_b128 v[204:207], v154 offset:21504
	ds_read_b128 v[208:211], v154 offset:22528
	ds_read_b128 v[212:215], v154 offset:23552
	global_load_lds_dwordx4 v[216:217], off
	s_add_i32 m0, s61, 0x2000
	v_lshl_add_u64 v[218:219], s[62:63], 0, v[136:137]
	s_add_u32 s62, s62, s12
	s_addc_u32 s63, s63, s13
	s_add_i32 s61, s55, s38
	global_load_lds_dwordx4 v[218:219], off
	v_lshl_add_u64 v[220:221], s[62:63], 0, v[132:133]
	s_mov_b32 m0, s61
	v_lshl_add_u64 v[222:223], s[62:63], 0, v[136:137]
	global_load_lds_dwordx4 v[220:221], off
	s_add_i32 m0, s61, 0x2000
	v_lshl_add_u64 v[224:225], s[34:35], 0, v[130:131]
	global_load_lds_dwordx4 v[222:223], off
	s_mov_b32 m0, s39
	v_lshl_add_u64 v[226:227], s[34:35], 0, v[134:135]
	global_load_lds_dwordx4 v[224:225], off
	s_mov_b32 m0, s40
	s_nop 0
	global_load_lds_dwordx4 v[226:227], off
	s_waitcnt vmcnt(8) lgkmcnt(0)
	s_barrier
; #define PG8_STAGE(bufoff, gbase, voff) do { _Pragma("unroll") for (int _i = 0; _i < 2; ++_i) \
;         __builtin_amdgcn_global_load_lds((const unsigned*)((const char*)(gbase) + (voff)[_i]), (PG8_LAS unsigned*)(lds + (bufoff) + ldsw + _i * 8192), 16, 0, 0); } while (0)
; #define PG8_LDA(dst, b, h) do { _Pragma("unroll") for (int m = 0; m < 4; ++m) _Pragma("unroll") for (int k = 0; k < 2; ++k) dst[m][k] = *(const PG8_LAS bf16x8*)(lds + PG8_SA(b, h) + aoff + m * 2048 + k * 1024); } while (0)
; #define PG8_LDB(dst, b, h) do { _Pragma("unroll") for (int n = 0; n < 2; ++n) _Pragma("unroll") for (int k = 0; k < 2; ++k) dst[n][k] = *(const PG8_LAS bf16x8*)(lds + PG8_SB(b, h) + boff + n * 2048 + k * 1024); } while (0)
; #define PG8_MMA(ai, bj, At, Bt) do { __builtin_amdgcn_s_setprio(1); _Pragma("unroll") for (int m = 0; m < 4; ++m) _Pragma("unroll") for (int n = 0; n < 2; ++n) _Pragma("unroll") for (int k = 0; k < 2; ++k) \
;         acc[ai][bj][m][n] = __builtin_amdgcn_mfma_f32_16x16x32_bf16(Bt[n][k], At[m][k], acc[ai][bj][m][n], 0, 0, 0); __builtin_amdgcn_s_setprio(0); } while (0)
; #define PG8_WAIT_V(n) asm volatile("s_waitcnt vmcnt(" #n ")" ::: "memory")
; #define PG8_WAIT_L(n) asm volatile("s_waitcnt lgkmcnt(" #n ")" ::: "memory")
; #define PG8_BAR __builtin_amdgcn_s_barrier()
; #define PG8_SCHED __builtin_amdgcn_sched_barrier(0)
; template <class Epi, class Sched, bool ALIGN_EPI = false, bool SP2 = false>
; __device__ __forceinline__ void gemm_phase(PG8_LAS unsigned char* lds, const Gemm g, const Sched& S, const Epi& E) {
;     ...
;             PG8_WAIT_V(8); PG8_WAIT_L(0); PG8_BAR; PG8_MMA(1, 0, At, B0); PG8_MMA(1, 1, At, B1); PG8_BAR; PG8_SCHED;
;             PG8_LDB(B0, 1, 0); PG8_LDB(B1, 1, 1); PG8_SCHED; PG8_LDA(At, 1, 0); PG8_STAGE(PG8_SA(0, 1), a2 + hstep, voffA);
;             PG8_WAIT_V(8); PG8_WAIT_L(0); PG8_BAR; PG8_MMA(0, 0, At, B0); PG8_MMA(0, 1, At, B1); PG8_BAR; PG8_SCHED;
	s_setprio 1
	v_mfma_f32_16x16x32_bf16 v[62:65], v[146:149], v[184:187], v[62:65]
	v_mfma_f32_16x16x32_bf16 v[58:61], v[160:163], v[184:187], v[58:61]
	v_mfma_f32_16x16x32_bf16 v[46:49], v[146:149], v[192:195], v[46:49]
	v_mfma_f32_16x16x32_bf16 v[42:45], v[160:163], v[192:195], v[42:45]
	v_mfma_f32_16x16x32_bf16 v[30:33], v[146:149], v[200:203], v[30:33]
	v_mfma_f32_16x16x32_bf16 v[26:29], v[160:163], v[200:203], v[26:29]
	v_mfma_f32_16x16x32_bf16 v[14:17], v[146:149], v[208:211], v[14:17]
	v_mfma_f32_16x16x32_bf16 v[10:13], v[160:163], v[208:211], v[10:13]
	v_mfma_f32_16x16x32_bf16 v[62:65], v[156:159], v[188:191], v[62:65]
	v_mfma_f32_16x16x32_bf16 v[58:61], v[164:167], v[188:191], v[58:61]
	v_mfma_f32_16x16x32_bf16 v[46:49], v[156:159], v[196:199], v[46:49]
	v_mfma_f32_16x16x32_bf16 v[42:45], v[164:167], v[196:199], v[42:45]
	v_mfma_f32_16x16x32_bf16 v[30:33], v[156:159], v[204:207], v[30:33]
	v_mfma_f32_16x16x32_bf16 v[26:29], v[164:167], v[204:207], v[26:29]
	v_mfma_f32_16x16x32_bf16 v[14:17], v[156:159], v[212:215], v[14:17]
	v_mfma_f32_16x16x32_bf16 v[10:13], v[164:167], v[212:215], v[10:13]
	v_mfma_f32_16x16x32_bf16 v[54:57], v[168:171], v[184:187], v[54:57]
	v_mfma_f32_16x16x32_bf16 v[50:53], v[176:179], v[184:187], v[50:53]
	v_mfma_f32_16x16x32_bf16 v[38:41], v[168:171], v[192:195], v[38:41]
	v_mfma_f32_16x16x32_bf16 v[34:37], v[176:179], v[192:195], v[34:37]
	v_mfma_f32_16x16x32_bf16 v[22:25], v[168:171], v[200:203], v[22:25]
	v_mfma_f32_16x16x32_bf16 v[18:21], v[176:179], v[200:203], v[18:21]
	v_mfma_f32_16x16x32_bf16 v[6:9], v[168:171], v[208:211], v[6:9]
	v_mfma_f32_16x16x32_bf16 v[2:5], v[176:179], v[208:211], v[2:5]
	v_mfma_f32_16x16x32_bf16 v[54:57], v[172:175], v[188:191], v[54:57]
	v_mfma_f32_16x16x32_bf16 v[50:53], v[180:183], v[188:191], v[50:53]
	v_mfma_f32_16x16x32_bf16 v[38:41], v[172:175], v[196:199], v[38:41]
	v_mfma_f32_16x16x32_bf16 v[34:37], v[180:183], v[196:199], v[34:37]
	v_mfma_f32_16x16x32_bf16 v[22:25], v[172:175], v[204:207], v[22:25]
	v_mfma_f32_16x16x32_bf16 v[18:21], v[180:183], v[204:207], v[18:21]
	v_mfma_f32_16x16x32_bf16 v[6:9], v[172:175], v[212:215], v[6:9]
	v_mfma_f32_16x16x32_bf16 v[2:5], v[180:183], v[212:215], v[2:5]
	s_setprio 0
	s_barrier
	s_add_i32 s61, 0, 0x18000
	v_add_u32_e32 v155, s61, v150
	s_add_i32 s62, 0, 0x1c000
	ds_read_b128 v[146:149], v155
	ds_read_b128 v[156:159], v155 offset:1024
	ds_read_b128 v[160:163], v155 offset:2048
	ds_read_b128 v[164:167], v155 offset:3072
	v_add_u32_e32 v155, s62, v150
	ds_read_b128 v[168:171], v155
	ds_read_b128 v[172:175], v155 offset:1024
	ds_read_b128 v[176:179], v155 offset:2048
	ds_read_b128 v[180:183], v155 offset:3072
	s_add_u32 s34, s34, s12
	s_addc_u32 s35, s35, s13
	s_mov_b32 m0, s41
	v_lshl_add_u64 v[228:229], s[34:35], 0, v[130:131]
	ds_read_b128 v[184:187], v154 offset:32768
	ds_read_b128 v[188:191], v154 offset:33792
	ds_read_b128 v[192:195], v154 offset:34816
	ds_read_b128 v[196:199], v154 offset:35840
	ds_read_b128 v[200:203], v154 offset:36864
	ds_read_b128 v[204:207], v154 offset:37888
	ds_read_b128 v[208:211], v154 offset:38912
	ds_read_b128 v[212:215], v154 offset:39936
	global_load_lds_dwordx4 v[228:229], off
	s_mov_b32 m0, s42
	v_lshl_add_u64 v[228:229], s[34:35], 0, v[134:135]
	global_load_lds_dwordx4 v[228:229], off
	s_waitcnt vmcnt(8) lgkmcnt(0)
	s_barrier
	s_setprio 1
	v_mfma_f32_16x16x32_bf16 v[126:129], v[146:149], v[184:187], v[126:129]
	v_mfma_f32_16x16x32_bf16 v[122:125], v[160:163], v[184:187], v[122:125]
	v_mfma_f32_16x16x32_bf16 v[110:113], v[146:149], v[192:195], v[110:113]
	v_mfma_f32_16x16x32_bf16 v[106:109], v[160:163], v[192:195], v[106:109]
	v_mfma_f32_16x16x32_bf16 v[94:97], v[146:149], v[200:203], v[94:97]
	v_mfma_f32_16x16x32_bf16 v[90:93], v[160:163], v[200:203], v[90:93]
	v_mfma_f32_16x16x32_bf16 v[78:81], v[146:149], v[208:211], v[78:81]
	v_mfma_f32_16x16x32_bf16 v[74:77], v[160:163], v[208:211], v[74:77]
	v_mfma_f32_16x16x32_bf16 v[126:129], v[156:159], v[188:191], v[126:129]
	v_mfma_f32_16x16x32_bf16 v[122:125], v[164:167], v[188:191], v[122:125]
	v_mfma_f32_16x16x32_bf16 v[110:113], v[156:159], v[196:199], v[110:113]
	v_mfma_f32_16x16x32_bf16 v[106:109], v[164:167], v[196:199], v[106:109]
	v_mfma_f32_16x16x32_bf16 v[94:97], v[156:159], v[204:207], v[94:97]
	v_mfma_f32_16x16x32_bf16 v[90:93], v[164:167], v[204:207], v[90:93]
	v_mfma_f32_16x16x32_bf16 v[78:81], v[156:159], v[212:215], v[78:81]
	v_mfma_f32_16x16x32_bf16 v[74:77], v[164:167], v[212:215], v[74:77]
	v_mfma_f32_16x16x32_bf16 v[118:121], v[168:171], v[184:187], v[118:121]
	v_mfma_f32_16x16x32_bf16 v[114:117], v[176:179], v[184:187], v[114:117]
	v_mfma_f32_16x16x32_bf16 v[102:105], v[168:171], v[192:195], v[102:105]
	v_mfma_f32_16x16x32_bf16 v[98:101], v[176:179], v[192:195], v[98:101]
	v_mfma_f32_16x16x32_bf16 v[86:89], v[168:171], v[200:203], v[86:89]
	v_mfma_f32_16x16x32_bf16 v[82:85], v[176:179], v[200:203], v[82:85]
	v_mfma_f32_16x16x32_bf16 v[70:73], v[168:171], v[208:211], v[70:73]
	v_mfma_f32_16x16x32_bf16 v[66:69], v[176:179], v[208:211], v[66:69]
	v_mfma_f32_16x16x32_bf16 v[118:121], v[172:175], v[188:191], v[118:121]
	v_mfma_f32_16x16x32_bf16 v[114:117], v[180:183], v[188:191], v[114:117]
	v_mfma_f32_16x16x32_bf16 v[102:105], v[172:175], v[196:199], v[102:105]
	v_mfma_f32_16x16x32_bf16 v[98:101], v[180:183], v[196:199], v[98:101]
	v_mfma_f32_16x16x32_bf16 v[86:89], v[172:175], v[204:207], v[86:89]
	v_mfma_f32_16x16x32_bf16 v[82:85], v[180:183], v[204:207], v[82:85]
	v_mfma_f32_16x16x32_bf16 v[70:73], v[172:175], v[212:215], v[70:73]
	v_mfma_f32_16x16x32_bf16 v[66:69], v[180:183], v[212:215], v[66:69]
	s_setprio 0
	s_barrier
; #define PG8_STAGE(bufoff, gbase, voff) do { _Pragma("unroll") for (int _i = 0; _i < 2; ++_i) \
;         __builtin_amdgcn_global_load_lds((const unsigned*)((const char*)(gbase) + (voff)[_i]), (PG8_LAS unsigned*)(lds + (bufoff) + ldsw + _i * 8192), 16, 0, 0); } while (0)
; #define PG8_LDA(dst, b, h) do { _Pragma("unroll") for (int m = 0; m < 4; ++m) _Pragma("unroll") for (int k = 0; k < 2; ++k) dst[m][k] = *(const PG8_LAS bf16x8*)(lds + PG8_SA(b, h) + aoff + m * 2048 + k * 1024); } while (0)
; #define PG8_MMA(ai, bj, At, Bt) do { __builtin_amdgcn_s_setprio(1); _Pragma("unroll") for (int m = 0; m < 4; ++m) _Pragma("unroll") for (int n = 0; n < 2; ++n) _Pragma("unroll") for (int k = 0; k < 2; ++k) \
;         acc[ai][bj][m][n] = __builtin_amdgcn_mfma_f32_16x16x32_bf16(Bt[n][k], At[m][k], acc[ai][bj][m][n], 0, 0, 0); __builtin_amdgcn_s_setprio(0); } while (0)
; #define PG8_WAIT_V(n) asm volatile("s_waitcnt vmcnt(" #n ")" ::: "memory")
; #define PG8_WAIT_L(n) asm volatile("s_waitcnt lgkmcnt(" #n ")" ::: "memory")
; #define PG8_BAR __builtin_amdgcn_s_barrier()
; #define PG8_SCHED __builtin_amdgcn_sched_barrier(0)
; template <class Epi, class Sched, bool ALIGN_EPI = false, bool SP2 = false>
; __device__ __forceinline__ void gemm_phase(PG8_LAS unsigned char* lds, const Gemm g, const Sched& S, const Epi& E) {
;     ...
;             PG8_LDA(At, 1, 1); PG8_STAGE(PG8_SB(1, 0), b3, voffB); PG8_STAGE(PG8_SB(1, 1), b3 + hstep, voffB); PG8_STAGE(PG8_SA(1, 0), a3, voffA);
;             PG8_WAIT_V(8); PG8_WAIT_L(0); PG8_BAR; PG8_MMA(1, 0, At, B0); PG8_MMA(1, 1, At, B1); PG8_BAR; PG8_SCHED;
	s_add_i32 s34, s61, s38
	v_lshl_add_u64 v[216:217], v[216:217], 0, s[20:21]
	s_mov_b32 m0, s34
	ds_read_b128 v[184:187], v154 offset:49152
	ds_read_b128 v[188:191], v154 offset:50176
	ds_read_b128 v[192:195], v154 offset:51200
	ds_read_b128 v[196:199], v154 offset:52224
	ds_read_b128 v[200:203], v154 offset:53248
	ds_read_b128 v[204:207], v154 offset:54272
	ds_read_b128 v[208:211], v154 offset:55296
	ds_read_b128 v[212:215], v154 offset:56320
	global_load_lds_dwordx4 v[216:217], off
	v_lshl_add_u64 v[216:217], v[218:219], 0, s[20:21]
	s_add_i32 m0, s34, 0x2000
	s_add_i32 s34, s62, s38
	global_load_lds_dwordx4 v[216:217], off
	s_mov_b32 m0, s34
	v_lshl_add_u64 v[216:217], v[220:221], 0, s[20:21]
	global_load_lds_dwordx4 v[216:217], off
	s_add_i32 m0, s34, 0x2000
	v_lshl_add_u64 v[216:217], v[222:223], 0, s[20:21]
	global_load_lds_dwordx4 v[216:217], off
	s_mov_b32 m0, s46
	v_lshl_add_u64 v[216:217], v[224:225], 0, s[20:21]
	global_load_lds_dwordx4 v[216:217], off
	s_mov_b32 m0, s47
	v_lshl_add_u64 v[216:217], v[226:227], 0, s[20:21]
	global_load_lds_dwordx4 v[216:217], off
	s_waitcnt vmcnt(8) lgkmcnt(0)
	s_barrier
	s_setprio 1
	v_mfma_f32_16x16x32_bf16 v[62:65], v[146:149], v[184:187], v[62:65]
	v_mfma_f32_16x16x32_bf16 v[58:61], v[160:163], v[184:187], v[58:61]
	v_mfma_f32_16x16x32_bf16 v[46:49], v[146:149], v[192:195], v[46:49]
	v_mfma_f32_16x16x32_bf16 v[42:45], v[160:163], v[192:195], v[42:45]
	v_mfma_f32_16x16x32_bf16 v[30:33], v[146:149], v[200:203], v[30:33]
	v_mfma_f32_16x16x32_bf16 v[26:29], v[160:163], v[200:203], v[26:29]
	v_mfma_f32_16x16x32_bf16 v[14:17], v[146:149], v[208:211], v[14:17]
	v_mfma_f32_16x16x32_bf16 v[10:13], v[160:163], v[208:211], v[10:13]
	v_mfma_f32_16x16x32_bf16 v[62:65], v[156:159], v[188:191], v[62:65]
	v_mfma_f32_16x16x32_bf16 v[58:61], v[164:167], v[188:191], v[58:61]
	v_mfma_f32_16x16x32_bf16 v[46:49], v[156:159], v[196:199], v[46:49]
	v_mfma_f32_16x16x32_bf16 v[42:45], v[164:167], v[196:199], v[42:45]
	v_mfma_f32_16x16x32_bf16 v[30:33], v[156:159], v[204:207], v[30:33]
	v_mfma_f32_16x16x32_bf16 v[26:29], v[164:167], v[204:207], v[26:29]
	v_mfma_f32_16x16x32_bf16 v[14:17], v[156:159], v[212:215], v[14:17]
	v_mfma_f32_16x16x32_bf16 v[10:13], v[164:167], v[212:215], v[10:13]
	v_mfma_f32_16x16x32_bf16 v[54:57], v[168:171], v[184:187], v[54:57]
	v_mfma_f32_16x16x32_bf16 v[50:53], v[176:179], v[184:187], v[50:53]
	v_mfma_f32_16x16x32_bf16 v[38:41], v[168:171], v[192:195], v[38:41]
	v_mfma_f32_16x16x32_bf16 v[34:37], v[176:179], v[192:195], v[34:37]
	v_mfma_f32_16x16x32_bf16 v[22:25], v[168:171], v[200:203], v[22:25]
	v_mfma_f32_16x16x32_bf16 v[18:21], v[176:179], v[200:203], v[18:21]
	v_mfma_f32_16x16x32_bf16 v[6:9], v[168:171], v[208:211], v[6:9]
	v_mfma_f32_16x16x32_bf16 v[2:5], v[176:179], v[208:211], v[2:5]
	v_mfma_f32_16x16x32_bf16 v[54:57], v[172:175], v[188:191], v[54:57]
	v_mfma_f32_16x16x32_bf16 v[50:53], v[180:183], v[188:191], v[50:53]
	v_mfma_f32_16x16x32_bf16 v[38:41], v[172:175], v[196:199], v[38:41]
	v_mfma_f32_16x16x32_bf16 v[34:37], v[180:183], v[196:199], v[34:37]
	v_mfma_f32_16x16x32_bf16 v[22:25], v[172:175], v[204:207], v[22:25]
	v_mfma_f32_16x16x32_bf16 v[18:21], v[180:183], v[204:207], v[18:21]
	v_mfma_f32_16x16x32_bf16 v[6:9], v[172:175], v[212:215], v[6:9]
	v_mfma_f32_16x16x32_bf16 v[2:5], v[180:183], v[212:215], v[2:5]
	s_setprio 0
	s_barrier
	s_add_u32 s58, s58, 0x100
	s_addc_u32 s59, s59, 0
	s_add_u32 s30, s30, 0x100
	s_addc_u32 s31, s31, 0
	s_cmp_ge_i32 s60, s52
	s_mov_b32 s34, s60
	s_cbranch_scc0 .LBB0_497

; #define PG8_STAGE(bufoff, gbase, voff) do { _Pragma("unroll") for (int _i = 0; _i < 2; ++_i) \
;         __builtin_amdgcn_global_load_lds((const unsigned*)((const char*)(gbase) + (voff)[_i]), (PG8_LAS unsigned*)(lds + (bufoff) + ldsw + _i * 8192), 16, 0, 0); } while (0)
; #define PG8_LDA(dst, b, h) do { _Pragma("unroll") for (int m = 0; m < 4; ++m) _Pragma("unroll") for (int k = 0; k < 2; ++k) dst[m][k] = *(const PG8_LAS bf16x8*)(lds + PG8_SA(b, h) + aoff + m * 2048 + k * 1024); } while (0)
; #define PG8_LDB(dst, b, h) do { _Pragma("unroll") for (int n = 0; n < 2; ++n) _Pragma("unroll") for (int k = 0; k < 2; ++k) dst[n][k] = *(const PG8_LAS bf16x8*)(lds + PG8_SB(b, h) + boff + n * 2048 + k * 1024); } while (0)
; #define PG8_MMA(ai, bj, At, Bt) do { __builtin_amdgcn_s_setprio(1); _Pragma("unroll") for (int m = 0; m < 4; ++m) _Pragma("unroll") for (int n = 0; n < 2; ++n) _Pragma("unroll") for (int k = 0; k < 2; ++k) \
;         acc[ai][bj][m][n] = __builtin_amdgcn_mfma_f32_16x16x32_bf16(Bt[n][k], At[m][k], acc[ai][bj][m][n], 0, 0, 0); __builtin_amdgcn_s_setprio(0); } while (0)
; #define PG8_WAIT_V(n) asm volatile("s_waitcnt vmcnt(" #n ")" ::: "memory")
; #define PG8_WAIT_L(n) asm volatile("s_waitcnt lgkmcnt(" #n ")" ::: "memory")
; #define PG8_BAR __builtin_amdgcn_s_barrier()
; #define PG8_SCHED __builtin_amdgcn_sched_barrier(0)
; template <class Epi, class Sched, bool ALIGN_EPI = false, bool SP2 = false>
; __device__ __forceinline__ void gemm_phase(PG8_LAS unsigned char* lds, const Gemm g, const Sched& S, const Epi& E) {
;     ...
;             const bool last = (t == nt - 2);
;             const char* a1 = cA + (size_t)(t + 1) * kstep;
;             const char* a2 = last ? nA : cA + (size_t)(t + 2) * kstep; const char* b2 = last ? nB : cB + (size_t)(t + 2) * kstep;
;             const char* a3 = a2 + kstep; const char* b3 = b2 + kstep;
;             if (last && has_next) S.a_ready(nxt);
;             if constexpr (SP2) {
;             PG8_LDB(B0, 0, 0); PG8_LDB(B1, 0, 1); PG8_SCHED; PG8_LDA(At, 0, 0); PG8_STAGE(PG8_SA(1, 1), a1 + hstep, voffA);
;             PG8_WAIT_V(8); PG8_WAIT_L(0); PG8_BAR; PG8_MMA(0, 0, At, B0); PG8_MMA(0, 1, At, B1); PG8_BAR; PG8_SCHED;
;             PG8_LDA(At, 0, 1); PG8_STAGE(PG8_SB(0, 0), b2, voffB); PG8_STAGE(PG8_SB(0, 1), b2 + hstep, voffB); PG8_STAGE(PG8_SA(0, 0), a2, voffA);
.LBB0_582:
	ds_read_b128 v[152:155], v148
	ds_read_b128 v[156:159], v148 offset:1024
	ds_read_b128 v[160:163], v148 offset:2048
	ds_read_b128 v[164:167], v148 offset:3072
	ds_read_b128 v[168:171], v149
	ds_read_b128 v[172:175], v149 offset:1024
	ds_read_b128 v[176:179], v149 offset:2048
	ds_read_b128 v[180:183], v149 offset:3072
	s_add_i32 s60, s30, 2
	s_add_u32 s61, s28, 0x80
	s_addc_u32 s31, s29, 0
	s_cmp_eq_u32 s45, s30
	s_cselect_b32 s30, s6, s61
	s_cselect_b32 s31, s7, s31
	s_cselect_b32 s63, s25, s59
	s_cselect_b32 s62, s24, s58
	v_lshl_add_u64 v[216:217], s[28:29], 0, v[140:141]
	s_add_i32 m0, s0, 0xc000
	ds_read_b128 v[184:187], v150
	ds_read_b128 v[188:191], v150 offset:1024
	ds_read_b128 v[192:195], v150 offset:2048
	ds_read_b128 v[196:199], v150 offset:3072
	ds_read_b128 v[200:203], v150 offset:4096
	ds_read_b128 v[204:207], v150 offset:5120
	ds_read_b128 v[208:211], v150 offset:6144
	ds_read_b128 v[212:215], v150 offset:7168
	global_load_lds_dwordx4 v[216:217], off
	s_add_i32 m0, s0, 0xe000
	v_lshl_add_u64 v[216:217], s[28:29], 0, v[138:139]
	global_load_lds_dwordx4 v[216:217], off
	s_waitcnt vmcnt(8) lgkmcnt(0)
	s_barrier
	s_setprio 1
	v_mfma_f32_16x16x32_bf16 v[122:125], v[152:155], v[184:187], v[122:125]
	v_mfma_f32_16x16x32_bf16 v[126:129], v[160:163], v[184:187], v[126:129]
	v_mfma_f32_16x16x32_bf16 v[110:113], v[152:155], v[192:195], v[110:113]
	v_mfma_f32_16x16x32_bf16 v[106:109], v[160:163], v[192:195], v[106:109]
	v_mfma_f32_16x16x32_bf16 v[94:97], v[152:155], v[200:203], v[94:97]
	v_mfma_f32_16x16x32_bf16 v[90:93], v[160:163], v[200:203], v[90:93]
	v_mfma_f32_16x16x32_bf16 v[78:81], v[152:155], v[208:211], v[78:81]
	v_mfma_f32_16x16x32_bf16 v[74:77], v[160:163], v[208:211], v[74:77]
	v_mfma_f32_16x16x32_bf16 v[122:125], v[156:159], v[188:191], v[122:125]
	v_mfma_f32_16x16x32_bf16 v[126:129], v[164:167], v[188:191], v[126:129]
	v_mfma_f32_16x16x32_bf16 v[110:113], v[156:159], v[196:199], v[110:113]
	v_mfma_f32_16x16x32_bf16 v[106:109], v[164:167], v[196:199], v[106:109]
	v_mfma_f32_16x16x32_bf16 v[94:97], v[156:159], v[204:207], v[94:97]
	v_mfma_f32_16x16x32_bf16 v[90:93], v[164:167], v[204:207], v[90:93]
	v_mfma_f32_16x16x32_bf16 v[78:81], v[156:159], v[212:215], v[78:81]
	v_mfma_f32_16x16x32_bf16 v[74:77], v[164:167], v[212:215], v[74:77]
	v_mfma_f32_16x16x32_bf16 v[118:121], v[168:171], v[184:187], v[118:121]
	v_mfma_f32_16x16x32_bf16 v[114:117], v[176:179], v[184:187], v[114:117]
	v_mfma_f32_16x16x32_bf16 v[102:105], v[168:171], v[192:195], v[102:105]
	v_mfma_f32_16x16x32_bf16 v[98:101], v[176:179], v[192:195], v[98:101]
	v_mfma_f32_16x16x32_bf16 v[86:89], v[168:171], v[200:203], v[86:89]
	v_mfma_f32_16x16x32_bf16 v[82:85], v[176:179], v[200:203], v[82:85]
	v_mfma_f32_16x16x32_bf16 v[70:73], v[168:171], v[208:211], v[70:73]
	v_mfma_f32_16x16x32_bf16 v[66:69], v[176:179], v[208:211], v[66:69]
	v_mfma_f32_16x16x32_bf16 v[118:121], v[172:175], v[188:191], v[118:121]
	v_mfma_f32_16x16x32_bf16 v[114:117], v[180:183], v[188:191], v[114:117]
	v_mfma_f32_16x16x32_bf16 v[102:105], v[172:175], v[196:199], v[102:105]
	v_mfma_f32_16x16x32_bf16 v[98:101], v[180:183], v[196:199], v[98:101]
	v_mfma_f32_16x16x32_bf16 v[86:89], v[172:175], v[204:207], v[86:89]
	v_mfma_f32_16x16x32_bf16 v[82:85], v[180:183], v[204:207], v[82:85]
	v_mfma_f32_16x16x32_bf16 v[70:73], v[172:175], v[212:215], v[70:73]
	v_mfma_f32_16x16x32_bf16 v[66:69], v[180:183], v[212:215], v[66:69]
	s_setprio 0
	s_barrier
	s_add_i32 s61, s52, s38
	v_lshl_add_u64 v[216:217], s[62:63], 0, v[132:133]
	s_mov_b32 m0, s61
	ds_read_b128 v[184:187], v150 offset:16384
	ds_read_b128 v[188:191], v150 offset:17408
	ds_read_b128 v[192:195], v150 offset:18432
	ds_read_b128 v[196:199], v150 offset:19456
	ds_read_b128 v[200:203], v150 offset:20480
	ds_read_b128 v[204:207], v150 offset:21504
	ds_read_b128 v[208:211], v150 offset:22528
	ds_read_b128 v[212:215], v150 offset:23552
	global_load_lds_dwordx4 v[216:217], off
	s_add_i32 m0, s61, 0x2000
	v_lshl_add_u64 v[218:219], s[62:63], 0, v[136:137]
	s_add_u32 s62, s62, s10
	s_addc_u32 s63, s63, s11
	s_add_i32 s61, s53, s38
	global_load_lds_dwordx4 v[218:219], off
	v_lshl_add_u64 v[220:221], s[62:63], 0, v[132:133]
	s_mov_b32 m0, s61
	v_lshl_add_u64 v[222:223], s[62:63], 0, v[136:137]
	global_load_lds_dwordx4 v[220:221], off
	s_add_i32 m0, s61, 0x2000
	v_lshl_add_u64 v[224:225], s[30:31], 0, v[130:131]
	global_load_lds_dwordx4 v[222:223], off
	s_mov_b32 m0, s0
	v_lshl_add_u64 v[226:227], s[30:31], 0, v[134:135]
	global_load_lds_dwordx4 v[224:225], off
	s_mov_b32 m0, s1
	s_nop 0
	global_load_lds_dwordx4 v[226:227], off
	s_waitcnt vmcnt(8) lgkmcnt(0)
	s_barrier
; #define PG8_STAGE(bufoff, gbase, voff) do { _Pragma("unroll") for (int _i = 0; _i < 2; ++_i) \
;         __builtin_amdgcn_global_load_lds((const unsigned*)((const char*)(gbase) + (voff)[_i]), (PG8_LAS unsigned*)(lds + (bufoff) + ldsw + _i * 8192), 16, 0, 0); } while (0)
; #define PG8_LDA(dst, b, h) do { _Pragma("unroll") for (int m = 0; m < 4; ++m) _Pragma("unroll") for (int k = 0; k < 2; ++k) dst[m][k] = *(const PG8_LAS bf16x8*)(lds + PG8_SA(b, h) + aoff + m * 2048 + k * 1024); } while (0)
; #define PG8_LDB(dst, b, h) do { _Pragma("unroll") for (int n = 0; n < 2; ++n) _Pragma("unroll") for (int k = 0; k < 2; ++k) dst[n][k] = *(const PG8_LAS bf16x8*)(lds + PG8_SB(b, h) + boff + n * 2048 + k * 1024); } while (0)
; #define PG8_MMA(ai, bj, At, Bt) do { __builtin_amdgcn_s_setprio(1); _Pragma("unroll") for (int m = 0; m < 4; ++m) _Pragma("unroll") for (int n = 0; n < 2; ++n) _Pragma("unroll") for (int k = 0; k < 2; ++k) \
;         acc[ai][bj][m][n] = __builtin_amdgcn_mfma_f32_16x16x32_bf16(Bt[n][k], At[m][k], acc[ai][bj][m][n], 0, 0, 0); __builtin_amdgcn_s_setprio(0); } while (0)
; #define PG8_WAIT_V(n) asm volatile("s_waitcnt vmcnt(" #n ")" ::: "memory")
; #define PG8_WAIT_L(n) asm volatile("s_waitcnt lgkmcnt(" #n ")" ::: "memory")
; #define PG8_BAR __builtin_amdgcn_s_barrier()
; #define PG8_SCHED __builtin_amdgcn_sched_barrier(0)
; template <class Epi, class Sched, bool ALIGN_EPI = false, bool SP2 = false>
; __device__ __forceinline__ void gemm_phase(PG8_LAS unsigned char* lds, const Gemm g, const Sched& S, const Epi& E) {
;     ...
;             PG8_WAIT_V(8); PG8_WAIT_L(0); PG8_BAR; PG8_MMA(1, 0, At, B0); PG8_MMA(1, 1, At, B1); PG8_BAR; PG8_SCHED;
;             PG8_LDB(B0, 1, 0); PG8_LDB(B1, 1, 1); PG8_SCHED; PG8_LDA(At, 1, 0); PG8_STAGE(PG8_SA(0, 1), a2 + hstep, voffA);
;             PG8_WAIT_V(8); PG8_WAIT_L(0); PG8_BAR; PG8_MMA(0, 0, At, B0); PG8_MMA(0, 1, At, B1); PG8_BAR; PG8_SCHED;
	s_setprio 1
	v_mfma_f32_16x16x32_bf16 v[62:65], v[152:155], v[184:187], v[62:65]
	v_mfma_f32_16x16x32_bf16 v[58:61], v[160:163], v[184:187], v[58:61]
	v_mfma_f32_16x16x32_bf16 v[46:49], v[152:155], v[192:195], v[46:49]
	v_mfma_f32_16x16x32_bf16 v[42:45], v[160:163], v[192:195], v[42:45]
	v_mfma_f32_16x16x32_bf16 v[30:33], v[152:155], v[200:203], v[30:33]
	v_mfma_f32_16x16x32_bf16 v[26:29], v[160:163], v[200:203], v[26:29]
	v_mfma_f32_16x16x32_bf16 v[14:17], v[152:155], v[208:211], v[14:17]
	v_mfma_f32_16x16x32_bf16 v[10:13], v[160:163], v[208:211], v[10:13]
	v_mfma_f32_16x16x32_bf16 v[62:65], v[156:159], v[188:191], v[62:65]
	v_mfma_f32_16x16x32_bf16 v[58:61], v[164:167], v[188:191], v[58:61]
	v_mfma_f32_16x16x32_bf16 v[46:49], v[156:159], v[196:199], v[46:49]
	v_mfma_f32_16x16x32_bf16 v[42:45], v[164:167], v[196:199], v[42:45]
	v_mfma_f32_16x16x32_bf16 v[30:33], v[156:159], v[204:207], v[30:33]
	v_mfma_f32_16x16x32_bf16 v[26:29], v[164:167], v[204:207], v[26:29]
	v_mfma_f32_16x16x32_bf16 v[14:17], v[156:159], v[212:215], v[14:17]
	v_mfma_f32_16x16x32_bf16 v[10:13], v[164:167], v[212:215], v[10:13]
	v_mfma_f32_16x16x32_bf16 v[54:57], v[168:171], v[184:187], v[54:57]
	v_mfma_f32_16x16x32_bf16 v[50:53], v[176:179], v[184:187], v[50:53]
	v_mfma_f32_16x16x32_bf16 v[38:41], v[168:171], v[192:195], v[38:41]
	v_mfma_f32_16x16x32_bf16 v[34:37], v[176:179], v[192:195], v[34:37]
	v_mfma_f32_16x16x32_bf16 v[22:25], v[168:171], v[200:203], v[22:25]
	v_mfma_f32_16x16x32_bf16 v[18:21], v[176:179], v[200:203], v[18:21]
	v_mfma_f32_16x16x32_bf16 v[6:9], v[168:171], v[208:211], v[6:9]
	v_mfma_f32_16x16x32_bf16 v[2:5], v[176:179], v[208:211], v[2:5]
	v_mfma_f32_16x16x32_bf16 v[54:57], v[172:175], v[188:191], v[54:57]
	v_mfma_f32_16x16x32_bf16 v[50:53], v[180:183], v[188:191], v[50:53]
	v_mfma_f32_16x16x32_bf16 v[38:41], v[172:175], v[196:199], v[38:41]
	v_mfma_f32_16x16x32_bf16 v[34:37], v[180:183], v[196:199], v[34:37]
	v_mfma_f32_16x16x32_bf16 v[22:25], v[172:175], v[204:207], v[22:25]
	v_mfma_f32_16x16x32_bf16 v[18:21], v[180:183], v[204:207], v[18:21]
	v_mfma_f32_16x16x32_bf16 v[6:9], v[172:175], v[212:215], v[6:9]
	v_mfma_f32_16x16x32_bf16 v[2:5], v[180:183], v[212:215], v[2:5]
	s_setprio 0
	s_barrier
	s_add_i32 s61, 0, 0x18000
	v_add_u32_e32 v151, s61, v146
	s_add_i32 s62, 0, 0x1c000
	ds_read_b128 v[152:155], v151
	ds_read_b128 v[156:159], v151 offset:1024
	ds_read_b128 v[160:163], v151 offset:2048
	ds_read_b128 v[164:167], v151 offset:3072
	v_add_u32_e32 v151, s62, v146
	ds_read_b128 v[168:171], v151
	ds_read_b128 v[172:175], v151 offset:1024
	ds_read_b128 v[176:179], v151 offset:2048
	ds_read_b128 v[180:183], v151 offset:3072
	s_add_u32 s30, s30, s10
	s_addc_u32 s31, s31, s11
	s_mov_b32 m0, s39
	v_lshl_add_u64 v[228:229], s[30:31], 0, v[130:131]
	ds_read_b128 v[184:187], v150 offset:32768
	ds_read_b128 v[188:191], v150 offset:33792
	ds_read_b128 v[192:195], v150 offset:34816
	ds_read_b128 v[196:199], v150 offset:35840
	ds_read_b128 v[200:203], v150 offset:36864
	ds_read_b128 v[204:207], v150 offset:37888
	ds_read_b128 v[208:211], v150 offset:38912
	ds_read_b128 v[212:215], v150 offset:39936
	global_load_lds_dwordx4 v[228:229], off
	s_mov_b32 m0, s40
	v_lshl_add_u64 v[228:229], s[30:31], 0, v[134:135]
	global_load_lds_dwordx4 v[228:229], off
	s_waitcnt vmcnt(8) lgkmcnt(0)
	s_barrier
	s_setprio 1
	v_mfma_f32_16x16x32_bf16 v[122:125], v[152:155], v[184:187], v[122:125]
	v_mfma_f32_16x16x32_bf16 v[126:129], v[160:163], v[184:187], v[126:129]
	v_mfma_f32_16x16x32_bf16 v[110:113], v[152:155], v[192:195], v[110:113]
	v_mfma_f32_16x16x32_bf16 v[106:109], v[160:163], v[192:195], v[106:109]
	v_mfma_f32_16x16x32_bf16 v[94:97], v[152:155], v[200:203], v[94:97]
	v_mfma_f32_16x16x32_bf16 v[90:93], v[160:163], v[200:203], v[90:93]
	v_mfma_f32_16x16x32_bf16 v[78:81], v[152:155], v[208:211], v[78:81]
	v_mfma_f32_16x16x32_bf16 v[74:77], v[160:163], v[208:211], v[74:77]
	v_mfma_f32_16x16x32_bf16 v[122:125], v[156:159], v[188:191], v[122:125]
	v_mfma_f32_16x16x32_bf16 v[126:129], v[164:167], v[188:191], v[126:129]
	v_mfma_f32_16x16x32_bf16 v[110:113], v[156:159], v[196:199], v[110:113]
	v_mfma_f32_16x16x32_bf16 v[106:109], v[164:167], v[196:199], v[106:109]
	v_mfma_f32_16x16x32_bf16 v[94:97], v[156:159], v[204:207], v[94:97]
	v_mfma_f32_16x16x32_bf16 v[90:93], v[164:167], v[204:207], v[90:93]
	v_mfma_f32_16x16x32_bf16 v[78:81], v[156:159], v[212:215], v[78:81]
	v_mfma_f32_16x16x32_bf16 v[74:77], v[164:167], v[212:215], v[74:77]
	v_mfma_f32_16x16x32_bf16 v[118:121], v[168:171], v[184:187], v[118:121]
	v_mfma_f32_16x16x32_bf16 v[114:117], v[176:179], v[184:187], v[114:117]
	v_mfma_f32_16x16x32_bf16 v[102:105], v[168:171], v[192:195], v[102:105]
	v_mfma_f32_16x16x32_bf16 v[98:101], v[176:179], v[192:195], v[98:101]
	v_mfma_f32_16x16x32_bf16 v[86:89], v[168:171], v[200:203], v[86:89]
	v_mfma_f32_16x16x32_bf16 v[82:85], v[176:179], v[200:203], v[82:85]
	v_mfma_f32_16x16x32_bf16 v[70:73], v[168:171], v[208:211], v[70:73]
	v_mfma_f32_16x16x32_bf16 v[66:69], v[176:179], v[208:211], v[66:69]
	v_mfma_f32_16x16x32_bf16 v[118:121], v[172:175], v[188:191], v[118:121]
	v_mfma_f32_16x16x32_bf16 v[114:117], v[180:183], v[188:191], v[114:117]
	v_mfma_f32_16x16x32_bf16 v[102:105], v[172:175], v[196:199], v[102:105]
	v_mfma_f32_16x16x32_bf16 v[98:101], v[180:183], v[196:199], v[98:101]
	v_mfma_f32_16x16x32_bf16 v[86:89], v[172:175], v[204:207], v[86:89]
	v_mfma_f32_16x16x32_bf16 v[82:85], v[180:183], v[204:207], v[82:85]
	v_mfma_f32_16x16x32_bf16 v[70:73], v[172:175], v[212:215], v[70:73]
	v_mfma_f32_16x16x32_bf16 v[66:69], v[180:183], v[212:215], v[66:69]
	s_setprio 0
	s_barrier
; #define PG8_STAGE(bufoff, gbase, voff) do { _Pragma("unroll") for (int _i = 0; _i < 2; ++_i) \
;         __builtin_amdgcn_global_load_lds((const unsigned*)((const char*)(gbase) + (voff)[_i]), (PG8_LAS unsigned*)(lds + (bufoff) + ldsw + _i * 8192), 16, 0, 0); } while (0)
; #define PG8_LDA(dst, b, h) do { _Pragma("unroll") for (int m = 0; m < 4; ++m) _Pragma("unroll") for (int k = 0; k < 2; ++k) dst[m][k] = *(const PG8_LAS bf16x8*)(lds + PG8_SA(b, h) + aoff + m * 2048 + k * 1024); } while (0)
; #define PG8_MMA(ai, bj, At, Bt) do { __builtin_amdgcn_s_setprio(1); _Pragma("unroll") for (int m = 0; m < 4; ++m) _Pragma("unroll") for (int n = 0; n < 2; ++n) _Pragma("unroll") for (int k = 0; k < 2; ++k) \
;         acc[ai][bj][m][n] = __builtin_amdgcn_mfma_f32_16x16x32_bf16(Bt[n][k], At[m][k], acc[ai][bj][m][n], 0, 0, 0); __builtin_amdgcn_s_setprio(0); } while (0)
; #define PG8_WAIT_V(n) asm volatile("s_waitcnt vmcnt(" #n ")" ::: "memory")
; #define PG8_WAIT_L(n) asm volatile("s_waitcnt lgkmcnt(" #n ")" ::: "memory")
; #define PG8_BAR __builtin_amdgcn_s_barrier()
; #define PG8_SCHED __builtin_amdgcn_sched_barrier(0)
; template <class Epi, class Sched, bool ALIGN_EPI = false, bool SP2 = false>
; __device__ __forceinline__ void gemm_phase(PG8_LAS unsigned char* lds, const Gemm g, const Sched& S, const Epi& E) {
;     ...
;             PG8_LDA(At, 1, 1); PG8_STAGE(PG8_SB(1, 0), b3, voffB); PG8_STAGE(PG8_SB(1, 1), b3 + hstep, voffB); PG8_STAGE(PG8_SA(1, 0), a3, voffA);
;             PG8_WAIT_V(8); PG8_WAIT_L(0); PG8_BAR; PG8_MMA(1, 0, At, B0); PG8_MMA(1, 1, At, B1); PG8_BAR; PG8_SCHED;
	s_add_i32 s30, s61, s38
	v_lshl_add_u64 v[216:217], v[216:217], 0, s[18:19]
	s_mov_b32 m0, s30
	ds_read_b128 v[184:187], v150 offset:49152
	ds_read_b128 v[188:191], v150 offset:50176
	ds_read_b128 v[192:195], v150 offset:51200
	ds_read_b128 v[196:199], v150 offset:52224
	ds_read_b128 v[200:203], v150 offset:53248
	ds_read_b128 v[204:207], v150 offset:54272
	ds_read_b128 v[208:211], v150 offset:55296
	ds_read_b128 v[212:215], v150 offset:56320
	global_load_lds_dwordx4 v[216:217], off
	v_lshl_add_u64 v[216:217], v[218:219], 0, s[18:19]
	s_add_i32 m0, s30, 0x2000
	s_add_i32 s30, s62, s38
	global_load_lds_dwordx4 v[216:217], off
	s_mov_b32 m0, s30
	v_lshl_add_u64 v[216:217], v[220:221], 0, s[18:19]
	global_load_lds_dwordx4 v[216:217], off
	s_add_i32 m0, s30, 0x2000
	v_lshl_add_u64 v[216:217], v[222:223], 0, s[18:19]
	global_load_lds_dwordx4 v[216:217], off
	s_mov_b32 m0, s42
	v_lshl_add_u64 v[216:217], v[224:225], 0, s[18:19]
	global_load_lds_dwordx4 v[216:217], off
	s_mov_b32 m0, s43
	v_lshl_add_u64 v[216:217], v[226:227], 0, s[18:19]
	global_load_lds_dwordx4 v[216:217], off
	s_waitcnt vmcnt(8) lgkmcnt(0)
	s_barrier
	s_setprio 1
	v_mfma_f32_16x16x32_bf16 v[62:65], v[152:155], v[184:187], v[62:65]
	v_mfma_f32_16x16x32_bf16 v[58:61], v[160:163], v[184:187], v[58:61]
	v_mfma_f32_16x16x32_bf16 v[46:49], v[152:155], v[192:195], v[46:49]
	v_mfma_f32_16x16x32_bf16 v[42:45], v[160:163], v[192:195], v[42:45]
	v_mfma_f32_16x16x32_bf16 v[30:33], v[152:155], v[200:203], v[30:33]
	v_mfma_f32_16x16x32_bf16 v[26:29], v[160:163], v[200:203], v[26:29]
	v_mfma_f32_16x16x32_bf16 v[14:17], v[152:155], v[208:211], v[14:17]
	v_mfma_f32_16x16x32_bf16 v[10:13], v[160:163], v[208:211], v[10:13]
	v_mfma_f32_16x16x32_bf16 v[62:65], v[156:159], v[188:191], v[62:65]
	v_mfma_f32_16x16x32_bf16 v[58:61], v[164:167], v[188:191], v[58:61]
	v_mfma_f32_16x16x32_bf16 v[46:49], v[156:159], v[196:199], v[46:49]
	v_mfma_f32_16x16x32_bf16 v[42:45], v[164:167], v[196:199], v[42:45]
	v_mfma_f32_16x16x32_bf16 v[30:33], v[156:159], v[204:207], v[30:33]
	v_mfma_f32_16x16x32_bf16 v[26:29], v[164:167], v[204:207], v[26:29]
	v_mfma_f32_16x16x32_bf16 v[14:17], v[156:159], v[212:215], v[14:17]
	v_mfma_f32_16x16x32_bf16 v[10:13], v[164:167], v[212:215], v[10:13]
	v_mfma_f32_16x16x32_bf16 v[54:57], v[168:171], v[184:187], v[54:57]
	v_mfma_f32_16x16x32_bf16 v[50:53], v[176:179], v[184:187], v[50:53]
	v_mfma_f32_16x16x32_bf16 v[38:41], v[168:171], v[192:195], v[38:41]
	v_mfma_f32_16x16x32_bf16 v[34:37], v[176:179], v[192:195], v[34:37]
	v_mfma_f32_16x16x32_bf16 v[22:25], v[168:171], v[200:203], v[22:25]
	v_mfma_f32_16x16x32_bf16 v[18:21], v[176:179], v[200:203], v[18:21]
	v_mfma_f32_16x16x32_bf16 v[6:9], v[168:171], v[208:211], v[6:9]
	v_mfma_f32_16x16x32_bf16 v[2:5], v[176:179], v[208:211], v[2:5]
	v_mfma_f32_16x16x32_bf16 v[54:57], v[172:175], v[188:191], v[54:57]
	v_mfma_f32_16x16x32_bf16 v[50:53], v[180:183], v[188:191], v[50:53]
	v_mfma_f32_16x16x32_bf16 v[38:41], v[172:175], v[196:199], v[38:41]
	v_mfma_f32_16x16x32_bf16 v[34:37], v[180:183], v[196:199], v[34:37]
	v_mfma_f32_16x16x32_bf16 v[22:25], v[172:175], v[204:207], v[22:25]
	v_mfma_f32_16x16x32_bf16 v[18:21], v[180:183], v[204:207], v[18:21]
	v_mfma_f32_16x16x32_bf16 v[6:9], v[172:175], v[212:215], v[6:9]
	v_mfma_f32_16x16x32_bf16 v[2:5], v[180:183], v[212:215], v[2:5]
	s_setprio 0
	s_barrier
	s_add_u32 s58, s58, 0x100
	s_addc_u32 s59, s59, 0
	s_add_u32 s28, s28, 0x100
	s_addc_u32 s29, s29, 0
	s_cmp_ge_i32 s60, s44
	s_mov_b32 s30, s60
	s_cbranch_scc0 .LBB0_582

; #define PG8_STAGE(bufoff, gbase, voff) do { _Pragma("unroll") for (int _i = 0; _i < 2; ++_i) \
;         __builtin_amdgcn_global_load_lds((const unsigned*)((const char*)(gbase) + (voff)[_i]), (PG8_LAS unsigned*)(lds + (bufoff) + ldsw + _i * 8192), 16, 0, 0); } while (0)
; #define PG8_LDA(dst, b, h) do { _Pragma("unroll") for (int m = 0; m < 4; ++m) _Pragma("unroll") for (int k = 0; k < 2; ++k) dst[m][k] = *(const PG8_LAS bf16x8*)(lds + PG8_SA(b, h) + aoff + m * 2048 + k * 1024); } while (0)
; #define PG8_LDB(dst, b, h) do { _Pragma("unroll") for (int n = 0; n < 2; ++n) _Pragma("unroll") for (int k = 0; k < 2; ++k) dst[n][k] = *(const PG8_LAS bf16x8*)(lds + PG8_SB(b, h) + boff + n * 2048 + k * 1024); } while (0)
; #define PG8_MMA(ai, bj, At, Bt) do { __builtin_amdgcn_s_setprio(1); _Pragma("unroll") for (int m = 0; m < 4; ++m) _Pragma("unroll") for (int n = 0; n < 2; ++n) _Pragma("unroll") for (int k = 0; k < 2; ++k) \
;         acc[ai][bj][m][n] = __builtin_amdgcn_mfma_f32_16x16x32_bf16(Bt[n][k], At[m][k], acc[ai][bj][m][n], 0, 0, 0); __builtin_amdgcn_s_setprio(0); } while (0)
; #define PG8_WAIT_V(n) asm volatile("s_waitcnt vmcnt(" #n ")" ::: "memory")
; #define PG8_WAIT_L(n) asm volatile("s_waitcnt lgkmcnt(" #n ")" ::: "memory")
; #define PG8_BAR __builtin_amdgcn_s_barrier()
; #define PG8_SCHED __builtin_amdgcn_sched_barrier(0)
; template <class Epi, class Sched, bool ALIGN_EPI = false, bool SP2 = false>
; __device__ __forceinline__ void gemm_phase(PG8_LAS unsigned char* lds, const Gemm g, const Sched& S, const Epi& E) {
;     ...
;             const bool last = (t == nt - 2);
;             const char* a1 = cA + (size_t)(t + 1) * kstep;
;             const char* a2 = last ? nA : cA + (size_t)(t + 2) * kstep; const char* b2 = last ? nB : cB + (size_t)(t + 2) * kstep;
;             const char* a3 = a2 + kstep; const char* b3 = b2 + kstep;
;             if (last && has_next) S.a_ready(nxt);
;             if constexpr (SP2) {
;             PG8_LDB(B0, 0, 0); PG8_LDB(B1, 0, 1); PG8_SCHED; PG8_LDA(At, 0, 0); PG8_STAGE(PG8_SA(1, 1), a1 + hstep, voffA);
;             PG8_WAIT_V(8); PG8_WAIT_L(0); PG8_BAR; PG8_MMA(0, 0, At, B0); PG8_MMA(0, 1, At, B1); PG8_BAR; PG8_SCHED;
;             PG8_LDA(At, 0, 1); PG8_STAGE(PG8_SB(0, 0), b2, voffB); PG8_STAGE(PG8_SB(0, 1), b2 + hstep, voffB); PG8_STAGE(PG8_SA(0, 0), a2, voffA);
.LBB0_749:
	ds_read_b128 v[152:155], v148
	ds_read_b128 v[156:159], v148 offset:1024
	ds_read_b128 v[160:163], v148 offset:2048
	ds_read_b128 v[164:167], v148 offset:3072
	ds_read_b128 v[168:171], v149
	ds_read_b128 v[172:175], v149 offset:1024
	ds_read_b128 v[176:179], v149 offset:2048
	ds_read_b128 v[180:183], v149 offset:3072
	s_add_i32 s60, s30, 2
	s_add_u32 s61, s28, 0x80
	s_addc_u32 s31, s29, 0
	s_cmp_eq_u32 s48, s30
	s_cselect_b32 s30, s6, s61
	s_cselect_b32 s31, s7, s31
	s_cselect_b32 s63, s25, s59
	s_cselect_b32 s62, s24, s58
	v_lshl_add_u64 v[216:217], s[28:29], 0, v[140:141]
	s_add_i32 m0, s40, 0xc000
	ds_read_b128 v[184:187], v150
	ds_read_b128 v[188:191], v150 offset:1024
	ds_read_b128 v[192:195], v150 offset:2048
	ds_read_b128 v[196:199], v150 offset:3072
	ds_read_b128 v[200:203], v150 offset:4096
	ds_read_b128 v[204:207], v150 offset:5120
	ds_read_b128 v[208:211], v150 offset:6144
	ds_read_b128 v[212:215], v150 offset:7168
	global_load_lds_dwordx4 v[216:217], off
	s_add_i32 m0, s40, 0xe000
	v_lshl_add_u64 v[216:217], s[28:29], 0, v[138:139]
	global_load_lds_dwordx4 v[216:217], off
	s_waitcnt vmcnt(8) lgkmcnt(0)
	s_barrier
	s_setprio 1
	v_mfma_f32_16x16x32_bf16 v[122:125], v[152:155], v[184:187], v[122:125]
	v_mfma_f32_16x16x32_bf16 v[118:121], v[160:163], v[184:187], v[118:121]
	v_mfma_f32_16x16x32_bf16 v[110:113], v[152:155], v[192:195], v[110:113]
	v_mfma_f32_16x16x32_bf16 v[102:105], v[160:163], v[192:195], v[102:105]
	v_mfma_f32_16x16x32_bf16 v[94:97], v[152:155], v[200:203], v[94:97]
	v_mfma_f32_16x16x32_bf16 v[86:89], v[160:163], v[200:203], v[86:89]
	v_mfma_f32_16x16x32_bf16 v[78:81], v[152:155], v[208:211], v[78:81]
	v_mfma_f32_16x16x32_bf16 v[70:73], v[160:163], v[208:211], v[70:73]
	v_mfma_f32_16x16x32_bf16 v[122:125], v[156:159], v[188:191], v[122:125]
	v_mfma_f32_16x16x32_bf16 v[118:121], v[164:167], v[188:191], v[118:121]
	v_mfma_f32_16x16x32_bf16 v[110:113], v[156:159], v[196:199], v[110:113]
	v_mfma_f32_16x16x32_bf16 v[102:105], v[164:167], v[196:199], v[102:105]
	v_mfma_f32_16x16x32_bf16 v[94:97], v[156:159], v[204:207], v[94:97]
	v_mfma_f32_16x16x32_bf16 v[86:89], v[164:167], v[204:207], v[86:89]
	v_mfma_f32_16x16x32_bf16 v[78:81], v[156:159], v[212:215], v[78:81]
	v_mfma_f32_16x16x32_bf16 v[70:73], v[164:167], v[212:215], v[70:73]
	v_mfma_f32_16x16x32_bf16 v[126:129], v[168:171], v[184:187], v[126:129]
	v_mfma_f32_16x16x32_bf16 v[114:117], v[176:179], v[184:187], v[114:117]
	v_mfma_f32_16x16x32_bf16 v[106:109], v[168:171], v[192:195], v[106:109]
	v_mfma_f32_16x16x32_bf16 v[98:101], v[176:179], v[192:195], v[98:101]
	v_mfma_f32_16x16x32_bf16 v[90:93], v[168:171], v[200:203], v[90:93]
	v_mfma_f32_16x16x32_bf16 v[82:85], v[176:179], v[200:203], v[82:85]
	v_mfma_f32_16x16x32_bf16 v[74:77], v[168:171], v[208:211], v[74:77]
	v_mfma_f32_16x16x32_bf16 v[66:69], v[176:179], v[208:211], v[66:69]
	v_mfma_f32_16x16x32_bf16 v[126:129], v[172:175], v[188:191], v[126:129]
	v_mfma_f32_16x16x32_bf16 v[114:117], v[180:183], v[188:191], v[114:117]
	v_mfma_f32_16x16x32_bf16 v[106:109], v[172:175], v[196:199], v[106:109]
	v_mfma_f32_16x16x32_bf16 v[98:101], v[180:183], v[196:199], v[98:101]
	v_mfma_f32_16x16x32_bf16 v[90:93], v[172:175], v[204:207], v[90:93]
	v_mfma_f32_16x16x32_bf16 v[82:85], v[180:183], v[204:207], v[82:85]
	v_mfma_f32_16x16x32_bf16 v[74:77], v[172:175], v[212:215], v[74:77]
	v_mfma_f32_16x16x32_bf16 v[66:69], v[180:183], v[212:215], v[66:69]
	s_setprio 0
	s_barrier
	s_add_i32 s61, s53, s37
	v_lshl_add_u64 v[216:217], s[62:63], 0, v[134:135]
	s_mov_b32 m0, s61
	ds_read_b128 v[184:187], v150 offset:16384
	ds_read_b128 v[188:191], v150 offset:17408
	ds_read_b128 v[192:195], v150 offset:18432
	ds_read_b128 v[196:199], v150 offset:19456
	ds_read_b128 v[200:203], v150 offset:20480
	ds_read_b128 v[204:207], v150 offset:21504
	ds_read_b128 v[208:211], v150 offset:22528
	ds_read_b128 v[212:215], v150 offset:23552
	global_load_lds_dwordx4 v[216:217], off
	s_add_i32 m0, s61, 0x2000
	v_lshl_add_u64 v[218:219], s[62:63], 0, v[130:131]
	s_add_u32 s62, s62, s10
	s_addc_u32 s63, s63, s11
	s_add_i32 s61, s54, s37
	global_load_lds_dwordx4 v[218:219], off
	v_lshl_add_u64 v[220:221], s[62:63], 0, v[134:135]
	s_mov_b32 m0, s61
	v_lshl_add_u64 v[222:223], s[62:63], 0, v[130:131]
	global_load_lds_dwordx4 v[220:221], off
	s_add_i32 m0, s61, 0x2000
	v_lshl_add_u64 v[224:225], s[30:31], 0, v[136:137]
	global_load_lds_dwordx4 v[222:223], off
	s_mov_b32 m0, s40
	v_lshl_add_u64 v[226:227], s[30:31], 0, v[132:133]
	global_load_lds_dwordx4 v[224:225], off
	s_mov_b32 m0, s41
	s_nop 0
	global_load_lds_dwordx4 v[226:227], off
	s_waitcnt vmcnt(8) lgkmcnt(0)
	s_barrier
; #define PG8_STAGE(bufoff, gbase, voff) do { _Pragma("unroll") for (int _i = 0; _i < 2; ++_i) \
;         __builtin_amdgcn_global_load_lds((const unsigned*)((const char*)(gbase) + (voff)[_i]), (PG8_LAS unsigned*)(lds + (bufoff) + ldsw + _i * 8192), 16, 0, 0); } while (0)
; #define PG8_LDA(dst, b, h) do { _Pragma("unroll") for (int m = 0; m < 4; ++m) _Pragma("unroll") for (int k = 0; k < 2; ++k) dst[m][k] = *(const PG8_LAS bf16x8*)(lds + PG8_SA(b, h) + aoff + m * 2048 + k * 1024); } while (0)
; #define PG8_LDB(dst, b, h) do { _Pragma("unroll") for (int n = 0; n < 2; ++n) _Pragma("unroll") for (int k = 0; k < 2; ++k) dst[n][k] = *(const PG8_LAS bf16x8*)(lds + PG8_SB(b, h) + boff + n * 2048 + k * 1024); } while (0)
; #define PG8_MMA(ai, bj, At, Bt) do { __builtin_amdgcn_s_setprio(1); _Pragma("unroll") for (int m = 0; m < 4; ++m) _Pragma("unroll") for (int n = 0; n < 2; ++n) _Pragma("unroll") for (int k = 0; k < 2; ++k) \
;         acc[ai][bj][m][n] = __builtin_amdgcn_mfma_f32_16x16x32_bf16(Bt[n][k], At[m][k], acc[ai][bj][m][n], 0, 0, 0); __builtin_amdgcn_s_setprio(0); } while (0)
; #define PG8_WAIT_V(n) asm volatile("s_waitcnt vmcnt(" #n ")" ::: "memory")
; #define PG8_WAIT_L(n) asm volatile("s_waitcnt lgkmcnt(" #n ")" ::: "memory")
; #define PG8_BAR __builtin_amdgcn_s_barrier()
; #define PG8_SCHED __builtin_amdgcn_sched_barrier(0)
; template <class Epi, class Sched, bool ALIGN_EPI = false, bool SP2 = false>
; __device__ __forceinline__ void gemm_phase(PG8_LAS unsigned char* lds, const Gemm g, const Sched& S, const Epi& E) {
;     ...
;             PG8_WAIT_V(8); PG8_WAIT_L(0); PG8_BAR; PG8_MMA(1, 0, At, B0); PG8_MMA(1, 1, At, B1); PG8_BAR; PG8_SCHED;
;             PG8_LDB(B0, 1, 0); PG8_LDB(B1, 1, 1); PG8_SCHED; PG8_LDA(At, 1, 0); PG8_STAGE(PG8_SA(0, 1), a2 + hstep, voffA);
;             PG8_WAIT_V(8); PG8_WAIT_L(0); PG8_BAR; PG8_MMA(0, 0, At, B0); PG8_MMA(0, 1, At, B1); PG8_BAR; PG8_SCHED;
	s_setprio 1
	v_mfma_f32_16x16x32_bf16 v[62:65], v[152:155], v[184:187], v[62:65]
	v_mfma_f32_16x16x32_bf16 v[54:57], v[160:163], v[184:187], v[54:57]
	v_mfma_f32_16x16x32_bf16 v[46:49], v[152:155], v[192:195], v[46:49]
	v_mfma_f32_16x16x32_bf16 v[38:41], v[160:163], v[192:195], v[38:41]
	v_mfma_f32_16x16x32_bf16 v[30:33], v[152:155], v[200:203], v[30:33]
	v_mfma_f32_16x16x32_bf16 v[22:25], v[160:163], v[200:203], v[22:25]
	v_mfma_f32_16x16x32_bf16 v[14:17], v[152:155], v[208:211], v[14:17]
	v_mfma_f32_16x16x32_bf16 v[6:9], v[160:163], v[208:211], v[6:9]
	v_mfma_f32_16x16x32_bf16 v[62:65], v[156:159], v[188:191], v[62:65]
	v_mfma_f32_16x16x32_bf16 v[54:57], v[164:167], v[188:191], v[54:57]
	v_mfma_f32_16x16x32_bf16 v[46:49], v[156:159], v[196:199], v[46:49]
	v_mfma_f32_16x16x32_bf16 v[38:41], v[164:167], v[196:199], v[38:41]
	v_mfma_f32_16x16x32_bf16 v[30:33], v[156:159], v[204:207], v[30:33]
	v_mfma_f32_16x16x32_bf16 v[22:25], v[164:167], v[204:207], v[22:25]
	v_mfma_f32_16x16x32_bf16 v[14:17], v[156:159], v[212:215], v[14:17]
	v_mfma_f32_16x16x32_bf16 v[6:9], v[164:167], v[212:215], v[6:9]
	v_mfma_f32_16x16x32_bf16 v[58:61], v[168:171], v[184:187], v[58:61]
	v_mfma_f32_16x16x32_bf16 v[50:53], v[176:179], v[184:187], v[50:53]
	v_mfma_f32_16x16x32_bf16 v[42:45], v[168:171], v[192:195], v[42:45]
	v_mfma_f32_16x16x32_bf16 v[34:37], v[176:179], v[192:195], v[34:37]
	v_mfma_f32_16x16x32_bf16 v[26:29], v[168:171], v[200:203], v[26:29]
	v_mfma_f32_16x16x32_bf16 v[18:21], v[176:179], v[200:203], v[18:21]
	v_mfma_f32_16x16x32_bf16 v[10:13], v[168:171], v[208:211], v[10:13]
	v_mfma_f32_16x16x32_bf16 v[2:5], v[176:179], v[208:211], v[2:5]
	v_mfma_f32_16x16x32_bf16 v[58:61], v[172:175], v[188:191], v[58:61]
	v_mfma_f32_16x16x32_bf16 v[50:53], v[180:183], v[188:191], v[50:53]
	v_mfma_f32_16x16x32_bf16 v[42:45], v[172:175], v[196:199], v[42:45]
	v_mfma_f32_16x16x32_bf16 v[34:37], v[180:183], v[196:199], v[34:37]
	v_mfma_f32_16x16x32_bf16 v[26:29], v[172:175], v[204:207], v[26:29]
	v_mfma_f32_16x16x32_bf16 v[18:21], v[180:183], v[204:207], v[18:21]
	v_mfma_f32_16x16x32_bf16 v[10:13], v[172:175], v[212:215], v[10:13]
	v_mfma_f32_16x16x32_bf16 v[2:5], v[180:183], v[212:215], v[2:5]
	s_setprio 0
	s_barrier
	s_add_i32 s61, 0, 0x18000
	v_add_u32_e32 v151, s61, v146
	s_add_i32 s62, 0, 0x1c000
	ds_read_b128 v[152:155], v151
	ds_read_b128 v[156:159], v151 offset:1024
	ds_read_b128 v[160:163], v151 offset:2048
	ds_read_b128 v[164:167], v151 offset:3072
	v_add_u32_e32 v151, s62, v146
	ds_read_b128 v[168:171], v151
	ds_read_b128 v[172:175], v151 offset:1024
	ds_read_b128 v[176:179], v151 offset:2048
	ds_read_b128 v[180:183], v151 offset:3072
	s_add_u32 s30, s30, s10
	s_addc_u32 s31, s31, s11
	s_mov_b32 m0, s42
	v_lshl_add_u64 v[228:229], s[30:31], 0, v[136:137]
	ds_read_b128 v[184:187], v150 offset:32768
	ds_read_b128 v[188:191], v150 offset:33792
	ds_read_b128 v[192:195], v150 offset:34816
	ds_read_b128 v[196:199], v150 offset:35840
	ds_read_b128 v[200:203], v150 offset:36864
	ds_read_b128 v[204:207], v150 offset:37888
	ds_read_b128 v[208:211], v150 offset:38912
	ds_read_b128 v[212:215], v150 offset:39936
	global_load_lds_dwordx4 v[228:229], off
	s_mov_b32 m0, s43
	v_lshl_add_u64 v[228:229], s[30:31], 0, v[132:133]
	global_load_lds_dwordx4 v[228:229], off
	s_waitcnt vmcnt(8) lgkmcnt(0)
	s_barrier
	s_setprio 1
	v_mfma_f32_16x16x32_bf16 v[122:125], v[152:155], v[184:187], v[122:125]
	v_mfma_f32_16x16x32_bf16 v[118:121], v[160:163], v[184:187], v[118:121]
	v_mfma_f32_16x16x32_bf16 v[110:113], v[152:155], v[192:195], v[110:113]
	v_mfma_f32_16x16x32_bf16 v[102:105], v[160:163], v[192:195], v[102:105]
	v_mfma_f32_16x16x32_bf16 v[94:97], v[152:155], v[200:203], v[94:97]
	v_mfma_f32_16x16x32_bf16 v[86:89], v[160:163], v[200:203], v[86:89]
	v_mfma_f32_16x16x32_bf16 v[78:81], v[152:155], v[208:211], v[78:81]
	v_mfma_f32_16x16x32_bf16 v[70:73], v[160:163], v[208:211], v[70:73]
	v_mfma_f32_16x16x32_bf16 v[122:125], v[156:159], v[188:191], v[122:125]
	v_mfma_f32_16x16x32_bf16 v[118:121], v[164:167], v[188:191], v[118:121]
	v_mfma_f32_16x16x32_bf16 v[110:113], v[156:159], v[196:199], v[110:113]
	v_mfma_f32_16x16x32_bf16 v[102:105], v[164:167], v[196:199], v[102:105]
	v_mfma_f32_16x16x32_bf16 v[94:97], v[156:159], v[204:207], v[94:97]
	v_mfma_f32_16x16x32_bf16 v[86:89], v[164:167], v[204:207], v[86:89]
	v_mfma_f32_16x16x32_bf16 v[78:81], v[156:159], v[212:215], v[78:81]
	v_mfma_f32_16x16x32_bf16 v[70:73], v[164:167], v[212:215], v[70:73]
	v_mfma_f32_16x16x32_bf16 v[126:129], v[168:171], v[184:187], v[126:129]
	v_mfma_f32_16x16x32_bf16 v[114:117], v[176:179], v[184:187], v[114:117]
	v_mfma_f32_16x16x32_bf16 v[106:109], v[168:171], v[192:195], v[106:109]
	v_mfma_f32_16x16x32_bf16 v[98:101], v[176:179], v[192:195], v[98:101]
	v_mfma_f32_16x16x32_bf16 v[90:93], v[168:171], v[200:203], v[90:93]
	v_mfma_f32_16x16x32_bf16 v[82:85], v[176:179], v[200:203], v[82:85]
	v_mfma_f32_16x16x32_bf16 v[74:77], v[168:171], v[208:211], v[74:77]
	v_mfma_f32_16x16x32_bf16 v[66:69], v[176:179], v[208:211], v[66:69]
	v_mfma_f32_16x16x32_bf16 v[126:129], v[172:175], v[188:191], v[126:129]
	v_mfma_f32_16x16x32_bf16 v[114:117], v[180:183], v[188:191], v[114:117]
	v_mfma_f32_16x16x32_bf16 v[106:109], v[172:175], v[196:199], v[106:109]
	v_mfma_f32_16x16x32_bf16 v[98:101], v[180:183], v[196:199], v[98:101]
	v_mfma_f32_16x16x32_bf16 v[90:93], v[172:175], v[204:207], v[90:93]
	v_mfma_f32_16x16x32_bf16 v[82:85], v[180:183], v[204:207], v[82:85]
	v_mfma_f32_16x16x32_bf16 v[74:77], v[172:175], v[212:215], v[74:77]
	v_mfma_f32_16x16x32_bf16 v[66:69], v[180:183], v[212:215], v[66:69]
	s_setprio 0
	s_barrier
; #define PG8_STAGE(bufoff, gbase, voff) do { _Pragma("unroll") for (int _i = 0; _i < 2; ++_i) \
;         __builtin_amdgcn_global_load_lds((const unsigned*)((const char*)(gbase) + (voff)[_i]), (PG8_LAS unsigned*)(lds + (bufoff) + ldsw + _i * 8192), 16, 0, 0); } while (0)
; #define PG8_LDA(dst, b, h) do { _Pragma("unroll") for (int m = 0; m < 4; ++m) _Pragma("unroll") for (int k = 0; k < 2; ++k) dst[m][k] = *(const PG8_LAS bf16x8*)(lds + PG8_SA(b, h) + aoff + m * 2048 + k * 1024); } while (0)
; #define PG8_MMA(ai, bj, At, Bt) do { __builtin_amdgcn_s_setprio(1); _Pragma("unroll") for (int m = 0; m < 4; ++m) _Pragma("unroll") for (int n = 0; n < 2; ++n) _Pragma("unroll") for (int k = 0; k < 2; ++k) \
;         acc[ai][bj][m][n] = __builtin_amdgcn_mfma_f32_16x16x32_bf16(Bt[n][k], At[m][k], acc[ai][bj][m][n], 0, 0, 0); __builtin_amdgcn_s_setprio(0); } while (0)
; #define PG8_WAIT_V(n) asm volatile("s_waitcnt vmcnt(" #n ")" ::: "memory")
; #define PG8_WAIT_L(n) asm volatile("s_waitcnt lgkmcnt(" #n ")" ::: "memory")
; #define PG8_BAR __builtin_amdgcn_s_barrier()
; #define PG8_SCHED __builtin_amdgcn_sched_barrier(0)
; template <class Epi, class Sched, bool ALIGN_EPI = false, bool SP2 = false>
; __device__ __forceinline__ void gemm_phase(PG8_LAS unsigned char* lds, const Gemm g, const Sched& S, const Epi& E) {
;     ...
;             PG8_LDA(At, 1, 1); PG8_STAGE(PG8_SB(1, 0), b3, voffB); PG8_STAGE(PG8_SB(1, 1), b3 + hstep, voffB); PG8_STAGE(PG8_SA(1, 0), a3, voffA);
;             PG8_WAIT_V(8); PG8_WAIT_L(0); PG8_BAR; PG8_MMA(1, 0, At, B0); PG8_MMA(1, 1, At, B1); PG8_BAR; PG8_SCHED;
	s_add_i32 s30, s61, s37
	v_lshl_add_u64 v[216:217], v[216:217], 0, s[18:19]
	s_mov_b32 m0, s30
	ds_read_b128 v[184:187], v150 offset:49152
	ds_read_b128 v[188:191], v150 offset:50176
	ds_read_b128 v[192:195], v150 offset:51200
	ds_read_b128 v[196:199], v150 offset:52224
	ds_read_b128 v[200:203], v150 offset:53248
	ds_read_b128 v[204:207], v150 offset:54272
	ds_read_b128 v[208:211], v150 offset:55296
	ds_read_b128 v[212:215], v150 offset:56320
	global_load_lds_dwordx4 v[216:217], off
	v_lshl_add_u64 v[216:217], v[218:219], 0, s[18:19]
	s_add_i32 m0, s30, 0x2000
	s_add_i32 s30, s62, s37
	global_load_lds_dwordx4 v[216:217], off
	s_mov_b32 m0, s30
	v_lshl_add_u64 v[216:217], v[220:221], 0, s[18:19]
	global_load_lds_dwordx4 v[216:217], off
	s_add_i32 m0, s30, 0x2000
	v_lshl_add_u64 v[216:217], v[222:223], 0, s[18:19]
	global_load_lds_dwordx4 v[216:217], off
	s_mov_b32 m0, s45
	v_lshl_add_u64 v[216:217], v[224:225], 0, s[18:19]
	global_load_lds_dwordx4 v[216:217], off
	s_mov_b32 m0, s46
	v_lshl_add_u64 v[216:217], v[226:227], 0, s[18:19]
	global_load_lds_dwordx4 v[216:217], off
	s_waitcnt vmcnt(8) lgkmcnt(0)
	s_barrier
	s_setprio 1
	v_mfma_f32_16x16x32_bf16 v[62:65], v[152:155], v[184:187], v[62:65]
	v_mfma_f32_16x16x32_bf16 v[54:57], v[160:163], v[184:187], v[54:57]
	v_mfma_f32_16x16x32_bf16 v[46:49], v[152:155], v[192:195], v[46:49]
	v_mfma_f32_16x16x32_bf16 v[38:41], v[160:163], v[192:195], v[38:41]
	v_mfma_f32_16x16x32_bf16 v[30:33], v[152:155], v[200:203], v[30:33]
	v_mfma_f32_16x16x32_bf16 v[22:25], v[160:163], v[200:203], v[22:25]
	v_mfma_f32_16x16x32_bf16 v[14:17], v[152:155], v[208:211], v[14:17]
	v_mfma_f32_16x16x32_bf16 v[6:9], v[160:163], v[208:211], v[6:9]
	v_mfma_f32_16x16x32_bf16 v[62:65], v[156:159], v[188:191], v[62:65]
	v_mfma_f32_16x16x32_bf16 v[54:57], v[164:167], v[188:191], v[54:57]
	v_mfma_f32_16x16x32_bf16 v[46:49], v[156:159], v[196:199], v[46:49]
	v_mfma_f32_16x16x32_bf16 v[38:41], v[164:167], v[196:199], v[38:41]
	v_mfma_f32_16x16x32_bf16 v[30:33], v[156:159], v[204:207], v[30:33]
	v_mfma_f32_16x16x32_bf16 v[22:25], v[164:167], v[204:207], v[22:25]
	v_mfma_f32_16x16x32_bf16 v[14:17], v[156:159], v[212:215], v[14:17]
	v_mfma_f32_16x16x32_bf16 v[6:9], v[164:167], v[212:215], v[6:9]
	v_mfma_f32_16x16x32_bf16 v[58:61], v[168:171], v[184:187], v[58:61]
	v_mfma_f32_16x16x32_bf16 v[50:53], v[176:179], v[184:187], v[50:53]
	v_mfma_f32_16x16x32_bf16 v[42:45], v[168:171], v[192:195], v[42:45]
	v_mfma_f32_16x16x32_bf16 v[34:37], v[176:179], v[192:195], v[34:37]
	v_mfma_f32_16x16x32_bf16 v[26:29], v[168:171], v[200:203], v[26:29]
	v_mfma_f32_16x16x32_bf16 v[18:21], v[176:179], v[200:203], v[18:21]
	v_mfma_f32_16x16x32_bf16 v[10:13], v[168:171], v[208:211], v[10:13]
	v_mfma_f32_16x16x32_bf16 v[2:5], v[176:179], v[208:211], v[2:5]
	v_mfma_f32_16x16x32_bf16 v[58:61], v[172:175], v[188:191], v[58:61]
	v_mfma_f32_16x16x32_bf16 v[50:53], v[180:183], v[188:191], v[50:53]
	v_mfma_f32_16x16x32_bf16 v[42:45], v[172:175], v[196:199], v[42:45]
	v_mfma_f32_16x16x32_bf16 v[34:37], v[180:183], v[196:199], v[34:37]
	v_mfma_f32_16x16x32_bf16 v[26:29], v[172:175], v[204:207], v[26:29]
	v_mfma_f32_16x16x32_bf16 v[18:21], v[180:183], v[204:207], v[18:21]
	v_mfma_f32_16x16x32_bf16 v[10:13], v[172:175], v[212:215], v[10:13]
	v_mfma_f32_16x16x32_bf16 v[2:5], v[180:183], v[212:215], v[2:5]
	s_setprio 0
	s_barrier
	s_add_u32 s58, s58, 0x100
	s_addc_u32 s59, s59, 0
	s_add_u32 s28, s28, 0x100
	s_addc_u32 s29, s29, 0
	s_cmp_ge_i32 s60, s47
	s_mov_b32 s30, s60
	s_cbranch_scc0 .LBB0_749

; #define PG8_STAGE(bufoff, gbase, voff) do { _Pragma("unroll") for (int _i = 0; _i < 2; ++_i) \
;         __builtin_amdgcn_global_load_lds((const unsigned*)((const char*)(gbase) + (voff)[_i]), (PG8_LAS unsigned*)(lds + (bufoff) + ldsw + _i * 8192), 16, 0, 0); } while (0)
; #define PG8_LDA(dst, b, h) do { _Pragma("unroll") for (int m = 0; m < 4; ++m) _Pragma("unroll") for (int k = 0; k < 2; ++k) dst[m][k] = *(const PG8_LAS bf16x8*)(lds + PG8_SA(b, h) + aoff + m * 2048 + k * 1024); } while (0)
; #define PG8_LDB(dst, b, h) do { _Pragma("unroll") for (int n = 0; n < 2; ++n) _Pragma("unroll") for (int k = 0; k < 2; ++k) dst[n][k] = *(const PG8_LAS bf16x8*)(lds + PG8_SB(b, h) + boff + n * 2048 + k * 1024); } while (0)
; #define PG8_WAIT_V(n) asm volatile("s_waitcnt vmcnt(" #n ")" ::: "memory")
; #define PG8_WAIT_L(n) asm volatile("s_waitcnt lgkmcnt(" #n ")" ::: "memory")
; #define PG8_BAR __builtin_amdgcn_s_barrier()
; #define PG8_SCHED __builtin_amdgcn_sched_barrier(0)
; template <class Epi, class Sched, bool ALIGN_EPI = false, bool SP2 = false>
; __device__ __forceinline__ void gemm_phase(PG8_LAS unsigned char* lds, const Gemm g, const Sched& S, const Epi& E) {
;     ...
;         const bool has_next = S.next(ui + 1, nxt);
;         const char* nA = has_next ? (const char*)g.A + (size_t)nxt.pm * tstep : cA; const char* nB = has_next ? (const char*)g.Bt + (size_t)nxt.pn * tstep : cB;
;         for (int t = 0; t < nt; t += 2) {
;             const bool last = (t == nt - 2);
;             const char* a1 = cA + (size_t)(t + 1) * kstep;
;             const char* a2 = last ? nA : cA + (size_t)(t + 2) * kstep; const char* b2 = last ? nB : cB + (size_t)(t + 2) * kstep;
;             const char* a3 = a2 + kstep; const char* b3 = b2 + kstep;
;             if (last && has_next) S.a_ready(nxt);
;             if constexpr (SP2) {
;             PG8_LDB(B0, 0, 0); PG8_LDB(B1, 0, 1); PG8_SCHED; PG8_LDA(At, 0, 0); PG8_STAGE(PG8_SA(1, 1), a1 + hstep, voffA);
;             PG8_WAIT_V(8); PG8_WAIT_L(0); PG8_BAR; PG8_MMA(0, 0, At, B0); PG8_MMA(0, 1, At, B1); PG8_BAR; PG8_SCHED;
;             PG8_LDA(At, 0, 1); PG8_STAGE(PG8_SB(0, 0), b2, voffB); PG8_STAGE(PG8_SB(0, 1), b2 + hstep, voffB); PG8_STAGE(PG8_SA(0, 0), a2, voffA);
;             PG8_WAIT_V(8); PG8_WAIT_L(0); PG8_BAR; PG8_MMA(1, 0, At, B0); PG8_MMA(1, 1, At, B1); PG8_BAR; PG8_SCHED;
.LBB0_834:
	ds_read_b128 v[152:155], v148
	ds_read_b128 v[156:159], v148 offset:1024
	ds_read_b128 v[160:163], v148 offset:2048
	ds_read_b128 v[164:167], v148 offset:3072
	ds_read_b128 v[168:171], v149
	ds_read_b128 v[172:175], v149 offset:1024
	ds_read_b128 v[176:179], v149 offset:2048
	ds_read_b128 v[180:183], v149 offset:3072
	s_add_i32 s58, s30, 2
	s_add_u32 s59, s28, 0x80
	s_addc_u32 s31, s29, 0
	s_cmp_eq_u32 s45, s30
	s_cselect_b32 s30, s6, s59
	s_cselect_b32 s31, s7, s31
	s_cselect_b32 s61, s25, s57
	s_cselect_b32 s60, s24, s56
	v_lshl_add_u64 v[216:217], s[28:29], 0, v[140:141]
	s_add_i32 m0, s0, 0xc000
	ds_read_b128 v[184:187], v150
	ds_read_b128 v[188:191], v150 offset:1024
	ds_read_b128 v[192:195], v150 offset:2048
	ds_read_b128 v[196:199], v150 offset:3072
	ds_read_b128 v[200:203], v150 offset:4096
	ds_read_b128 v[204:207], v150 offset:5120
	ds_read_b128 v[208:211], v150 offset:6144
	ds_read_b128 v[212:215], v150 offset:7168
	global_load_lds_dwordx4 v[216:217], off
	s_add_i32 m0, s0, 0xe000
	v_lshl_add_u64 v[216:217], s[28:29], 0, v[138:139]
	global_load_lds_dwordx4 v[216:217], off
	s_waitcnt vmcnt(8) lgkmcnt(0)
	s_barrier
	s_setprio 1
	v_mfma_f32_16x16x32_bf16 v[122:125], v[152:155], v[184:187], v[122:125]
	v_mfma_f32_16x16x32_bf16 v[126:129], v[160:163], v[184:187], v[126:129]
	v_mfma_f32_16x16x32_bf16 v[110:113], v[152:155], v[192:195], v[110:113]
	v_mfma_f32_16x16x32_bf16 v[106:109], v[160:163], v[192:195], v[106:109]
	v_mfma_f32_16x16x32_bf16 v[94:97], v[152:155], v[200:203], v[94:97]
	v_mfma_f32_16x16x32_bf16 v[90:93], v[160:163], v[200:203], v[90:93]
	v_mfma_f32_16x16x32_bf16 v[78:81], v[152:155], v[208:211], v[78:81]
	v_mfma_f32_16x16x32_bf16 v[74:77], v[160:163], v[208:211], v[74:77]
	v_mfma_f32_16x16x32_bf16 v[122:125], v[156:159], v[188:191], v[122:125]
	v_mfma_f32_16x16x32_bf16 v[126:129], v[164:167], v[188:191], v[126:129]
	v_mfma_f32_16x16x32_bf16 v[110:113], v[156:159], v[196:199], v[110:113]
	v_mfma_f32_16x16x32_bf16 v[106:109], v[164:167], v[196:199], v[106:109]
	v_mfma_f32_16x16x32_bf16 v[94:97], v[156:159], v[204:207], v[94:97]
	v_mfma_f32_16x16x32_bf16 v[90:93], v[164:167], v[204:207], v[90:93]
	v_mfma_f32_16x16x32_bf16 v[78:81], v[156:159], v[212:215], v[78:81]
	v_mfma_f32_16x16x32_bf16 v[74:77], v[164:167], v[212:215], v[74:77]
	v_mfma_f32_16x16x32_bf16 v[118:121], v[168:171], v[184:187], v[118:121]
	v_mfma_f32_16x16x32_bf16 v[114:117], v[176:179], v[184:187], v[114:117]
	v_mfma_f32_16x16x32_bf16 v[102:105], v[168:171], v[192:195], v[102:105]
	v_mfma_f32_16x16x32_bf16 v[98:101], v[176:179], v[192:195], v[98:101]
	v_mfma_f32_16x16x32_bf16 v[86:89], v[168:171], v[200:203], v[86:89]
	v_mfma_f32_16x16x32_bf16 v[82:85], v[176:179], v[200:203], v[82:85]
	v_mfma_f32_16x16x32_bf16 v[70:73], v[168:171], v[208:211], v[70:73]
	v_mfma_f32_16x16x32_bf16 v[66:69], v[176:179], v[208:211], v[66:69]
	v_mfma_f32_16x16x32_bf16 v[118:121], v[172:175], v[188:191], v[118:121]
	v_mfma_f32_16x16x32_bf16 v[114:117], v[180:183], v[188:191], v[114:117]
	v_mfma_f32_16x16x32_bf16 v[102:105], v[172:175], v[196:199], v[102:105]
	v_mfma_f32_16x16x32_bf16 v[98:101], v[180:183], v[196:199], v[98:101]
	v_mfma_f32_16x16x32_bf16 v[86:89], v[172:175], v[204:207], v[86:89]
	v_mfma_f32_16x16x32_bf16 v[82:85], v[180:183], v[204:207], v[82:85]
	v_mfma_f32_16x16x32_bf16 v[70:73], v[172:175], v[212:215], v[70:73]
	v_mfma_f32_16x16x32_bf16 v[66:69], v[180:183], v[212:215], v[66:69]
	s_setprio 0
	s_barrier
	s_add_i32 s59, s48, s38
	v_lshl_add_u64 v[216:217], s[60:61], 0, v[132:133]
	s_mov_b32 m0, s59
	ds_read_b128 v[184:187], v150 offset:16384
	ds_read_b128 v[188:191], v150 offset:17408
	ds_read_b128 v[192:195], v150 offset:18432
	ds_read_b128 v[196:199], v150 offset:19456
	ds_read_b128 v[200:203], v150 offset:20480
	ds_read_b128 v[204:207], v150 offset:21504
	ds_read_b128 v[208:211], v150 offset:22528
	ds_read_b128 v[212:215], v150 offset:23552
	global_load_lds_dwordx4 v[216:217], off
	s_add_i32 m0, s59, 0x2000
	v_lshl_add_u64 v[218:219], s[60:61], 0, v[136:137]
	s_add_u32 s60, s60, s10
	s_addc_u32 s61, s61, s11
	s_add_i32 s59, s49, s38
	global_load_lds_dwordx4 v[218:219], off
	v_lshl_add_u64 v[220:221], s[60:61], 0, v[132:133]
	s_mov_b32 m0, s59
	v_lshl_add_u64 v[222:223], s[60:61], 0, v[136:137]
	global_load_lds_dwordx4 v[220:221], off
	s_add_i32 m0, s59, 0x2000
	v_lshl_add_u64 v[224:225], s[30:31], 0, v[130:131]
	global_load_lds_dwordx4 v[222:223], off
	s_mov_b32 m0, s0
	v_lshl_add_u64 v[226:227], s[30:31], 0, v[134:135]
	global_load_lds_dwordx4 v[224:225], off
	s_mov_b32 m0, s1
	s_nop 0
	global_load_lds_dwordx4 v[226:227], off
	s_waitcnt vmcnt(8) lgkmcnt(0)
	s_barrier
; #define PG8_STAGE(bufoff, gbase, voff) do { _Pragma("unroll") for (int _i = 0; _i < 2; ++_i) \
;         __builtin_amdgcn_global_load_lds((const unsigned*)((const char*)(gbase) + (voff)[_i]), (PG8_LAS unsigned*)(lds + (bufoff) + ldsw + _i * 8192), 16, 0, 0); } while (0)
; #define PG8_LDA(dst, b, h) do { _Pragma("unroll") for (int m = 0; m < 4; ++m) _Pragma("unroll") for (int k = 0; k < 2; ++k) dst[m][k] = *(const PG8_LAS bf16x8*)(lds + PG8_SA(b, h) + aoff + m * 2048 + k * 1024); } while (0)
; #define PG8_LDB(dst, b, h) do { _Pragma("unroll") for (int n = 0; n < 2; ++n) _Pragma("unroll") for (int k = 0; k < 2; ++k) dst[n][k] = *(const PG8_LAS bf16x8*)(lds + PG8_SB(b, h) + boff + n * 2048 + k * 1024); } while (0)
; #define PG8_MMA(ai, bj, At, Bt) do { __builtin_amdgcn_s_setprio(1); _Pragma("unroll") for (int m = 0; m < 4; ++m) _Pragma("unroll") for (int n = 0; n < 2; ++n) _Pragma("unroll") for (int k = 0; k < 2; ++k) \
;         acc[ai][bj][m][n] = __builtin_amdgcn_mfma_f32_16x16x32_bf16(Bt[n][k], At[m][k], acc[ai][bj][m][n], 0, 0, 0); __builtin_amdgcn_s_setprio(0); } while (0)
; #define PG8_WAIT_V(n) asm volatile("s_waitcnt vmcnt(" #n ")" ::: "memory")
; #define PG8_WAIT_L(n) asm volatile("s_waitcnt lgkmcnt(" #n ")" ::: "memory")
; #define PG8_BAR __builtin_amdgcn_s_barrier()
; #define PG8_SCHED __builtin_amdgcn_sched_barrier(0)
; template <class Epi, class Sched, bool ALIGN_EPI = false, bool SP2 = false>
; __device__ __forceinline__ void gemm_phase(PG8_LAS unsigned char* lds, const Gemm g, const Sched& S, const Epi& E) {
;     ...
;             PG8_WAIT_V(8); PG8_WAIT_L(0); PG8_BAR; PG8_MMA(1, 0, At, B0); PG8_MMA(1, 1, At, B1); PG8_BAR; PG8_SCHED;
;             PG8_LDB(B0, 1, 0); PG8_LDB(B1, 1, 1); PG8_SCHED; PG8_LDA(At, 1, 0); PG8_STAGE(PG8_SA(0, 1), a2 + hstep, voffA);
;             PG8_WAIT_V(8); PG8_WAIT_L(0); PG8_BAR; PG8_MMA(0, 0, At, B0); PG8_MMA(0, 1, At, B1); PG8_BAR; PG8_SCHED;
	s_setprio 1
	v_mfma_f32_16x16x32_bf16 v[62:65], v[152:155], v[184:187], v[62:65]
	v_mfma_f32_16x16x32_bf16 v[58:61], v[160:163], v[184:187], v[58:61]
	v_mfma_f32_16x16x32_bf16 v[46:49], v[152:155], v[192:195], v[46:49]
	v_mfma_f32_16x16x32_bf16 v[42:45], v[160:163], v[192:195], v[42:45]
	v_mfma_f32_16x16x32_bf16 v[30:33], v[152:155], v[200:203], v[30:33]
	v_mfma_f32_16x16x32_bf16 v[26:29], v[160:163], v[200:203], v[26:29]
	v_mfma_f32_16x16x32_bf16 v[14:17], v[152:155], v[208:211], v[14:17]
	v_mfma_f32_16x16x32_bf16 v[10:13], v[160:163], v[208:211], v[10:13]
	v_mfma_f32_16x16x32_bf16 v[62:65], v[156:159], v[188:191], v[62:65]
	v_mfma_f32_16x16x32_bf16 v[58:61], v[164:167], v[188:191], v[58:61]
	v_mfma_f32_16x16x32_bf16 v[46:49], v[156:159], v[196:199], v[46:49]
	v_mfma_f32_16x16x32_bf16 v[42:45], v[164:167], v[196:199], v[42:45]
	v_mfma_f32_16x16x32_bf16 v[30:33], v[156:159], v[204:207], v[30:33]
	v_mfma_f32_16x16x32_bf16 v[26:29], v[164:167], v[204:207], v[26:29]
	v_mfma_f32_16x16x32_bf16 v[14:17], v[156:159], v[212:215], v[14:17]
	v_mfma_f32_16x16x32_bf16 v[10:13], v[164:167], v[212:215], v[10:13]
	v_mfma_f32_16x16x32_bf16 v[54:57], v[168:171], v[184:187], v[54:57]
	v_mfma_f32_16x16x32_bf16 v[50:53], v[176:179], v[184:187], v[50:53]
	v_mfma_f32_16x16x32_bf16 v[38:41], v[168:171], v[192:195], v[38:41]
	v_mfma_f32_16x16x32_bf16 v[34:37], v[176:179], v[192:195], v[34:37]
	v_mfma_f32_16x16x32_bf16 v[22:25], v[168:171], v[200:203], v[22:25]
	v_mfma_f32_16x16x32_bf16 v[18:21], v[176:179], v[200:203], v[18:21]
	v_mfma_f32_16x16x32_bf16 v[6:9], v[168:171], v[208:211], v[6:9]
	v_mfma_f32_16x16x32_bf16 v[2:5], v[176:179], v[208:211], v[2:5]
	v_mfma_f32_16x16x32_bf16 v[54:57], v[172:175], v[188:191], v[54:57]
	v_mfma_f32_16x16x32_bf16 v[50:53], v[180:183], v[188:191], v[50:53]
	v_mfma_f32_16x16x32_bf16 v[38:41], v[172:175], v[196:199], v[38:41]
	v_mfma_f32_16x16x32_bf16 v[34:37], v[180:183], v[196:199], v[34:37]
	v_mfma_f32_16x16x32_bf16 v[22:25], v[172:175], v[204:207], v[22:25]
	v_mfma_f32_16x16x32_bf16 v[18:21], v[180:183], v[204:207], v[18:21]
	v_mfma_f32_16x16x32_bf16 v[6:9], v[172:175], v[212:215], v[6:9]
	v_mfma_f32_16x16x32_bf16 v[2:5], v[180:183], v[212:215], v[2:5]
	s_setprio 0
	s_barrier
	s_add_i32 s59, 0, 0x18000
	v_add_u32_e32 v151, s59, v146
	s_add_i32 s60, 0, 0x1c000
	ds_read_b128 v[152:155], v151
	ds_read_b128 v[156:159], v151 offset:1024
	ds_read_b128 v[160:163], v151 offset:2048
	ds_read_b128 v[164:167], v151 offset:3072
	v_add_u32_e32 v151, s60, v146
	ds_read_b128 v[168:171], v151
	ds_read_b128 v[172:175], v151 offset:1024
	ds_read_b128 v[176:179], v151 offset:2048
	ds_read_b128 v[180:183], v151 offset:3072
	s_add_u32 s30, s30, s10
	s_addc_u32 s31, s31, s11
	s_mov_b32 m0, s39
	v_lshl_add_u64 v[228:229], s[30:31], 0, v[130:131]
	ds_read_b128 v[184:187], v150 offset:32768
	ds_read_b128 v[188:191], v150 offset:33792
	ds_read_b128 v[192:195], v150 offset:34816
	ds_read_b128 v[196:199], v150 offset:35840
	ds_read_b128 v[200:203], v150 offset:36864
	ds_read_b128 v[204:207], v150 offset:37888
	ds_read_b128 v[208:211], v150 offset:38912
	ds_read_b128 v[212:215], v150 offset:39936
	global_load_lds_dwordx4 v[228:229], off
	s_mov_b32 m0, s40
	v_lshl_add_u64 v[228:229], s[30:31], 0, v[134:135]
	global_load_lds_dwordx4 v[228:229], off
	s_waitcnt vmcnt(8) lgkmcnt(0)
	s_barrier
	s_setprio 1
	v_mfma_f32_16x16x32_bf16 v[122:125], v[152:155], v[184:187], v[122:125]
	v_mfma_f32_16x16x32_bf16 v[126:129], v[160:163], v[184:187], v[126:129]
	v_mfma_f32_16x16x32_bf16 v[110:113], v[152:155], v[192:195], v[110:113]
	v_mfma_f32_16x16x32_bf16 v[106:109], v[160:163], v[192:195], v[106:109]
	v_mfma_f32_16x16x32_bf16 v[94:97], v[152:155], v[200:203], v[94:97]
	v_mfma_f32_16x16x32_bf16 v[90:93], v[160:163], v[200:203], v[90:93]
	v_mfma_f32_16x16x32_bf16 v[78:81], v[152:155], v[208:211], v[78:81]
	v_mfma_f32_16x16x32_bf16 v[74:77], v[160:163], v[208:211], v[74:77]
	v_mfma_f32_16x16x32_bf16 v[122:125], v[156:159], v[188:191], v[122:125]
	v_mfma_f32_16x16x32_bf16 v[126:129], v[164:167], v[188:191], v[126:129]
	v_mfma_f32_16x16x32_bf16 v[110:113], v[156:159], v[196:199], v[110:113]
	v_mfma_f32_16x16x32_bf16 v[106:109], v[164:167], v[196:199], v[106:109]
	v_mfma_f32_16x16x32_bf16 v[94:97], v[156:159], v[204:207], v[94:97]
	v_mfma_f32_16x16x32_bf16 v[90:93], v[164:167], v[204:207], v[90:93]
	v_mfma_f32_16x16x32_bf16 v[78:81], v[156:159], v[212:215], v[78:81]
	v_mfma_f32_16x16x32_bf16 v[74:77], v[164:167], v[212:215], v[74:77]
	v_mfma_f32_16x16x32_bf16 v[118:121], v[168:171], v[184:187], v[118:121]
	v_mfma_f32_16x16x32_bf16 v[114:117], v[176:179], v[184:187], v[114:117]
	v_mfma_f32_16x16x32_bf16 v[102:105], v[168:171], v[192:195], v[102:105]
	v_mfma_f32_16x16x32_bf16 v[98:101], v[176:179], v[192:195], v[98:101]
	v_mfma_f32_16x16x32_bf16 v[86:89], v[168:171], v[200:203], v[86:89]
	v_mfma_f32_16x16x32_bf16 v[82:85], v[176:179], v[200:203], v[82:85]
	v_mfma_f32_16x16x32_bf16 v[70:73], v[168:171], v[208:211], v[70:73]
	v_mfma_f32_16x16x32_bf16 v[66:69], v[176:179], v[208:211], v[66:69]
	v_mfma_f32_16x16x32_bf16 v[118:121], v[172:175], v[188:191], v[118:121]
	v_mfma_f32_16x16x32_bf16 v[114:117], v[180:183], v[188:191], v[114:117]
	v_mfma_f32_16x16x32_bf16 v[102:105], v[172:175], v[196:199], v[102:105]
	v_mfma_f32_16x16x32_bf16 v[98:101], v[180:183], v[196:199], v[98:101]
	v_mfma_f32_16x16x32_bf16 v[86:89], v[172:175], v[204:207], v[86:89]
	v_mfma_f32_16x16x32_bf16 v[82:85], v[180:183], v[204:207], v[82:85]
	v_mfma_f32_16x16x32_bf16 v[70:73], v[172:175], v[212:215], v[70:73]
	v_mfma_f32_16x16x32_bf16 v[66:69], v[180:183], v[212:215], v[66:69]
	s_setprio 0
	s_barrier
; #define PG8_STAGE(bufoff, gbase, voff) do { _Pragma("unroll") for (int _i = 0; _i < 2; ++_i) \
;         __builtin_amdgcn_global_load_lds((const unsigned*)((const char*)(gbase) + (voff)[_i]), (PG8_LAS unsigned*)(lds + (bufoff) + ldsw + _i * 8192), 16, 0, 0); } while (0)
; #define PG8_LDA(dst, b, h) do { _Pragma("unroll") for (int m = 0; m < 4; ++m) _Pragma("unroll") for (int k = 0; k < 2; ++k) dst[m][k] = *(const PG8_LAS bf16x8*)(lds + PG8_SA(b, h) + aoff + m * 2048 + k * 1024); } while (0)
; #define PG8_MMA(ai, bj, At, Bt) do { __builtin_amdgcn_s_setprio(1); _Pragma("unroll") for (int m = 0; m < 4; ++m) _Pragma("unroll") for (int n = 0; n < 2; ++n) _Pragma("unroll") for (int k = 0; k < 2; ++k) \
;         acc[ai][bj][m][n] = __builtin_amdgcn_mfma_f32_16x16x32_bf16(Bt[n][k], At[m][k], acc[ai][bj][m][n], 0, 0, 0); __builtin_amdgcn_s_setprio(0); } while (0)
; #define PG8_WAIT_V(n) asm volatile("s_waitcnt vmcnt(" #n ")" ::: "memory")
; #define PG8_WAIT_L(n) asm volatile("s_waitcnt lgkmcnt(" #n ")" ::: "memory")
; #define PG8_BAR __builtin_amdgcn_s_barrier()
; #define PG8_SCHED __builtin_amdgcn_sched_barrier(0)
; template <class Epi, class Sched, bool ALIGN_EPI = false, bool SP2 = false>
; __device__ __forceinline__ void gemm_phase(PG8_LAS unsigned char* lds, const Gemm g, const Sched& S, const Epi& E) {
;     ...
;         for (int t = 0; t < nt; t += 2) {
;     ...
;             PG8_LDA(At, 1, 1); PG8_STAGE(PG8_SB(1, 0), b3, voffB); PG8_STAGE(PG8_SB(1, 1), b3 + hstep, voffB); PG8_STAGE(PG8_SA(1, 0), a3, voffA);
;             PG8_WAIT_V(8); PG8_WAIT_L(0); PG8_BAR; PG8_MMA(1, 0, At, B0); PG8_MMA(1, 1, At, B1); PG8_BAR; PG8_SCHED;
	s_add_i32 s30, s59, s38
	v_lshl_add_u64 v[216:217], v[216:217], 0, s[18:19]
	s_mov_b32 m0, s30
	ds_read_b128 v[184:187], v150 offset:49152
	ds_read_b128 v[188:191], v150 offset:50176
	ds_read_b128 v[192:195], v150 offset:51200
	ds_read_b128 v[196:199], v150 offset:52224
	ds_read_b128 v[200:203], v150 offset:53248
	ds_read_b128 v[204:207], v150 offset:54272
	ds_read_b128 v[208:211], v150 offset:55296
	ds_read_b128 v[212:215], v150 offset:56320
	global_load_lds_dwordx4 v[216:217], off
	v_lshl_add_u64 v[216:217], v[218:219], 0, s[18:19]
	s_add_i32 m0, s30, 0x2000
	s_add_i32 s30, s60, s38
	global_load_lds_dwordx4 v[216:217], off
	s_mov_b32 m0, s30
	v_lshl_add_u64 v[216:217], v[220:221], 0, s[18:19]
	global_load_lds_dwordx4 v[216:217], off
	s_add_i32 m0, s30, 0x2000
	v_lshl_add_u64 v[216:217], v[222:223], 0, s[18:19]
	global_load_lds_dwordx4 v[216:217], off
	s_mov_b32 m0, s42
	v_lshl_add_u64 v[216:217], v[224:225], 0, s[18:19]
	global_load_lds_dwordx4 v[216:217], off
	s_mov_b32 m0, s43
	v_lshl_add_u64 v[216:217], v[226:227], 0, s[18:19]
	global_load_lds_dwordx4 v[216:217], off
	s_waitcnt vmcnt(8) lgkmcnt(0)
	s_barrier
	s_setprio 1
	v_mfma_f32_16x16x32_bf16 v[62:65], v[152:155], v[184:187], v[62:65]
	v_mfma_f32_16x16x32_bf16 v[58:61], v[160:163], v[184:187], v[58:61]
	v_mfma_f32_16x16x32_bf16 v[46:49], v[152:155], v[192:195], v[46:49]
	v_mfma_f32_16x16x32_bf16 v[42:45], v[160:163], v[192:195], v[42:45]
	v_mfma_f32_16x16x32_bf16 v[30:33], v[152:155], v[200:203], v[30:33]
	v_mfma_f32_16x16x32_bf16 v[26:29], v[160:163], v[200:203], v[26:29]
	v_mfma_f32_16x16x32_bf16 v[14:17], v[152:155], v[208:211], v[14:17]
	v_mfma_f32_16x16x32_bf16 v[10:13], v[160:163], v[208:211], v[10:13]
	v_mfma_f32_16x16x32_bf16 v[62:65], v[156:159], v[188:191], v[62:65]
	v_mfma_f32_16x16x32_bf16 v[58:61], v[164:167], v[188:191], v[58:61]
	v_mfma_f32_16x16x32_bf16 v[46:49], v[156:159], v[196:199], v[46:49]
	v_mfma_f32_16x16x32_bf16 v[42:45], v[164:167], v[196:199], v[42:45]
	v_mfma_f32_16x16x32_bf16 v[30:33], v[156:159], v[204:207], v[30:33]
	v_mfma_f32_16x16x32_bf16 v[26:29], v[164:167], v[204:207], v[26:29]
	v_mfma_f32_16x16x32_bf16 v[14:17], v[156:159], v[212:215], v[14:17]
	v_mfma_f32_16x16x32_bf16 v[10:13], v[164:167], v[212:215], v[10:13]
	v_mfma_f32_16x16x32_bf16 v[54:57], v[168:171], v[184:187], v[54:57]
	v_mfma_f32_16x16x32_bf16 v[50:53], v[176:179], v[184:187], v[50:53]
	v_mfma_f32_16x16x32_bf16 v[38:41], v[168:171], v[192:195], v[38:41]
	v_mfma_f32_16x16x32_bf16 v[34:37], v[176:179], v[192:195], v[34:37]
	v_mfma_f32_16x16x32_bf16 v[22:25], v[168:171], v[200:203], v[22:25]
	v_mfma_f32_16x16x32_bf16 v[18:21], v[176:179], v[200:203], v[18:21]
	v_mfma_f32_16x16x32_bf16 v[6:9], v[168:171], v[208:211], v[6:9]
	v_mfma_f32_16x16x32_bf16 v[2:5], v[176:179], v[208:211], v[2:5]
	v_mfma_f32_16x16x32_bf16 v[54:57], v[172:175], v[188:191], v[54:57]
	v_mfma_f32_16x16x32_bf16 v[50:53], v[180:183], v[188:191], v[50:53]
	v_mfma_f32_16x16x32_bf16 v[38:41], v[172:175], v[196:199], v[38:41]
	v_mfma_f32_16x16x32_bf16 v[34:37], v[180:183], v[196:199], v[34:37]
	v_mfma_f32_16x16x32_bf16 v[22:25], v[172:175], v[204:207], v[22:25]
	v_mfma_f32_16x16x32_bf16 v[18:21], v[180:183], v[204:207], v[18:21]
	v_mfma_f32_16x16x32_bf16 v[6:9], v[172:175], v[212:215], v[6:9]
	v_mfma_f32_16x16x32_bf16 v[2:5], v[180:183], v[212:215], v[2:5]
	s_setprio 0
	s_barrier
	s_add_u32 s56, s56, 0x100
	s_addc_u32 s57, s57, 0
	s_add_u32 s28, s28, 0x100
	s_addc_u32 s29, s29, 0
	s_cmp_ge_i32 s58, s44
	s_mov_b32 s30, s58
	s_cbranch_scc0 .LBB0_834

; #define PG8_STAGE(bufoff, gbase, voff) do { _Pragma("unroll") for (int _i = 0; _i < 2; ++_i) \
;         __builtin_amdgcn_global_load_lds((const unsigned*)((const char*)(gbase) + (voff)[_i]), (PG8_LAS unsigned*)(lds + (bufoff) + ldsw + _i * 8192), 16, 0, 0); } while (0)
; #define PG8_LDA(dst, b, h) do { _Pragma("unroll") for (int m = 0; m < 4; ++m) _Pragma("unroll") for (int k = 0; k < 2; ++k) dst[m][k] = *(const PG8_LAS bf16x8*)(lds + PG8_SA(b, h) + aoff + m * 2048 + k * 1024); } while (0)
; #define PG8_LDB(dst, b, h) do { _Pragma("unroll") for (int n = 0; n < 2; ++n) _Pragma("unroll") for (int k = 0; k < 2; ++k) dst[n][k] = *(const PG8_LAS bf16x8*)(lds + PG8_SB(b, h) + boff + n * 2048 + k * 1024); } while (0)
; #define PG8_WAIT_V(n) asm volatile("s_waitcnt vmcnt(" #n ")" ::: "memory")
; #define PG8_WAIT_L(n) asm volatile("s_waitcnt lgkmcnt(" #n ")" ::: "memory")
; #define PG8_BAR __builtin_amdgcn_s_barrier()
; #define PG8_SCHED __builtin_amdgcn_sched_barrier(0)
; template <class Epi, class Sched, bool ALIGN_EPI = false, bool SP2 = false>
; __device__ __forceinline__ void gemm_phase(PG8_LAS unsigned char* lds, const Gemm g, const Sched& S, const Epi& E) {
;     ...
;         const bool has_next = S.next(ui + 1, nxt);
;         const char* nA = has_next ? (const char*)g.A + (size_t)nxt.pm * tstep : cA; const char* nB = has_next ? (const char*)g.Bt + (size_t)nxt.pn * tstep : cB;
;         for (int t = 0; t < nt; t += 2) {
;             const bool last = (t == nt - 2);
;             const char* a1 = cA + (size_t)(t + 1) * kstep;
;             const char* a2 = last ? nA : cA + (size_t)(t + 2) * kstep; const char* b2 = last ? nB : cB + (size_t)(t + 2) * kstep;
;             const char* a3 = a2 + kstep; const char* b3 = b2 + kstep;
;             if (last && has_next) S.a_ready(nxt);
;             if constexpr (SP2) {
;             PG8_LDB(B0, 0, 0); PG8_LDB(B1, 0, 1); PG8_SCHED; PG8_LDA(At, 0, 0); PG8_STAGE(PG8_SA(1, 1), a1 + hstep, voffA);
;             PG8_WAIT_V(8); PG8_WAIT_L(0); PG8_BAR; PG8_MMA(0, 0, At, B0); PG8_MMA(0, 1, At, B1); PG8_BAR; PG8_SCHED;
;             PG8_LDA(At, 0, 1); PG8_STAGE(PG8_SB(0, 0), b2, voffB); PG8_STAGE(PG8_SB(0, 1), b2 + hstep, voffB); PG8_STAGE(PG8_SA(0, 0), a2, voffA);
;             PG8_WAIT_V(8); PG8_WAIT_L(0); PG8_BAR; PG8_MMA(1, 0, At, B0); PG8_MMA(1, 1, At, B1); PG8_BAR; PG8_SCHED;
.LBB0_1154:
	ds_read_b128 v[130:133], v160
	ds_read_b128 v[134:137], v160 offset:1024
	ds_read_b128 v[164:167], v160 offset:2048
	ds_read_b128 v[168:171], v160 offset:3072
	ds_read_b128 v[172:175], v161
	ds_read_b128 v[176:179], v161 offset:1024
	ds_read_b128 v[180:183], v161 offset:2048
	ds_read_b128 v[184:187], v161 offset:3072
	s_add_i32 s81, s36, 2
	s_add_u32 s70, s34, 0x80
	s_addc_u32 s37, s35, 0
	s_cmp_eq_u32 s55, s36
	s_cselect_b32 s36, s4, s70
	s_cselect_b32 s37, s5, s37
	s_cselect_b32 s71, s31, s80
	s_cselect_b32 s70, s30, s45
	v_lshl_add_u64 v[158:159], s[34:35], 0, v[152:153]
	s_add_i32 m0, s42, 0xc000
	ds_read_b128 v[188:191], v162
	ds_read_b128 v[192:195], v162 offset:1024
	ds_read_b128 v[196:199], v162 offset:2048
	ds_read_b128 v[200:203], v162 offset:3072
	ds_read_b128 v[204:207], v162 offset:4096
	ds_read_b128 v[208:211], v162 offset:5120
	ds_read_b128 v[212:215], v162 offset:6144
	ds_read_b128 v[216:219], v162 offset:7168
	global_load_lds_dwordx4 v[158:159], off
	s_add_i32 m0, s42, 0xe000
	v_lshl_add_u64 v[158:159], s[34:35], 0, v[150:151]
	global_load_lds_dwordx4 v[158:159], off
	s_waitcnt vmcnt(8) lgkmcnt(0)
	s_barrier
	s_setprio 1
	v_mfma_f32_16x16x32_bf16 v[126:129], v[130:133], v[188:191], v[126:129]
	v_mfma_f32_16x16x32_bf16 v[122:125], v[164:167], v[188:191], v[122:125]
	v_mfma_f32_16x16x32_bf16 v[110:113], v[130:133], v[196:199], v[110:113]
	v_mfma_f32_16x16x32_bf16 v[106:109], v[164:167], v[196:199], v[106:109]
	v_mfma_f32_16x16x32_bf16 v[94:97], v[130:133], v[204:207], v[94:97]
	v_mfma_f32_16x16x32_bf16 v[90:93], v[164:167], v[204:207], v[90:93]
	v_mfma_f32_16x16x32_bf16 v[78:81], v[130:133], v[212:215], v[78:81]
	v_mfma_f32_16x16x32_bf16 v[74:77], v[164:167], v[212:215], v[74:77]
	v_mfma_f32_16x16x32_bf16 v[126:129], v[134:137], v[192:195], v[126:129]
	v_mfma_f32_16x16x32_bf16 v[122:125], v[168:171], v[192:195], v[122:125]
	v_mfma_f32_16x16x32_bf16 v[110:113], v[134:137], v[200:203], v[110:113]
	v_mfma_f32_16x16x32_bf16 v[106:109], v[168:171], v[200:203], v[106:109]
	v_mfma_f32_16x16x32_bf16 v[94:97], v[134:137], v[208:211], v[94:97]
	v_mfma_f32_16x16x32_bf16 v[90:93], v[168:171], v[208:211], v[90:93]
	v_mfma_f32_16x16x32_bf16 v[78:81], v[134:137], v[216:219], v[78:81]
	v_mfma_f32_16x16x32_bf16 v[74:77], v[168:171], v[216:219], v[74:77]
	v_mfma_f32_16x16x32_bf16 v[118:121], v[172:175], v[188:191], v[118:121]
	v_mfma_f32_16x16x32_bf16 v[114:117], v[180:183], v[188:191], v[114:117]
	v_mfma_f32_16x16x32_bf16 v[102:105], v[172:175], v[196:199], v[102:105]
	v_mfma_f32_16x16x32_bf16 v[98:101], v[180:183], v[196:199], v[98:101]
	v_mfma_f32_16x16x32_bf16 v[86:89], v[172:175], v[204:207], v[86:89]
	v_mfma_f32_16x16x32_bf16 v[82:85], v[180:183], v[204:207], v[82:85]
	v_mfma_f32_16x16x32_bf16 v[70:73], v[172:175], v[212:215], v[70:73]
	v_mfma_f32_16x16x32_bf16 v[66:69], v[180:183], v[212:215], v[66:69]
	v_mfma_f32_16x16x32_bf16 v[118:121], v[176:179], v[192:195], v[118:121]
	v_mfma_f32_16x16x32_bf16 v[114:117], v[184:187], v[192:195], v[114:117]
	v_mfma_f32_16x16x32_bf16 v[102:105], v[176:179], v[200:203], v[102:105]
	v_mfma_f32_16x16x32_bf16 v[98:101], v[184:187], v[200:203], v[98:101]
	v_mfma_f32_16x16x32_bf16 v[86:89], v[176:179], v[208:211], v[86:89]
	v_mfma_f32_16x16x32_bf16 v[82:85], v[184:187], v[208:211], v[82:85]
	v_mfma_f32_16x16x32_bf16 v[70:73], v[176:179], v[216:219], v[70:73]
	v_mfma_f32_16x16x32_bf16 v[66:69], v[184:187], v[216:219], v[66:69]
	s_setprio 0
	s_barrier
	s_add_i32 s72, s69, s41
	v_lshl_add_u64 v[158:159], s[70:71], 0, v[140:141]
	s_mov_b32 m0, s72
	ds_read_b128 v[188:191], v162 offset:16384
	ds_read_b128 v[192:195], v162 offset:17408
	ds_read_b128 v[196:199], v162 offset:18432
	ds_read_b128 v[200:203], v162 offset:19456
	ds_read_b128 v[204:207], v162 offset:20480
	ds_read_b128 v[208:211], v162 offset:21504
	ds_read_b128 v[212:215], v162 offset:22528
	ds_read_b128 v[216:219], v162 offset:23552
	global_load_lds_dwordx4 v[158:159], off
	s_add_i32 m0, s72, 0x2000
	v_lshl_add_u64 v[220:221], s[70:71], 0, v[144:145]
	s_add_u32 s70, s70, s8
	s_addc_u32 s71, s71, s9
	s_add_i32 s72, s86, s41
	global_load_lds_dwordx4 v[220:221], off
	v_lshl_add_u64 v[222:223], s[70:71], 0, v[140:141]
	s_mov_b32 m0, s72
	v_lshl_add_u64 v[224:225], s[70:71], 0, v[144:145]
	global_load_lds_dwordx4 v[222:223], off
	s_add_i32 m0, s72, 0x2000
	v_lshl_add_u64 v[226:227], s[36:37], 0, v[138:139]
	global_load_lds_dwordx4 v[224:225], off
	s_mov_b32 m0, s42
	v_lshl_add_u64 v[228:229], s[36:37], 0, v[142:143]
	global_load_lds_dwordx4 v[226:227], off
	s_mov_b32 m0, s46
	s_nop 0
	global_load_lds_dwordx4 v[228:229], off
	s_waitcnt vmcnt(8) lgkmcnt(0)
	s_barrier
; #define PG8_STAGE(bufoff, gbase, voff) do { _Pragma("unroll") for (int _i = 0; _i < 2; ++_i) \
;         __builtin_amdgcn_global_load_lds((const unsigned*)((const char*)(gbase) + (voff)[_i]), (PG8_LAS unsigned*)(lds + (bufoff) + ldsw + _i * 8192), 16, 0, 0); } while (0)
; #define PG8_LDA(dst, b, h) do { _Pragma("unroll") for (int m = 0; m < 4; ++m) _Pragma("unroll") for (int k = 0; k < 2; ++k) dst[m][k] = *(const PG8_LAS bf16x8*)(lds + PG8_SA(b, h) + aoff + m * 2048 + k * 1024); } while (0)
; #define PG8_LDB(dst, b, h) do { _Pragma("unroll") for (int n = 0; n < 2; ++n) _Pragma("unroll") for (int k = 0; k < 2; ++k) dst[n][k] = *(const PG8_LAS bf16x8*)(lds + PG8_SB(b, h) + boff + n * 2048 + k * 1024); } while (0)
; #define PG8_MMA(ai, bj, At, Bt) do { __builtin_amdgcn_s_setprio(1); _Pragma("unroll") for (int m = 0; m < 4; ++m) _Pragma("unroll") for (int n = 0; n < 2; ++n) _Pragma("unroll") for (int k = 0; k < 2; ++k) \
;         acc[ai][bj][m][n] = __builtin_amdgcn_mfma_f32_16x16x32_bf16(Bt[n][k], At[m][k], acc[ai][bj][m][n], 0, 0, 0); __builtin_amdgcn_s_setprio(0); } while (0)
; #define PG8_WAIT_V(n) asm volatile("s_waitcnt vmcnt(" #n ")" ::: "memory")
; #define PG8_WAIT_L(n) asm volatile("s_waitcnt lgkmcnt(" #n ")" ::: "memory")
; #define PG8_BAR __builtin_amdgcn_s_barrier()
; #define PG8_SCHED __builtin_amdgcn_sched_barrier(0)
; template <class Epi, class Sched, bool ALIGN_EPI = false, bool SP2 = false>
; __device__ __forceinline__ void gemm_phase(PG8_LAS unsigned char* lds, const Gemm g, const Sched& S, const Epi& E) {
;     ...
;             PG8_WAIT_V(8); PG8_WAIT_L(0); PG8_BAR; PG8_MMA(1, 0, At, B0); PG8_MMA(1, 1, At, B1); PG8_BAR; PG8_SCHED;
;             PG8_LDB(B0, 1, 0); PG8_LDB(B1, 1, 1); PG8_SCHED; PG8_LDA(At, 1, 0); PG8_STAGE(PG8_SA(0, 1), a2 + hstep, voffA);
;             PG8_WAIT_V(8); PG8_WAIT_L(0); PG8_BAR; PG8_MMA(0, 0, At, B0); PG8_MMA(0, 1, At, B1); PG8_BAR; PG8_SCHED;
	s_setprio 1
	v_mfma_f32_16x16x32_bf16 v[62:65], v[130:133], v[188:191], v[62:65]
	v_mfma_f32_16x16x32_bf16 v[58:61], v[164:167], v[188:191], v[58:61]
	v_mfma_f32_16x16x32_bf16 v[46:49], v[130:133], v[196:199], v[46:49]
	v_mfma_f32_16x16x32_bf16 v[42:45], v[164:167], v[196:199], v[42:45]
	v_mfma_f32_16x16x32_bf16 v[30:33], v[130:133], v[204:207], v[30:33]
	v_mfma_f32_16x16x32_bf16 v[26:29], v[164:167], v[204:207], v[26:29]
	v_mfma_f32_16x16x32_bf16 v[14:17], v[130:133], v[212:215], v[14:17]
	v_mfma_f32_16x16x32_bf16 v[10:13], v[164:167], v[212:215], v[10:13]
	v_mfma_f32_16x16x32_bf16 v[62:65], v[134:137], v[192:195], v[62:65]
	v_mfma_f32_16x16x32_bf16 v[58:61], v[168:171], v[192:195], v[58:61]
	v_mfma_f32_16x16x32_bf16 v[46:49], v[134:137], v[200:203], v[46:49]
	v_mfma_f32_16x16x32_bf16 v[42:45], v[168:171], v[200:203], v[42:45]
	v_mfma_f32_16x16x32_bf16 v[30:33], v[134:137], v[208:211], v[30:33]
	v_mfma_f32_16x16x32_bf16 v[26:29], v[168:171], v[208:211], v[26:29]
	v_mfma_f32_16x16x32_bf16 v[14:17], v[134:137], v[216:219], v[14:17]
	v_mfma_f32_16x16x32_bf16 v[10:13], v[168:171], v[216:219], v[10:13]
	v_mfma_f32_16x16x32_bf16 v[54:57], v[172:175], v[188:191], v[54:57]
	v_mfma_f32_16x16x32_bf16 v[50:53], v[180:183], v[188:191], v[50:53]
	v_mfma_f32_16x16x32_bf16 v[38:41], v[172:175], v[196:199], v[38:41]
	v_mfma_f32_16x16x32_bf16 v[34:37], v[180:183], v[196:199], v[34:37]
	v_mfma_f32_16x16x32_bf16 v[22:25], v[172:175], v[204:207], v[22:25]
	v_mfma_f32_16x16x32_bf16 v[18:21], v[180:183], v[204:207], v[18:21]
	v_mfma_f32_16x16x32_bf16 v[6:9], v[172:175], v[212:215], v[6:9]
	v_mfma_f32_16x16x32_bf16 v[2:5], v[180:183], v[212:215], v[2:5]
	v_mfma_f32_16x16x32_bf16 v[54:57], v[176:179], v[192:195], v[54:57]
	v_mfma_f32_16x16x32_bf16 v[50:53], v[184:187], v[192:195], v[50:53]
	v_mfma_f32_16x16x32_bf16 v[38:41], v[176:179], v[200:203], v[38:41]
	v_mfma_f32_16x16x32_bf16 v[34:37], v[184:187], v[200:203], v[34:37]
	v_mfma_f32_16x16x32_bf16 v[22:25], v[176:179], v[208:211], v[22:25]
	v_mfma_f32_16x16x32_bf16 v[18:21], v[184:187], v[208:211], v[18:21]
	v_mfma_f32_16x16x32_bf16 v[6:9], v[176:179], v[216:219], v[6:9]
	v_mfma_f32_16x16x32_bf16 v[2:5], v[184:187], v[216:219], v[2:5]
	s_setprio 0
	s_barrier
	s_add_i32 s70, 0, 0x18000
	v_add_u32_e32 v146, s70, v149
	s_add_i32 s71, 0, 0x1c000
	ds_read_b128 v[130:133], v146
	ds_read_b128 v[134:137], v146 offset:1024
	ds_read_b128 v[164:167], v146 offset:2048
	ds_read_b128 v[168:171], v146 offset:3072
	v_add_u32_e32 v146, s71, v149
	ds_read_b128 v[172:175], v146
	ds_read_b128 v[176:179], v146 offset:1024
	ds_read_b128 v[180:183], v146 offset:2048
	ds_read_b128 v[184:187], v146 offset:3072
	s_add_u32 s36, s36, s8
	s_addc_u32 s37, s37, s9
	s_mov_b32 m0, s47
	v_lshl_add_u64 v[230:231], s[36:37], 0, v[138:139]
	ds_read_b128 v[188:191], v162 offset:32768
	ds_read_b128 v[192:195], v162 offset:33792
	ds_read_b128 v[196:199], v162 offset:34816
	ds_read_b128 v[200:203], v162 offset:35840
	ds_read_b128 v[204:207], v162 offset:36864
	ds_read_b128 v[208:211], v162 offset:37888
	ds_read_b128 v[212:215], v162 offset:38912
	ds_read_b128 v[216:219], v162 offset:39936
	global_load_lds_dwordx4 v[230:231], off
	s_mov_b32 m0, s48
	v_lshl_add_u64 v[230:231], s[36:37], 0, v[142:143]
	global_load_lds_dwordx4 v[230:231], off
	s_waitcnt vmcnt(8) lgkmcnt(0)
	s_barrier
	s_setprio 1
	v_mfma_f32_16x16x32_bf16 v[126:129], v[130:133], v[188:191], v[126:129]
	v_mfma_f32_16x16x32_bf16 v[122:125], v[164:167], v[188:191], v[122:125]
	v_mfma_f32_16x16x32_bf16 v[110:113], v[130:133], v[196:199], v[110:113]
	v_mfma_f32_16x16x32_bf16 v[106:109], v[164:167], v[196:199], v[106:109]
	v_mfma_f32_16x16x32_bf16 v[94:97], v[130:133], v[204:207], v[94:97]
	v_mfma_f32_16x16x32_bf16 v[90:93], v[164:167], v[204:207], v[90:93]
	v_mfma_f32_16x16x32_bf16 v[78:81], v[130:133], v[212:215], v[78:81]
	v_mfma_f32_16x16x32_bf16 v[74:77], v[164:167], v[212:215], v[74:77]
	v_mfma_f32_16x16x32_bf16 v[126:129], v[134:137], v[192:195], v[126:129]
	v_mfma_f32_16x16x32_bf16 v[122:125], v[168:171], v[192:195], v[122:125]
	v_mfma_f32_16x16x32_bf16 v[110:113], v[134:137], v[200:203], v[110:113]
	v_mfma_f32_16x16x32_bf16 v[106:109], v[168:171], v[200:203], v[106:109]
	v_mfma_f32_16x16x32_bf16 v[94:97], v[134:137], v[208:211], v[94:97]
	v_mfma_f32_16x16x32_bf16 v[90:93], v[168:171], v[208:211], v[90:93]
	v_mfma_f32_16x16x32_bf16 v[78:81], v[134:137], v[216:219], v[78:81]
	v_mfma_f32_16x16x32_bf16 v[74:77], v[168:171], v[216:219], v[74:77]
	v_mfma_f32_16x16x32_bf16 v[118:121], v[172:175], v[188:191], v[118:121]
	v_mfma_f32_16x16x32_bf16 v[114:117], v[180:183], v[188:191], v[114:117]
	v_mfma_f32_16x16x32_bf16 v[102:105], v[172:175], v[196:199], v[102:105]
	v_mfma_f32_16x16x32_bf16 v[98:101], v[180:183], v[196:199], v[98:101]
	v_mfma_f32_16x16x32_bf16 v[86:89], v[172:175], v[204:207], v[86:89]
	v_mfma_f32_16x16x32_bf16 v[82:85], v[180:183], v[204:207], v[82:85]
	v_mfma_f32_16x16x32_bf16 v[70:73], v[172:175], v[212:215], v[70:73]
	v_mfma_f32_16x16x32_bf16 v[66:69], v[180:183], v[212:215], v[66:69]
	v_mfma_f32_16x16x32_bf16 v[118:121], v[176:179], v[192:195], v[118:121]
	v_mfma_f32_16x16x32_bf16 v[114:117], v[184:187], v[192:195], v[114:117]
	v_mfma_f32_16x16x32_bf16 v[102:105], v[176:179], v[200:203], v[102:105]
	v_mfma_f32_16x16x32_bf16 v[98:101], v[184:187], v[200:203], v[98:101]
	v_mfma_f32_16x16x32_bf16 v[86:89], v[176:179], v[208:211], v[86:89]
	v_mfma_f32_16x16x32_bf16 v[82:85], v[184:187], v[208:211], v[82:85]
	v_mfma_f32_16x16x32_bf16 v[70:73], v[176:179], v[216:219], v[70:73]
	v_mfma_f32_16x16x32_bf16 v[66:69], v[184:187], v[216:219], v[66:69]
	s_setprio 0
	s_barrier
; #define PG8_STAGE(bufoff, gbase, voff) do { _Pragma("unroll") for (int _i = 0; _i < 2; ++_i) \
;         __builtin_amdgcn_global_load_lds((const unsigned*)((const char*)(gbase) + (voff)[_i]), (PG8_LAS unsigned*)(lds + (bufoff) + ldsw + _i * 8192), 16, 0, 0); } while (0)
; #define PG8_LDA(dst, b, h) do { _Pragma("unroll") for (int m = 0; m < 4; ++m) _Pragma("unroll") for (int k = 0; k < 2; ++k) dst[m][k] = *(const PG8_LAS bf16x8*)(lds + PG8_SA(b, h) + aoff + m * 2048 + k * 1024); } while (0)
; #define PG8_MMA(ai, bj, At, Bt) do { __builtin_amdgcn_s_setprio(1); _Pragma("unroll") for (int m = 0; m < 4; ++m) _Pragma("unroll") for (int n = 0; n < 2; ++n) _Pragma("unroll") for (int k = 0; k < 2; ++k) \
;         acc[ai][bj][m][n] = __builtin_amdgcn_mfma_f32_16x16x32_bf16(Bt[n][k], At[m][k], acc[ai][bj][m][n], 0, 0, 0); __builtin_amdgcn_s_setprio(0); } while (0)
; #define PG8_WAIT_V(n) asm volatile("s_waitcnt vmcnt(" #n ")" ::: "memory")
; #define PG8_WAIT_L(n) asm volatile("s_waitcnt lgkmcnt(" #n ")" ::: "memory")
; #define PG8_BAR __builtin_amdgcn_s_barrier()
; #define PG8_SCHED __builtin_amdgcn_sched_barrier(0)
; template <class Epi, class Sched, bool ALIGN_EPI = false, bool SP2 = false>
; __device__ __forceinline__ void gemm_phase(PG8_LAS unsigned char* lds, const Gemm g, const Sched& S, const Epi& E) {
;     ...
;         for (int t = 0; t < nt; t += 2) {
;     ...
;             PG8_LDA(At, 1, 1); PG8_STAGE(PG8_SB(1, 0), b3, voffB); PG8_STAGE(PG8_SB(1, 1), b3 + hstep, voffB); PG8_STAGE(PG8_SA(1, 0), a3, voffA);
;             PG8_WAIT_V(8); PG8_WAIT_L(0); PG8_BAR; PG8_MMA(1, 0, At, B0); PG8_MMA(1, 1, At, B1); PG8_BAR; PG8_SCHED;
	s_add_i32 s36, s70, s41
	v_lshl_add_u64 v[158:159], v[158:159], 0, s[24:25]
	s_mov_b32 m0, s36
	ds_read_b128 v[188:191], v162 offset:49152
	ds_read_b128 v[192:195], v162 offset:50176
	ds_read_b128 v[196:199], v162 offset:51200
	ds_read_b128 v[200:203], v162 offset:52224
	ds_read_b128 v[204:207], v162 offset:53248
	ds_read_b128 v[208:211], v162 offset:54272
	ds_read_b128 v[212:215], v162 offset:55296
	ds_read_b128 v[216:219], v162 offset:56320
	global_load_lds_dwordx4 v[158:159], off
	v_lshl_add_u64 v[158:159], v[220:221], 0, s[24:25]
	s_add_i32 m0, s36, 0x2000
	s_add_i32 s36, s71, s41
	global_load_lds_dwordx4 v[158:159], off
	s_mov_b32 m0, s36
	v_lshl_add_u64 v[158:159], v[222:223], 0, s[24:25]
	global_load_lds_dwordx4 v[158:159], off
	s_add_i32 m0, s36, 0x2000
	v_lshl_add_u64 v[158:159], v[224:225], 0, s[24:25]
	global_load_lds_dwordx4 v[158:159], off
	s_mov_b32 m0, s52
	v_lshl_add_u64 v[158:159], v[226:227], 0, s[24:25]
	global_load_lds_dwordx4 v[158:159], off
	s_mov_b32 m0, s53
	v_lshl_add_u64 v[158:159], v[228:229], 0, s[24:25]
	global_load_lds_dwordx4 v[158:159], off
	s_waitcnt vmcnt(8) lgkmcnt(0)
	s_barrier
	s_setprio 1
	v_mfma_f32_16x16x32_bf16 v[62:65], v[130:133], v[188:191], v[62:65]
	v_mfma_f32_16x16x32_bf16 v[58:61], v[164:167], v[188:191], v[58:61]
	v_mfma_f32_16x16x32_bf16 v[46:49], v[130:133], v[196:199], v[46:49]
	v_mfma_f32_16x16x32_bf16 v[42:45], v[164:167], v[196:199], v[42:45]
	v_mfma_f32_16x16x32_bf16 v[30:33], v[130:133], v[204:207], v[30:33]
	v_mfma_f32_16x16x32_bf16 v[26:29], v[164:167], v[204:207], v[26:29]
	v_mfma_f32_16x16x32_bf16 v[14:17], v[130:133], v[212:215], v[14:17]
	v_mfma_f32_16x16x32_bf16 v[10:13], v[164:167], v[212:215], v[10:13]
	v_mfma_f32_16x16x32_bf16 v[62:65], v[134:137], v[192:195], v[62:65]
	v_mfma_f32_16x16x32_bf16 v[58:61], v[168:171], v[192:195], v[58:61]
	v_mfma_f32_16x16x32_bf16 v[46:49], v[134:137], v[200:203], v[46:49]
	v_mfma_f32_16x16x32_bf16 v[42:45], v[168:171], v[200:203], v[42:45]
	v_mfma_f32_16x16x32_bf16 v[30:33], v[134:137], v[208:211], v[30:33]
	v_mfma_f32_16x16x32_bf16 v[26:29], v[168:171], v[208:211], v[26:29]
	v_mfma_f32_16x16x32_bf16 v[14:17], v[134:137], v[216:219], v[14:17]
	v_mfma_f32_16x16x32_bf16 v[10:13], v[168:171], v[216:219], v[10:13]
	v_mfma_f32_16x16x32_bf16 v[54:57], v[172:175], v[188:191], v[54:57]
	v_mfma_f32_16x16x32_bf16 v[50:53], v[180:183], v[188:191], v[50:53]
	v_mfma_f32_16x16x32_bf16 v[38:41], v[172:175], v[196:199], v[38:41]
	v_mfma_f32_16x16x32_bf16 v[34:37], v[180:183], v[196:199], v[34:37]
	v_mfma_f32_16x16x32_bf16 v[22:25], v[172:175], v[204:207], v[22:25]
	v_mfma_f32_16x16x32_bf16 v[18:21], v[180:183], v[204:207], v[18:21]
	v_mfma_f32_16x16x32_bf16 v[6:9], v[172:175], v[212:215], v[6:9]
	v_mfma_f32_16x16x32_bf16 v[2:5], v[180:183], v[212:215], v[2:5]
	v_mfma_f32_16x16x32_bf16 v[54:57], v[176:179], v[192:195], v[54:57]
	v_mfma_f32_16x16x32_bf16 v[50:53], v[184:187], v[192:195], v[50:53]
	v_mfma_f32_16x16x32_bf16 v[38:41], v[176:179], v[200:203], v[38:41]
	v_mfma_f32_16x16x32_bf16 v[34:37], v[184:187], v[200:203], v[34:37]
	v_mfma_f32_16x16x32_bf16 v[22:25], v[176:179], v[208:211], v[22:25]
	v_mfma_f32_16x16x32_bf16 v[18:21], v[184:187], v[208:211], v[18:21]
	v_mfma_f32_16x16x32_bf16 v[6:9], v[176:179], v[216:219], v[6:9]
	v_mfma_f32_16x16x32_bf16 v[2:5], v[184:187], v[216:219], v[2:5]
	s_setprio 0
	s_barrier
	s_add_u32 s45, s45, 0x100
	s_addc_u32 s80, s80, 0
	s_add_u32 s34, s34, 0x100
	s_addc_u32 s35, s35, 0
	s_cmp_ge_i32 s81, s54
	s_mov_b32 s36, s81
	s_cbranch_scc0 .LBB0_1154

; #define PG8_STAGE(bufoff, gbase, voff) do { _Pragma("unroll") for (int _i = 0; _i < 2; ++_i) \
;         __builtin_amdgcn_global_load_lds((const unsigned*)((const char*)(gbase) + (voff)[_i]), (PG8_LAS unsigned*)(lds + (bufoff) + ldsw + _i * 8192), 16, 0, 0); } while (0)
; #define PG8_LDA(dst, b, h) do { _Pragma("unroll") for (int m = 0; m < 4; ++m) _Pragma("unroll") for (int k = 0; k < 2; ++k) dst[m][k] = *(const PG8_LAS bf16x8*)(lds + PG8_SA(b, h) + aoff + m * 2048 + k * 1024); } while (0)
; #define PG8_LDB(dst, b, h) do { _Pragma("unroll") for (int n = 0; n < 2; ++n) _Pragma("unroll") for (int k = 0; k < 2; ++k) dst[n][k] = *(const PG8_LAS bf16x8*)(lds + PG8_SB(b, h) + boff + n * 2048 + k * 1024); } while (0)
; #define PG8_WAIT_V(n) asm volatile("s_waitcnt vmcnt(" #n ")" ::: "memory")
; #define PG8_WAIT_L(n) asm volatile("s_waitcnt lgkmcnt(" #n ")" ::: "memory")
; #define PG8_BAR __builtin_amdgcn_s_barrier()
; #define PG8_SCHED __builtin_amdgcn_sched_barrier(0)
; template <class Epi, class Sched, bool ALIGN_EPI = false, bool SP2 = false>
; __device__ __forceinline__ void gemm_phase(PG8_LAS unsigned char* lds, const Gemm g, const Sched& S, const Epi& E) {
;     ...
;         const bool has_next = S.next(ui + 1, nxt);
;         const char* nA = has_next ? (const char*)g.A + (size_t)nxt.pm * tstep : cA; const char* nB = has_next ? (const char*)g.Bt + (size_t)nxt.pn * tstep : cB;
;         for (int t = 0; t < nt; t += 2) {
;             const bool last = (t == nt - 2);
;             const char* a1 = cA + (size_t)(t + 1) * kstep;
;             const char* a2 = last ? nA : cA + (size_t)(t + 2) * kstep; const char* b2 = last ? nB : cB + (size_t)(t + 2) * kstep;
;             const char* a3 = a2 + kstep; const char* b3 = b2 + kstep;
;             if (last && has_next) S.a_ready(nxt);
;             if constexpr (SP2) {
;             PG8_LDB(B0, 0, 0); PG8_LDB(B1, 0, 1); PG8_SCHED; PG8_LDA(At, 0, 0); PG8_STAGE(PG8_SA(1, 1), a1 + hstep, voffA);
;             PG8_WAIT_V(8); PG8_WAIT_L(0); PG8_BAR; PG8_MMA(0, 0, At, B0); PG8_MMA(0, 1, At, B1); PG8_BAR; PG8_SCHED;
;             PG8_LDA(At, 0, 1); PG8_STAGE(PG8_SB(0, 0), b2, voffB); PG8_STAGE(PG8_SB(0, 1), b2 + hstep, voffB); PG8_STAGE(PG8_SA(0, 0), a2, voffA);
;             PG8_WAIT_V(8); PG8_WAIT_L(0); PG8_BAR; PG8_MMA(1, 0, At, B0); PG8_MMA(1, 1, At, B1); PG8_BAR; PG8_SCHED;
.LBB0_1375:
	ds_read_b128 v[166:169], v162
	ds_read_b128 v[170:173], v162 offset:1024
	ds_read_b128 v[174:177], v162 offset:2048
	ds_read_b128 v[178:181], v162 offset:3072
	ds_read_b128 v[182:185], v163
	ds_read_b128 v[186:189], v163 offset:1024
	ds_read_b128 v[190:193], v163 offset:2048
	ds_read_b128 v[194:197], v163 offset:3072
	s_add_i32 s87, s36, 2
	s_add_u32 s70, s34, 0x80
	s_addc_u32 s37, s35, 0
	s_cmp_eq_u32 s52, s36
	s_cselect_b32 s36, s4, s70
	s_cselect_b32 s37, s5, s37
	s_cselect_b32 s71, s31, s86
	s_cselect_b32 s70, s30, s81
	v_lshl_add_u64 v[230:231], s[34:35], 0, v[140:141]
	s_add_i32 m0, s42, 0xc000
	ds_read_b128 v[198:201], v164
	ds_read_b128 v[202:205], v164 offset:1024
	ds_read_b128 v[206:209], v164 offset:2048
	ds_read_b128 v[210:213], v164 offset:3072
	ds_read_b128 v[214:217], v164 offset:4096
	ds_read_b128 v[218:221], v164 offset:5120
	ds_read_b128 v[222:225], v164 offset:6144
	ds_read_b128 v[226:229], v164 offset:7168
	global_load_lds_dwordx4 v[230:231], off
	s_add_i32 m0, s42, 0xe000
	v_lshl_add_u64 v[230:231], s[34:35], 0, v[138:139]
	global_load_lds_dwordx4 v[230:231], off
	s_waitcnt vmcnt(8) lgkmcnt(0)
	s_barrier
	s_setprio 1
	v_mfma_f32_16x16x32_bf16 v[122:125], v[166:169], v[198:201], v[122:125]
	v_mfma_f32_16x16x32_bf16 v[126:129], v[174:177], v[198:201], v[126:129]
	v_mfma_f32_16x16x32_bf16 v[110:113], v[166:169], v[206:209], v[110:113]
	v_mfma_f32_16x16x32_bf16 v[106:109], v[174:177], v[206:209], v[106:109]
	v_mfma_f32_16x16x32_bf16 v[94:97], v[166:169], v[214:217], v[94:97]
	v_mfma_f32_16x16x32_bf16 v[90:93], v[174:177], v[214:217], v[90:93]
	v_mfma_f32_16x16x32_bf16 v[78:81], v[166:169], v[222:225], v[78:81]
	v_mfma_f32_16x16x32_bf16 v[74:77], v[174:177], v[222:225], v[74:77]
	v_mfma_f32_16x16x32_bf16 v[122:125], v[170:173], v[202:205], v[122:125]
	v_mfma_f32_16x16x32_bf16 v[126:129], v[178:181], v[202:205], v[126:129]
	v_mfma_f32_16x16x32_bf16 v[110:113], v[170:173], v[210:213], v[110:113]
	v_mfma_f32_16x16x32_bf16 v[106:109], v[178:181], v[210:213], v[106:109]
	v_mfma_f32_16x16x32_bf16 v[94:97], v[170:173], v[218:221], v[94:97]
	v_mfma_f32_16x16x32_bf16 v[90:93], v[178:181], v[218:221], v[90:93]
	v_mfma_f32_16x16x32_bf16 v[78:81], v[170:173], v[226:229], v[78:81]
	v_mfma_f32_16x16x32_bf16 v[74:77], v[178:181], v[226:229], v[74:77]
	v_mfma_f32_16x16x32_bf16 v[118:121], v[182:185], v[198:201], v[118:121]
	v_mfma_f32_16x16x32_bf16 v[114:117], v[190:193], v[198:201], v[114:117]
	v_mfma_f32_16x16x32_bf16 v[102:105], v[182:185], v[206:209], v[102:105]
	v_mfma_f32_16x16x32_bf16 v[98:101], v[190:193], v[206:209], v[98:101]
	v_mfma_f32_16x16x32_bf16 v[86:89], v[182:185], v[214:217], v[86:89]
	v_mfma_f32_16x16x32_bf16 v[82:85], v[190:193], v[214:217], v[82:85]
	v_mfma_f32_16x16x32_bf16 v[70:73], v[182:185], v[222:225], v[70:73]
	v_mfma_f32_16x16x32_bf16 v[66:69], v[190:193], v[222:225], v[66:69]
	v_mfma_f32_16x16x32_bf16 v[118:121], v[186:189], v[202:205], v[118:121]
	v_mfma_f32_16x16x32_bf16 v[114:117], v[194:197], v[202:205], v[114:117]
	v_mfma_f32_16x16x32_bf16 v[102:105], v[186:189], v[210:213], v[102:105]
	v_mfma_f32_16x16x32_bf16 v[98:101], v[194:197], v[210:213], v[98:101]
	v_mfma_f32_16x16x32_bf16 v[86:89], v[186:189], v[218:221], v[86:89]
	v_mfma_f32_16x16x32_bf16 v[82:85], v[194:197], v[218:221], v[82:85]
	v_mfma_f32_16x16x32_bf16 v[70:73], v[186:189], v[226:229], v[70:73]
	v_mfma_f32_16x16x32_bf16 v[66:69], v[194:197], v[226:229], v[66:69]
	s_setprio 0
	s_barrier
	s_add_i32 s72, s55, s41
	v_lshl_add_u64 v[230:231], s[70:71], 0, v[132:133]
	s_mov_b32 m0, s72
	ds_read_b128 v[198:201], v164 offset:16384
	ds_read_b128 v[202:205], v164 offset:17408
	ds_read_b128 v[206:209], v164 offset:18432
	ds_read_b128 v[210:213], v164 offset:19456
	ds_read_b128 v[214:217], v164 offset:20480
	ds_read_b128 v[218:221], v164 offset:21504
	ds_read_b128 v[222:225], v164 offset:22528
	ds_read_b128 v[226:229], v164 offset:23552
	global_load_lds_dwordx4 v[230:231], off
	s_add_i32 m0, s72, 0x2000
	v_lshl_add_u64 v[232:233], s[70:71], 0, v[136:137]
	s_add_u32 s70, s70, s14
	s_addc_u32 s71, s71, s15
	s_add_i32 s72, s56, s41
	global_load_lds_dwordx4 v[232:233], off
	v_lshl_add_u64 v[234:235], s[70:71], 0, v[132:133]
	s_mov_b32 m0, s72
	v_lshl_add_u64 v[236:237], s[70:71], 0, v[136:137]
	global_load_lds_dwordx4 v[234:235], off
	s_add_i32 m0, s72, 0x2000
	v_lshl_add_u64 v[238:239], s[36:37], 0, v[130:131]
	global_load_lds_dwordx4 v[236:237], off
	s_mov_b32 m0, s42
	v_lshl_add_u64 v[240:241], s[36:37], 0, v[134:135]
	global_load_lds_dwordx4 v[238:239], off
	s_mov_b32 m0, s43
	s_nop 0
	global_load_lds_dwordx4 v[240:241], off
	s_waitcnt vmcnt(8) lgkmcnt(0)
	s_barrier
; #define PG8_STAGE(bufoff, gbase, voff) do { _Pragma("unroll") for (int _i = 0; _i < 2; ++_i) \
;         __builtin_amdgcn_global_load_lds((const unsigned*)((const char*)(gbase) + (voff)[_i]), (PG8_LAS unsigned*)(lds + (bufoff) + ldsw + _i * 8192), 16, 0, 0); } while (0)
; #define PG8_LDA(dst, b, h) do { _Pragma("unroll") for (int m = 0; m < 4; ++m) _Pragma("unroll") for (int k = 0; k < 2; ++k) dst[m][k] = *(const PG8_LAS bf16x8*)(lds + PG8_SA(b, h) + aoff + m * 2048 + k * 1024); } while (0)
; #define PG8_LDB(dst, b, h) do { _Pragma("unroll") for (int n = 0; n < 2; ++n) _Pragma("unroll") for (int k = 0; k < 2; ++k) dst[n][k] = *(const PG8_LAS bf16x8*)(lds + PG8_SB(b, h) + boff + n * 2048 + k * 1024); } while (0)
; #define PG8_MMA(ai, bj, At, Bt) do { __builtin_amdgcn_s_setprio(1); _Pragma("unroll") for (int m = 0; m < 4; ++m) _Pragma("unroll") for (int n = 0; n < 2; ++n) _Pragma("unroll") for (int k = 0; k < 2; ++k) \
;         acc[ai][bj][m][n] = __builtin_amdgcn_mfma_f32_16x16x32_bf16(Bt[n][k], At[m][k], acc[ai][bj][m][n], 0, 0, 0); __builtin_amdgcn_s_setprio(0); } while (0)
; #define PG8_WAIT_V(n) asm volatile("s_waitcnt vmcnt(" #n ")" ::: "memory")
; #define PG8_WAIT_L(n) asm volatile("s_waitcnt lgkmcnt(" #n ")" ::: "memory")
; #define PG8_BAR __builtin_amdgcn_s_barrier()
; #define PG8_SCHED __builtin_amdgcn_sched_barrier(0)
; template <class Epi, class Sched, bool ALIGN_EPI = false, bool SP2 = false>
; __device__ __forceinline__ void gemm_phase(PG8_LAS unsigned char* lds, const Gemm g, const Sched& S, const Epi& E) {
;     ...
;             PG8_WAIT_V(8); PG8_WAIT_L(0); PG8_BAR; PG8_MMA(1, 0, At, B0); PG8_MMA(1, 1, At, B1); PG8_BAR; PG8_SCHED;
;             PG8_LDB(B0, 1, 0); PG8_LDB(B1, 1, 1); PG8_SCHED; PG8_LDA(At, 1, 0); PG8_STAGE(PG8_SA(0, 1), a2 + hstep, voffA);
;             PG8_WAIT_V(8); PG8_WAIT_L(0); PG8_BAR; PG8_MMA(0, 0, At, B0); PG8_MMA(0, 1, At, B1); PG8_BAR; PG8_SCHED;
	s_setprio 1
	v_mfma_f32_16x16x32_bf16 v[62:65], v[166:169], v[198:201], v[62:65]
	v_mfma_f32_16x16x32_bf16 v[58:61], v[174:177], v[198:201], v[58:61]
	v_mfma_f32_16x16x32_bf16 v[46:49], v[166:169], v[206:209], v[46:49]
	v_mfma_f32_16x16x32_bf16 v[42:45], v[174:177], v[206:209], v[42:45]
	v_mfma_f32_16x16x32_bf16 v[30:33], v[166:169], v[214:217], v[30:33]
	v_mfma_f32_16x16x32_bf16 v[26:29], v[174:177], v[214:217], v[26:29]
	v_mfma_f32_16x16x32_bf16 v[14:17], v[166:169], v[222:225], v[14:17]
	v_mfma_f32_16x16x32_bf16 v[10:13], v[174:177], v[222:225], v[10:13]
	v_mfma_f32_16x16x32_bf16 v[62:65], v[170:173], v[202:205], v[62:65]
	v_mfma_f32_16x16x32_bf16 v[58:61], v[178:181], v[202:205], v[58:61]
	v_mfma_f32_16x16x32_bf16 v[46:49], v[170:173], v[210:213], v[46:49]
	v_mfma_f32_16x16x32_bf16 v[42:45], v[178:181], v[210:213], v[42:45]
	v_mfma_f32_16x16x32_bf16 v[30:33], v[170:173], v[218:221], v[30:33]
	v_mfma_f32_16x16x32_bf16 v[26:29], v[178:181], v[218:221], v[26:29]
	v_mfma_f32_16x16x32_bf16 v[14:17], v[170:173], v[226:229], v[14:17]
	v_mfma_f32_16x16x32_bf16 v[10:13], v[178:181], v[226:229], v[10:13]
	v_mfma_f32_16x16x32_bf16 v[54:57], v[182:185], v[198:201], v[54:57]
	v_mfma_f32_16x16x32_bf16 v[50:53], v[190:193], v[198:201], v[50:53]
	v_mfma_f32_16x16x32_bf16 v[38:41], v[182:185], v[206:209], v[38:41]
	v_mfma_f32_16x16x32_bf16 v[34:37], v[190:193], v[206:209], v[34:37]
	v_mfma_f32_16x16x32_bf16 v[22:25], v[182:185], v[214:217], v[22:25]
	v_mfma_f32_16x16x32_bf16 v[18:21], v[190:193], v[214:217], v[18:21]
	v_mfma_f32_16x16x32_bf16 v[6:9], v[182:185], v[222:225], v[6:9]
	v_mfma_f32_16x16x32_bf16 v[2:5], v[190:193], v[222:225], v[2:5]
	v_mfma_f32_16x16x32_bf16 v[54:57], v[186:189], v[202:205], v[54:57]
	v_mfma_f32_16x16x32_bf16 v[50:53], v[194:197], v[202:205], v[50:53]
	v_mfma_f32_16x16x32_bf16 v[38:41], v[186:189], v[210:213], v[38:41]
	v_mfma_f32_16x16x32_bf16 v[34:37], v[194:197], v[210:213], v[34:37]
	v_mfma_f32_16x16x32_bf16 v[22:25], v[186:189], v[218:221], v[22:25]
	v_mfma_f32_16x16x32_bf16 v[18:21], v[194:197], v[218:221], v[18:21]
	v_mfma_f32_16x16x32_bf16 v[6:9], v[186:189], v[226:229], v[6:9]
	v_mfma_f32_16x16x32_bf16 v[2:5], v[194:197], v[226:229], v[2:5]
	s_setprio 0
	s_barrier
	s_add_i32 s70, 0, 0x18000
	v_add_u32_e32 v165, s70, v160
	s_add_i32 s71, 0, 0x1c000
	ds_read_b128 v[166:169], v165
	ds_read_b128 v[170:173], v165 offset:1024
	ds_read_b128 v[174:177], v165 offset:2048
	ds_read_b128 v[178:181], v165 offset:3072
	v_add_u32_e32 v165, s71, v160
	ds_read_b128 v[182:185], v165
	ds_read_b128 v[186:189], v165 offset:1024
	ds_read_b128 v[190:193], v165 offset:2048
	ds_read_b128 v[194:197], v165 offset:3072
	s_add_u32 s36, s36, s14
	s_addc_u32 s37, s37, s15
	s_mov_b32 m0, s44
	v_lshl_add_u64 v[242:243], s[36:37], 0, v[130:131]
	ds_read_b128 v[198:201], v164 offset:32768
	ds_read_b128 v[202:205], v164 offset:33792
	ds_read_b128 v[206:209], v164 offset:34816
	ds_read_b128 v[210:213], v164 offset:35840
	ds_read_b128 v[214:217], v164 offset:36864
	ds_read_b128 v[218:221], v164 offset:37888
	ds_read_b128 v[222:225], v164 offset:38912
	ds_read_b128 v[226:229], v164 offset:39936
	global_load_lds_dwordx4 v[242:243], off
	s_mov_b32 m0, s45
	v_lshl_add_u64 v[242:243], s[36:37], 0, v[134:135]
	global_load_lds_dwordx4 v[242:243], off
	s_waitcnt vmcnt(8) lgkmcnt(0)
	s_barrier
	s_setprio 1
	v_mfma_f32_16x16x32_bf16 v[122:125], v[166:169], v[198:201], v[122:125]
	v_mfma_f32_16x16x32_bf16 v[126:129], v[174:177], v[198:201], v[126:129]
	v_mfma_f32_16x16x32_bf16 v[110:113], v[166:169], v[206:209], v[110:113]
	v_mfma_f32_16x16x32_bf16 v[106:109], v[174:177], v[206:209], v[106:109]
	v_mfma_f32_16x16x32_bf16 v[94:97], v[166:169], v[214:217], v[94:97]
	v_mfma_f32_16x16x32_bf16 v[90:93], v[174:177], v[214:217], v[90:93]
	v_mfma_f32_16x16x32_bf16 v[78:81], v[166:169], v[222:225], v[78:81]
	v_mfma_f32_16x16x32_bf16 v[74:77], v[174:177], v[222:225], v[74:77]
	v_mfma_f32_16x16x32_bf16 v[122:125], v[170:173], v[202:205], v[122:125]
	v_mfma_f32_16x16x32_bf16 v[126:129], v[178:181], v[202:205], v[126:129]
	v_mfma_f32_16x16x32_bf16 v[110:113], v[170:173], v[210:213], v[110:113]
	v_mfma_f32_16x16x32_bf16 v[106:109], v[178:181], v[210:213], v[106:109]
	v_mfma_f32_16x16x32_bf16 v[94:97], v[170:173], v[218:221], v[94:97]
	v_mfma_f32_16x16x32_bf16 v[90:93], v[178:181], v[218:221], v[90:93]
	v_mfma_f32_16x16x32_bf16 v[78:81], v[170:173], v[226:229], v[78:81]
	v_mfma_f32_16x16x32_bf16 v[74:77], v[178:181], v[226:229], v[74:77]
	v_mfma_f32_16x16x32_bf16 v[118:121], v[182:185], v[198:201], v[118:121]
	v_mfma_f32_16x16x32_bf16 v[114:117], v[190:193], v[198:201], v[114:117]
	v_mfma_f32_16x16x32_bf16 v[102:105], v[182:185], v[206:209], v[102:105]
	v_mfma_f32_16x16x32_bf16 v[98:101], v[190:193], v[206:209], v[98:101]
	v_mfma_f32_16x16x32_bf16 v[86:89], v[182:185], v[214:217], v[86:89]
	v_mfma_f32_16x16x32_bf16 v[82:85], v[190:193], v[214:217], v[82:85]
	v_mfma_f32_16x16x32_bf16 v[70:73], v[182:185], v[222:225], v[70:73]
	v_mfma_f32_16x16x32_bf16 v[66:69], v[190:193], v[222:225], v[66:69]
	v_mfma_f32_16x16x32_bf16 v[118:121], v[186:189], v[202:205], v[118:121]
	v_mfma_f32_16x16x32_bf16 v[114:117], v[194:197], v[202:205], v[114:117]
	v_mfma_f32_16x16x32_bf16 v[102:105], v[186:189], v[210:213], v[102:105]
	v_mfma_f32_16x16x32_bf16 v[98:101], v[194:197], v[210:213], v[98:101]
	v_mfma_f32_16x16x32_bf16 v[86:89], v[186:189], v[218:221], v[86:89]
	v_mfma_f32_16x16x32_bf16 v[82:85], v[194:197], v[218:221], v[82:85]
	v_mfma_f32_16x16x32_bf16 v[70:73], v[186:189], v[226:229], v[70:73]
	v_mfma_f32_16x16x32_bf16 v[66:69], v[194:197], v[226:229], v[66:69]
	s_setprio 0
	s_barrier
; #define PG8_STAGE(bufoff, gbase, voff) do { _Pragma("unroll") for (int _i = 0; _i < 2; ++_i) \
;         __builtin_amdgcn_global_load_lds((const unsigned*)((const char*)(gbase) + (voff)[_i]), (PG8_LAS unsigned*)(lds + (bufoff) + ldsw + _i * 8192), 16, 0, 0); } while (0)
; #define PG8_LDA(dst, b, h) do { _Pragma("unroll") for (int m = 0; m < 4; ++m) _Pragma("unroll") for (int k = 0; k < 2; ++k) dst[m][k] = *(const PG8_LAS bf16x8*)(lds + PG8_SA(b, h) + aoff + m * 2048 + k * 1024); } while (0)
; #define PG8_MMA(ai, bj, At, Bt) do { __builtin_amdgcn_s_setprio(1); _Pragma("unroll") for (int m = 0; m < 4; ++m) _Pragma("unroll") for (int n = 0; n < 2; ++n) _Pragma("unroll") for (int k = 0; k < 2; ++k) \
;         acc[ai][bj][m][n] = __builtin_amdgcn_mfma_f32_16x16x32_bf16(Bt[n][k], At[m][k], acc[ai][bj][m][n], 0, 0, 0); __builtin_amdgcn_s_setprio(0); } while (0)
; #define PG8_WAIT_V(n) asm volatile("s_waitcnt vmcnt(" #n ")" ::: "memory")
; #define PG8_WAIT_L(n) asm volatile("s_waitcnt lgkmcnt(" #n ")" ::: "memory")
; #define PG8_BAR __builtin_amdgcn_s_barrier()
; #define PG8_SCHED __builtin_amdgcn_sched_barrier(0)
; template <class Epi, class Sched, bool ALIGN_EPI = false, bool SP2 = false>
; __device__ __forceinline__ void gemm_phase(PG8_LAS unsigned char* lds, const Gemm g, const Sched& S, const Epi& E) {
;     ...
;         for (int t = 0; t < nt; t += 2) {
;     ...
;             PG8_LDA(At, 1, 1); PG8_STAGE(PG8_SB(1, 0), b3, voffB); PG8_STAGE(PG8_SB(1, 1), b3 + hstep, voffB); PG8_STAGE(PG8_SA(1, 0), a3, voffA);
;             PG8_WAIT_V(8); PG8_WAIT_L(0); PG8_BAR; PG8_MMA(1, 0, At, B0); PG8_MMA(1, 1, At, B1); PG8_BAR; PG8_SCHED;
	s_add_i32 s36, s70, s41
	v_lshl_add_u64 v[230:231], v[230:231], 0, s[24:25]
	s_mov_b32 m0, s36
	ds_read_b128 v[198:201], v164 offset:49152
	ds_read_b128 v[202:205], v164 offset:50176
	ds_read_b128 v[206:209], v164 offset:51200
	ds_read_b128 v[210:213], v164 offset:52224
	ds_read_b128 v[214:217], v164 offset:53248
	ds_read_b128 v[218:221], v164 offset:54272
	ds_read_b128 v[222:225], v164 offset:55296
	ds_read_b128 v[226:229], v164 offset:56320
	global_load_lds_dwordx4 v[230:231], off
	v_lshl_add_u64 v[230:231], v[232:233], 0, s[24:25]
	s_add_i32 m0, s36, 0x2000
	s_add_i32 s36, s71, s41
	global_load_lds_dwordx4 v[230:231], off
	s_mov_b32 m0, s36
	v_lshl_add_u64 v[230:231], v[234:235], 0, s[24:25]
	global_load_lds_dwordx4 v[230:231], off
	s_add_i32 m0, s36, 0x2000
	v_lshl_add_u64 v[230:231], v[236:237], 0, s[24:25]
	global_load_lds_dwordx4 v[230:231], off
	s_mov_b32 m0, s47
	v_lshl_add_u64 v[230:231], v[238:239], 0, s[24:25]
	global_load_lds_dwordx4 v[230:231], off
	s_mov_b32 m0, s48
	v_lshl_add_u64 v[230:231], v[240:241], 0, s[24:25]
	global_load_lds_dwordx4 v[230:231], off
	s_waitcnt vmcnt(8) lgkmcnt(0)
	s_barrier
	s_setprio 1
	v_mfma_f32_16x16x32_bf16 v[62:65], v[166:169], v[198:201], v[62:65]
	v_mfma_f32_16x16x32_bf16 v[58:61], v[174:177], v[198:201], v[58:61]
	v_mfma_f32_16x16x32_bf16 v[46:49], v[166:169], v[206:209], v[46:49]
	v_mfma_f32_16x16x32_bf16 v[42:45], v[174:177], v[206:209], v[42:45]
	v_mfma_f32_16x16x32_bf16 v[30:33], v[166:169], v[214:217], v[30:33]
	v_mfma_f32_16x16x32_bf16 v[26:29], v[174:177], v[214:217], v[26:29]
	v_mfma_f32_16x16x32_bf16 v[14:17], v[166:169], v[222:225], v[14:17]
	v_mfma_f32_16x16x32_bf16 v[10:13], v[174:177], v[222:225], v[10:13]
	v_mfma_f32_16x16x32_bf16 v[62:65], v[170:173], v[202:205], v[62:65]
	v_mfma_f32_16x16x32_bf16 v[58:61], v[178:181], v[202:205], v[58:61]
	v_mfma_f32_16x16x32_bf16 v[46:49], v[170:173], v[210:213], v[46:49]
	v_mfma_f32_16x16x32_bf16 v[42:45], v[178:181], v[210:213], v[42:45]
	v_mfma_f32_16x16x32_bf16 v[30:33], v[170:173], v[218:221], v[30:33]
	v_mfma_f32_16x16x32_bf16 v[26:29], v[178:181], v[218:221], v[26:29]
	v_mfma_f32_16x16x32_bf16 v[14:17], v[170:173], v[226:229], v[14:17]
	v_mfma_f32_16x16x32_bf16 v[10:13], v[178:181], v[226:229], v[10:13]
	v_mfma_f32_16x16x32_bf16 v[54:57], v[182:185], v[198:201], v[54:57]
	v_mfma_f32_16x16x32_bf16 v[50:53], v[190:193], v[198:201], v[50:53]
	v_mfma_f32_16x16x32_bf16 v[38:41], v[182:185], v[206:209], v[38:41]
	v_mfma_f32_16x16x32_bf16 v[34:37], v[190:193], v[206:209], v[34:37]
	v_mfma_f32_16x16x32_bf16 v[22:25], v[182:185], v[214:217], v[22:25]
	v_mfma_f32_16x16x32_bf16 v[18:21], v[190:193], v[214:217], v[18:21]
	v_mfma_f32_16x16x32_bf16 v[6:9], v[182:185], v[222:225], v[6:9]
	v_mfma_f32_16x16x32_bf16 v[2:5], v[190:193], v[222:225], v[2:5]
	v_mfma_f32_16x16x32_bf16 v[54:57], v[186:189], v[202:205], v[54:57]
	v_mfma_f32_16x16x32_bf16 v[50:53], v[194:197], v[202:205], v[50:53]
	v_mfma_f32_16x16x32_bf16 v[38:41], v[186:189], v[210:213], v[38:41]
	v_mfma_f32_16x16x32_bf16 v[34:37], v[194:197], v[210:213], v[34:37]
	v_mfma_f32_16x16x32_bf16 v[22:25], v[186:189], v[218:221], v[22:25]
	v_mfma_f32_16x16x32_bf16 v[18:21], v[194:197], v[218:221], v[18:21]
	v_mfma_f32_16x16x32_bf16 v[6:9], v[186:189], v[226:229], v[6:9]
	v_mfma_f32_16x16x32_bf16 v[2:5], v[194:197], v[226:229], v[2:5]
	s_setprio 0
	s_barrier
	s_add_u32 s81, s81, 0x100
	s_addc_u32 s86, s86, 0
	s_add_u32 s34, s34, 0x100
	s_addc_u32 s35, s35, 0
	s_cmp_ge_i32 s87, s49
	s_mov_b32 s36, s87
	s_cbranch_scc0 .LBB0_1375

; #define PG8_STAGE(bufoff, gbase, voff) do { _Pragma("unroll") for (int _i = 0; _i < 2; ++_i) \
;         __builtin_amdgcn_global_load_lds((const unsigned*)((const char*)(gbase) + (voff)[_i]), (PG8_LAS unsigned*)(lds + (bufoff) + ldsw + _i * 8192), 16, 0, 0); } while (0)
; #define PG8_LDA(dst, b, h) do { _Pragma("unroll") for (int m = 0; m < 4; ++m) _Pragma("unroll") for (int k = 0; k < 2; ++k) dst[m][k] = *(const PG8_LAS bf16x8*)(lds + PG8_SA(b, h) + aoff + m * 2048 + k * 1024); } while (0)
; #define PG8_LDB(dst, b, h) do { _Pragma("unroll") for (int n = 0; n < 2; ++n) _Pragma("unroll") for (int k = 0; k < 2; ++k) dst[n][k] = *(const PG8_LAS bf16x8*)(lds + PG8_SB(b, h) + boff + n * 2048 + k * 1024); } while (0)
; #define PG8_WAIT_V(n) asm volatile("s_waitcnt vmcnt(" #n ")" ::: "memory")
; #define PG8_WAIT_L(n) asm volatile("s_waitcnt lgkmcnt(" #n ")" ::: "memory")
; #define PG8_BAR __builtin_amdgcn_s_barrier()
; #define PG8_SCHED __builtin_amdgcn_sched_barrier(0)
; template <class Epi, class Sched, bool ALIGN_EPI = false, bool SP2 = false>
; __device__ __forceinline__ void gemm_phase(PG8_LAS unsigned char* lds, const Gemm g, const Sched& S, const Epi& E) {
;     ...
;         const bool has_next = S.next(ui + 1, nxt);
;         const char* nA = has_next ? (const char*)g.A + (size_t)nxt.pm * tstep : cA; const char* nB = has_next ? (const char*)g.Bt + (size_t)nxt.pn * tstep : cB;
;         for (int t = 0; t < nt; t += 2) {
;             const bool last = (t == nt - 2);
;             const char* a1 = cA + (size_t)(t + 1) * kstep;
;             const char* a2 = last ? nA : cA + (size_t)(t + 2) * kstep; const char* b2 = last ? nB : cB + (size_t)(t + 2) * kstep;
;             const char* a3 = a2 + kstep; const char* b3 = b2 + kstep;
;             if (last && has_next) S.a_ready(nxt);
;             if constexpr (SP2) {
;             PG8_LDB(B0, 0, 0); PG8_LDB(B1, 0, 1); PG8_SCHED; PG8_LDA(At, 0, 0); PG8_STAGE(PG8_SA(1, 1), a1 + hstep, voffA);
;             PG8_WAIT_V(8); PG8_WAIT_L(0); PG8_BAR; PG8_MMA(0, 0, At, B0); PG8_MMA(0, 1, At, B1); PG8_BAR; PG8_SCHED;
;             PG8_LDA(At, 0, 1); PG8_STAGE(PG8_SB(0, 0), b2, voffB); PG8_STAGE(PG8_SB(0, 1), b2 + hstep, voffB); PG8_STAGE(PG8_SA(0, 0), a2, voffA);
;             PG8_WAIT_V(8); PG8_WAIT_L(0); PG8_BAR; PG8_MMA(1, 0, At, B0); PG8_MMA(1, 1, At, B1); PG8_BAR; PG8_SCHED;
.LBB0_1404:
	ds_read_b128 v[166:169], v162
	ds_read_b128 v[170:173], v162 offset:1024
	ds_read_b128 v[174:177], v162 offset:2048
	ds_read_b128 v[178:181], v162 offset:3072
	ds_read_b128 v[182:185], v163
	ds_read_b128 v[186:189], v163 offset:1024
	ds_read_b128 v[190:193], v163 offset:2048
	ds_read_b128 v[194:197], v163 offset:3072
	s_add_i32 s86, s34, 2
	s_add_u32 s70, s30, 0x80
	s_addc_u32 s35, s31, 0
	s_cmp_eq_u32 s49, s34
	s_cselect_b32 s34, s6, s70
	s_cselect_b32 s35, s7, s35
	s_cselect_b32 s71, s29, s81
	s_cselect_b32 s70, s28, s80
	v_lshl_add_u64 v[230:231], s[30:31], 0, v[140:141]
	s_add_i32 m0, s41, 0xc000
	ds_read_b128 v[198:201], v164
	ds_read_b128 v[202:205], v164 offset:1024
	ds_read_b128 v[206:209], v164 offset:2048
	ds_read_b128 v[210:213], v164 offset:3072
	ds_read_b128 v[214:217], v164 offset:4096
	ds_read_b128 v[218:221], v164 offset:5120
	ds_read_b128 v[222:225], v164 offset:6144
	ds_read_b128 v[226:229], v164 offset:7168
	global_load_lds_dwordx4 v[230:231], off
	s_add_i32 m0, s41, 0xe000
	v_lshl_add_u64 v[230:231], s[30:31], 0, v[138:139]
	global_load_lds_dwordx4 v[230:231], off
	s_waitcnt vmcnt(8) lgkmcnt(0)
	s_barrier
	s_setprio 1
	v_mfma_f32_16x16x32_bf16 v[122:125], v[166:169], v[198:201], v[122:125]
	v_mfma_f32_16x16x32_bf16 v[126:129], v[174:177], v[198:201], v[126:129]
	v_mfma_f32_16x16x32_bf16 v[110:113], v[166:169], v[206:209], v[110:113]
	v_mfma_f32_16x16x32_bf16 v[106:109], v[174:177], v[206:209], v[106:109]
	v_mfma_f32_16x16x32_bf16 v[94:97], v[166:169], v[214:217], v[94:97]
	v_mfma_f32_16x16x32_bf16 v[90:93], v[174:177], v[214:217], v[90:93]
	v_mfma_f32_16x16x32_bf16 v[78:81], v[166:169], v[222:225], v[78:81]
	v_mfma_f32_16x16x32_bf16 v[74:77], v[174:177], v[222:225], v[74:77]
	v_mfma_f32_16x16x32_bf16 v[122:125], v[170:173], v[202:205], v[122:125]
	v_mfma_f32_16x16x32_bf16 v[126:129], v[178:181], v[202:205], v[126:129]
	v_mfma_f32_16x16x32_bf16 v[110:113], v[170:173], v[210:213], v[110:113]
	v_mfma_f32_16x16x32_bf16 v[106:109], v[178:181], v[210:213], v[106:109]
	v_mfma_f32_16x16x32_bf16 v[94:97], v[170:173], v[218:221], v[94:97]
	v_mfma_f32_16x16x32_bf16 v[90:93], v[178:181], v[218:221], v[90:93]
	v_mfma_f32_16x16x32_bf16 v[78:81], v[170:173], v[226:229], v[78:81]
	v_mfma_f32_16x16x32_bf16 v[74:77], v[178:181], v[226:229], v[74:77]
	v_mfma_f32_16x16x32_bf16 v[118:121], v[182:185], v[198:201], v[118:121]
	v_mfma_f32_16x16x32_bf16 v[114:117], v[190:193], v[198:201], v[114:117]
	v_mfma_f32_16x16x32_bf16 v[102:105], v[182:185], v[206:209], v[102:105]
	v_mfma_f32_16x16x32_bf16 v[98:101], v[190:193], v[206:209], v[98:101]
	v_mfma_f32_16x16x32_bf16 v[86:89], v[182:185], v[214:217], v[86:89]
	v_mfma_f32_16x16x32_bf16 v[82:85], v[190:193], v[214:217], v[82:85]
	v_mfma_f32_16x16x32_bf16 v[70:73], v[182:185], v[222:225], v[70:73]
	v_mfma_f32_16x16x32_bf16 v[66:69], v[190:193], v[222:225], v[66:69]
	v_mfma_f32_16x16x32_bf16 v[118:121], v[186:189], v[202:205], v[118:121]
	v_mfma_f32_16x16x32_bf16 v[114:117], v[194:197], v[202:205], v[114:117]
	v_mfma_f32_16x16x32_bf16 v[102:105], v[186:189], v[210:213], v[102:105]
	v_mfma_f32_16x16x32_bf16 v[98:101], v[194:197], v[210:213], v[98:101]
	v_mfma_f32_16x16x32_bf16 v[86:89], v[186:189], v[218:221], v[86:89]
	v_mfma_f32_16x16x32_bf16 v[82:85], v[194:197], v[218:221], v[82:85]
	v_mfma_f32_16x16x32_bf16 v[70:73], v[186:189], v[226:229], v[70:73]
	v_mfma_f32_16x16x32_bf16 v[66:69], v[194:197], v[226:229], v[66:69]
	s_setprio 0
	s_barrier
	s_add_i32 s72, s54, s40
	v_lshl_add_u64 v[230:231], s[70:71], 0, v[132:133]
	s_mov_b32 m0, s72
	ds_read_b128 v[198:201], v164 offset:16384
	ds_read_b128 v[202:205], v164 offset:17408
	ds_read_b128 v[206:209], v164 offset:18432
	ds_read_b128 v[210:213], v164 offset:19456
	ds_read_b128 v[214:217], v164 offset:20480
	ds_read_b128 v[218:221], v164 offset:21504
	ds_read_b128 v[222:225], v164 offset:22528
	ds_read_b128 v[226:229], v164 offset:23552
	global_load_lds_dwordx4 v[230:231], off
	s_add_i32 m0, s72, 0x2000
	v_lshl_add_u64 v[232:233], s[70:71], 0, v[136:137]
	s_add_u32 s70, s70, s12
	s_addc_u32 s71, s71, s13
	s_add_i32 s72, s55, s40
	global_load_lds_dwordx4 v[232:233], off
	v_lshl_add_u64 v[234:235], s[70:71], 0, v[132:133]
	s_mov_b32 m0, s72
	v_lshl_add_u64 v[236:237], s[70:71], 0, v[136:137]
	global_load_lds_dwordx4 v[234:235], off
	s_add_i32 m0, s72, 0x2000
	v_lshl_add_u64 v[238:239], s[34:35], 0, v[130:131]
	global_load_lds_dwordx4 v[236:237], off
	s_mov_b32 m0, s41
	v_lshl_add_u64 v[240:241], s[34:35], 0, v[134:135]
	global_load_lds_dwordx4 v[238:239], off
	s_mov_b32 m0, s42
	s_nop 0
	global_load_lds_dwordx4 v[240:241], off
	s_waitcnt vmcnt(8) lgkmcnt(0)
	s_barrier
; #define PG8_STAGE(bufoff, gbase, voff) do { _Pragma("unroll") for (int _i = 0; _i < 2; ++_i) \
;         __builtin_amdgcn_global_load_lds((const unsigned*)((const char*)(gbase) + (voff)[_i]), (PG8_LAS unsigned*)(lds + (bufoff) + ldsw + _i * 8192), 16, 0, 0); } while (0)
; #define PG8_LDA(dst, b, h) do { _Pragma("unroll") for (int m = 0; m < 4; ++m) _Pragma("unroll") for (int k = 0; k < 2; ++k) dst[m][k] = *(const PG8_LAS bf16x8*)(lds + PG8_SA(b, h) + aoff + m * 2048 + k * 1024); } while (0)
; #define PG8_LDB(dst, b, h) do { _Pragma("unroll") for (int n = 0; n < 2; ++n) _Pragma("unroll") for (int k = 0; k < 2; ++k) dst[n][k] = *(const PG8_LAS bf16x8*)(lds + PG8_SB(b, h) + boff + n * 2048 + k * 1024); } while (0)
; #define PG8_MMA(ai, bj, At, Bt) do { __builtin_amdgcn_s_setprio(1); _Pragma("unroll") for (int m = 0; m < 4; ++m) _Pragma("unroll") for (int n = 0; n < 2; ++n) _Pragma("unroll") for (int k = 0; k < 2; ++k) \
;         acc[ai][bj][m][n] = __builtin_amdgcn_mfma_f32_16x16x32_bf16(Bt[n][k], At[m][k], acc[ai][bj][m][n], 0, 0, 0); __builtin_amdgcn_s_setprio(0); } while (0)
; #define PG8_WAIT_V(n) asm volatile("s_waitcnt vmcnt(" #n ")" ::: "memory")
; #define PG8_WAIT_L(n) asm volatile("s_waitcnt lgkmcnt(" #n ")" ::: "memory")
; #define PG8_BAR __builtin_amdgcn_s_barrier()
; #define PG8_SCHED __builtin_amdgcn_sched_barrier(0)
; template <class Epi, class Sched, bool ALIGN_EPI = false, bool SP2 = false>
; __device__ __forceinline__ void gemm_phase(PG8_LAS unsigned char* lds, const Gemm g, const Sched& S, const Epi& E) {
;     ...
;             PG8_WAIT_V(8); PG8_WAIT_L(0); PG8_BAR; PG8_MMA(1, 0, At, B0); PG8_MMA(1, 1, At, B1); PG8_BAR; PG8_SCHED;
;             PG8_LDB(B0, 1, 0); PG8_LDB(B1, 1, 1); PG8_SCHED; PG8_LDA(At, 1, 0); PG8_STAGE(PG8_SA(0, 1), a2 + hstep, voffA);
;             PG8_WAIT_V(8); PG8_WAIT_L(0); PG8_BAR; PG8_MMA(0, 0, At, B0); PG8_MMA(0, 1, At, B1); PG8_BAR; PG8_SCHED;
	s_setprio 1
	v_mfma_f32_16x16x32_bf16 v[62:65], v[166:169], v[198:201], v[62:65]
	v_mfma_f32_16x16x32_bf16 v[58:61], v[174:177], v[198:201], v[58:61]
	v_mfma_f32_16x16x32_bf16 v[46:49], v[166:169], v[206:209], v[46:49]
	v_mfma_f32_16x16x32_bf16 v[42:45], v[174:177], v[206:209], v[42:45]
	v_mfma_f32_16x16x32_bf16 v[30:33], v[166:169], v[214:217], v[30:33]
	v_mfma_f32_16x16x32_bf16 v[26:29], v[174:177], v[214:217], v[26:29]
	v_mfma_f32_16x16x32_bf16 v[14:17], v[166:169], v[222:225], v[14:17]
	v_mfma_f32_16x16x32_bf16 v[10:13], v[174:177], v[222:225], v[10:13]
	v_mfma_f32_16x16x32_bf16 v[62:65], v[170:173], v[202:205], v[62:65]
	v_mfma_f32_16x16x32_bf16 v[58:61], v[178:181], v[202:205], v[58:61]
	v_mfma_f32_16x16x32_bf16 v[46:49], v[170:173], v[210:213], v[46:49]
	v_mfma_f32_16x16x32_bf16 v[42:45], v[178:181], v[210:213], v[42:45]
	v_mfma_f32_16x16x32_bf16 v[30:33], v[170:173], v[218:221], v[30:33]
	v_mfma_f32_16x16x32_bf16 v[26:29], v[178:181], v[218:221], v[26:29]
	v_mfma_f32_16x16x32_bf16 v[14:17], v[170:173], v[226:229], v[14:17]
	v_mfma_f32_16x16x32_bf16 v[10:13], v[178:181], v[226:229], v[10:13]
	v_mfma_f32_16x16x32_bf16 v[54:57], v[182:185], v[198:201], v[54:57]
	v_mfma_f32_16x16x32_bf16 v[50:53], v[190:193], v[198:201], v[50:53]
	v_mfma_f32_16x16x32_bf16 v[38:41], v[182:185], v[206:209], v[38:41]
	v_mfma_f32_16x16x32_bf16 v[34:37], v[190:193], v[206:209], v[34:37]
	v_mfma_f32_16x16x32_bf16 v[22:25], v[182:185], v[214:217], v[22:25]
	v_mfma_f32_16x16x32_bf16 v[18:21], v[190:193], v[214:217], v[18:21]
	v_mfma_f32_16x16x32_bf16 v[6:9], v[182:185], v[222:225], v[6:9]
	v_mfma_f32_16x16x32_bf16 v[2:5], v[190:193], v[222:225], v[2:5]
	v_mfma_f32_16x16x32_bf16 v[54:57], v[186:189], v[202:205], v[54:57]
	v_mfma_f32_16x16x32_bf16 v[50:53], v[194:197], v[202:205], v[50:53]
	v_mfma_f32_16x16x32_bf16 v[38:41], v[186:189], v[210:213], v[38:41]
	v_mfma_f32_16x16x32_bf16 v[34:37], v[194:197], v[210:213], v[34:37]
	v_mfma_f32_16x16x32_bf16 v[22:25], v[186:189], v[218:221], v[22:25]
	v_mfma_f32_16x16x32_bf16 v[18:21], v[194:197], v[218:221], v[18:21]
	v_mfma_f32_16x16x32_bf16 v[6:9], v[186:189], v[226:229], v[6:9]
	v_mfma_f32_16x16x32_bf16 v[2:5], v[194:197], v[226:229], v[2:5]
	s_setprio 0
	s_barrier
	s_add_i32 s70, 0, 0x18000
	v_add_u32_e32 v165, s70, v160
	s_add_i32 s71, 0, 0x1c000
	ds_read_b128 v[166:169], v165
	ds_read_b128 v[170:173], v165 offset:1024
	ds_read_b128 v[174:177], v165 offset:2048
	ds_read_b128 v[178:181], v165 offset:3072
	v_add_u32_e32 v165, s71, v160
	ds_read_b128 v[182:185], v165
	ds_read_b128 v[186:189], v165 offset:1024
	ds_read_b128 v[190:193], v165 offset:2048
	ds_read_b128 v[194:197], v165 offset:3072
	s_add_u32 s34, s34, s12
	s_addc_u32 s35, s35, s13
	s_mov_b32 m0, s43
	v_lshl_add_u64 v[242:243], s[34:35], 0, v[130:131]
	ds_read_b128 v[198:201], v164 offset:32768
	ds_read_b128 v[202:205], v164 offset:33792
	ds_read_b128 v[206:209], v164 offset:34816
	ds_read_b128 v[210:213], v164 offset:35840
	ds_read_b128 v[214:217], v164 offset:36864
	ds_read_b128 v[218:221], v164 offset:37888
	ds_read_b128 v[222:225], v164 offset:38912
	ds_read_b128 v[226:229], v164 offset:39936
	global_load_lds_dwordx4 v[242:243], off
	s_mov_b32 m0, s44
	v_lshl_add_u64 v[242:243], s[34:35], 0, v[134:135]
	global_load_lds_dwordx4 v[242:243], off
	s_waitcnt vmcnt(8) lgkmcnt(0)
	s_barrier
	s_setprio 1
	v_mfma_f32_16x16x32_bf16 v[122:125], v[166:169], v[198:201], v[122:125]
	v_mfma_f32_16x16x32_bf16 v[126:129], v[174:177], v[198:201], v[126:129]
	v_mfma_f32_16x16x32_bf16 v[110:113], v[166:169], v[206:209], v[110:113]
	v_mfma_f32_16x16x32_bf16 v[106:109], v[174:177], v[206:209], v[106:109]
	v_mfma_f32_16x16x32_bf16 v[94:97], v[166:169], v[214:217], v[94:97]
	v_mfma_f32_16x16x32_bf16 v[90:93], v[174:177], v[214:217], v[90:93]
	v_mfma_f32_16x16x32_bf16 v[78:81], v[166:169], v[222:225], v[78:81]
	v_mfma_f32_16x16x32_bf16 v[74:77], v[174:177], v[222:225], v[74:77]
	v_mfma_f32_16x16x32_bf16 v[122:125], v[170:173], v[202:205], v[122:125]
	v_mfma_f32_16x16x32_bf16 v[126:129], v[178:181], v[202:205], v[126:129]
	v_mfma_f32_16x16x32_bf16 v[110:113], v[170:173], v[210:213], v[110:113]
	v_mfma_f32_16x16x32_bf16 v[106:109], v[178:181], v[210:213], v[106:109]
	v_mfma_f32_16x16x32_bf16 v[94:97], v[170:173], v[218:221], v[94:97]
	v_mfma_f32_16x16x32_bf16 v[90:93], v[178:181], v[218:221], v[90:93]
	v_mfma_f32_16x16x32_bf16 v[78:81], v[170:173], v[226:229], v[78:81]
	v_mfma_f32_16x16x32_bf16 v[74:77], v[178:181], v[226:229], v[74:77]
	v_mfma_f32_16x16x32_bf16 v[118:121], v[182:185], v[198:201], v[118:121]
	v_mfma_f32_16x16x32_bf16 v[114:117], v[190:193], v[198:201], v[114:117]
	v_mfma_f32_16x16x32_bf16 v[102:105], v[182:185], v[206:209], v[102:105]
	v_mfma_f32_16x16x32_bf16 v[98:101], v[190:193], v[206:209], v[98:101]
	v_mfma_f32_16x16x32_bf16 v[86:89], v[182:185], v[214:217], v[86:89]
	v_mfma_f32_16x16x32_bf16 v[82:85], v[190:193], v[214:217], v[82:85]
	v_mfma_f32_16x16x32_bf16 v[70:73], v[182:185], v[222:225], v[70:73]
	v_mfma_f32_16x16x32_bf16 v[66:69], v[190:193], v[222:225], v[66:69]
	v_mfma_f32_16x16x32_bf16 v[118:121], v[186:189], v[202:205], v[118:121]
	v_mfma_f32_16x16x32_bf16 v[114:117], v[194:197], v[202:205], v[114:117]
	v_mfma_f32_16x16x32_bf16 v[102:105], v[186:189], v[210:213], v[102:105]
	v_mfma_f32_16x16x32_bf16 v[98:101], v[194:197], v[210:213], v[98:101]
	v_mfma_f32_16x16x32_bf16 v[86:89], v[186:189], v[218:221], v[86:89]
	v_mfma_f32_16x16x32_bf16 v[82:85], v[194:197], v[218:221], v[82:85]
	v_mfma_f32_16x16x32_bf16 v[70:73], v[186:189], v[226:229], v[70:73]
	v_mfma_f32_16x16x32_bf16 v[66:69], v[194:197], v[226:229], v[66:69]
	s_setprio 0
	s_barrier
; #define PG8_STAGE(bufoff, gbase, voff) do { _Pragma("unroll") for (int _i = 0; _i < 2; ++_i) \
;         __builtin_amdgcn_global_load_lds((const unsigned*)((const char*)(gbase) + (voff)[_i]), (PG8_LAS unsigned*)(lds + (bufoff) + ldsw + _i * 8192), 16, 0, 0); } while (0)
; #define PG8_LDA(dst, b, h) do { _Pragma("unroll") for (int m = 0; m < 4; ++m) _Pragma("unroll") for (int k = 0; k < 2; ++k) dst[m][k] = *(const PG8_LAS bf16x8*)(lds + PG8_SA(b, h) + aoff + m * 2048 + k * 1024); } while (0)
; #define PG8_MMA(ai, bj, At, Bt) do { __builtin_amdgcn_s_setprio(1); _Pragma("unroll") for (int m = 0; m < 4; ++m) _Pragma("unroll") for (int n = 0; n < 2; ++n) _Pragma("unroll") for (int k = 0; k < 2; ++k) \
;         acc[ai][bj][m][n] = __builtin_amdgcn_mfma_f32_16x16x32_bf16(Bt[n][k], At[m][k], acc[ai][bj][m][n], 0, 0, 0); __builtin_amdgcn_s_setprio(0); } while (0)
; #define PG8_WAIT_V(n) asm volatile("s_waitcnt vmcnt(" #n ")" ::: "memory")
; #define PG8_WAIT_L(n) asm volatile("s_waitcnt lgkmcnt(" #n ")" ::: "memory")
; #define PG8_BAR __builtin_amdgcn_s_barrier()
; #define PG8_SCHED __builtin_amdgcn_sched_barrier(0)
; template <class Epi, class Sched, bool ALIGN_EPI = false, bool SP2 = false>
; __device__ __forceinline__ void gemm_phase(PG8_LAS unsigned char* lds, const Gemm g, const Sched& S, const Epi& E) {
;     ...
;         for (int t = 0; t < nt; t += 2) {
;     ...
;             PG8_LDA(At, 1, 1); PG8_STAGE(PG8_SB(1, 0), b3, voffB); PG8_STAGE(PG8_SB(1, 1), b3 + hstep, voffB); PG8_STAGE(PG8_SA(1, 0), a3, voffA);
;             PG8_WAIT_V(8); PG8_WAIT_L(0); PG8_BAR; PG8_MMA(1, 0, At, B0); PG8_MMA(1, 1, At, B1); PG8_BAR; PG8_SCHED;
	s_add_i32 s34, s70, s40
	v_lshl_add_u64 v[230:231], v[230:231], 0, s[22:23]
	s_mov_b32 m0, s34
	ds_read_b128 v[198:201], v164 offset:49152
	ds_read_b128 v[202:205], v164 offset:50176
	ds_read_b128 v[206:209], v164 offset:51200
	ds_read_b128 v[210:213], v164 offset:52224
	ds_read_b128 v[214:217], v164 offset:53248
	ds_read_b128 v[218:221], v164 offset:54272
	ds_read_b128 v[222:225], v164 offset:55296
	ds_read_b128 v[226:229], v164 offset:56320
	global_load_lds_dwordx4 v[230:231], off
	v_lshl_add_u64 v[230:231], v[232:233], 0, s[22:23]
	s_add_i32 m0, s34, 0x2000
	s_add_i32 s34, s71, s40
	global_load_lds_dwordx4 v[230:231], off
	s_mov_b32 m0, s34
	v_lshl_add_u64 v[230:231], v[234:235], 0, s[22:23]
	global_load_lds_dwordx4 v[230:231], off
	s_add_i32 m0, s34, 0x2000
	v_lshl_add_u64 v[230:231], v[236:237], 0, s[22:23]
	global_load_lds_dwordx4 v[230:231], off
	s_mov_b32 m0, s46
	v_lshl_add_u64 v[230:231], v[238:239], 0, s[22:23]
	global_load_lds_dwordx4 v[230:231], off
	s_mov_b32 m0, s47
	v_lshl_add_u64 v[230:231], v[240:241], 0, s[22:23]
	global_load_lds_dwordx4 v[230:231], off
	s_waitcnt vmcnt(8) lgkmcnt(0)
	s_barrier
	s_setprio 1
	v_mfma_f32_16x16x32_bf16 v[62:65], v[166:169], v[198:201], v[62:65]
	v_mfma_f32_16x16x32_bf16 v[58:61], v[174:177], v[198:201], v[58:61]
	v_mfma_f32_16x16x32_bf16 v[46:49], v[166:169], v[206:209], v[46:49]
	v_mfma_f32_16x16x32_bf16 v[42:45], v[174:177], v[206:209], v[42:45]
	v_mfma_f32_16x16x32_bf16 v[30:33], v[166:169], v[214:217], v[30:33]
	v_mfma_f32_16x16x32_bf16 v[26:29], v[174:177], v[214:217], v[26:29]
	v_mfma_f32_16x16x32_bf16 v[14:17], v[166:169], v[222:225], v[14:17]
	v_mfma_f32_16x16x32_bf16 v[10:13], v[174:177], v[222:225], v[10:13]
	v_mfma_f32_16x16x32_bf16 v[62:65], v[170:173], v[202:205], v[62:65]
	v_mfma_f32_16x16x32_bf16 v[58:61], v[178:181], v[202:205], v[58:61]
	v_mfma_f32_16x16x32_bf16 v[46:49], v[170:173], v[210:213], v[46:49]
	v_mfma_f32_16x16x32_bf16 v[42:45], v[178:181], v[210:213], v[42:45]
	v_mfma_f32_16x16x32_bf16 v[30:33], v[170:173], v[218:221], v[30:33]
	v_mfma_f32_16x16x32_bf16 v[26:29], v[178:181], v[218:221], v[26:29]
	v_mfma_f32_16x16x32_bf16 v[14:17], v[170:173], v[226:229], v[14:17]
	v_mfma_f32_16x16x32_bf16 v[10:13], v[178:181], v[226:229], v[10:13]
	v_mfma_f32_16x16x32_bf16 v[54:57], v[182:185], v[198:201], v[54:57]
	v_mfma_f32_16x16x32_bf16 v[50:53], v[190:193], v[198:201], v[50:53]
	v_mfma_f32_16x16x32_bf16 v[38:41], v[182:185], v[206:209], v[38:41]
	v_mfma_f32_16x16x32_bf16 v[34:37], v[190:193], v[206:209], v[34:37]
	v_mfma_f32_16x16x32_bf16 v[22:25], v[182:185], v[214:217], v[22:25]
	v_mfma_f32_16x16x32_bf16 v[18:21], v[190:193], v[214:217], v[18:21]
	v_mfma_f32_16x16x32_bf16 v[6:9], v[182:185], v[222:225], v[6:9]
	v_mfma_f32_16x16x32_bf16 v[2:5], v[190:193], v[222:225], v[2:5]
	v_mfma_f32_16x16x32_bf16 v[54:57], v[186:189], v[202:205], v[54:57]
	v_mfma_f32_16x16x32_bf16 v[50:53], v[194:197], v[202:205], v[50:53]
	v_mfma_f32_16x16x32_bf16 v[38:41], v[186:189], v[210:213], v[38:41]
	v_mfma_f32_16x16x32_bf16 v[34:37], v[194:197], v[210:213], v[34:37]
	v_mfma_f32_16x16x32_bf16 v[22:25], v[186:189], v[218:221], v[22:25]
	v_mfma_f32_16x16x32_bf16 v[18:21], v[194:197], v[218:221], v[18:21]
	v_mfma_f32_16x16x32_bf16 v[6:9], v[186:189], v[226:229], v[6:9]
	v_mfma_f32_16x16x32_bf16 v[2:5], v[194:197], v[226:229], v[2:5]
	s_setprio 0
	s_barrier
	s_add_u32 s80, s80, 0x100
	s_addc_u32 s81, s81, 0
	s_add_u32 s30, s30, 0x100
	s_addc_u32 s31, s31, 0
	s_cmp_ge_i32 s86, s48
	s_mov_b32 s34, s86
	s_cbranch_scc0 .LBB0_1404

; #define PG8_STAGE(bufoff, gbase, voff) do { _Pragma("unroll") for (int _i = 0; _i < 2; ++_i) \
;         __builtin_amdgcn_global_load_lds((const unsigned*)((const char*)(gbase) + (voff)[_i]), (PG8_LAS unsigned*)(lds + (bufoff) + ldsw + _i * 8192), 16, 0, 0); } while (0)
; #define PG8_LDA(dst, b, h) do { _Pragma("unroll") for (int m = 0; m < 4; ++m) _Pragma("unroll") for (int k = 0; k < 2; ++k) dst[m][k] = *(const PG8_LAS bf16x8*)(lds + PG8_SA(b, h) + aoff + m * 2048 + k * 1024); } while (0)
; #define PG8_LDB(dst, b, h) do { _Pragma("unroll") for (int n = 0; n < 2; ++n) _Pragma("unroll") for (int k = 0; k < 2; ++k) dst[n][k] = *(const PG8_LAS bf16x8*)(lds + PG8_SB(b, h) + boff + n * 2048 + k * 1024); } while (0)
; #define PG8_WAIT_V(n) asm volatile("s_waitcnt vmcnt(" #n ")" ::: "memory")
; #define PG8_WAIT_L(n) asm volatile("s_waitcnt lgkmcnt(" #n ")" ::: "memory")
; #define PG8_BAR __builtin_amdgcn_s_barrier()
; #define PG8_SCHED __builtin_amdgcn_sched_barrier(0)
; template <class Epi, class Sched, bool ALIGN_EPI = false, bool SP2 = false>
; __device__ __forceinline__ void gemm_phase(PG8_LAS unsigned char* lds, const Gemm g, const Sched& S, const Epi& E) {
;     ...
;         const bool has_next = S.next(ui + 1, nxt);
;         const char* nA = has_next ? (const char*)g.A + (size_t)nxt.pm * tstep : cA; const char* nB = has_next ? (const char*)g.Bt + (size_t)nxt.pn * tstep : cB;
;         for (int t = 0; t < nt; t += 2) {
;             const bool last = (t == nt - 2);
;             const char* a1 = cA + (size_t)(t + 1) * kstep;
;             const char* a2 = last ? nA : cA + (size_t)(t + 2) * kstep; const char* b2 = last ? nB : cB + (size_t)(t + 2) * kstep;
;             const char* a3 = a2 + kstep; const char* b3 = b2 + kstep;
;             if (last && has_next) S.a_ready(nxt);
;             if constexpr (SP2) {
;             PG8_LDB(B0, 0, 0); PG8_LDB(B1, 0, 1); PG8_SCHED; PG8_LDA(At, 0, 0); PG8_STAGE(PG8_SA(1, 1), a1 + hstep, voffA);
;             PG8_WAIT_V(8); PG8_WAIT_L(0); PG8_BAR; PG8_MMA(0, 0, At, B0); PG8_MMA(0, 1, At, B1); PG8_BAR; PG8_SCHED;
;             PG8_LDA(At, 0, 1); PG8_STAGE(PG8_SB(0, 0), b2, voffB); PG8_STAGE(PG8_SB(0, 1), b2 + hstep, voffB); PG8_STAGE(PG8_SA(0, 0), a2, voffA);
;             PG8_WAIT_V(8); PG8_WAIT_L(0); PG8_BAR; PG8_MMA(1, 0, At, B0); PG8_MMA(1, 1, At, B1); PG8_BAR; PG8_SCHED;
.LBB0_1433:
	ds_read_b128 v[156:159], v1
	ds_read_b128 v[160:163], v1 offset:1024
	ds_read_b128 v[164:167], v1 offset:2048
	ds_read_b128 v[168:171], v1 offset:3072
	ds_read_b128 v[172:175], v146
	ds_read_b128 v[176:179], v146 offset:1024
	ds_read_b128 v[180:183], v146 offset:2048
	ds_read_b128 v[184:187], v146 offset:3072
	s_add_i32 s80, s30, 2
	s_add_u32 s70, s28, 0x80
	s_addc_u32 s31, s29, 0
	s_cmp_eq_u32 s47, s30
	s_cselect_b32 s30, s4, s70
	s_cselect_b32 s31, s5, s31
	s_cselect_b32 s71, s27, s69
	s_cselect_b32 s70, s26, s68
	v_lshl_add_u64 v[152:153], s[28:29], 0, v[140:141]
	s_add_i32 m0, s39, 0xc000
	ds_read_b128 v[188:191], v147
	ds_read_b128 v[192:195], v147 offset:1024
	ds_read_b128 v[196:199], v147 offset:2048
	ds_read_b128 v[200:203], v147 offset:3072
	ds_read_b128 v[204:207], v147 offset:4096
	ds_read_b128 v[208:211], v147 offset:5120
	ds_read_b128 v[212:215], v147 offset:6144
	ds_read_b128 v[216:219], v147 offset:7168
	global_load_lds_dwordx4 v[152:153], off
	s_add_i32 m0, s39, 0xe000
	v_lshl_add_u64 v[152:153], s[28:29], 0, v[138:139]
	global_load_lds_dwordx4 v[152:153], off
	s_waitcnt vmcnt(8) lgkmcnt(0)
	s_barrier
	s_setprio 1
	v_mfma_f32_16x16x32_bf16 v[122:125], v[156:159], v[188:191], v[122:125]
	v_mfma_f32_16x16x32_bf16 v[126:129], v[164:167], v[188:191], v[126:129]
	v_mfma_f32_16x16x32_bf16 v[110:113], v[156:159], v[196:199], v[110:113]
	v_mfma_f32_16x16x32_bf16 v[106:109], v[164:167], v[196:199], v[106:109]
	v_mfma_f32_16x16x32_bf16 v[94:97], v[156:159], v[204:207], v[94:97]
	v_mfma_f32_16x16x32_bf16 v[90:93], v[164:167], v[204:207], v[90:93]
	v_mfma_f32_16x16x32_bf16 v[78:81], v[156:159], v[212:215], v[78:81]
	v_mfma_f32_16x16x32_bf16 v[74:77], v[164:167], v[212:215], v[74:77]
	v_mfma_f32_16x16x32_bf16 v[122:125], v[160:163], v[192:195], v[122:125]
	v_mfma_f32_16x16x32_bf16 v[126:129], v[168:171], v[192:195], v[126:129]
	v_mfma_f32_16x16x32_bf16 v[110:113], v[160:163], v[200:203], v[110:113]
	v_mfma_f32_16x16x32_bf16 v[106:109], v[168:171], v[200:203], v[106:109]
	v_mfma_f32_16x16x32_bf16 v[94:97], v[160:163], v[208:211], v[94:97]
	v_mfma_f32_16x16x32_bf16 v[90:93], v[168:171], v[208:211], v[90:93]
	v_mfma_f32_16x16x32_bf16 v[78:81], v[160:163], v[216:219], v[78:81]
	v_mfma_f32_16x16x32_bf16 v[74:77], v[168:171], v[216:219], v[74:77]
	v_mfma_f32_16x16x32_bf16 v[118:121], v[172:175], v[188:191], v[118:121]
	v_mfma_f32_16x16x32_bf16 v[114:117], v[180:183], v[188:191], v[114:117]
	v_mfma_f32_16x16x32_bf16 v[102:105], v[172:175], v[196:199], v[102:105]
	v_mfma_f32_16x16x32_bf16 v[98:101], v[180:183], v[196:199], v[98:101]
	v_mfma_f32_16x16x32_bf16 v[86:89], v[172:175], v[204:207], v[86:89]
	v_mfma_f32_16x16x32_bf16 v[82:85], v[180:183], v[204:207], v[82:85]
	v_mfma_f32_16x16x32_bf16 v[70:73], v[172:175], v[212:215], v[70:73]
	v_mfma_f32_16x16x32_bf16 v[66:69], v[180:183], v[212:215], v[66:69]
	v_mfma_f32_16x16x32_bf16 v[118:121], v[176:179], v[192:195], v[118:121]
	v_mfma_f32_16x16x32_bf16 v[114:117], v[184:187], v[192:195], v[114:117]
	v_mfma_f32_16x16x32_bf16 v[102:105], v[176:179], v[200:203], v[102:105]
	v_mfma_f32_16x16x32_bf16 v[98:101], v[184:187], v[200:203], v[98:101]
	v_mfma_f32_16x16x32_bf16 v[86:89], v[176:179], v[208:211], v[86:89]
	v_mfma_f32_16x16x32_bf16 v[82:85], v[184:187], v[208:211], v[82:85]
	v_mfma_f32_16x16x32_bf16 v[70:73], v[176:179], v[216:219], v[70:73]
	v_mfma_f32_16x16x32_bf16 v[66:69], v[184:187], v[216:219], v[66:69]
	s_setprio 0
	s_barrier
	s_add_i32 s72, s52, s38
	v_lshl_add_u64 v[152:153], s[70:71], 0, v[132:133]
	s_mov_b32 m0, s72
	ds_read_b128 v[188:191], v147 offset:16384
	ds_read_b128 v[192:195], v147 offset:17408
	ds_read_b128 v[196:199], v147 offset:18432
	ds_read_b128 v[200:203], v147 offset:19456
	ds_read_b128 v[204:207], v147 offset:20480
	ds_read_b128 v[208:211], v147 offset:21504
	ds_read_b128 v[212:215], v147 offset:22528
	ds_read_b128 v[216:219], v147 offset:23552
	global_load_lds_dwordx4 v[152:153], off
	s_add_i32 m0, s72, 0x2000
	v_lshl_add_u64 v[220:221], s[70:71], 0, v[136:137]
	s_add_u32 s70, s70, s6
	s_addc_u32 s71, s71, s7
	s_add_i32 s72, s53, s38
	global_load_lds_dwordx4 v[220:221], off
	v_lshl_add_u64 v[222:223], s[70:71], 0, v[132:133]
	s_mov_b32 m0, s72
	v_lshl_add_u64 v[224:225], s[70:71], 0, v[136:137]
	global_load_lds_dwordx4 v[222:223], off
	s_add_i32 m0, s72, 0x2000
	v_lshl_add_u64 v[226:227], s[30:31], 0, v[130:131]
	global_load_lds_dwordx4 v[224:225], off
	s_mov_b32 m0, s39
	v_lshl_add_u64 v[228:229], s[30:31], 0, v[134:135]
	global_load_lds_dwordx4 v[226:227], off
	s_mov_b32 m0, s40
	s_nop 0
	global_load_lds_dwordx4 v[228:229], off
	s_waitcnt vmcnt(8) lgkmcnt(0)
	s_barrier
; #define PG8_STAGE(bufoff, gbase, voff) do { _Pragma("unroll") for (int _i = 0; _i < 2; ++_i) \
;         __builtin_amdgcn_global_load_lds((const unsigned*)((const char*)(gbase) + (voff)[_i]), (PG8_LAS unsigned*)(lds + (bufoff) + ldsw + _i * 8192), 16, 0, 0); } while (0)
; #define PG8_LDA(dst, b, h) do { _Pragma("unroll") for (int m = 0; m < 4; ++m) _Pragma("unroll") for (int k = 0; k < 2; ++k) dst[m][k] = *(const PG8_LAS bf16x8*)(lds + PG8_SA(b, h) + aoff + m * 2048 + k * 1024); } while (0)
; #define PG8_LDB(dst, b, h) do { _Pragma("unroll") for (int n = 0; n < 2; ++n) _Pragma("unroll") for (int k = 0; k < 2; ++k) dst[n][k] = *(const PG8_LAS bf16x8*)(lds + PG8_SB(b, h) + boff + n * 2048 + k * 1024); } while (0)
; #define PG8_MMA(ai, bj, At, Bt) do { __builtin_amdgcn_s_setprio(1); _Pragma("unroll") for (int m = 0; m < 4; ++m) _Pragma("unroll") for (int n = 0; n < 2; ++n) _Pragma("unroll") for (int k = 0; k < 2; ++k) \
;         acc[ai][bj][m][n] = __builtin_amdgcn_mfma_f32_16x16x32_bf16(Bt[n][k], At[m][k], acc[ai][bj][m][n], 0, 0, 0); __builtin_amdgcn_s_setprio(0); } while (0)
; #define PG8_WAIT_V(n) asm volatile("s_waitcnt vmcnt(" #n ")" ::: "memory")
; #define PG8_WAIT_L(n) asm volatile("s_waitcnt lgkmcnt(" #n ")" ::: "memory")
; #define PG8_BAR __builtin_amdgcn_s_barrier()
; #define PG8_SCHED __builtin_amdgcn_sched_barrier(0)
; template <class Epi, class Sched, bool ALIGN_EPI = false, bool SP2 = false>
; __device__ __forceinline__ void gemm_phase(PG8_LAS unsigned char* lds, const Gemm g, const Sched& S, const Epi& E) {
;     ...
;             PG8_WAIT_V(8); PG8_WAIT_L(0); PG8_BAR; PG8_MMA(1, 0, At, B0); PG8_MMA(1, 1, At, B1); PG8_BAR; PG8_SCHED;
;             PG8_LDB(B0, 1, 0); PG8_LDB(B1, 1, 1); PG8_SCHED; PG8_LDA(At, 1, 0); PG8_STAGE(PG8_SA(0, 1), a2 + hstep, voffA);
;             PG8_WAIT_V(8); PG8_WAIT_L(0); PG8_BAR; PG8_MMA(0, 0, At, B0); PG8_MMA(0, 1, At, B1); PG8_BAR; PG8_SCHED;
	s_setprio 1
	v_mfma_f32_16x16x32_bf16 v[62:65], v[156:159], v[188:191], v[62:65]
	v_mfma_f32_16x16x32_bf16 v[58:61], v[164:167], v[188:191], v[58:61]
	v_mfma_f32_16x16x32_bf16 v[46:49], v[156:159], v[196:199], v[46:49]
	v_mfma_f32_16x16x32_bf16 v[42:45], v[164:167], v[196:199], v[42:45]
	v_mfma_f32_16x16x32_bf16 v[30:33], v[156:159], v[204:207], v[30:33]
	v_mfma_f32_16x16x32_bf16 v[26:29], v[164:167], v[204:207], v[26:29]
	v_mfma_f32_16x16x32_bf16 v[14:17], v[156:159], v[212:215], v[14:17]
	v_mfma_f32_16x16x32_bf16 v[10:13], v[164:167], v[212:215], v[10:13]
	v_mfma_f32_16x16x32_bf16 v[62:65], v[160:163], v[192:195], v[62:65]
	v_mfma_f32_16x16x32_bf16 v[58:61], v[168:171], v[192:195], v[58:61]
	v_mfma_f32_16x16x32_bf16 v[46:49], v[160:163], v[200:203], v[46:49]
	v_mfma_f32_16x16x32_bf16 v[42:45], v[168:171], v[200:203], v[42:45]
	v_mfma_f32_16x16x32_bf16 v[30:33], v[160:163], v[208:211], v[30:33]
	v_mfma_f32_16x16x32_bf16 v[26:29], v[168:171], v[208:211], v[26:29]
	v_mfma_f32_16x16x32_bf16 v[14:17], v[160:163], v[216:219], v[14:17]
	v_mfma_f32_16x16x32_bf16 v[10:13], v[168:171], v[216:219], v[10:13]
	v_mfma_f32_16x16x32_bf16 v[54:57], v[172:175], v[188:191], v[54:57]
	v_mfma_f32_16x16x32_bf16 v[50:53], v[180:183], v[188:191], v[50:53]
	v_mfma_f32_16x16x32_bf16 v[38:41], v[172:175], v[196:199], v[38:41]
	v_mfma_f32_16x16x32_bf16 v[34:37], v[180:183], v[196:199], v[34:37]
	v_mfma_f32_16x16x32_bf16 v[22:25], v[172:175], v[204:207], v[22:25]
	v_mfma_f32_16x16x32_bf16 v[18:21], v[180:183], v[204:207], v[18:21]
	v_mfma_f32_16x16x32_bf16 v[6:9], v[172:175], v[212:215], v[6:9]
	v_mfma_f32_16x16x32_bf16 v[2:5], v[180:183], v[212:215], v[2:5]
	v_mfma_f32_16x16x32_bf16 v[54:57], v[176:179], v[192:195], v[54:57]
	v_mfma_f32_16x16x32_bf16 v[50:53], v[184:187], v[192:195], v[50:53]
	v_mfma_f32_16x16x32_bf16 v[38:41], v[176:179], v[200:203], v[38:41]
	v_mfma_f32_16x16x32_bf16 v[34:37], v[184:187], v[200:203], v[34:37]
	v_mfma_f32_16x16x32_bf16 v[22:25], v[176:179], v[208:211], v[22:25]
	v_mfma_f32_16x16x32_bf16 v[18:21], v[184:187], v[208:211], v[18:21]
	v_mfma_f32_16x16x32_bf16 v[6:9], v[176:179], v[216:219], v[6:9]
	v_mfma_f32_16x16x32_bf16 v[2:5], v[184:187], v[216:219], v[2:5]
	s_setprio 0
	s_barrier
	s_add_i32 s70, 0, 0x18000
	v_add_u32_e32 v148, s70, v150
	s_add_i32 s71, 0, 0x1c000
	ds_read_b128 v[156:159], v148
	ds_read_b128 v[160:163], v148 offset:1024
	ds_read_b128 v[164:167], v148 offset:2048
	ds_read_b128 v[168:171], v148 offset:3072
	v_add_u32_e32 v148, s71, v150
	ds_read_b128 v[172:175], v148
	ds_read_b128 v[176:179], v148 offset:1024
	ds_read_b128 v[180:183], v148 offset:2048
	ds_read_b128 v[184:187], v148 offset:3072
	s_add_u32 s30, s30, s6
	s_addc_u32 s31, s31, s7
	s_mov_b32 m0, s41
	v_lshl_add_u64 v[230:231], s[30:31], 0, v[130:131]
	ds_read_b128 v[188:191], v147 offset:32768
	ds_read_b128 v[192:195], v147 offset:33792
	ds_read_b128 v[196:199], v147 offset:34816
	ds_read_b128 v[200:203], v147 offset:35840
	ds_read_b128 v[204:207], v147 offset:36864
	ds_read_b128 v[208:211], v147 offset:37888
	ds_read_b128 v[212:215], v147 offset:38912
	ds_read_b128 v[216:219], v147 offset:39936
	global_load_lds_dwordx4 v[230:231], off
	s_mov_b32 m0, s42
	v_lshl_add_u64 v[230:231], s[30:31], 0, v[134:135]
	global_load_lds_dwordx4 v[230:231], off
	s_waitcnt vmcnt(8) lgkmcnt(0)
	s_barrier
	s_setprio 1
	v_mfma_f32_16x16x32_bf16 v[122:125], v[156:159], v[188:191], v[122:125]
	v_mfma_f32_16x16x32_bf16 v[126:129], v[164:167], v[188:191], v[126:129]
	v_mfma_f32_16x16x32_bf16 v[110:113], v[156:159], v[196:199], v[110:113]
	v_mfma_f32_16x16x32_bf16 v[106:109], v[164:167], v[196:199], v[106:109]
	v_mfma_f32_16x16x32_bf16 v[94:97], v[156:159], v[204:207], v[94:97]
	v_mfma_f32_16x16x32_bf16 v[90:93], v[164:167], v[204:207], v[90:93]
	v_mfma_f32_16x16x32_bf16 v[78:81], v[156:159], v[212:215], v[78:81]
	v_mfma_f32_16x16x32_bf16 v[74:77], v[164:167], v[212:215], v[74:77]
	v_mfma_f32_16x16x32_bf16 v[122:125], v[160:163], v[192:195], v[122:125]
	v_mfma_f32_16x16x32_bf16 v[126:129], v[168:171], v[192:195], v[126:129]
	v_mfma_f32_16x16x32_bf16 v[110:113], v[160:163], v[200:203], v[110:113]
	v_mfma_f32_16x16x32_bf16 v[106:109], v[168:171], v[200:203], v[106:109]
	v_mfma_f32_16x16x32_bf16 v[94:97], v[160:163], v[208:211], v[94:97]
	v_mfma_f32_16x16x32_bf16 v[90:93], v[168:171], v[208:211], v[90:93]
	v_mfma_f32_16x16x32_bf16 v[78:81], v[160:163], v[216:219], v[78:81]
	v_mfma_f32_16x16x32_bf16 v[74:77], v[168:171], v[216:219], v[74:77]
	v_mfma_f32_16x16x32_bf16 v[118:121], v[172:175], v[188:191], v[118:121]
	v_mfma_f32_16x16x32_bf16 v[114:117], v[180:183], v[188:191], v[114:117]
	v_mfma_f32_16x16x32_bf16 v[102:105], v[172:175], v[196:199], v[102:105]
	v_mfma_f32_16x16x32_bf16 v[98:101], v[180:183], v[196:199], v[98:101]
	v_mfma_f32_16x16x32_bf16 v[86:89], v[172:175], v[204:207], v[86:89]
	v_mfma_f32_16x16x32_bf16 v[82:85], v[180:183], v[204:207], v[82:85]
	v_mfma_f32_16x16x32_bf16 v[70:73], v[172:175], v[212:215], v[70:73]
	v_mfma_f32_16x16x32_bf16 v[66:69], v[180:183], v[212:215], v[66:69]
	v_mfma_f32_16x16x32_bf16 v[118:121], v[176:179], v[192:195], v[118:121]
	v_mfma_f32_16x16x32_bf16 v[114:117], v[184:187], v[192:195], v[114:117]
	v_mfma_f32_16x16x32_bf16 v[102:105], v[176:179], v[200:203], v[102:105]
	v_mfma_f32_16x16x32_bf16 v[98:101], v[184:187], v[200:203], v[98:101]
	v_mfma_f32_16x16x32_bf16 v[86:89], v[176:179], v[208:211], v[86:89]
	v_mfma_f32_16x16x32_bf16 v[82:85], v[184:187], v[208:211], v[82:85]
	v_mfma_f32_16x16x32_bf16 v[70:73], v[176:179], v[216:219], v[70:73]
	v_mfma_f32_16x16x32_bf16 v[66:69], v[184:187], v[216:219], v[66:69]
	s_setprio 0
	s_barrier
; #define PG8_STAGE(bufoff, gbase, voff) do { _Pragma("unroll") for (int _i = 0; _i < 2; ++_i) \
;         __builtin_amdgcn_global_load_lds((const unsigned*)((const char*)(gbase) + (voff)[_i]), (PG8_LAS unsigned*)(lds + (bufoff) + ldsw + _i * 8192), 16, 0, 0); } while (0)
; #define PG8_LDA(dst, b, h) do { _Pragma("unroll") for (int m = 0; m < 4; ++m) _Pragma("unroll") for (int k = 0; k < 2; ++k) dst[m][k] = *(const PG8_LAS bf16x8*)(lds + PG8_SA(b, h) + aoff + m * 2048 + k * 1024); } while (0)
; #define PG8_MMA(ai, bj, At, Bt) do { __builtin_amdgcn_s_setprio(1); _Pragma("unroll") for (int m = 0; m < 4; ++m) _Pragma("unroll") for (int n = 0; n < 2; ++n) _Pragma("unroll") for (int k = 0; k < 2; ++k) \
;         acc[ai][bj][m][n] = __builtin_amdgcn_mfma_f32_16x16x32_bf16(Bt[n][k], At[m][k], acc[ai][bj][m][n], 0, 0, 0); __builtin_amdgcn_s_setprio(0); } while (0)
; #define PG8_WAIT_V(n) asm volatile("s_waitcnt vmcnt(" #n ")" ::: "memory")
; #define PG8_WAIT_L(n) asm volatile("s_waitcnt lgkmcnt(" #n ")" ::: "memory")
; #define PG8_BAR __builtin_amdgcn_s_barrier()
; #define PG8_SCHED __builtin_amdgcn_sched_barrier(0)
; template <class Epi, class Sched, bool ALIGN_EPI = false, bool SP2 = false>
; __device__ __forceinline__ void gemm_phase(PG8_LAS unsigned char* lds, const Gemm g, const Sched& S, const Epi& E) {
;     ...
;         for (int t = 0; t < nt; t += 2) {
;     ...
;             PG8_LDA(At, 1, 1); PG8_STAGE(PG8_SB(1, 0), b3, voffB); PG8_STAGE(PG8_SB(1, 1), b3 + hstep, voffB); PG8_STAGE(PG8_SA(1, 0), a3, voffA);
;             PG8_WAIT_V(8); PG8_WAIT_L(0); PG8_BAR; PG8_MMA(1, 0, At, B0); PG8_MMA(1, 1, At, B1); PG8_BAR; PG8_SCHED;
	s_add_i32 s30, s70, s38
	v_lshl_add_u64 v[152:153], v[152:153], 0, s[20:21]
	s_mov_b32 m0, s30
	ds_read_b128 v[188:191], v147 offset:49152
	ds_read_b128 v[192:195], v147 offset:50176
	ds_read_b128 v[196:199], v147 offset:51200
	ds_read_b128 v[200:203], v147 offset:52224
	ds_read_b128 v[204:207], v147 offset:53248
	ds_read_b128 v[208:211], v147 offset:54272
	ds_read_b128 v[212:215], v147 offset:55296
	ds_read_b128 v[216:219], v147 offset:56320
	global_load_lds_dwordx4 v[152:153], off
	v_lshl_add_u64 v[152:153], v[220:221], 0, s[20:21]
	s_add_i32 m0, s30, 0x2000
	s_add_i32 s30, s71, s38
	global_load_lds_dwordx4 v[152:153], off
	s_mov_b32 m0, s30
	v_lshl_add_u64 v[152:153], v[222:223], 0, s[20:21]
	global_load_lds_dwordx4 v[152:153], off
	s_add_i32 m0, s30, 0x2000
	v_lshl_add_u64 v[152:153], v[224:225], 0, s[20:21]
	global_load_lds_dwordx4 v[152:153], off
	s_mov_b32 m0, s44
	v_lshl_add_u64 v[152:153], v[226:227], 0, s[20:21]
	global_load_lds_dwordx4 v[152:153], off
	s_mov_b32 m0, s45
	v_lshl_add_u64 v[152:153], v[228:229], 0, s[20:21]
	global_load_lds_dwordx4 v[152:153], off
	s_waitcnt vmcnt(8) lgkmcnt(0)
	s_barrier
	s_setprio 1
	v_mfma_f32_16x16x32_bf16 v[62:65], v[156:159], v[188:191], v[62:65]
	v_mfma_f32_16x16x32_bf16 v[58:61], v[164:167], v[188:191], v[58:61]
	v_mfma_f32_16x16x32_bf16 v[46:49], v[156:159], v[196:199], v[46:49]
	v_mfma_f32_16x16x32_bf16 v[42:45], v[164:167], v[196:199], v[42:45]
	v_mfma_f32_16x16x32_bf16 v[30:33], v[156:159], v[204:207], v[30:33]
	v_mfma_f32_16x16x32_bf16 v[26:29], v[164:167], v[204:207], v[26:29]
	v_mfma_f32_16x16x32_bf16 v[14:17], v[156:159], v[212:215], v[14:17]
	v_mfma_f32_16x16x32_bf16 v[10:13], v[164:167], v[212:215], v[10:13]
	v_mfma_f32_16x16x32_bf16 v[62:65], v[160:163], v[192:195], v[62:65]
	v_mfma_f32_16x16x32_bf16 v[58:61], v[168:171], v[192:195], v[58:61]
	v_mfma_f32_16x16x32_bf16 v[46:49], v[160:163], v[200:203], v[46:49]
	v_mfma_f32_16x16x32_bf16 v[42:45], v[168:171], v[200:203], v[42:45]
	v_mfma_f32_16x16x32_bf16 v[30:33], v[160:163], v[208:211], v[30:33]
	v_mfma_f32_16x16x32_bf16 v[26:29], v[168:171], v[208:211], v[26:29]
	v_mfma_f32_16x16x32_bf16 v[14:17], v[160:163], v[216:219], v[14:17]
	v_mfma_f32_16x16x32_bf16 v[10:13], v[168:171], v[216:219], v[10:13]
	v_mfma_f32_16x16x32_bf16 v[54:57], v[172:175], v[188:191], v[54:57]
	v_mfma_f32_16x16x32_bf16 v[50:53], v[180:183], v[188:191], v[50:53]
	v_mfma_f32_16x16x32_bf16 v[38:41], v[172:175], v[196:199], v[38:41]
	v_mfma_f32_16x16x32_bf16 v[34:37], v[180:183], v[196:199], v[34:37]
	v_mfma_f32_16x16x32_bf16 v[22:25], v[172:175], v[204:207], v[22:25]
	v_mfma_f32_16x16x32_bf16 v[18:21], v[180:183], v[204:207], v[18:21]
	v_mfma_f32_16x16x32_bf16 v[6:9], v[172:175], v[212:215], v[6:9]
	v_mfma_f32_16x16x32_bf16 v[2:5], v[180:183], v[212:215], v[2:5]
	v_mfma_f32_16x16x32_bf16 v[54:57], v[176:179], v[192:195], v[54:57]
	v_mfma_f32_16x16x32_bf16 v[50:53], v[184:187], v[192:195], v[50:53]
	v_mfma_f32_16x16x32_bf16 v[38:41], v[176:179], v[200:203], v[38:41]
	v_mfma_f32_16x16x32_bf16 v[34:37], v[184:187], v[200:203], v[34:37]
	v_mfma_f32_16x16x32_bf16 v[22:25], v[176:179], v[208:211], v[22:25]
	v_mfma_f32_16x16x32_bf16 v[18:21], v[184:187], v[208:211], v[18:21]
	v_mfma_f32_16x16x32_bf16 v[6:9], v[176:179], v[216:219], v[6:9]
	v_mfma_f32_16x16x32_bf16 v[2:5], v[184:187], v[216:219], v[2:5]
	s_setprio 0
	s_barrier
	s_add_u32 s68, s68, 0x100
	s_addc_u32 s69, s69, 0
	s_add_u32 s28, s28, 0x100
	s_addc_u32 s29, s29, 0
	s_cmp_ge_i32 s80, s46
	s_mov_b32 s30, s80
	s_cbranch_scc0 .LBB0_1433

; #define PG8_STAGE(bufoff, gbase, voff) do { _Pragma("unroll") for (int _i = 0; _i < 2; ++_i) \
;         __builtin_amdgcn_global_load_lds((const unsigned*)((const char*)(gbase) + (voff)[_i]), (PG8_LAS unsigned*)(lds + (bufoff) + ldsw + _i * 8192), 16, 0, 0); } while (0)
; #define PG8_LDA(dst, b, h) do { _Pragma("unroll") for (int m = 0; m < 4; ++m) _Pragma("unroll") for (int k = 0; k < 2; ++k) dst[m][k] = *(const PG8_LAS bf16x8*)(lds + PG8_SA(b, h) + aoff + m * 2048 + k * 1024); } while (0)
; #define PG8_LDB(dst, b, h) do { _Pragma("unroll") for (int n = 0; n < 2; ++n) _Pragma("unroll") for (int k = 0; k < 2; ++k) dst[n][k] = *(const PG8_LAS bf16x8*)(lds + PG8_SB(b, h) + boff + n * 2048 + k * 1024); } while (0)
; #define PG8_WAIT_V(n) asm volatile("s_waitcnt vmcnt(" #n ")" ::: "memory")
; #define PG8_WAIT_L(n) asm volatile("s_waitcnt lgkmcnt(" #n ")" ::: "memory")
; #define PG8_BAR __builtin_amdgcn_s_barrier()
; #define PG8_SCHED __builtin_amdgcn_sched_barrier(0)
; template <class Epi, class Sched, bool ALIGN_EPI = false, bool SP2 = false>
; __device__ __forceinline__ void gemm_phase(PG8_LAS unsigned char* lds, const Gemm g, const Sched& S, const Epi& E) {
;     ...
;         const bool has_next = S.next(ui + 1, nxt);
;         const char* nA = has_next ? (const char*)g.A + (size_t)nxt.pm * tstep : cA; const char* nB = has_next ? (const char*)g.Bt + (size_t)nxt.pn * tstep : cB;
;         for (int t = 0; t < nt; t += 2) {
;             const bool last = (t == nt - 2);
;             const char* a1 = cA + (size_t)(t + 1) * kstep;
;             const char* a2 = last ? nA : cA + (size_t)(t + 2) * kstep; const char* b2 = last ? nB : cB + (size_t)(t + 2) * kstep;
;             const char* a3 = a2 + kstep; const char* b3 = b2 + kstep;
;             if (last && has_next) S.a_ready(nxt);
;             if constexpr (SP2) {
;             PG8_LDB(B0, 0, 0); PG8_LDB(B1, 0, 1); PG8_SCHED; PG8_LDA(At, 0, 0); PG8_STAGE(PG8_SA(1, 1), a1 + hstep, voffA);
;             PG8_WAIT_V(8); PG8_WAIT_L(0); PG8_BAR; PG8_MMA(0, 0, At, B0); PG8_MMA(0, 1, At, B1); PG8_BAR; PG8_SCHED;
;             PG8_LDA(At, 0, 1); PG8_STAGE(PG8_SB(0, 0), b2, voffB); PG8_STAGE(PG8_SB(0, 1), b2 + hstep, voffB); PG8_STAGE(PG8_SA(0, 0), a2, voffA);
;             PG8_WAIT_V(8); PG8_WAIT_L(0); PG8_BAR; PG8_MMA(1, 0, At, B0); PG8_MMA(1, 1, At, B1); PG8_BAR; PG8_SCHED;
.LBB0_1518:
	ds_read_b128 v[146:149], v168
	ds_read_b128 v[172:175], v168 offset:1024
	ds_read_b128 v[176:179], v168 offset:2048
	ds_read_b128 v[180:183], v168 offset:3072
	ds_read_b128 v[184:187], v169
	ds_read_b128 v[188:191], v169 offset:1024
	ds_read_b128 v[192:195], v169 offset:2048
	ds_read_b128 v[196:199], v169 offset:3072
	s_add_i32 s88, s38, 2
	s_add_u32 s70, s36, 0x80
	s_addc_u32 s39, s37, 0
	s_cmp_eq_u32 s53, s38
	s_cselect_b32 s38, s4, s70
	s_cselect_b32 s39, s5, s39
	s_cselect_b32 s71, s35, s87
	s_cselect_b32 s70, s34, s86
	v_lshl_add_u64 v[150:151], s[36:37], 0, v[140:141]
	s_add_i32 m0, s43, 0xc000
	ds_read_b128 v[200:203], v170
	ds_read_b128 v[204:207], v170 offset:1024
	ds_read_b128 v[208:211], v170 offset:2048
	ds_read_b128 v[212:215], v170 offset:3072
	ds_read_b128 v[216:219], v170 offset:4096
	ds_read_b128 v[220:223], v170 offset:5120
	ds_read_b128 v[224:227], v170 offset:6144
	ds_read_b128 v[228:231], v170 offset:7168
	global_load_lds_dwordx4 v[150:151], off
	s_add_i32 m0, s43, 0xe000
	v_lshl_add_u64 v[150:151], s[36:37], 0, v[138:139]
	global_load_lds_dwordx4 v[150:151], off
	s_waitcnt vmcnt(8) lgkmcnt(0)
	s_barrier
	s_setprio 1
	v_mfma_f32_16x16x32_bf16 v[122:125], v[146:149], v[200:203], v[122:125]
	v_mfma_f32_16x16x32_bf16 v[126:129], v[176:179], v[200:203], v[126:129]
	v_mfma_f32_16x16x32_bf16 v[110:113], v[146:149], v[208:211], v[110:113]
	v_mfma_f32_16x16x32_bf16 v[106:109], v[176:179], v[208:211], v[106:109]
	v_mfma_f32_16x16x32_bf16 v[94:97], v[146:149], v[216:219], v[94:97]
	v_mfma_f32_16x16x32_bf16 v[90:93], v[176:179], v[216:219], v[90:93]
	v_mfma_f32_16x16x32_bf16 v[78:81], v[146:149], v[224:227], v[78:81]
	v_mfma_f32_16x16x32_bf16 v[74:77], v[176:179], v[224:227], v[74:77]
	v_mfma_f32_16x16x32_bf16 v[122:125], v[172:175], v[204:207], v[122:125]
	v_mfma_f32_16x16x32_bf16 v[126:129], v[180:183], v[204:207], v[126:129]
	v_mfma_f32_16x16x32_bf16 v[110:113], v[172:175], v[212:215], v[110:113]
	v_mfma_f32_16x16x32_bf16 v[106:109], v[180:183], v[212:215], v[106:109]
	v_mfma_f32_16x16x32_bf16 v[94:97], v[172:175], v[220:223], v[94:97]
	v_mfma_f32_16x16x32_bf16 v[90:93], v[180:183], v[220:223], v[90:93]
	v_mfma_f32_16x16x32_bf16 v[78:81], v[172:175], v[228:231], v[78:81]
	v_mfma_f32_16x16x32_bf16 v[74:77], v[180:183], v[228:231], v[74:77]
	v_mfma_f32_16x16x32_bf16 v[118:121], v[184:187], v[200:203], v[118:121]
	v_mfma_f32_16x16x32_bf16 v[114:117], v[192:195], v[200:203], v[114:117]
	v_mfma_f32_16x16x32_bf16 v[102:105], v[184:187], v[208:211], v[102:105]
	v_mfma_f32_16x16x32_bf16 v[98:101], v[192:195], v[208:211], v[98:101]
	v_mfma_f32_16x16x32_bf16 v[86:89], v[184:187], v[216:219], v[86:89]
	v_mfma_f32_16x16x32_bf16 v[82:85], v[192:195], v[216:219], v[82:85]
	v_mfma_f32_16x16x32_bf16 v[70:73], v[184:187], v[224:227], v[70:73]
	v_mfma_f32_16x16x32_bf16 v[66:69], v[192:195], v[224:227], v[66:69]
	v_mfma_f32_16x16x32_bf16 v[118:121], v[188:191], v[204:207], v[118:121]
	v_mfma_f32_16x16x32_bf16 v[114:117], v[196:199], v[204:207], v[114:117]
	v_mfma_f32_16x16x32_bf16 v[102:105], v[188:191], v[212:215], v[102:105]
	v_mfma_f32_16x16x32_bf16 v[98:101], v[196:199], v[212:215], v[98:101]
	v_mfma_f32_16x16x32_bf16 v[86:89], v[188:191], v[220:223], v[86:89]
	v_mfma_f32_16x16x32_bf16 v[82:85], v[196:199], v[220:223], v[82:85]
	v_mfma_f32_16x16x32_bf16 v[70:73], v[188:191], v[228:231], v[70:73]
	v_mfma_f32_16x16x32_bf16 v[66:69], v[196:199], v[228:231], v[66:69]
	s_setprio 0
	s_barrier
	s_add_i32 s72, s56, s42
	v_lshl_add_u64 v[150:151], s[70:71], 0, v[132:133]
	s_mov_b32 m0, s72
	ds_read_b128 v[200:203], v170 offset:16384
	ds_read_b128 v[204:207], v170 offset:17408
	ds_read_b128 v[208:211], v170 offset:18432
	ds_read_b128 v[212:215], v170 offset:19456
	ds_read_b128 v[216:219], v170 offset:20480
	ds_read_b128 v[220:223], v170 offset:21504
	ds_read_b128 v[224:227], v170 offset:22528
	ds_read_b128 v[228:231], v170 offset:23552
	global_load_lds_dwordx4 v[150:151], off
	s_add_i32 m0, s72, 0x2000
	v_lshl_add_u64 v[232:233], s[70:71], 0, v[136:137]
	s_add_u32 s70, s70, s14
	s_addc_u32 s71, s71, s15
	s_add_i32 s72, s57, s42
	global_load_lds_dwordx4 v[232:233], off
	v_lshl_add_u64 v[234:235], s[70:71], 0, v[132:133]
	s_mov_b32 m0, s72
	v_lshl_add_u64 v[236:237], s[70:71], 0, v[136:137]
	global_load_lds_dwordx4 v[234:235], off
	s_add_i32 m0, s72, 0x2000
	v_lshl_add_u64 v[238:239], s[38:39], 0, v[130:131]
	global_load_lds_dwordx4 v[236:237], off
	s_mov_b32 m0, s43
	v_lshl_add_u64 v[240:241], s[38:39], 0, v[134:135]
	global_load_lds_dwordx4 v[238:239], off
	s_mov_b32 m0, s44
	s_nop 0
	global_load_lds_dwordx4 v[240:241], off
	s_waitcnt vmcnt(8) lgkmcnt(0)
	s_barrier
; #define PG8_STAGE(bufoff, gbase, voff) do { _Pragma("unroll") for (int _i = 0; _i < 2; ++_i) \
;         __builtin_amdgcn_global_load_lds((const unsigned*)((const char*)(gbase) + (voff)[_i]), (PG8_LAS unsigned*)(lds + (bufoff) + ldsw + _i * 8192), 16, 0, 0); } while (0)
; #define PG8_LDA(dst, b, h) do { _Pragma("unroll") for (int m = 0; m < 4; ++m) _Pragma("unroll") for (int k = 0; k < 2; ++k) dst[m][k] = *(const PG8_LAS bf16x8*)(lds + PG8_SA(b, h) + aoff + m * 2048 + k * 1024); } while (0)
; #define PG8_LDB(dst, b, h) do { _Pragma("unroll") for (int n = 0; n < 2; ++n) _Pragma("unroll") for (int k = 0; k < 2; ++k) dst[n][k] = *(const PG8_LAS bf16x8*)(lds + PG8_SB(b, h) + boff + n * 2048 + k * 1024); } while (0)
; #define PG8_MMA(ai, bj, At, Bt) do { __builtin_amdgcn_s_setprio(1); _Pragma("unroll") for (int m = 0; m < 4; ++m) _Pragma("unroll") for (int n = 0; n < 2; ++n) _Pragma("unroll") for (int k = 0; k < 2; ++k) \
;         acc[ai][bj][m][n] = __builtin_amdgcn_mfma_f32_16x16x32_bf16(Bt[n][k], At[m][k], acc[ai][bj][m][n], 0, 0, 0); __builtin_amdgcn_s_setprio(0); } while (0)
; #define PG8_WAIT_V(n) asm volatile("s_waitcnt vmcnt(" #n ")" ::: "memory")
; #define PG8_WAIT_L(n) asm volatile("s_waitcnt lgkmcnt(" #n ")" ::: "memory")
; #define PG8_BAR __builtin_amdgcn_s_barrier()
; #define PG8_SCHED __builtin_amdgcn_sched_barrier(0)
; template <class Epi, class Sched, bool ALIGN_EPI = false, bool SP2 = false>
; __device__ __forceinline__ void gemm_phase(PG8_LAS unsigned char* lds, const Gemm g, const Sched& S, const Epi& E) {
;     ...
;             PG8_WAIT_V(8); PG8_WAIT_L(0); PG8_BAR; PG8_MMA(1, 0, At, B0); PG8_MMA(1, 1, At, B1); PG8_BAR; PG8_SCHED;
;             PG8_LDB(B0, 1, 0); PG8_LDB(B1, 1, 1); PG8_SCHED; PG8_LDA(At, 1, 0); PG8_STAGE(PG8_SA(0, 1), a2 + hstep, voffA);
;             PG8_WAIT_V(8); PG8_WAIT_L(0); PG8_BAR; PG8_MMA(0, 0, At, B0); PG8_MMA(0, 1, At, B1); PG8_BAR; PG8_SCHED;
	s_setprio 1
	v_mfma_f32_16x16x32_bf16 v[62:65], v[146:149], v[200:203], v[62:65]
	v_mfma_f32_16x16x32_bf16 v[58:61], v[176:179], v[200:203], v[58:61]
	v_mfma_f32_16x16x32_bf16 v[46:49], v[146:149], v[208:211], v[46:49]
	v_mfma_f32_16x16x32_bf16 v[42:45], v[176:179], v[208:211], v[42:45]
	v_mfma_f32_16x16x32_bf16 v[30:33], v[146:149], v[216:219], v[30:33]
	v_mfma_f32_16x16x32_bf16 v[26:29], v[176:179], v[216:219], v[26:29]
	v_mfma_f32_16x16x32_bf16 v[14:17], v[146:149], v[224:227], v[14:17]
	v_mfma_f32_16x16x32_bf16 v[10:13], v[176:179], v[224:227], v[10:13]
	v_mfma_f32_16x16x32_bf16 v[62:65], v[172:175], v[204:207], v[62:65]
	v_mfma_f32_16x16x32_bf16 v[58:61], v[180:183], v[204:207], v[58:61]
	v_mfma_f32_16x16x32_bf16 v[46:49], v[172:175], v[212:215], v[46:49]
	v_mfma_f32_16x16x32_bf16 v[42:45], v[180:183], v[212:215], v[42:45]
	v_mfma_f32_16x16x32_bf16 v[30:33], v[172:175], v[220:223], v[30:33]
	v_mfma_f32_16x16x32_bf16 v[26:29], v[180:183], v[220:223], v[26:29]
	v_mfma_f32_16x16x32_bf16 v[14:17], v[172:175], v[228:231], v[14:17]
	v_mfma_f32_16x16x32_bf16 v[10:13], v[180:183], v[228:231], v[10:13]
	v_mfma_f32_16x16x32_bf16 v[54:57], v[184:187], v[200:203], v[54:57]
	v_mfma_f32_16x16x32_bf16 v[50:53], v[192:195], v[200:203], v[50:53]
	v_mfma_f32_16x16x32_bf16 v[38:41], v[184:187], v[208:211], v[38:41]
	v_mfma_f32_16x16x32_bf16 v[34:37], v[192:195], v[208:211], v[34:37]
	v_mfma_f32_16x16x32_bf16 v[22:25], v[184:187], v[216:219], v[22:25]
	v_mfma_f32_16x16x32_bf16 v[18:21], v[192:195], v[216:219], v[18:21]
	v_mfma_f32_16x16x32_bf16 v[6:9], v[184:187], v[224:227], v[6:9]
	v_mfma_f32_16x16x32_bf16 v[2:5], v[192:195], v[224:227], v[2:5]
	v_mfma_f32_16x16x32_bf16 v[54:57], v[188:191], v[204:207], v[54:57]
	v_mfma_f32_16x16x32_bf16 v[50:53], v[196:199], v[204:207], v[50:53]
	v_mfma_f32_16x16x32_bf16 v[38:41], v[188:191], v[212:215], v[38:41]
	v_mfma_f32_16x16x32_bf16 v[34:37], v[196:199], v[212:215], v[34:37]
	v_mfma_f32_16x16x32_bf16 v[22:25], v[188:191], v[220:223], v[22:25]
	v_mfma_f32_16x16x32_bf16 v[18:21], v[196:199], v[220:223], v[18:21]
	v_mfma_f32_16x16x32_bf16 v[6:9], v[188:191], v[228:231], v[6:9]
	v_mfma_f32_16x16x32_bf16 v[2:5], v[196:199], v[228:231], v[2:5]
	s_setprio 0
	s_barrier
	s_add_i32 s70, 0, 0x18000
	v_add_u32_e32 v171, s70, v166
	s_add_i32 s71, 0, 0x1c000
	ds_read_b128 v[146:149], v171
	ds_read_b128 v[172:175], v171 offset:1024
	ds_read_b128 v[176:179], v171 offset:2048
	ds_read_b128 v[180:183], v171 offset:3072
	v_add_u32_e32 v171, s71, v166
	ds_read_b128 v[184:187], v171
	ds_read_b128 v[188:191], v171 offset:1024
	ds_read_b128 v[192:195], v171 offset:2048
	ds_read_b128 v[196:199], v171 offset:3072
	s_add_u32 s38, s38, s14
	s_addc_u32 s39, s39, s15
	s_mov_b32 m0, s45
	v_lshl_add_u64 v[242:243], s[38:39], 0, v[130:131]
	ds_read_b128 v[200:203], v170 offset:32768
	ds_read_b128 v[204:207], v170 offset:33792
	ds_read_b128 v[208:211], v170 offset:34816
	ds_read_b128 v[212:215], v170 offset:35840
	ds_read_b128 v[216:219], v170 offset:36864
	ds_read_b128 v[220:223], v170 offset:37888
	ds_read_b128 v[224:227], v170 offset:38912
	ds_read_b128 v[228:231], v170 offset:39936
	global_load_lds_dwordx4 v[242:243], off
	s_mov_b32 m0, s46
	v_lshl_add_u64 v[242:243], s[38:39], 0, v[134:135]
	global_load_lds_dwordx4 v[242:243], off
	s_waitcnt vmcnt(8) lgkmcnt(0)
	s_barrier
	s_setprio 1
	v_mfma_f32_16x16x32_bf16 v[122:125], v[146:149], v[200:203], v[122:125]
	v_mfma_f32_16x16x32_bf16 v[126:129], v[176:179], v[200:203], v[126:129]
	v_mfma_f32_16x16x32_bf16 v[110:113], v[146:149], v[208:211], v[110:113]
	v_mfma_f32_16x16x32_bf16 v[106:109], v[176:179], v[208:211], v[106:109]
	v_mfma_f32_16x16x32_bf16 v[94:97], v[146:149], v[216:219], v[94:97]
	v_mfma_f32_16x16x32_bf16 v[90:93], v[176:179], v[216:219], v[90:93]
	v_mfma_f32_16x16x32_bf16 v[78:81], v[146:149], v[224:227], v[78:81]
	v_mfma_f32_16x16x32_bf16 v[74:77], v[176:179], v[224:227], v[74:77]
	v_mfma_f32_16x16x32_bf16 v[122:125], v[172:175], v[204:207], v[122:125]
	v_mfma_f32_16x16x32_bf16 v[126:129], v[180:183], v[204:207], v[126:129]
	v_mfma_f32_16x16x32_bf16 v[110:113], v[172:175], v[212:215], v[110:113]
	v_mfma_f32_16x16x32_bf16 v[106:109], v[180:183], v[212:215], v[106:109]
	v_mfma_f32_16x16x32_bf16 v[94:97], v[172:175], v[220:223], v[94:97]
	v_mfma_f32_16x16x32_bf16 v[90:93], v[180:183], v[220:223], v[90:93]
	v_mfma_f32_16x16x32_bf16 v[78:81], v[172:175], v[228:231], v[78:81]
	v_mfma_f32_16x16x32_bf16 v[74:77], v[180:183], v[228:231], v[74:77]
	v_mfma_f32_16x16x32_bf16 v[118:121], v[184:187], v[200:203], v[118:121]
	v_mfma_f32_16x16x32_bf16 v[114:117], v[192:195], v[200:203], v[114:117]
	v_mfma_f32_16x16x32_bf16 v[102:105], v[184:187], v[208:211], v[102:105]
	v_mfma_f32_16x16x32_bf16 v[98:101], v[192:195], v[208:211], v[98:101]
	v_mfma_f32_16x16x32_bf16 v[86:89], v[184:187], v[216:219], v[86:89]
	v_mfma_f32_16x16x32_bf16 v[82:85], v[192:195], v[216:219], v[82:85]
	v_mfma_f32_16x16x32_bf16 v[70:73], v[184:187], v[224:227], v[70:73]
	v_mfma_f32_16x16x32_bf16 v[66:69], v[192:195], v[224:227], v[66:69]
	v_mfma_f32_16x16x32_bf16 v[118:121], v[188:191], v[204:207], v[118:121]
	v_mfma_f32_16x16x32_bf16 v[114:117], v[196:199], v[204:207], v[114:117]
	v_mfma_f32_16x16x32_bf16 v[102:105], v[188:191], v[212:215], v[102:105]
	v_mfma_f32_16x16x32_bf16 v[98:101], v[196:199], v[212:215], v[98:101]
	v_mfma_f32_16x16x32_bf16 v[86:89], v[188:191], v[220:223], v[86:89]
	v_mfma_f32_16x16x32_bf16 v[82:85], v[196:199], v[220:223], v[82:85]
	v_mfma_f32_16x16x32_bf16 v[70:73], v[188:191], v[228:231], v[70:73]
	v_mfma_f32_16x16x32_bf16 v[66:69], v[196:199], v[228:231], v[66:69]
	s_setprio 0
	s_barrier
; #define PG8_STAGE(bufoff, gbase, voff) do { _Pragma("unroll") for (int _i = 0; _i < 2; ++_i) \
;         __builtin_amdgcn_global_load_lds((const unsigned*)((const char*)(gbase) + (voff)[_i]), (PG8_LAS unsigned*)(lds + (bufoff) + ldsw + _i * 8192), 16, 0, 0); } while (0)
; #define PG8_LDA(dst, b, h) do { _Pragma("unroll") for (int m = 0; m < 4; ++m) _Pragma("unroll") for (int k = 0; k < 2; ++k) dst[m][k] = *(const PG8_LAS bf16x8*)(lds + PG8_SA(b, h) + aoff + m * 2048 + k * 1024); } while (0)
; #define PG8_MMA(ai, bj, At, Bt) do { __builtin_amdgcn_s_setprio(1); _Pragma("unroll") for (int m = 0; m < 4; ++m) _Pragma("unroll") for (int n = 0; n < 2; ++n) _Pragma("unroll") for (int k = 0; k < 2; ++k) \
;         acc[ai][bj][m][n] = __builtin_amdgcn_mfma_f32_16x16x32_bf16(Bt[n][k], At[m][k], acc[ai][bj][m][n], 0, 0, 0); __builtin_amdgcn_s_setprio(0); } while (0)
; #define PG8_WAIT_V(n) asm volatile("s_waitcnt vmcnt(" #n ")" ::: "memory")
; #define PG8_WAIT_L(n) asm volatile("s_waitcnt lgkmcnt(" #n ")" ::: "memory")
; #define PG8_BAR __builtin_amdgcn_s_barrier()
; #define PG8_SCHED __builtin_amdgcn_sched_barrier(0)
; template <class Epi, class Sched, bool ALIGN_EPI = false, bool SP2 = false>
; __device__ __forceinline__ void gemm_phase(PG8_LAS unsigned char* lds, const Gemm g, const Sched& S, const Epi& E) {
;     ...
;         for (int t = 0; t < nt; t += 2) {
;     ...
;             PG8_LDA(At, 1, 1); PG8_STAGE(PG8_SB(1, 0), b3, voffB); PG8_STAGE(PG8_SB(1, 1), b3 + hstep, voffB); PG8_STAGE(PG8_SA(1, 0), a3, voffA);
;             PG8_WAIT_V(8); PG8_WAIT_L(0); PG8_BAR; PG8_MMA(1, 0, At, B0); PG8_MMA(1, 1, At, B1); PG8_BAR; PG8_SCHED;
	s_add_i32 s38, s70, s42
	v_lshl_add_u64 v[150:151], v[150:151], 0, s[24:25]
	s_mov_b32 m0, s38
	ds_read_b128 v[200:203], v170 offset:49152
	ds_read_b128 v[204:207], v170 offset:50176
	ds_read_b128 v[208:211], v170 offset:51200
	ds_read_b128 v[212:215], v170 offset:52224
	ds_read_b128 v[216:219], v170 offset:53248
	ds_read_b128 v[220:223], v170 offset:54272
	ds_read_b128 v[224:227], v170 offset:55296
	ds_read_b128 v[228:231], v170 offset:56320
	global_load_lds_dwordx4 v[150:151], off
	v_lshl_add_u64 v[150:151], v[232:233], 0, s[24:25]
	s_add_i32 m0, s38, 0x2000
	s_add_i32 s38, s71, s42
	global_load_lds_dwordx4 v[150:151], off
	s_mov_b32 m0, s38
	v_lshl_add_u64 v[150:151], v[234:235], 0, s[24:25]
	global_load_lds_dwordx4 v[150:151], off
	s_add_i32 m0, s38, 0x2000
	v_lshl_add_u64 v[150:151], v[236:237], 0, s[24:25]
	global_load_lds_dwordx4 v[150:151], off
	s_mov_b32 m0, s48
	v_lshl_add_u64 v[150:151], v[238:239], 0, s[24:25]
	global_load_lds_dwordx4 v[150:151], off
	s_mov_b32 m0, s49
	v_lshl_add_u64 v[150:151], v[240:241], 0, s[24:25]
	global_load_lds_dwordx4 v[150:151], off
	s_waitcnt vmcnt(8) lgkmcnt(0)
	s_barrier
	s_setprio 1
	v_mfma_f32_16x16x32_bf16 v[62:65], v[146:149], v[200:203], v[62:65]
	v_mfma_f32_16x16x32_bf16 v[58:61], v[176:179], v[200:203], v[58:61]
	v_mfma_f32_16x16x32_bf16 v[46:49], v[146:149], v[208:211], v[46:49]
	v_mfma_f32_16x16x32_bf16 v[42:45], v[176:179], v[208:211], v[42:45]
	v_mfma_f32_16x16x32_bf16 v[30:33], v[146:149], v[216:219], v[30:33]
	v_mfma_f32_16x16x32_bf16 v[26:29], v[176:179], v[216:219], v[26:29]
	v_mfma_f32_16x16x32_bf16 v[14:17], v[146:149], v[224:227], v[14:17]
	v_mfma_f32_16x16x32_bf16 v[10:13], v[176:179], v[224:227], v[10:13]
	v_mfma_f32_16x16x32_bf16 v[62:65], v[172:175], v[204:207], v[62:65]
	v_mfma_f32_16x16x32_bf16 v[58:61], v[180:183], v[204:207], v[58:61]
	v_mfma_f32_16x16x32_bf16 v[46:49], v[172:175], v[212:215], v[46:49]
	v_mfma_f32_16x16x32_bf16 v[42:45], v[180:183], v[212:215], v[42:45]
	v_mfma_f32_16x16x32_bf16 v[30:33], v[172:175], v[220:223], v[30:33]
	v_mfma_f32_16x16x32_bf16 v[26:29], v[180:183], v[220:223], v[26:29]
	v_mfma_f32_16x16x32_bf16 v[14:17], v[172:175], v[228:231], v[14:17]
	v_mfma_f32_16x16x32_bf16 v[10:13], v[180:183], v[228:231], v[10:13]
	v_mfma_f32_16x16x32_bf16 v[54:57], v[184:187], v[200:203], v[54:57]
	v_mfma_f32_16x16x32_bf16 v[50:53], v[192:195], v[200:203], v[50:53]
	v_mfma_f32_16x16x32_bf16 v[38:41], v[184:187], v[208:211], v[38:41]
	v_mfma_f32_16x16x32_bf16 v[34:37], v[192:195], v[208:211], v[34:37]
	v_mfma_f32_16x16x32_bf16 v[22:25], v[184:187], v[216:219], v[22:25]
	v_mfma_f32_16x16x32_bf16 v[18:21], v[192:195], v[216:219], v[18:21]
	v_mfma_f32_16x16x32_bf16 v[6:9], v[184:187], v[224:227], v[6:9]
	v_mfma_f32_16x16x32_bf16 v[2:5], v[192:195], v[224:227], v[2:5]
	v_mfma_f32_16x16x32_bf16 v[54:57], v[188:191], v[204:207], v[54:57]
	v_mfma_f32_16x16x32_bf16 v[50:53], v[196:199], v[204:207], v[50:53]
	v_mfma_f32_16x16x32_bf16 v[38:41], v[188:191], v[212:215], v[38:41]
	v_mfma_f32_16x16x32_bf16 v[34:37], v[196:199], v[212:215], v[34:37]
	v_mfma_f32_16x16x32_bf16 v[22:25], v[188:191], v[220:223], v[22:25]
	v_mfma_f32_16x16x32_bf16 v[18:21], v[196:199], v[220:223], v[18:21]
	v_mfma_f32_16x16x32_bf16 v[6:9], v[188:191], v[228:231], v[6:9]
	v_mfma_f32_16x16x32_bf16 v[2:5], v[196:199], v[228:231], v[2:5]
	s_setprio 0
	s_barrier
	s_add_u32 s86, s86, 0x100
	s_addc_u32 s87, s87, 0
	s_add_u32 s36, s36, 0x100
	s_addc_u32 s37, s37, 0
	s_cmp_ge_i32 s88, s52
	s_mov_b32 s38, s88
	s_cbranch_scc0 .LBB0_1518
	v_readlane_b32 s74, v244, 3
	v_readlane_b32 s88, v244, 5
	v_readlane_b32 s75, v244, 4
	v_readlane_b32 s90, v244, 7
	v_readlane_b32 s91, v244, 8
	v_readlane_b32 s92, v244, 9
	v_readlane_b32 s93, v244, 10
	v_readlane_b32 s94, v244, 11
	v_readlane_b32 s95, v244, 12
	v_readlane_b32 s89, v244, 6

; #define PG8_STAGE(bufoff, gbase, voff) do { _Pragma("unroll") for (int _i = 0; _i < 2; ++_i) \
;         __builtin_amdgcn_global_load_lds((const unsigned*)((const char*)(gbase) + (voff)[_i]), (PG8_LAS unsigned*)(lds + (bufoff) + ldsw + _i * 8192), 16, 0, 0); } while (0)
; #define PG8_LDA(dst, b, h) do { _Pragma("unroll") for (int m = 0; m < 4; ++m) _Pragma("unroll") for (int k = 0; k < 2; ++k) dst[m][k] = *(const PG8_LAS bf16x8*)(lds + PG8_SA(b, h) + aoff + m * 2048 + k * 1024); } while (0)
; #define PG8_LDB(dst, b, h) do { _Pragma("unroll") for (int n = 0; n < 2; ++n) _Pragma("unroll") for (int k = 0; k < 2; ++k) dst[n][k] = *(const PG8_LAS bf16x8*)(lds + PG8_SB(b, h) + boff + n * 2048 + k * 1024); } while (0)
; #define PG8_WAIT_V(n) asm volatile("s_waitcnt vmcnt(" #n ")" ::: "memory")
; #define PG8_WAIT_L(n) asm volatile("s_waitcnt lgkmcnt(" #n ")" ::: "memory")
; #define PG8_BAR __builtin_amdgcn_s_barrier()
; #define PG8_SCHED __builtin_amdgcn_sched_barrier(0)
; template <class Epi, class Sched, bool ALIGN_EPI = false, bool SP2 = false>
; __device__ __forceinline__ void gemm_phase(PG8_LAS unsigned char* lds, const Gemm g, const Sched& S, const Epi& E) {
;     ...
;         const bool has_next = S.next(ui + 1, nxt);
;         const char* nA = has_next ? (const char*)g.A + (size_t)nxt.pm * tstep : cA; const char* nB = has_next ? (const char*)g.Bt + (size_t)nxt.pn * tstep : cB;
;         for (int t = 0; t < nt; t += 2) {
;             const bool last = (t == nt - 2);
;             const char* a1 = cA + (size_t)(t + 1) * kstep;
;             const char* a2 = last ? nA : cA + (size_t)(t + 2) * kstep; const char* b2 = last ? nB : cB + (size_t)(t + 2) * kstep;
;             const char* a3 = a2 + kstep; const char* b3 = b2 + kstep;
;             if (last && has_next) S.a_ready(nxt);
;             if constexpr (SP2) {
;             PG8_LDB(B0, 0, 0); PG8_LDB(B1, 0, 1); PG8_SCHED; PG8_LDA(At, 0, 0); PG8_STAGE(PG8_SA(1, 1), a1 + hstep, voffA);
;             PG8_WAIT_V(8); PG8_WAIT_L(0); PG8_BAR; PG8_MMA(0, 0, At, B0); PG8_MMA(0, 1, At, B1); PG8_BAR; PG8_SCHED;
;             PG8_LDA(At, 0, 1); PG8_STAGE(PG8_SB(0, 0), b2, voffB); PG8_STAGE(PG8_SB(0, 1), b2 + hstep, voffB); PG8_STAGE(PG8_SA(0, 0), a2, voffA);
;             PG8_WAIT_V(8); PG8_WAIT_L(0); PG8_BAR; PG8_MMA(1, 0, At, B0); PG8_MMA(1, 1, At, B1); PG8_BAR; PG8_SCHED;
.LBB0_1548:
	ds_read_b128 v[146:149], v1
	ds_read_b128 v[162:165], v1 offset:1024
	ds_read_b128 v[166:169], v1 offset:2048
	ds_read_b128 v[170:173], v1 offset:3072
	ds_read_b128 v[174:177], v152
	ds_read_b128 v[178:181], v152 offset:1024
	ds_read_b128 v[182:185], v152 offset:2048
	ds_read_b128 v[186:189], v152 offset:3072
	s_add_i32 s68, s28, 2
	s_add_u32 s69, s26, 0x80
	s_addc_u32 s29, s27, 0
	s_cmp_eq_u32 s45, s28
	s_cselect_b32 s28, s4, s69
	s_cselect_b32 s29, s5, s29
	s_cselect_b32 s71, s9, s57
	s_cselect_b32 s70, s8, s56
	v_lshl_add_u64 v[150:151], s[26:27], 0, v[140:141]
	s_add_i32 m0, s37, 0xc000
	ds_read_b128 v[190:193], v153
	ds_read_b128 v[194:197], v153 offset:1024
	ds_read_b128 v[198:201], v153 offset:2048
	ds_read_b128 v[202:205], v153 offset:3072
	ds_read_b128 v[206:209], v153 offset:4096
	ds_read_b128 v[210:213], v153 offset:5120
	ds_read_b128 v[214:217], v153 offset:6144
	ds_read_b128 v[218:221], v153 offset:7168
	global_load_lds_dwordx4 v[150:151], off
	s_add_i32 m0, s37, 0xe000
	v_lshl_add_u64 v[150:151], s[26:27], 0, v[138:139]
	global_load_lds_dwordx4 v[150:151], off
	s_waitcnt vmcnt(8) lgkmcnt(0)
	s_barrier
	s_setprio 1
	v_mfma_f32_16x16x32_bf16 v[122:125], v[146:149], v[190:193], v[122:125]
	v_mfma_f32_16x16x32_bf16 v[126:129], v[166:169], v[190:193], v[126:129]
	v_mfma_f32_16x16x32_bf16 v[110:113], v[146:149], v[198:201], v[110:113]
	v_mfma_f32_16x16x32_bf16 v[106:109], v[166:169], v[198:201], v[106:109]
	v_mfma_f32_16x16x32_bf16 v[94:97], v[146:149], v[206:209], v[94:97]
	v_mfma_f32_16x16x32_bf16 v[90:93], v[166:169], v[206:209], v[90:93]
	v_mfma_f32_16x16x32_bf16 v[78:81], v[146:149], v[214:217], v[78:81]
	v_mfma_f32_16x16x32_bf16 v[74:77], v[166:169], v[214:217], v[74:77]
	v_mfma_f32_16x16x32_bf16 v[122:125], v[162:165], v[194:197], v[122:125]
	v_mfma_f32_16x16x32_bf16 v[126:129], v[170:173], v[194:197], v[126:129]
	v_mfma_f32_16x16x32_bf16 v[110:113], v[162:165], v[202:205], v[110:113]
	v_mfma_f32_16x16x32_bf16 v[106:109], v[170:173], v[202:205], v[106:109]
	v_mfma_f32_16x16x32_bf16 v[94:97], v[162:165], v[210:213], v[94:97]
	v_mfma_f32_16x16x32_bf16 v[90:93], v[170:173], v[210:213], v[90:93]
	v_mfma_f32_16x16x32_bf16 v[78:81], v[162:165], v[218:221], v[78:81]
	v_mfma_f32_16x16x32_bf16 v[74:77], v[170:173], v[218:221], v[74:77]
	v_mfma_f32_16x16x32_bf16 v[118:121], v[174:177], v[190:193], v[118:121]
	v_mfma_f32_16x16x32_bf16 v[114:117], v[182:185], v[190:193], v[114:117]
	v_mfma_f32_16x16x32_bf16 v[102:105], v[174:177], v[198:201], v[102:105]
	v_mfma_f32_16x16x32_bf16 v[98:101], v[182:185], v[198:201], v[98:101]
	v_mfma_f32_16x16x32_bf16 v[86:89], v[174:177], v[206:209], v[86:89]
	v_mfma_f32_16x16x32_bf16 v[82:85], v[182:185], v[206:209], v[82:85]
	v_mfma_f32_16x16x32_bf16 v[70:73], v[174:177], v[214:217], v[70:73]
	v_mfma_f32_16x16x32_bf16 v[66:69], v[182:185], v[214:217], v[66:69]
	v_mfma_f32_16x16x32_bf16 v[118:121], v[178:181], v[194:197], v[118:121]
	v_mfma_f32_16x16x32_bf16 v[114:117], v[186:189], v[194:197], v[114:117]
	v_mfma_f32_16x16x32_bf16 v[102:105], v[178:181], v[202:205], v[102:105]
	v_mfma_f32_16x16x32_bf16 v[98:101], v[186:189], v[202:205], v[98:101]
	v_mfma_f32_16x16x32_bf16 v[86:89], v[178:181], v[210:213], v[86:89]
	v_mfma_f32_16x16x32_bf16 v[82:85], v[186:189], v[210:213], v[82:85]
	v_mfma_f32_16x16x32_bf16 v[70:73], v[178:181], v[218:221], v[70:73]
	v_mfma_f32_16x16x32_bf16 v[66:69], v[186:189], v[218:221], v[66:69]
	s_setprio 0
	s_barrier
	s_add_i32 s69, s48, s36
	v_lshl_add_u64 v[150:151], s[70:71], 0, v[132:133]
	s_mov_b32 m0, s69
	ds_read_b128 v[190:193], v153 offset:16384
	ds_read_b128 v[194:197], v153 offset:17408
	ds_read_b128 v[198:201], v153 offset:18432
	ds_read_b128 v[202:205], v153 offset:19456
	ds_read_b128 v[206:209], v153 offset:20480
	ds_read_b128 v[210:213], v153 offset:21504
	ds_read_b128 v[214:217], v153 offset:22528
	ds_read_b128 v[218:221], v153 offset:23552
	global_load_lds_dwordx4 v[150:151], off
	s_add_i32 m0, s69, 0x2000
	v_lshl_add_u64 v[158:159], s[70:71], 0, v[136:137]
	s_add_u32 s70, s70, s10
	s_addc_u32 s71, s71, s11
	s_add_i32 s69, s49, s36
	global_load_lds_dwordx4 v[158:159], off
	v_lshl_add_u64 v[222:223], s[70:71], 0, v[132:133]
	s_mov_b32 m0, s69
	v_lshl_add_u64 v[224:225], s[70:71], 0, v[136:137]
	global_load_lds_dwordx4 v[222:223], off
	s_add_i32 m0, s69, 0x2000
	v_lshl_add_u64 v[226:227], s[28:29], 0, v[130:131]
	global_load_lds_dwordx4 v[224:225], off
	s_mov_b32 m0, s37
	v_lshl_add_u64 v[228:229], s[28:29], 0, v[134:135]
	global_load_lds_dwordx4 v[226:227], off
	s_mov_b32 m0, s38
	s_nop 0
	global_load_lds_dwordx4 v[228:229], off
	s_waitcnt vmcnt(8) lgkmcnt(0)
	s_barrier
; #define PG8_STAGE(bufoff, gbase, voff) do { _Pragma("unroll") for (int _i = 0; _i < 2; ++_i) \
;         __builtin_amdgcn_global_load_lds((const unsigned*)((const char*)(gbase) + (voff)[_i]), (PG8_LAS unsigned*)(lds + (bufoff) + ldsw + _i * 8192), 16, 0, 0); } while (0)
; #define PG8_LDA(dst, b, h) do { _Pragma("unroll") for (int m = 0; m < 4; ++m) _Pragma("unroll") for (int k = 0; k < 2; ++k) dst[m][k] = *(const PG8_LAS bf16x8*)(lds + PG8_SA(b, h) + aoff + m * 2048 + k * 1024); } while (0)
; #define PG8_LDB(dst, b, h) do { _Pragma("unroll") for (int n = 0; n < 2; ++n) _Pragma("unroll") for (int k = 0; k < 2; ++k) dst[n][k] = *(const PG8_LAS bf16x8*)(lds + PG8_SB(b, h) + boff + n * 2048 + k * 1024); } while (0)
; #define PG8_MMA(ai, bj, At, Bt) do { __builtin_amdgcn_s_setprio(1); _Pragma("unroll") for (int m = 0; m < 4; ++m) _Pragma("unroll") for (int n = 0; n < 2; ++n) _Pragma("unroll") for (int k = 0; k < 2; ++k) \
;         acc[ai][bj][m][n] = __builtin_amdgcn_mfma_f32_16x16x32_bf16(Bt[n][k], At[m][k], acc[ai][bj][m][n], 0, 0, 0); __builtin_amdgcn_s_setprio(0); } while (0)
; #define PG8_WAIT_V(n) asm volatile("s_waitcnt vmcnt(" #n ")" ::: "memory")
; #define PG8_WAIT_L(n) asm volatile("s_waitcnt lgkmcnt(" #n ")" ::: "memory")
; #define PG8_BAR __builtin_amdgcn_s_barrier()
; #define PG8_SCHED __builtin_amdgcn_sched_barrier(0)
; template <class Epi, class Sched, bool ALIGN_EPI = false, bool SP2 = false>
; __device__ __forceinline__ void gemm_phase(PG8_LAS unsigned char* lds, const Gemm g, const Sched& S, const Epi& E) {
;     ...
;             PG8_WAIT_V(8); PG8_WAIT_L(0); PG8_BAR; PG8_MMA(1, 0, At, B0); PG8_MMA(1, 1, At, B1); PG8_BAR; PG8_SCHED;
;             PG8_LDB(B0, 1, 0); PG8_LDB(B1, 1, 1); PG8_SCHED; PG8_LDA(At, 1, 0); PG8_STAGE(PG8_SA(0, 1), a2 + hstep, voffA);
;             PG8_WAIT_V(8); PG8_WAIT_L(0); PG8_BAR; PG8_MMA(0, 0, At, B0); PG8_MMA(0, 1, At, B1); PG8_BAR; PG8_SCHED;
	s_setprio 1
	v_mfma_f32_16x16x32_bf16 v[62:65], v[146:149], v[190:193], v[62:65]
	v_mfma_f32_16x16x32_bf16 v[58:61], v[166:169], v[190:193], v[58:61]
	v_mfma_f32_16x16x32_bf16 v[46:49], v[146:149], v[198:201], v[46:49]
	v_mfma_f32_16x16x32_bf16 v[42:45], v[166:169], v[198:201], v[42:45]
	v_mfma_f32_16x16x32_bf16 v[30:33], v[146:149], v[206:209], v[30:33]
	v_mfma_f32_16x16x32_bf16 v[26:29], v[166:169], v[206:209], v[26:29]
	v_mfma_f32_16x16x32_bf16 v[14:17], v[146:149], v[214:217], v[14:17]
	v_mfma_f32_16x16x32_bf16 v[10:13], v[166:169], v[214:217], v[10:13]
	v_mfma_f32_16x16x32_bf16 v[62:65], v[162:165], v[194:197], v[62:65]
	v_mfma_f32_16x16x32_bf16 v[58:61], v[170:173], v[194:197], v[58:61]
	v_mfma_f32_16x16x32_bf16 v[46:49], v[162:165], v[202:205], v[46:49]
	v_mfma_f32_16x16x32_bf16 v[42:45], v[170:173], v[202:205], v[42:45]
	v_mfma_f32_16x16x32_bf16 v[30:33], v[162:165], v[210:213], v[30:33]
	v_mfma_f32_16x16x32_bf16 v[26:29], v[170:173], v[210:213], v[26:29]
	v_mfma_f32_16x16x32_bf16 v[14:17], v[162:165], v[218:221], v[14:17]
	v_mfma_f32_16x16x32_bf16 v[10:13], v[170:173], v[218:221], v[10:13]
	v_mfma_f32_16x16x32_bf16 v[54:57], v[174:177], v[190:193], v[54:57]
	v_mfma_f32_16x16x32_bf16 v[50:53], v[182:185], v[190:193], v[50:53]
	v_mfma_f32_16x16x32_bf16 v[38:41], v[174:177], v[198:201], v[38:41]
	v_mfma_f32_16x16x32_bf16 v[34:37], v[182:185], v[198:201], v[34:37]
	v_mfma_f32_16x16x32_bf16 v[22:25], v[174:177], v[206:209], v[22:25]
	v_mfma_f32_16x16x32_bf16 v[18:21], v[182:185], v[206:209], v[18:21]
	v_mfma_f32_16x16x32_bf16 v[6:9], v[174:177], v[214:217], v[6:9]
	v_mfma_f32_16x16x32_bf16 v[2:5], v[182:185], v[214:217], v[2:5]
	v_mfma_f32_16x16x32_bf16 v[54:57], v[178:181], v[194:197], v[54:57]
	v_mfma_f32_16x16x32_bf16 v[50:53], v[186:189], v[194:197], v[50:53]
	v_mfma_f32_16x16x32_bf16 v[38:41], v[178:181], v[202:205], v[38:41]
	v_mfma_f32_16x16x32_bf16 v[34:37], v[186:189], v[202:205], v[34:37]
	v_mfma_f32_16x16x32_bf16 v[22:25], v[178:181], v[210:213], v[22:25]
	v_mfma_f32_16x16x32_bf16 v[18:21], v[186:189], v[210:213], v[18:21]
	v_mfma_f32_16x16x32_bf16 v[6:9], v[178:181], v[218:221], v[6:9]
	v_mfma_f32_16x16x32_bf16 v[2:5], v[186:189], v[218:221], v[2:5]
	s_setprio 0
	s_barrier
	s_add_i32 s69, 0, 0x18000
	v_add_u32_e32 v154, s69, v156
	s_add_i32 s70, 0, 0x1c000
	ds_read_b128 v[146:149], v154
	ds_read_b128 v[162:165], v154 offset:1024
	ds_read_b128 v[166:169], v154 offset:2048
	ds_read_b128 v[170:173], v154 offset:3072
	v_add_u32_e32 v154, s70, v156
	ds_read_b128 v[174:177], v154
	ds_read_b128 v[178:181], v154 offset:1024
	ds_read_b128 v[182:185], v154 offset:2048
	ds_read_b128 v[186:189], v154 offset:3072
	s_add_u32 s28, s28, s10
	s_addc_u32 s29, s29, s11
	s_mov_b32 m0, s39
	v_lshl_add_u64 v[230:231], s[28:29], 0, v[130:131]
	ds_read_b128 v[190:193], v153 offset:32768
	ds_read_b128 v[194:197], v153 offset:33792
	ds_read_b128 v[198:201], v153 offset:34816
	ds_read_b128 v[202:205], v153 offset:35840
	ds_read_b128 v[206:209], v153 offset:36864
	ds_read_b128 v[210:213], v153 offset:37888
	ds_read_b128 v[214:217], v153 offset:38912
	ds_read_b128 v[218:221], v153 offset:39936
	global_load_lds_dwordx4 v[230:231], off
	s_mov_b32 m0, s40
	v_lshl_add_u64 v[230:231], s[28:29], 0, v[134:135]
	global_load_lds_dwordx4 v[230:231], off
	s_waitcnt vmcnt(8) lgkmcnt(0)
	s_barrier
	s_setprio 1
	v_mfma_f32_16x16x32_bf16 v[122:125], v[146:149], v[190:193], v[122:125]
	v_mfma_f32_16x16x32_bf16 v[126:129], v[166:169], v[190:193], v[126:129]
	v_mfma_f32_16x16x32_bf16 v[110:113], v[146:149], v[198:201], v[110:113]
	v_mfma_f32_16x16x32_bf16 v[106:109], v[166:169], v[198:201], v[106:109]
	v_mfma_f32_16x16x32_bf16 v[94:97], v[146:149], v[206:209], v[94:97]
	v_mfma_f32_16x16x32_bf16 v[90:93], v[166:169], v[206:209], v[90:93]
	v_mfma_f32_16x16x32_bf16 v[78:81], v[146:149], v[214:217], v[78:81]
	v_mfma_f32_16x16x32_bf16 v[74:77], v[166:169], v[214:217], v[74:77]
	v_mfma_f32_16x16x32_bf16 v[122:125], v[162:165], v[194:197], v[122:125]
	v_mfma_f32_16x16x32_bf16 v[126:129], v[170:173], v[194:197], v[126:129]
	v_mfma_f32_16x16x32_bf16 v[110:113], v[162:165], v[202:205], v[110:113]
	v_mfma_f32_16x16x32_bf16 v[106:109], v[170:173], v[202:205], v[106:109]
	v_mfma_f32_16x16x32_bf16 v[94:97], v[162:165], v[210:213], v[94:97]
	v_mfma_f32_16x16x32_bf16 v[90:93], v[170:173], v[210:213], v[90:93]
	v_mfma_f32_16x16x32_bf16 v[78:81], v[162:165], v[218:221], v[78:81]
	v_mfma_f32_16x16x32_bf16 v[74:77], v[170:173], v[218:221], v[74:77]
	v_mfma_f32_16x16x32_bf16 v[118:121], v[174:177], v[190:193], v[118:121]
	v_mfma_f32_16x16x32_bf16 v[114:117], v[182:185], v[190:193], v[114:117]
	v_mfma_f32_16x16x32_bf16 v[102:105], v[174:177], v[198:201], v[102:105]
	v_mfma_f32_16x16x32_bf16 v[98:101], v[182:185], v[198:201], v[98:101]
	v_mfma_f32_16x16x32_bf16 v[86:89], v[174:177], v[206:209], v[86:89]
	v_mfma_f32_16x16x32_bf16 v[82:85], v[182:185], v[206:209], v[82:85]
	v_mfma_f32_16x16x32_bf16 v[70:73], v[174:177], v[214:217], v[70:73]
	v_mfma_f32_16x16x32_bf16 v[66:69], v[182:185], v[214:217], v[66:69]
	v_mfma_f32_16x16x32_bf16 v[118:121], v[178:181], v[194:197], v[118:121]
	v_mfma_f32_16x16x32_bf16 v[114:117], v[186:189], v[194:197], v[114:117]
	v_mfma_f32_16x16x32_bf16 v[102:105], v[178:181], v[202:205], v[102:105]
	v_mfma_f32_16x16x32_bf16 v[98:101], v[186:189], v[202:205], v[98:101]
	v_mfma_f32_16x16x32_bf16 v[86:89], v[178:181], v[210:213], v[86:89]
	v_mfma_f32_16x16x32_bf16 v[82:85], v[186:189], v[210:213], v[82:85]
	v_mfma_f32_16x16x32_bf16 v[70:73], v[178:181], v[218:221], v[70:73]
	v_mfma_f32_16x16x32_bf16 v[66:69], v[186:189], v[218:221], v[66:69]
	s_setprio 0
	s_barrier
; #define PG8_STAGE(bufoff, gbase, voff) do { _Pragma("unroll") for (int _i = 0; _i < 2; ++_i) \
;         __builtin_amdgcn_global_load_lds((const unsigned*)((const char*)(gbase) + (voff)[_i]), (PG8_LAS unsigned*)(lds + (bufoff) + ldsw + _i * 8192), 16, 0, 0); } while (0)
; #define PG8_LDA(dst, b, h) do { _Pragma("unroll") for (int m = 0; m < 4; ++m) _Pragma("unroll") for (int k = 0; k < 2; ++k) dst[m][k] = *(const PG8_LAS bf16x8*)(lds + PG8_SA(b, h) + aoff + m * 2048 + k * 1024); } while (0)
; #define PG8_MMA(ai, bj, At, Bt) do { __builtin_amdgcn_s_setprio(1); _Pragma("unroll") for (int m = 0; m < 4; ++m) _Pragma("unroll") for (int n = 0; n < 2; ++n) _Pragma("unroll") for (int k = 0; k < 2; ++k) \
;         acc[ai][bj][m][n] = __builtin_amdgcn_mfma_f32_16x16x32_bf16(Bt[n][k], At[m][k], acc[ai][bj][m][n], 0, 0, 0); __builtin_amdgcn_s_setprio(0); } while (0)
; #define PG8_WAIT_V(n) asm volatile("s_waitcnt vmcnt(" #n ")" ::: "memory")
; #define PG8_WAIT_L(n) asm volatile("s_waitcnt lgkmcnt(" #n ")" ::: "memory")
; #define PG8_BAR __builtin_amdgcn_s_barrier()
; #define PG8_SCHED __builtin_amdgcn_sched_barrier(0)
; template <class Epi, class Sched, bool ALIGN_EPI = false, bool SP2 = false>
; __device__ __forceinline__ void gemm_phase(PG8_LAS unsigned char* lds, const Gemm g, const Sched& S, const Epi& E) {
;     ...
;         for (int t = 0; t < nt; t += 2) {
;     ...
;             PG8_LDA(At, 1, 1); PG8_STAGE(PG8_SB(1, 0), b3, voffB); PG8_STAGE(PG8_SB(1, 1), b3 + hstep, voffB); PG8_STAGE(PG8_SA(1, 0), a3, voffA);
;             PG8_WAIT_V(8); PG8_WAIT_L(0); PG8_BAR; PG8_MMA(1, 0, At, B0); PG8_MMA(1, 1, At, B1); PG8_BAR; PG8_SCHED;
	s_add_i32 s28, s69, s36
	v_lshl_add_u64 v[150:151], v[150:151], 0, s[20:21]
	s_mov_b32 m0, s28
	ds_read_b128 v[190:193], v153 offset:49152
	ds_read_b128 v[194:197], v153 offset:50176
	ds_read_b128 v[198:201], v153 offset:51200
	ds_read_b128 v[202:205], v153 offset:52224
	ds_read_b128 v[206:209], v153 offset:53248
	ds_read_b128 v[210:213], v153 offset:54272
	ds_read_b128 v[214:217], v153 offset:55296
	ds_read_b128 v[218:221], v153 offset:56320
	global_load_lds_dwordx4 v[150:151], off
	v_lshl_add_u64 v[150:151], v[158:159], 0, s[20:21]
	s_add_i32 m0, s28, 0x2000
	s_add_i32 s28, s70, s36
	global_load_lds_dwordx4 v[150:151], off
	s_mov_b32 m0, s28
	v_lshl_add_u64 v[150:151], v[222:223], 0, s[20:21]
	global_load_lds_dwordx4 v[150:151], off
	s_add_i32 m0, s28, 0x2000
	v_lshl_add_u64 v[150:151], v[224:225], 0, s[20:21]
	global_load_lds_dwordx4 v[150:151], off
	s_mov_b32 m0, s42
	v_lshl_add_u64 v[150:151], v[226:227], 0, s[20:21]
	global_load_lds_dwordx4 v[150:151], off
	s_mov_b32 m0, s43
	v_lshl_add_u64 v[150:151], v[228:229], 0, s[20:21]
	global_load_lds_dwordx4 v[150:151], off
	s_waitcnt vmcnt(8) lgkmcnt(0)
	s_barrier
	s_setprio 1
	v_mfma_f32_16x16x32_bf16 v[62:65], v[146:149], v[190:193], v[62:65]
	v_mfma_f32_16x16x32_bf16 v[58:61], v[166:169], v[190:193], v[58:61]
	v_mfma_f32_16x16x32_bf16 v[46:49], v[146:149], v[198:201], v[46:49]
	v_mfma_f32_16x16x32_bf16 v[42:45], v[166:169], v[198:201], v[42:45]
	v_mfma_f32_16x16x32_bf16 v[30:33], v[146:149], v[206:209], v[30:33]
	v_mfma_f32_16x16x32_bf16 v[26:29], v[166:169], v[206:209], v[26:29]
	v_mfma_f32_16x16x32_bf16 v[14:17], v[146:149], v[214:217], v[14:17]
	v_mfma_f32_16x16x32_bf16 v[10:13], v[166:169], v[214:217], v[10:13]
	v_mfma_f32_16x16x32_bf16 v[62:65], v[162:165], v[194:197], v[62:65]
	v_mfma_f32_16x16x32_bf16 v[58:61], v[170:173], v[194:197], v[58:61]
	v_mfma_f32_16x16x32_bf16 v[46:49], v[162:165], v[202:205], v[46:49]
	v_mfma_f32_16x16x32_bf16 v[42:45], v[170:173], v[202:205], v[42:45]
	v_mfma_f32_16x16x32_bf16 v[30:33], v[162:165], v[210:213], v[30:33]
	v_mfma_f32_16x16x32_bf16 v[26:29], v[170:173], v[210:213], v[26:29]
	v_mfma_f32_16x16x32_bf16 v[14:17], v[162:165], v[218:221], v[14:17]
	v_mfma_f32_16x16x32_bf16 v[10:13], v[170:173], v[218:221], v[10:13]
	v_mfma_f32_16x16x32_bf16 v[54:57], v[174:177], v[190:193], v[54:57]
	v_mfma_f32_16x16x32_bf16 v[50:53], v[182:185], v[190:193], v[50:53]
	v_mfma_f32_16x16x32_bf16 v[38:41], v[174:177], v[198:201], v[38:41]
	v_mfma_f32_16x16x32_bf16 v[34:37], v[182:185], v[198:201], v[34:37]
	v_mfma_f32_16x16x32_bf16 v[22:25], v[174:177], v[206:209], v[22:25]
	v_mfma_f32_16x16x32_bf16 v[18:21], v[182:185], v[206:209], v[18:21]
	v_mfma_f32_16x16x32_bf16 v[6:9], v[174:177], v[214:217], v[6:9]
	v_mfma_f32_16x16x32_bf16 v[2:5], v[182:185], v[214:217], v[2:5]
	v_mfma_f32_16x16x32_bf16 v[54:57], v[178:181], v[194:197], v[54:57]
	v_mfma_f32_16x16x32_bf16 v[50:53], v[186:189], v[194:197], v[50:53]
	v_mfma_f32_16x16x32_bf16 v[38:41], v[178:181], v[202:205], v[38:41]
	v_mfma_f32_16x16x32_bf16 v[34:37], v[186:189], v[202:205], v[34:37]
	v_mfma_f32_16x16x32_bf16 v[22:25], v[178:181], v[210:213], v[22:25]
	v_mfma_f32_16x16x32_bf16 v[18:21], v[186:189], v[210:213], v[18:21]
	v_mfma_f32_16x16x32_bf16 v[6:9], v[178:181], v[218:221], v[6:9]
	v_mfma_f32_16x16x32_bf16 v[2:5], v[186:189], v[218:221], v[2:5]
	s_setprio 0
	s_barrier
	s_add_u32 s56, s56, 0x100
	s_addc_u32 s57, s57, 0
	s_add_u32 s26, s26, 0x100
	s_addc_u32 s27, s27, 0
	s_cmp_ge_i32 s68, s44
	s_mov_b32 s28, s68
	s_cbranch_scc0 .LBB0_1548

; #define PG8_STAGE(bufoff, gbase, voff) do { _Pragma("unroll") for (int _i = 0; _i < 2; ++_i) \
;         __builtin_amdgcn_global_load_lds((const unsigned*)((const char*)(gbase) + (voff)[_i]), (PG8_LAS unsigned*)(lds + (bufoff) + ldsw + _i * 8192), 16, 0, 0); } while (0)
; #define PG8_LDA(dst, b, h) do { _Pragma("unroll") for (int m = 0; m < 4; ++m) _Pragma("unroll") for (int k = 0; k < 2; ++k) dst[m][k] = *(const PG8_LAS bf16x8*)(lds + PG8_SA(b, h) + aoff + m * 2048 + k * 1024); } while (0)
; #define PG8_LDB(dst, b, h) do { _Pragma("unroll") for (int n = 0; n < 2; ++n) _Pragma("unroll") for (int k = 0; k < 2; ++k) dst[n][k] = *(const PG8_LAS bf16x8*)(lds + PG8_SB(b, h) + boff + n * 2048 + k * 1024); } while (0)
; #define PG8_WAIT_V(n) asm volatile("s_waitcnt vmcnt(" #n ")" ::: "memory")
; #define PG8_WAIT_L(n) asm volatile("s_waitcnt lgkmcnt(" #n ")" ::: "memory")
; #define PG8_BAR __builtin_amdgcn_s_barrier()
; #define PG8_SCHED __builtin_amdgcn_sched_barrier(0)
; template <class Epi, class Sched, bool ALIGN_EPI = false, bool SP2 = false>
; __device__ __forceinline__ void gemm_phase(PG8_LAS unsigned char* lds, const Gemm g, const Sched& S, const Epi& E) {
;     ...
;         const bool has_next = S.next(ui + 1, nxt);
;         const char* nA = has_next ? (const char*)g.A + (size_t)nxt.pm * tstep : cA; const char* nB = has_next ? (const char*)g.Bt + (size_t)nxt.pn * tstep : cB;
;         for (int t = 0; t < nt; t += 2) {
;             const bool last = (t == nt - 2);
;             const char* a1 = cA + (size_t)(t + 1) * kstep;
;             const char* a2 = last ? nA : cA + (size_t)(t + 2) * kstep; const char* b2 = last ? nB : cB + (size_t)(t + 2) * kstep;
;             const char* a3 = a2 + kstep; const char* b3 = b2 + kstep;
;             if (last && has_next) S.a_ready(nxt);
;             if constexpr (SP2) {
;             PG8_LDB(B0, 0, 0); PG8_LDB(B1, 0, 1); PG8_SCHED; PG8_LDA(At, 0, 0); PG8_STAGE(PG8_SA(1, 1), a1 + hstep, voffA);
;             PG8_WAIT_V(8); PG8_WAIT_L(0); PG8_BAR; PG8_MMA(0, 0, At, B0); PG8_MMA(0, 1, At, B1); PG8_BAR; PG8_SCHED;
;             PG8_LDA(At, 0, 1); PG8_STAGE(PG8_SB(0, 0), b2, voffB); PG8_STAGE(PG8_SB(0, 1), b2 + hstep, voffB); PG8_STAGE(PG8_SA(0, 0), a2, voffA);
;             PG8_WAIT_V(8); PG8_WAIT_L(0); PG8_BAR; PG8_MMA(1, 0, At, B0); PG8_MMA(1, 1, At, B1); PG8_BAR; PG8_SCHED;
.LBB0_1724:
	ds_read_b128 v[148:151], v157
	ds_read_b128 v[152:155], v157 offset:1024
	ds_read_b128 v[160:163], v157 offset:2048
	ds_read_b128 v[164:167], v157 offset:3072
	ds_read_b128 v[168:171], v158
	ds_read_b128 v[172:175], v158 offset:1024
	ds_read_b128 v[176:179], v158 offset:2048
	ds_read_b128 v[180:183], v158 offset:3072
	s_add_i32 s80, s38, 2
	s_add_u32 s70, s36, 0x80
	s_addc_u32 s39, s37, 0
	s_cmp_eq_u32 s59, s38
	s_cselect_b32 s38, s4, s70
	s_cselect_b32 s39, s5, s39
	s_cselect_b32 s71, s35, s45
	s_cselect_b32 s70, s34, s44
	v_lshl_add_u64 v[216:217], s[36:37], 0, v[142:143]
	s_add_i32 m0, s48, 0xc000
	ds_read_b128 v[184:187], v159
	ds_read_b128 v[188:191], v159 offset:1024
	ds_read_b128 v[192:195], v159 offset:2048
	ds_read_b128 v[196:199], v159 offset:3072
	ds_read_b128 v[200:203], v159 offset:4096
	ds_read_b128 v[204:207], v159 offset:5120
	ds_read_b128 v[208:211], v159 offset:6144
	ds_read_b128 v[212:215], v159 offset:7168
	global_load_lds_dwordx4 v[216:217], off
	s_add_i32 m0, s48, 0xe000
	v_lshl_add_u64 v[216:217], s[36:37], 0, v[140:141]
	global_load_lds_dwordx4 v[216:217], off
	s_waitcnt vmcnt(8) lgkmcnt(0)
	s_barrier
	s_setprio 1
	v_mfma_f32_16x16x32_bf16 v[122:125], v[148:151], v[184:187], v[122:125]
	v_mfma_f32_16x16x32_bf16 v[126:129], v[160:163], v[184:187], v[126:129]
	v_mfma_f32_16x16x32_bf16 v[110:113], v[148:151], v[192:195], v[110:113]
	v_mfma_f32_16x16x32_bf16 v[106:109], v[160:163], v[192:195], v[106:109]
	v_mfma_f32_16x16x32_bf16 v[94:97], v[148:151], v[200:203], v[94:97]
	v_mfma_f32_16x16x32_bf16 v[90:93], v[160:163], v[200:203], v[90:93]
	v_mfma_f32_16x16x32_bf16 v[78:81], v[148:151], v[208:211], v[78:81]
	v_mfma_f32_16x16x32_bf16 v[74:77], v[160:163], v[208:211], v[74:77]
	v_mfma_f32_16x16x32_bf16 v[122:125], v[152:155], v[188:191], v[122:125]
	v_mfma_f32_16x16x32_bf16 v[126:129], v[164:167], v[188:191], v[126:129]
	v_mfma_f32_16x16x32_bf16 v[110:113], v[152:155], v[196:199], v[110:113]
	v_mfma_f32_16x16x32_bf16 v[106:109], v[164:167], v[196:199], v[106:109]
	v_mfma_f32_16x16x32_bf16 v[94:97], v[152:155], v[204:207], v[94:97]
	v_mfma_f32_16x16x32_bf16 v[90:93], v[164:167], v[204:207], v[90:93]
	v_mfma_f32_16x16x32_bf16 v[78:81], v[152:155], v[212:215], v[78:81]
	v_mfma_f32_16x16x32_bf16 v[74:77], v[164:167], v[212:215], v[74:77]
	v_mfma_f32_16x16x32_bf16 v[118:121], v[168:171], v[184:187], v[118:121]
	v_mfma_f32_16x16x32_bf16 v[114:117], v[176:179], v[184:187], v[114:117]
	v_mfma_f32_16x16x32_bf16 v[102:105], v[168:171], v[192:195], v[102:105]
	v_mfma_f32_16x16x32_bf16 v[98:101], v[176:179], v[192:195], v[98:101]
	v_mfma_f32_16x16x32_bf16 v[86:89], v[168:171], v[200:203], v[86:89]
	v_mfma_f32_16x16x32_bf16 v[82:85], v[176:179], v[200:203], v[82:85]
	v_mfma_f32_16x16x32_bf16 v[70:73], v[168:171], v[208:211], v[70:73]
	v_mfma_f32_16x16x32_bf16 v[66:69], v[176:179], v[208:211], v[66:69]
	v_mfma_f32_16x16x32_bf16 v[118:121], v[172:175], v[188:191], v[118:121]
	v_mfma_f32_16x16x32_bf16 v[114:117], v[180:183], v[188:191], v[114:117]
	v_mfma_f32_16x16x32_bf16 v[102:105], v[172:175], v[196:199], v[102:105]
	v_mfma_f32_16x16x32_bf16 v[98:101], v[180:183], v[196:199], v[98:101]
	v_mfma_f32_16x16x32_bf16 v[86:89], v[172:175], v[204:207], v[86:89]
	v_mfma_f32_16x16x32_bf16 v[82:85], v[180:183], v[204:207], v[82:85]
	v_mfma_f32_16x16x32_bf16 v[70:73], v[172:175], v[212:215], v[70:73]
	v_mfma_f32_16x16x32_bf16 v[66:69], v[180:183], v[212:215], v[66:69]
	s_setprio 0
	s_barrier
	s_add_i32 s72, s62, s47
	v_lshl_add_u64 v[216:217], s[70:71], 0, v[134:135]
	s_mov_b32 m0, s72
	ds_read_b128 v[184:187], v159 offset:16384
	ds_read_b128 v[188:191], v159 offset:17408
	ds_read_b128 v[192:195], v159 offset:18432
	ds_read_b128 v[196:199], v159 offset:19456
	ds_read_b128 v[200:203], v159 offset:20480
	ds_read_b128 v[204:207], v159 offset:21504
	ds_read_b128 v[208:211], v159 offset:22528
	ds_read_b128 v[212:215], v159 offset:23552
	global_load_lds_dwordx4 v[216:217], off
	s_add_i32 m0, s72, 0x2000
	v_lshl_add_u64 v[218:219], s[70:71], 0, v[138:139]
	s_add_u32 s70, s70, s8
	s_addc_u32 s71, s71, s9
	s_add_i32 s72, s63, s47
	global_load_lds_dwordx4 v[218:219], off
	v_lshl_add_u64 v[220:221], s[70:71], 0, v[134:135]
	s_mov_b32 m0, s72
	v_lshl_add_u64 v[222:223], s[70:71], 0, v[138:139]
	global_load_lds_dwordx4 v[220:221], off
	s_add_i32 m0, s72, 0x2000
	v_lshl_add_u64 v[224:225], s[38:39], 0, v[132:133]
	global_load_lds_dwordx4 v[222:223], off
	s_mov_b32 m0, s48
	v_lshl_add_u64 v[226:227], s[38:39], 0, v[136:137]
	global_load_lds_dwordx4 v[224:225], off
	s_mov_b32 m0, s49
	s_nop 0
	global_load_lds_dwordx4 v[226:227], off
	s_waitcnt vmcnt(8) lgkmcnt(0)
	s_barrier
; #define PG8_STAGE(bufoff, gbase, voff) do { _Pragma("unroll") for (int _i = 0; _i < 2; ++_i) \
;         __builtin_amdgcn_global_load_lds((const unsigned*)((const char*)(gbase) + (voff)[_i]), (PG8_LAS unsigned*)(lds + (bufoff) + ldsw + _i * 8192), 16, 0, 0); } while (0)
; #define PG8_LDA(dst, b, h) do { _Pragma("unroll") for (int m = 0; m < 4; ++m) _Pragma("unroll") for (int k = 0; k < 2; ++k) dst[m][k] = *(const PG8_LAS bf16x8*)(lds + PG8_SA(b, h) + aoff + m * 2048 + k * 1024); } while (0)
; #define PG8_LDB(dst, b, h) do { _Pragma("unroll") for (int n = 0; n < 2; ++n) _Pragma("unroll") for (int k = 0; k < 2; ++k) dst[n][k] = *(const PG8_LAS bf16x8*)(lds + PG8_SB(b, h) + boff + n * 2048 + k * 1024); } while (0)
; #define PG8_MMA(ai, bj, At, Bt) do { __builtin_amdgcn_s_setprio(1); _Pragma("unroll") for (int m = 0; m < 4; ++m) _Pragma("unroll") for (int n = 0; n < 2; ++n) _Pragma("unroll") for (int k = 0; k < 2; ++k) \
;         acc[ai][bj][m][n] = __builtin_amdgcn_mfma_f32_16x16x32_bf16(Bt[n][k], At[m][k], acc[ai][bj][m][n], 0, 0, 0); __builtin_amdgcn_s_setprio(0); } while (0)
; #define PG8_WAIT_V(n) asm volatile("s_waitcnt vmcnt(" #n ")" ::: "memory")
; #define PG8_WAIT_L(n) asm volatile("s_waitcnt lgkmcnt(" #n ")" ::: "memory")
; #define PG8_BAR __builtin_amdgcn_s_barrier()
; #define PG8_SCHED __builtin_amdgcn_sched_barrier(0)
; template <class Epi, class Sched, bool ALIGN_EPI = false, bool SP2 = false>
; __device__ __forceinline__ void gemm_phase(PG8_LAS unsigned char* lds, const Gemm g, const Sched& S, const Epi& E) {
;     ...
;             PG8_WAIT_V(8); PG8_WAIT_L(0); PG8_BAR; PG8_MMA(1, 0, At, B0); PG8_MMA(1, 1, At, B1); PG8_BAR; PG8_SCHED;
;             PG8_LDB(B0, 1, 0); PG8_LDB(B1, 1, 1); PG8_SCHED; PG8_LDA(At, 1, 0); PG8_STAGE(PG8_SA(0, 1), a2 + hstep, voffA);
;             PG8_WAIT_V(8); PG8_WAIT_L(0); PG8_BAR; PG8_MMA(0, 0, At, B0); PG8_MMA(0, 1, At, B1); PG8_BAR; PG8_SCHED;
	s_setprio 1
	v_mfma_f32_16x16x32_bf16 v[62:65], v[148:151], v[184:187], v[62:65]
	v_mfma_f32_16x16x32_bf16 v[58:61], v[160:163], v[184:187], v[58:61]
	v_mfma_f32_16x16x32_bf16 v[46:49], v[148:151], v[192:195], v[46:49]
	v_mfma_f32_16x16x32_bf16 v[42:45], v[160:163], v[192:195], v[42:45]
	v_mfma_f32_16x16x32_bf16 v[30:33], v[148:151], v[200:203], v[30:33]
	v_mfma_f32_16x16x32_bf16 v[26:29], v[160:163], v[200:203], v[26:29]
	v_mfma_f32_16x16x32_bf16 v[14:17], v[148:151], v[208:211], v[14:17]
	v_mfma_f32_16x16x32_bf16 v[10:13], v[160:163], v[208:211], v[10:13]
	v_mfma_f32_16x16x32_bf16 v[62:65], v[152:155], v[188:191], v[62:65]
	v_mfma_f32_16x16x32_bf16 v[58:61], v[164:167], v[188:191], v[58:61]
	v_mfma_f32_16x16x32_bf16 v[46:49], v[152:155], v[196:199], v[46:49]
	v_mfma_f32_16x16x32_bf16 v[42:45], v[164:167], v[196:199], v[42:45]
	v_mfma_f32_16x16x32_bf16 v[30:33], v[152:155], v[204:207], v[30:33]
	v_mfma_f32_16x16x32_bf16 v[26:29], v[164:167], v[204:207], v[26:29]
	v_mfma_f32_16x16x32_bf16 v[14:17], v[152:155], v[212:215], v[14:17]
	v_mfma_f32_16x16x32_bf16 v[10:13], v[164:167], v[212:215], v[10:13]
	v_mfma_f32_16x16x32_bf16 v[54:57], v[168:171], v[184:187], v[54:57]
	v_mfma_f32_16x16x32_bf16 v[50:53], v[176:179], v[184:187], v[50:53]
	v_mfma_f32_16x16x32_bf16 v[38:41], v[168:171], v[192:195], v[38:41]
	v_mfma_f32_16x16x32_bf16 v[34:37], v[176:179], v[192:195], v[34:37]
	v_mfma_f32_16x16x32_bf16 v[22:25], v[168:171], v[200:203], v[22:25]
	v_mfma_f32_16x16x32_bf16 v[18:21], v[176:179], v[200:203], v[18:21]
	v_mfma_f32_16x16x32_bf16 v[6:9], v[168:171], v[208:211], v[6:9]
	v_mfma_f32_16x16x32_bf16 v[2:5], v[176:179], v[208:211], v[2:5]
	v_mfma_f32_16x16x32_bf16 v[54:57], v[172:175], v[188:191], v[54:57]
	v_mfma_f32_16x16x32_bf16 v[50:53], v[180:183], v[188:191], v[50:53]
	v_mfma_f32_16x16x32_bf16 v[38:41], v[172:175], v[196:199], v[38:41]
	v_mfma_f32_16x16x32_bf16 v[34:37], v[180:183], v[196:199], v[34:37]
	v_mfma_f32_16x16x32_bf16 v[22:25], v[172:175], v[204:207], v[22:25]
	v_mfma_f32_16x16x32_bf16 v[18:21], v[180:183], v[204:207], v[18:21]
	v_mfma_f32_16x16x32_bf16 v[6:9], v[172:175], v[212:215], v[6:9]
	v_mfma_f32_16x16x32_bf16 v[2:5], v[180:183], v[212:215], v[2:5]
	s_setprio 0
	s_barrier
	s_add_i32 s70, 0, 0x18000
	s_add_i32 s71, 0, 0x1c000
	v_add_u32_e32 v164, s70, v156
	v_add_u32_e32 v180, s71, v156
	ds_read_b128 v[148:151], v164
	ds_read_b128 v[152:155], v164 offset:1024
	ds_read_b128 v[160:163], v164 offset:2048
	ds_read_b128 v[164:167], v164 offset:3072
	ds_read_b128 v[168:171], v180
	ds_read_b128 v[172:175], v180 offset:1024
	ds_read_b128 v[176:179], v180 offset:2048
	ds_read_b128 v[180:183], v180 offset:3072
	s_add_u32 s38, s38, s8
	s_addc_u32 s39, s39, s9
	s_mov_b32 m0, s52
	v_lshl_add_u64 v[228:229], s[38:39], 0, v[132:133]
	ds_read_b128 v[184:187], v159 offset:32768
	ds_read_b128 v[188:191], v159 offset:33792
	ds_read_b128 v[192:195], v159 offset:34816
	ds_read_b128 v[196:199], v159 offset:35840
	ds_read_b128 v[200:203], v159 offset:36864
	ds_read_b128 v[204:207], v159 offset:37888
	ds_read_b128 v[208:211], v159 offset:38912
	ds_read_b128 v[212:215], v159 offset:39936
	global_load_lds_dwordx4 v[228:229], off
	s_mov_b32 m0, s53
	v_lshl_add_u64 v[228:229], s[38:39], 0, v[136:137]
	global_load_lds_dwordx4 v[228:229], off
	s_waitcnt vmcnt(8) lgkmcnt(0)
	s_barrier
	s_setprio 1
	v_mfma_f32_16x16x32_bf16 v[122:125], v[148:151], v[184:187], v[122:125]
	v_mfma_f32_16x16x32_bf16 v[126:129], v[160:163], v[184:187], v[126:129]
	v_mfma_f32_16x16x32_bf16 v[110:113], v[148:151], v[192:195], v[110:113]
	v_mfma_f32_16x16x32_bf16 v[106:109], v[160:163], v[192:195], v[106:109]
	v_mfma_f32_16x16x32_bf16 v[94:97], v[148:151], v[200:203], v[94:97]
	v_mfma_f32_16x16x32_bf16 v[90:93], v[160:163], v[200:203], v[90:93]
	v_mfma_f32_16x16x32_bf16 v[78:81], v[148:151], v[208:211], v[78:81]
	v_mfma_f32_16x16x32_bf16 v[74:77], v[160:163], v[208:211], v[74:77]
	v_mfma_f32_16x16x32_bf16 v[122:125], v[152:155], v[188:191], v[122:125]
	v_mfma_f32_16x16x32_bf16 v[126:129], v[164:167], v[188:191], v[126:129]
	v_mfma_f32_16x16x32_bf16 v[110:113], v[152:155], v[196:199], v[110:113]
	v_mfma_f32_16x16x32_bf16 v[106:109], v[164:167], v[196:199], v[106:109]
	v_mfma_f32_16x16x32_bf16 v[94:97], v[152:155], v[204:207], v[94:97]
	v_mfma_f32_16x16x32_bf16 v[90:93], v[164:167], v[204:207], v[90:93]
	v_mfma_f32_16x16x32_bf16 v[78:81], v[152:155], v[212:215], v[78:81]
	v_mfma_f32_16x16x32_bf16 v[74:77], v[164:167], v[212:215], v[74:77]
	v_mfma_f32_16x16x32_bf16 v[118:121], v[168:171], v[184:187], v[118:121]
	v_mfma_f32_16x16x32_bf16 v[114:117], v[176:179], v[184:187], v[114:117]
	v_mfma_f32_16x16x32_bf16 v[102:105], v[168:171], v[192:195], v[102:105]
	v_mfma_f32_16x16x32_bf16 v[98:101], v[176:179], v[192:195], v[98:101]
	v_mfma_f32_16x16x32_bf16 v[86:89], v[168:171], v[200:203], v[86:89]
	v_mfma_f32_16x16x32_bf16 v[82:85], v[176:179], v[200:203], v[82:85]
	v_mfma_f32_16x16x32_bf16 v[70:73], v[168:171], v[208:211], v[70:73]
	v_mfma_f32_16x16x32_bf16 v[66:69], v[176:179], v[208:211], v[66:69]
	v_mfma_f32_16x16x32_bf16 v[118:121], v[172:175], v[188:191], v[118:121]
	v_mfma_f32_16x16x32_bf16 v[114:117], v[180:183], v[188:191], v[114:117]
	v_mfma_f32_16x16x32_bf16 v[102:105], v[172:175], v[196:199], v[102:105]
	v_mfma_f32_16x16x32_bf16 v[98:101], v[180:183], v[196:199], v[98:101]
	v_mfma_f32_16x16x32_bf16 v[86:89], v[172:175], v[204:207], v[86:89]
	v_mfma_f32_16x16x32_bf16 v[82:85], v[180:183], v[204:207], v[82:85]
	v_mfma_f32_16x16x32_bf16 v[70:73], v[172:175], v[212:215], v[70:73]
	v_mfma_f32_16x16x32_bf16 v[66:69], v[180:183], v[212:215], v[66:69]
	s_setprio 0
	s_barrier
; #define PG8_STAGE(bufoff, gbase, voff) do { _Pragma("unroll") for (int _i = 0; _i < 2; ++_i) \
;         __builtin_amdgcn_global_load_lds((const unsigned*)((const char*)(gbase) + (voff)[_i]), (PG8_LAS unsigned*)(lds + (bufoff) + ldsw + _i * 8192), 16, 0, 0); } while (0)
; #define PG8_LDA(dst, b, h) do { _Pragma("unroll") for (int m = 0; m < 4; ++m) _Pragma("unroll") for (int k = 0; k < 2; ++k) dst[m][k] = *(const PG8_LAS bf16x8*)(lds + PG8_SA(b, h) + aoff + m * 2048 + k * 1024); } while (0)
; #define PG8_MMA(ai, bj, At, Bt) do { __builtin_amdgcn_s_setprio(1); _Pragma("unroll") for (int m = 0; m < 4; ++m) _Pragma("unroll") for (int n = 0; n < 2; ++n) _Pragma("unroll") for (int k = 0; k < 2; ++k) \
;         acc[ai][bj][m][n] = __builtin_amdgcn_mfma_f32_16x16x32_bf16(Bt[n][k], At[m][k], acc[ai][bj][m][n], 0, 0, 0); __builtin_amdgcn_s_setprio(0); } while (0)
; #define PG8_WAIT_V(n) asm volatile("s_waitcnt vmcnt(" #n ")" ::: "memory")
; #define PG8_WAIT_L(n) asm volatile("s_waitcnt lgkmcnt(" #n ")" ::: "memory")
; #define PG8_BAR __builtin_amdgcn_s_barrier()
; #define PG8_SCHED __builtin_amdgcn_sched_barrier(0)
; template <class Epi, class Sched, bool ALIGN_EPI = false, bool SP2 = false>
; __device__ __forceinline__ void gemm_phase(PG8_LAS unsigned char* lds, const Gemm g, const Sched& S, const Epi& E) {
;     ...
;         for (int t = 0; t < nt; t += 2) {
;     ...
;             PG8_LDA(At, 1, 1); PG8_STAGE(PG8_SB(1, 0), b3, voffB); PG8_STAGE(PG8_SB(1, 1), b3 + hstep, voffB); PG8_STAGE(PG8_SA(1, 0), a3, voffA);
;             PG8_WAIT_V(8); PG8_WAIT_L(0); PG8_BAR; PG8_MMA(1, 0, At, B0); PG8_MMA(1, 1, At, B1); PG8_BAR; PG8_SCHED;
	s_add_i32 s38, s70, s47
	v_lshl_add_u64 v[216:217], v[216:217], 0, s[24:25]
	s_mov_b32 m0, s38
	ds_read_b128 v[184:187], v159 offset:49152
	ds_read_b128 v[188:191], v159 offset:50176
	ds_read_b128 v[192:195], v159 offset:51200
	ds_read_b128 v[196:199], v159 offset:52224
	ds_read_b128 v[200:203], v159 offset:53248
	ds_read_b128 v[204:207], v159 offset:54272
	ds_read_b128 v[208:211], v159 offset:55296
	ds_read_b128 v[212:215], v159 offset:56320
	global_load_lds_dwordx4 v[216:217], off
	v_lshl_add_u64 v[216:217], v[218:219], 0, s[24:25]
	s_add_i32 m0, s38, 0x2000
	s_add_i32 s38, s71, s47
	global_load_lds_dwordx4 v[216:217], off
	s_mov_b32 m0, s38
	v_lshl_add_u64 v[216:217], v[220:221], 0, s[24:25]
	global_load_lds_dwordx4 v[216:217], off
	s_add_i32 m0, s38, 0x2000
	v_lshl_add_u64 v[216:217], v[222:223], 0, s[24:25]
	global_load_lds_dwordx4 v[216:217], off
	s_mov_b32 m0, s55
	v_lshl_add_u64 v[216:217], v[224:225], 0, s[24:25]
	global_load_lds_dwordx4 v[216:217], off
	s_mov_b32 m0, s56
	v_lshl_add_u64 v[216:217], v[226:227], 0, s[24:25]
	global_load_lds_dwordx4 v[216:217], off
	s_waitcnt vmcnt(8) lgkmcnt(0)
	s_barrier
	s_setprio 1
	v_mfma_f32_16x16x32_bf16 v[62:65], v[148:151], v[184:187], v[62:65]
	v_mfma_f32_16x16x32_bf16 v[58:61], v[160:163], v[184:187], v[58:61]
	v_mfma_f32_16x16x32_bf16 v[46:49], v[148:151], v[192:195], v[46:49]
	v_mfma_f32_16x16x32_bf16 v[42:45], v[160:163], v[192:195], v[42:45]
	v_mfma_f32_16x16x32_bf16 v[30:33], v[148:151], v[200:203], v[30:33]
	v_mfma_f32_16x16x32_bf16 v[26:29], v[160:163], v[200:203], v[26:29]
	v_mfma_f32_16x16x32_bf16 v[14:17], v[148:151], v[208:211], v[14:17]
	v_mfma_f32_16x16x32_bf16 v[10:13], v[160:163], v[208:211], v[10:13]
	v_mfma_f32_16x16x32_bf16 v[62:65], v[152:155], v[188:191], v[62:65]
	v_mfma_f32_16x16x32_bf16 v[58:61], v[164:167], v[188:191], v[58:61]
	v_mfma_f32_16x16x32_bf16 v[46:49], v[152:155], v[196:199], v[46:49]
	v_mfma_f32_16x16x32_bf16 v[42:45], v[164:167], v[196:199], v[42:45]
	v_mfma_f32_16x16x32_bf16 v[30:33], v[152:155], v[204:207], v[30:33]
	v_mfma_f32_16x16x32_bf16 v[26:29], v[164:167], v[204:207], v[26:29]
	v_mfma_f32_16x16x32_bf16 v[14:17], v[152:155], v[212:215], v[14:17]
	v_mfma_f32_16x16x32_bf16 v[10:13], v[164:167], v[212:215], v[10:13]
	v_mfma_f32_16x16x32_bf16 v[54:57], v[168:171], v[184:187], v[54:57]
	v_mfma_f32_16x16x32_bf16 v[50:53], v[176:179], v[184:187], v[50:53]
	v_mfma_f32_16x16x32_bf16 v[38:41], v[168:171], v[192:195], v[38:41]
	v_mfma_f32_16x16x32_bf16 v[34:37], v[176:179], v[192:195], v[34:37]
	v_mfma_f32_16x16x32_bf16 v[22:25], v[168:171], v[200:203], v[22:25]
	v_mfma_f32_16x16x32_bf16 v[18:21], v[176:179], v[200:203], v[18:21]
	v_mfma_f32_16x16x32_bf16 v[6:9], v[168:171], v[208:211], v[6:9]
	v_mfma_f32_16x16x32_bf16 v[2:5], v[176:179], v[208:211], v[2:5]
	v_mfma_f32_16x16x32_bf16 v[54:57], v[172:175], v[188:191], v[54:57]
	v_mfma_f32_16x16x32_bf16 v[50:53], v[180:183], v[188:191], v[50:53]
	v_mfma_f32_16x16x32_bf16 v[38:41], v[172:175], v[196:199], v[38:41]
	v_mfma_f32_16x16x32_bf16 v[34:37], v[180:183], v[196:199], v[34:37]
	v_mfma_f32_16x16x32_bf16 v[22:25], v[172:175], v[204:207], v[22:25]
	v_mfma_f32_16x16x32_bf16 v[18:21], v[180:183], v[204:207], v[18:21]
	v_mfma_f32_16x16x32_bf16 v[6:9], v[172:175], v[212:215], v[6:9]
	v_mfma_f32_16x16x32_bf16 v[2:5], v[180:183], v[212:215], v[2:5]
	s_setprio 0
	s_barrier
	s_add_u32 s44, s44, 0x100
	s_addc_u32 s45, s45, 0
	s_add_u32 s36, s36, 0x100
	s_addc_u32 s37, s37, 0
	s_cmp_ge_i32 s80, s57
	s_mov_b32 s38, s80
	s_cbranch_scc0 .LBB0_1724

; #define PG8_STAGE(bufoff, gbase, voff) do { _Pragma("unroll") for (int _i = 0; _i < 2; ++_i) \
;         __builtin_amdgcn_global_load_lds((const unsigned*)((const char*)(gbase) + (voff)[_i]), (PG8_LAS unsigned*)(lds + (bufoff) + ldsw + _i * 8192), 16, 0, 0); } while (0)
; #define PG8_LDA(dst, b, h) do { _Pragma("unroll") for (int m = 0; m < 4; ++m) _Pragma("unroll") for (int k = 0; k < 2; ++k) dst[m][k] = *(const PG8_LAS bf16x8*)(lds + PG8_SA(b, h) + aoff + m * 2048 + k * 1024); } while (0)
; #define PG8_LDB(dst, b, h) do { _Pragma("unroll") for (int n = 0; n < 2; ++n) _Pragma("unroll") for (int k = 0; k < 2; ++k) dst[n][k] = *(const PG8_LAS bf16x8*)(lds + PG8_SB(b, h) + boff + n * 2048 + k * 1024); } while (0)
; #define PG8_WAIT_V(n) asm volatile("s_waitcnt vmcnt(" #n ")" ::: "memory")
; #define PG8_WAIT_L(n) asm volatile("s_waitcnt lgkmcnt(" #n ")" ::: "memory")
; #define PG8_BAR __builtin_amdgcn_s_barrier()
; #define PG8_SCHED __builtin_amdgcn_sched_barrier(0)
; template <class Epi, class Sched, bool ALIGN_EPI = false, bool SP2 = false>
; __device__ __forceinline__ void gemm_phase(PG8_LAS unsigned char* lds, const Gemm g, const Sched& S, const Epi& E) {
;     ...
;         const bool has_next = S.next(ui + 1, nxt);
;         const char* nA = has_next ? (const char*)g.A + (size_t)nxt.pm * tstep : cA; const char* nB = has_next ? (const char*)g.Bt + (size_t)nxt.pn * tstep : cB;
;         for (int t = 0; t < nt; t += 2) {
;             const bool last = (t == nt - 2);
;             const char* a1 = cA + (size_t)(t + 1) * kstep;
;             const char* a2 = last ? nA : cA + (size_t)(t + 2) * kstep; const char* b2 = last ? nB : cB + (size_t)(t + 2) * kstep;
;             const char* a3 = a2 + kstep; const char* b3 = b2 + kstep;
;             if (last && has_next) S.a_ready(nxt);
;             if constexpr (SP2) {
;             PG8_LDB(B0, 0, 0); PG8_LDB(B1, 0, 1); PG8_SCHED; PG8_LDA(At, 0, 0); PG8_STAGE(PG8_SA(1, 1), a1 + hstep, voffA);
;             PG8_WAIT_V(8); PG8_WAIT_L(0); PG8_BAR; PG8_MMA(0, 0, At, B0); PG8_MMA(0, 1, At, B1); PG8_BAR; PG8_SCHED;
;             PG8_LDA(At, 0, 1); PG8_STAGE(PG8_SB(0, 0), b2, voffB); PG8_STAGE(PG8_SB(0, 1), b2 + hstep, voffB); PG8_STAGE(PG8_SA(0, 0), a2, voffA);
;             PG8_WAIT_V(8); PG8_WAIT_L(0); PG8_BAR; PG8_MMA(1, 0, At, B0); PG8_MMA(1, 1, At, B1); PG8_BAR; PG8_SCHED;
.LBB0_1809:
	ds_read_b128 v[152:155], v148
	ds_read_b128 v[156:159], v148 offset:1024
	ds_read_b128 v[160:163], v148 offset:2048
	ds_read_b128 v[164:167], v148 offset:3072
	ds_read_b128 v[168:171], v149
	ds_read_b128 v[172:175], v149 offset:1024
	ds_read_b128 v[176:179], v149 offset:2048
	ds_read_b128 v[180:183], v149 offset:3072
	s_add_i32 s56, s26, 2
	s_add_u32 s57, s24, 0x80
	s_addc_u32 s27, s25, 0
	s_cmp_eq_u32 s43, s26
	s_cselect_b32 s26, s4, s57
	s_cselect_b32 s27, s5, s27
	s_cselect_b32 s59, s23, s55
	s_cselect_b32 s58, s22, s54
	v_lshl_add_u64 v[216:217], s[24:25], 0, v[140:141]
	s_add_i32 m0, s35, 0xc000
	ds_read_b128 v[184:187], v150
	ds_read_b128 v[188:191], v150 offset:1024
	ds_read_b128 v[192:195], v150 offset:2048
	ds_read_b128 v[196:199], v150 offset:3072
	ds_read_b128 v[200:203], v150 offset:4096
	ds_read_b128 v[204:207], v150 offset:5120
	ds_read_b128 v[208:211], v150 offset:6144
	ds_read_b128 v[212:215], v150 offset:7168
	global_load_lds_dwordx4 v[216:217], off
	s_add_i32 m0, s35, 0xe000
	v_lshl_add_u64 v[216:217], s[24:25], 0, v[138:139]
	global_load_lds_dwordx4 v[216:217], off
	s_waitcnt vmcnt(8) lgkmcnt(0)
	s_barrier
	s_setprio 1
	v_mfma_f32_16x16x32_bf16 v[122:125], v[152:155], v[184:187], v[122:125]
	v_mfma_f32_16x16x32_bf16 v[126:129], v[160:163], v[184:187], v[126:129]
	v_mfma_f32_16x16x32_bf16 v[110:113], v[152:155], v[192:195], v[110:113]
	v_mfma_f32_16x16x32_bf16 v[106:109], v[160:163], v[192:195], v[106:109]
	v_mfma_f32_16x16x32_bf16 v[94:97], v[152:155], v[200:203], v[94:97]
	v_mfma_f32_16x16x32_bf16 v[90:93], v[160:163], v[200:203], v[90:93]
	v_mfma_f32_16x16x32_bf16 v[78:81], v[152:155], v[208:211], v[78:81]
	v_mfma_f32_16x16x32_bf16 v[74:77], v[160:163], v[208:211], v[74:77]
	v_mfma_f32_16x16x32_bf16 v[122:125], v[156:159], v[188:191], v[122:125]
	v_mfma_f32_16x16x32_bf16 v[126:129], v[164:167], v[188:191], v[126:129]
	v_mfma_f32_16x16x32_bf16 v[110:113], v[156:159], v[196:199], v[110:113]
	v_mfma_f32_16x16x32_bf16 v[106:109], v[164:167], v[196:199], v[106:109]
	v_mfma_f32_16x16x32_bf16 v[94:97], v[156:159], v[204:207], v[94:97]
	v_mfma_f32_16x16x32_bf16 v[90:93], v[164:167], v[204:207], v[90:93]
	v_mfma_f32_16x16x32_bf16 v[78:81], v[156:159], v[212:215], v[78:81]
	v_mfma_f32_16x16x32_bf16 v[74:77], v[164:167], v[212:215], v[74:77]
	v_mfma_f32_16x16x32_bf16 v[118:121], v[168:171], v[184:187], v[118:121]
	v_mfma_f32_16x16x32_bf16 v[114:117], v[176:179], v[184:187], v[114:117]
	v_mfma_f32_16x16x32_bf16 v[102:105], v[168:171], v[192:195], v[102:105]
	v_mfma_f32_16x16x32_bf16 v[98:101], v[176:179], v[192:195], v[98:101]
	v_mfma_f32_16x16x32_bf16 v[86:89], v[168:171], v[200:203], v[86:89]
	v_mfma_f32_16x16x32_bf16 v[82:85], v[176:179], v[200:203], v[82:85]
	v_mfma_f32_16x16x32_bf16 v[70:73], v[168:171], v[208:211], v[70:73]
	v_mfma_f32_16x16x32_bf16 v[66:69], v[176:179], v[208:211], v[66:69]
	v_mfma_f32_16x16x32_bf16 v[118:121], v[172:175], v[188:191], v[118:121]
	v_mfma_f32_16x16x32_bf16 v[114:117], v[180:183], v[188:191], v[114:117]
	v_mfma_f32_16x16x32_bf16 v[102:105], v[172:175], v[196:199], v[102:105]
	v_mfma_f32_16x16x32_bf16 v[98:101], v[180:183], v[196:199], v[98:101]
	v_mfma_f32_16x16x32_bf16 v[86:89], v[172:175], v[204:207], v[86:89]
	v_mfma_f32_16x16x32_bf16 v[82:85], v[180:183], v[204:207], v[82:85]
	v_mfma_f32_16x16x32_bf16 v[70:73], v[172:175], v[212:215], v[70:73]
	v_mfma_f32_16x16x32_bf16 v[66:69], v[180:183], v[212:215], v[66:69]
	s_setprio 0
	s_barrier
	s_add_i32 s57, s46, s34
	v_lshl_add_u64 v[216:217], s[58:59], 0, v[132:133]
	s_mov_b32 m0, s57
	ds_read_b128 v[184:187], v150 offset:16384
	ds_read_b128 v[188:191], v150 offset:17408
	ds_read_b128 v[192:195], v150 offset:18432
	ds_read_b128 v[196:199], v150 offset:19456
	ds_read_b128 v[200:203], v150 offset:20480
	ds_read_b128 v[204:207], v150 offset:21504
	ds_read_b128 v[208:211], v150 offset:22528
	ds_read_b128 v[212:215], v150 offset:23552
	global_load_lds_dwordx4 v[216:217], off
	s_add_i32 m0, s57, 0x2000
	v_lshl_add_u64 v[218:219], s[58:59], 0, v[136:137]
	s_add_u32 s58, s58, s8
	s_addc_u32 s59, s59, s9
	s_add_i32 s57, s47, s34
	global_load_lds_dwordx4 v[218:219], off
	v_lshl_add_u64 v[220:221], s[58:59], 0, v[132:133]
	s_mov_b32 m0, s57
	v_lshl_add_u64 v[222:223], s[58:59], 0, v[136:137]
	global_load_lds_dwordx4 v[220:221], off
	s_add_i32 m0, s57, 0x2000
	v_lshl_add_u64 v[224:225], s[26:27], 0, v[130:131]
	global_load_lds_dwordx4 v[222:223], off
	s_mov_b32 m0, s35
	v_lshl_add_u64 v[226:227], s[26:27], 0, v[134:135]
	global_load_lds_dwordx4 v[224:225], off
	s_mov_b32 m0, s36
	s_nop 0
	global_load_lds_dwordx4 v[226:227], off
	s_waitcnt vmcnt(8) lgkmcnt(0)
	s_barrier
; #define PG8_STAGE(bufoff, gbase, voff) do { _Pragma("unroll") for (int _i = 0; _i < 2; ++_i) \
;         __builtin_amdgcn_global_load_lds((const unsigned*)((const char*)(gbase) + (voff)[_i]), (PG8_LAS unsigned*)(lds + (bufoff) + ldsw + _i * 8192), 16, 0, 0); } while (0)
; #define PG8_LDA(dst, b, h) do { _Pragma("unroll") for (int m = 0; m < 4; ++m) _Pragma("unroll") for (int k = 0; k < 2; ++k) dst[m][k] = *(const PG8_LAS bf16x8*)(lds + PG8_SA(b, h) + aoff + m * 2048 + k * 1024); } while (0)
; #define PG8_LDB(dst, b, h) do { _Pragma("unroll") for (int n = 0; n < 2; ++n) _Pragma("unroll") for (int k = 0; k < 2; ++k) dst[n][k] = *(const PG8_LAS bf16x8*)(lds + PG8_SB(b, h) + boff + n * 2048 + k * 1024); } while (0)
; #define PG8_MMA(ai, bj, At, Bt) do { __builtin_amdgcn_s_setprio(1); _Pragma("unroll") for (int m = 0; m < 4; ++m) _Pragma("unroll") for (int n = 0; n < 2; ++n) _Pragma("unroll") for (int k = 0; k < 2; ++k) \
;         acc[ai][bj][m][n] = __builtin_amdgcn_mfma_f32_16x16x32_bf16(Bt[n][k], At[m][k], acc[ai][bj][m][n], 0, 0, 0); __builtin_amdgcn_s_setprio(0); } while (0)
; #define PG8_WAIT_V(n) asm volatile("s_waitcnt vmcnt(" #n ")" ::: "memory")
; #define PG8_WAIT_L(n) asm volatile("s_waitcnt lgkmcnt(" #n ")" ::: "memory")
; #define PG8_BAR __builtin_amdgcn_s_barrier()
; #define PG8_SCHED __builtin_amdgcn_sched_barrier(0)
; template <class Epi, class Sched, bool ALIGN_EPI = false, bool SP2 = false>
; __device__ __forceinline__ void gemm_phase(PG8_LAS unsigned char* lds, const Gemm g, const Sched& S, const Epi& E) {
;     ...
;             PG8_WAIT_V(8); PG8_WAIT_L(0); PG8_BAR; PG8_MMA(1, 0, At, B0); PG8_MMA(1, 1, At, B1); PG8_BAR; PG8_SCHED;
;             PG8_LDB(B0, 1, 0); PG8_LDB(B1, 1, 1); PG8_SCHED; PG8_LDA(At, 1, 0); PG8_STAGE(PG8_SA(0, 1), a2 + hstep, voffA);
;             PG8_WAIT_V(8); PG8_WAIT_L(0); PG8_BAR; PG8_MMA(0, 0, At, B0); PG8_MMA(0, 1, At, B1); PG8_BAR; PG8_SCHED;
	s_setprio 1
	v_mfma_f32_16x16x32_bf16 v[62:65], v[152:155], v[184:187], v[62:65]
	v_mfma_f32_16x16x32_bf16 v[58:61], v[160:163], v[184:187], v[58:61]
	v_mfma_f32_16x16x32_bf16 v[46:49], v[152:155], v[192:195], v[46:49]
	v_mfma_f32_16x16x32_bf16 v[42:45], v[160:163], v[192:195], v[42:45]
	v_mfma_f32_16x16x32_bf16 v[30:33], v[152:155], v[200:203], v[30:33]
	v_mfma_f32_16x16x32_bf16 v[26:29], v[160:163], v[200:203], v[26:29]
	v_mfma_f32_16x16x32_bf16 v[14:17], v[152:155], v[208:211], v[14:17]
	v_mfma_f32_16x16x32_bf16 v[10:13], v[160:163], v[208:211], v[10:13]
	v_mfma_f32_16x16x32_bf16 v[62:65], v[156:159], v[188:191], v[62:65]
	v_mfma_f32_16x16x32_bf16 v[58:61], v[164:167], v[188:191], v[58:61]
	v_mfma_f32_16x16x32_bf16 v[46:49], v[156:159], v[196:199], v[46:49]
	v_mfma_f32_16x16x32_bf16 v[42:45], v[164:167], v[196:199], v[42:45]
	v_mfma_f32_16x16x32_bf16 v[30:33], v[156:159], v[204:207], v[30:33]
	v_mfma_f32_16x16x32_bf16 v[26:29], v[164:167], v[204:207], v[26:29]
	v_mfma_f32_16x16x32_bf16 v[14:17], v[156:159], v[212:215], v[14:17]
	v_mfma_f32_16x16x32_bf16 v[10:13], v[164:167], v[212:215], v[10:13]
	v_mfma_f32_16x16x32_bf16 v[54:57], v[168:171], v[184:187], v[54:57]
	v_mfma_f32_16x16x32_bf16 v[50:53], v[176:179], v[184:187], v[50:53]
	v_mfma_f32_16x16x32_bf16 v[38:41], v[168:171], v[192:195], v[38:41]
	v_mfma_f32_16x16x32_bf16 v[34:37], v[176:179], v[192:195], v[34:37]
	v_mfma_f32_16x16x32_bf16 v[22:25], v[168:171], v[200:203], v[22:25]
	v_mfma_f32_16x16x32_bf16 v[18:21], v[176:179], v[200:203], v[18:21]
	v_mfma_f32_16x16x32_bf16 v[6:9], v[168:171], v[208:211], v[6:9]
	v_mfma_f32_16x16x32_bf16 v[2:5], v[176:179], v[208:211], v[2:5]
	v_mfma_f32_16x16x32_bf16 v[54:57], v[172:175], v[188:191], v[54:57]
	v_mfma_f32_16x16x32_bf16 v[50:53], v[180:183], v[188:191], v[50:53]
	v_mfma_f32_16x16x32_bf16 v[38:41], v[172:175], v[196:199], v[38:41]
	v_mfma_f32_16x16x32_bf16 v[34:37], v[180:183], v[196:199], v[34:37]
	v_mfma_f32_16x16x32_bf16 v[22:25], v[172:175], v[204:207], v[22:25]
	v_mfma_f32_16x16x32_bf16 v[18:21], v[180:183], v[204:207], v[18:21]
	v_mfma_f32_16x16x32_bf16 v[6:9], v[172:175], v[212:215], v[6:9]
	v_mfma_f32_16x16x32_bf16 v[2:5], v[180:183], v[212:215], v[2:5]
	s_setprio 0
	s_barrier
	s_add_i32 s57, 0, 0x18000
	v_add_u32_e32 v151, s57, v146
	s_add_i32 s58, 0, 0x1c000
	ds_read_b128 v[152:155], v151
	ds_read_b128 v[156:159], v151 offset:1024
	ds_read_b128 v[160:163], v151 offset:2048
	ds_read_b128 v[164:167], v151 offset:3072
	v_add_u32_e32 v151, s58, v146
	ds_read_b128 v[168:171], v151
	ds_read_b128 v[172:175], v151 offset:1024
	ds_read_b128 v[176:179], v151 offset:2048
	ds_read_b128 v[180:183], v151 offset:3072
	s_add_u32 s26, s26, s8
	s_addc_u32 s27, s27, s9
	s_mov_b32 m0, s37
	v_lshl_add_u64 v[228:229], s[26:27], 0, v[130:131]
	ds_read_b128 v[184:187], v150 offset:32768
	ds_read_b128 v[188:191], v150 offset:33792
	ds_read_b128 v[192:195], v150 offset:34816
	ds_read_b128 v[196:199], v150 offset:35840
	ds_read_b128 v[200:203], v150 offset:36864
	ds_read_b128 v[204:207], v150 offset:37888
	ds_read_b128 v[208:211], v150 offset:38912
	ds_read_b128 v[212:215], v150 offset:39936
	global_load_lds_dwordx4 v[228:229], off
	s_mov_b32 m0, s38
	v_lshl_add_u64 v[228:229], s[26:27], 0, v[134:135]
	global_load_lds_dwordx4 v[228:229], off
	s_waitcnt vmcnt(8) lgkmcnt(0)
	s_barrier
	s_setprio 1
	v_mfma_f32_16x16x32_bf16 v[122:125], v[152:155], v[184:187], v[122:125]
	v_mfma_f32_16x16x32_bf16 v[126:129], v[160:163], v[184:187], v[126:129]
	v_mfma_f32_16x16x32_bf16 v[110:113], v[152:155], v[192:195], v[110:113]
	v_mfma_f32_16x16x32_bf16 v[106:109], v[160:163], v[192:195], v[106:109]
	v_mfma_f32_16x16x32_bf16 v[94:97], v[152:155], v[200:203], v[94:97]
	v_mfma_f32_16x16x32_bf16 v[90:93], v[160:163], v[200:203], v[90:93]
	v_mfma_f32_16x16x32_bf16 v[78:81], v[152:155], v[208:211], v[78:81]
	v_mfma_f32_16x16x32_bf16 v[74:77], v[160:163], v[208:211], v[74:77]
	v_mfma_f32_16x16x32_bf16 v[122:125], v[156:159], v[188:191], v[122:125]
	v_mfma_f32_16x16x32_bf16 v[126:129], v[164:167], v[188:191], v[126:129]
	v_mfma_f32_16x16x32_bf16 v[110:113], v[156:159], v[196:199], v[110:113]
	v_mfma_f32_16x16x32_bf16 v[106:109], v[164:167], v[196:199], v[106:109]
	v_mfma_f32_16x16x32_bf16 v[94:97], v[156:159], v[204:207], v[94:97]
	v_mfma_f32_16x16x32_bf16 v[90:93], v[164:167], v[204:207], v[90:93]
	v_mfma_f32_16x16x32_bf16 v[78:81], v[156:159], v[212:215], v[78:81]
	v_mfma_f32_16x16x32_bf16 v[74:77], v[164:167], v[212:215], v[74:77]
	v_mfma_f32_16x16x32_bf16 v[118:121], v[168:171], v[184:187], v[118:121]
	v_mfma_f32_16x16x32_bf16 v[114:117], v[176:179], v[184:187], v[114:117]
	v_mfma_f32_16x16x32_bf16 v[102:105], v[168:171], v[192:195], v[102:105]
	v_mfma_f32_16x16x32_bf16 v[98:101], v[176:179], v[192:195], v[98:101]
	v_mfma_f32_16x16x32_bf16 v[86:89], v[168:171], v[200:203], v[86:89]
	v_mfma_f32_16x16x32_bf16 v[82:85], v[176:179], v[200:203], v[82:85]
	v_mfma_f32_16x16x32_bf16 v[70:73], v[168:171], v[208:211], v[70:73]
	v_mfma_f32_16x16x32_bf16 v[66:69], v[176:179], v[208:211], v[66:69]
	v_mfma_f32_16x16x32_bf16 v[118:121], v[172:175], v[188:191], v[118:121]
	v_mfma_f32_16x16x32_bf16 v[114:117], v[180:183], v[188:191], v[114:117]
	v_mfma_f32_16x16x32_bf16 v[102:105], v[172:175], v[196:199], v[102:105]
	v_mfma_f32_16x16x32_bf16 v[98:101], v[180:183], v[196:199], v[98:101]
	v_mfma_f32_16x16x32_bf16 v[86:89], v[172:175], v[204:207], v[86:89]
	v_mfma_f32_16x16x32_bf16 v[82:85], v[180:183], v[204:207], v[82:85]
	v_mfma_f32_16x16x32_bf16 v[70:73], v[172:175], v[212:215], v[70:73]
	v_mfma_f32_16x16x32_bf16 v[66:69], v[180:183], v[212:215], v[66:69]
	s_setprio 0
	s_barrier
; #define PG8_STAGE(bufoff, gbase, voff) do { _Pragma("unroll") for (int _i = 0; _i < 2; ++_i) \
;         __builtin_amdgcn_global_load_lds((const unsigned*)((const char*)(gbase) + (voff)[_i]), (PG8_LAS unsigned*)(lds + (bufoff) + ldsw + _i * 8192), 16, 0, 0); } while (0)
; #define PG8_LDA(dst, b, h) do { _Pragma("unroll") for (int m = 0; m < 4; ++m) _Pragma("unroll") for (int k = 0; k < 2; ++k) dst[m][k] = *(const PG8_LAS bf16x8*)(lds + PG8_SA(b, h) + aoff + m * 2048 + k * 1024); } while (0)
; #define PG8_MMA(ai, bj, At, Bt) do { __builtin_amdgcn_s_setprio(1); _Pragma("unroll") for (int m = 0; m < 4; ++m) _Pragma("unroll") for (int n = 0; n < 2; ++n) _Pragma("unroll") for (int k = 0; k < 2; ++k) \
;         acc[ai][bj][m][n] = __builtin_amdgcn_mfma_f32_16x16x32_bf16(Bt[n][k], At[m][k], acc[ai][bj][m][n], 0, 0, 0); __builtin_amdgcn_s_setprio(0); } while (0)
; #define PG8_WAIT_V(n) asm volatile("s_waitcnt vmcnt(" #n ")" ::: "memory")
; #define PG8_WAIT_L(n) asm volatile("s_waitcnt lgkmcnt(" #n ")" ::: "memory")
; #define PG8_BAR __builtin_amdgcn_s_barrier()
; #define PG8_SCHED __builtin_amdgcn_sched_barrier(0)
; template <class Epi, class Sched, bool ALIGN_EPI = false, bool SP2 = false>
; __device__ __forceinline__ void gemm_phase(PG8_LAS unsigned char* lds, const Gemm g, const Sched& S, const Epi& E) {
;     ...
;             PG8_LDA(At, 1, 1); PG8_STAGE(PG8_SB(1, 0), b3, voffB); PG8_STAGE(PG8_SB(1, 1), b3 + hstep, voffB); PG8_STAGE(PG8_SA(1, 0), a3, voffA);
;             PG8_WAIT_V(8); PG8_WAIT_L(0); PG8_BAR; PG8_MMA(1, 0, At, B0); PG8_MMA(1, 1, At, B1); PG8_BAR; PG8_SCHED;
	s_add_i32 s26, s57, s34
	v_lshl_add_u64 v[216:217], v[216:217], 0, s[16:17]
	s_mov_b32 m0, s26
	ds_read_b128 v[184:187], v150 offset:49152
	ds_read_b128 v[188:191], v150 offset:50176
	ds_read_b128 v[192:195], v150 offset:51200
	ds_read_b128 v[196:199], v150 offset:52224
	ds_read_b128 v[200:203], v150 offset:53248
	ds_read_b128 v[204:207], v150 offset:54272
	ds_read_b128 v[208:211], v150 offset:55296
	ds_read_b128 v[212:215], v150 offset:56320
	global_load_lds_dwordx4 v[216:217], off
	v_lshl_add_u64 v[216:217], v[218:219], 0, s[16:17]
	s_add_i32 m0, s26, 0x2000
	s_add_i32 s26, s58, s34
	global_load_lds_dwordx4 v[216:217], off
	s_mov_b32 m0, s26
	v_lshl_add_u64 v[216:217], v[220:221], 0, s[16:17]
	global_load_lds_dwordx4 v[216:217], off
	s_add_i32 m0, s26, 0x2000
	v_lshl_add_u64 v[216:217], v[222:223], 0, s[16:17]
	global_load_lds_dwordx4 v[216:217], off
	s_mov_b32 m0, s40
	v_lshl_add_u64 v[216:217], v[224:225], 0, s[16:17]
	global_load_lds_dwordx4 v[216:217], off
	s_mov_b32 m0, s41
	v_lshl_add_u64 v[216:217], v[226:227], 0, s[16:17]
	global_load_lds_dwordx4 v[216:217], off
	s_waitcnt vmcnt(8) lgkmcnt(0)
	s_barrier
	s_setprio 1
	v_mfma_f32_16x16x32_bf16 v[62:65], v[152:155], v[184:187], v[62:65]
	v_mfma_f32_16x16x32_bf16 v[58:61], v[160:163], v[184:187], v[58:61]
	v_mfma_f32_16x16x32_bf16 v[46:49], v[152:155], v[192:195], v[46:49]
	v_mfma_f32_16x16x32_bf16 v[42:45], v[160:163], v[192:195], v[42:45]
	v_mfma_f32_16x16x32_bf16 v[30:33], v[152:155], v[200:203], v[30:33]
	v_mfma_f32_16x16x32_bf16 v[26:29], v[160:163], v[200:203], v[26:29]
	v_mfma_f32_16x16x32_bf16 v[14:17], v[152:155], v[208:211], v[14:17]
	v_mfma_f32_16x16x32_bf16 v[10:13], v[160:163], v[208:211], v[10:13]
	v_mfma_f32_16x16x32_bf16 v[62:65], v[156:159], v[188:191], v[62:65]
	v_mfma_f32_16x16x32_bf16 v[58:61], v[164:167], v[188:191], v[58:61]
	v_mfma_f32_16x16x32_bf16 v[46:49], v[156:159], v[196:199], v[46:49]
	v_mfma_f32_16x16x32_bf16 v[42:45], v[164:167], v[196:199], v[42:45]
	v_mfma_f32_16x16x32_bf16 v[30:33], v[156:159], v[204:207], v[30:33]
	v_mfma_f32_16x16x32_bf16 v[26:29], v[164:167], v[204:207], v[26:29]
	v_mfma_f32_16x16x32_bf16 v[14:17], v[156:159], v[212:215], v[14:17]
	v_mfma_f32_16x16x32_bf16 v[10:13], v[164:167], v[212:215], v[10:13]
	v_mfma_f32_16x16x32_bf16 v[54:57], v[168:171], v[184:187], v[54:57]
	v_mfma_f32_16x16x32_bf16 v[50:53], v[176:179], v[184:187], v[50:53]
	v_mfma_f32_16x16x32_bf16 v[38:41], v[168:171], v[192:195], v[38:41]
	v_mfma_f32_16x16x32_bf16 v[34:37], v[176:179], v[192:195], v[34:37]
	v_mfma_f32_16x16x32_bf16 v[22:25], v[168:171], v[200:203], v[22:25]
	v_mfma_f32_16x16x32_bf16 v[18:21], v[176:179], v[200:203], v[18:21]
	v_mfma_f32_16x16x32_bf16 v[6:9], v[168:171], v[208:211], v[6:9]
	v_mfma_f32_16x16x32_bf16 v[2:5], v[176:179], v[208:211], v[2:5]
	v_mfma_f32_16x16x32_bf16 v[54:57], v[172:175], v[188:191], v[54:57]
	v_mfma_f32_16x16x32_bf16 v[50:53], v[180:183], v[188:191], v[50:53]
	v_mfma_f32_16x16x32_bf16 v[38:41], v[172:175], v[196:199], v[38:41]
	v_mfma_f32_16x16x32_bf16 v[34:37], v[180:183], v[196:199], v[34:37]
	v_mfma_f32_16x16x32_bf16 v[22:25], v[172:175], v[204:207], v[22:25]
	v_mfma_f32_16x16x32_bf16 v[18:21], v[180:183], v[204:207], v[18:21]
	v_mfma_f32_16x16x32_bf16 v[6:9], v[172:175], v[212:215], v[6:9]
	v_mfma_f32_16x16x32_bf16 v[2:5], v[180:183], v[212:215], v[2:5]
	s_setprio 0
	s_barrier
	s_add_u32 s54, s54, 0x100
	s_addc_u32 s55, s55, 0
	s_add_u32 s24, s24, 0x100
	s_addc_u32 s25, s25, 0
	s_cmp_ge_i32 s56, s42
	s_mov_b32 s26, s56
	s_cbranch_scc0 .LBB0_1809

; #define PG8_STAGE(bufoff, gbase, voff) do { _Pragma("unroll") for (int _i = 0; _i < 2; ++_i) \
;         __builtin_amdgcn_global_load_lds((const unsigned*)((const char*)(gbase) + (voff)[_i]), (PG8_LAS unsigned*)(lds + (bufoff) + ldsw + _i * 8192), 16, 0, 0); } while (0)
; #define PG8_LDA(dst, b, h) do { _Pragma("unroll") for (int m = 0; m < 4; ++m) _Pragma("unroll") for (int k = 0; k < 2; ++k) dst[m][k] = *(const PG8_LAS bf16x8*)(lds + PG8_SA(b, h) + aoff + m * 2048 + k * 1024); } while (0)
; #define PG8_LDB(dst, b, h) do { _Pragma("unroll") for (int n = 0; n < 2; ++n) _Pragma("unroll") for (int k = 0; k < 2; ++k) dst[n][k] = *(const PG8_LAS bf16x8*)(lds + PG8_SB(b, h) + boff + n * 2048 + k * 1024); } while (0)
; #define PG8_MMA(ai, bj, At, Bt) do { __builtin_amdgcn_s_setprio(1); _Pragma("unroll") for (int m = 0; m < 4; ++m) _Pragma("unroll") for (int n = 0; n < 2; ++n) _Pragma("unroll") for (int k = 0; k < 2; ++k) \
;         acc[ai][bj][m][n] = __builtin_amdgcn_mfma_f32_16x16x32_bf16(Bt[n][k], At[m][k], acc[ai][bj][m][n], 0, 0, 0); __builtin_amdgcn_s_setprio(0); } while (0)
; #define PG8_WAIT_V(n) asm volatile("s_waitcnt vmcnt(" #n ")" ::: "memory")
; template <class Epi, class Sched, bool ALIGN_EPI = false, bool SP2 = false>
; __device__ __forceinline__ void gemm_phase(PG8_LAS unsigned char* lds, const Gemm g, const Sched& S, const Epi& E) {
;     ...
;         const char* nA = has_next ? (const char*)g.A + (size_t)nxt.pm * tstep : cA; const char* nB = has_next ? (const char*)g.Bt + (size_t)nxt.pn * tstep : cB;
;         for (int t = 0; t < nt; t += 2) {
;             const bool last = (t == nt - 2);
;             const char* a1 = cA + (size_t)(t + 1) * kstep;
;             const char* a2 = last ? nA : cA + (size_t)(t + 2) * kstep; const char* b2 = last ? nB : cB + (size_t)(t + 2) * kstep;
;             const char* a3 = a2 + kstep; const char* b3 = b2 + kstep;
;             if (last && has_next) S.a_ready(nxt);
;             if constexpr (SP2) {
;             PG8_LDB(B0, 0, 0); PG8_LDB(B1, 0, 1); PG8_SCHED; PG8_LDA(At, 0, 0); PG8_STAGE(PG8_SA(1, 1), a1 + hstep, voffA);
;             PG8_WAIT_V(8); PG8_WAIT_L(0); PG8_BAR; PG8_MMA(0, 0, At, B0); PG8_MMA(0, 1, At, B1); PG8_BAR; PG8_SCHED;
;             PG8_LDA(At, 0, 1); PG8_STAGE(PG8_SB(0, 0), b2, voffB); PG8_STAGE(PG8_SB(0, 1), b2 + hstep, voffB); PG8_STAGE(PG8_SA(0, 0), a2, voffA);
.LBB0_1976:
	ds_read_b128 v[152:155], v148
	ds_read_b128 v[156:159], v148 offset:1024
	ds_read_b128 v[160:163], v148 offset:2048
	ds_read_b128 v[164:167], v148 offset:3072
	ds_read_b128 v[168:171], v149
	ds_read_b128 v[172:175], v149 offset:1024
	ds_read_b128 v[176:179], v149 offset:2048
	ds_read_b128 v[180:183], v149 offset:3072
	s_add_i32 s58, s26, 2
	s_add_u32 s59, s24, 0x80
	s_addc_u32 s27, s25, 0
	s_cmp_eq_u32 s44, s26
	s_cselect_b32 s26, s4, s59
	s_cselect_b32 s27, s5, s27
	s_cselect_b32 s61, s23, s57
	s_cselect_b32 s60, s22, s56
	v_lshl_add_u64 v[216:217], s[24:25], 0, v[140:141]
	s_add_i32 m0, s36, 0xc000
	ds_read_b128 v[184:187], v150
	ds_read_b128 v[188:191], v150 offset:1024
	ds_read_b128 v[192:195], v150 offset:2048
	ds_read_b128 v[196:199], v150 offset:3072
	ds_read_b128 v[200:203], v150 offset:4096
	ds_read_b128 v[204:207], v150 offset:5120
	ds_read_b128 v[208:211], v150 offset:6144
	ds_read_b128 v[212:215], v150 offset:7168
	global_load_lds_dwordx4 v[216:217], off
	s_add_i32 m0, s36, 0xe000
	v_lshl_add_u64 v[216:217], s[24:25], 0, v[138:139]
	global_load_lds_dwordx4 v[216:217], off
	s_waitcnt vmcnt(8) lgkmcnt(0)
	s_barrier
	s_setprio 1
	v_mfma_f32_16x16x32_bf16 v[122:125], v[152:155], v[184:187], v[122:125]
	v_mfma_f32_16x16x32_bf16 v[118:121], v[160:163], v[184:187], v[118:121]
	v_mfma_f32_16x16x32_bf16 v[110:113], v[152:155], v[192:195], v[110:113]
	v_mfma_f32_16x16x32_bf16 v[102:105], v[160:163], v[192:195], v[102:105]
	v_mfma_f32_16x16x32_bf16 v[94:97], v[152:155], v[200:203], v[94:97]
	v_mfma_f32_16x16x32_bf16 v[86:89], v[160:163], v[200:203], v[86:89]
	v_mfma_f32_16x16x32_bf16 v[78:81], v[152:155], v[208:211], v[78:81]
	v_mfma_f32_16x16x32_bf16 v[70:73], v[160:163], v[208:211], v[70:73]
	v_mfma_f32_16x16x32_bf16 v[122:125], v[156:159], v[188:191], v[122:125]
	v_mfma_f32_16x16x32_bf16 v[118:121], v[164:167], v[188:191], v[118:121]
	v_mfma_f32_16x16x32_bf16 v[110:113], v[156:159], v[196:199], v[110:113]
	v_mfma_f32_16x16x32_bf16 v[102:105], v[164:167], v[196:199], v[102:105]
	v_mfma_f32_16x16x32_bf16 v[94:97], v[156:159], v[204:207], v[94:97]
	v_mfma_f32_16x16x32_bf16 v[86:89], v[164:167], v[204:207], v[86:89]
	v_mfma_f32_16x16x32_bf16 v[78:81], v[156:159], v[212:215], v[78:81]
	v_mfma_f32_16x16x32_bf16 v[70:73], v[164:167], v[212:215], v[70:73]
	v_mfma_f32_16x16x32_bf16 v[126:129], v[168:171], v[184:187], v[126:129]
	v_mfma_f32_16x16x32_bf16 v[114:117], v[176:179], v[184:187], v[114:117]
	v_mfma_f32_16x16x32_bf16 v[106:109], v[168:171], v[192:195], v[106:109]
	v_mfma_f32_16x16x32_bf16 v[98:101], v[176:179], v[192:195], v[98:101]
	v_mfma_f32_16x16x32_bf16 v[90:93], v[168:171], v[200:203], v[90:93]
	v_mfma_f32_16x16x32_bf16 v[82:85], v[176:179], v[200:203], v[82:85]
	v_mfma_f32_16x16x32_bf16 v[74:77], v[168:171], v[208:211], v[74:77]
	v_mfma_f32_16x16x32_bf16 v[66:69], v[176:179], v[208:211], v[66:69]
	v_mfma_f32_16x16x32_bf16 v[126:129], v[172:175], v[188:191], v[126:129]
	v_mfma_f32_16x16x32_bf16 v[114:117], v[180:183], v[188:191], v[114:117]
	v_mfma_f32_16x16x32_bf16 v[106:109], v[172:175], v[196:199], v[106:109]
	v_mfma_f32_16x16x32_bf16 v[98:101], v[180:183], v[196:199], v[98:101]
	v_mfma_f32_16x16x32_bf16 v[90:93], v[172:175], v[204:207], v[90:93]
	v_mfma_f32_16x16x32_bf16 v[82:85], v[180:183], v[204:207], v[82:85]
	v_mfma_f32_16x16x32_bf16 v[74:77], v[172:175], v[212:215], v[74:77]
	v_mfma_f32_16x16x32_bf16 v[66:69], v[180:183], v[212:215], v[66:69]
	s_setprio 0
	s_barrier
	s_add_i32 s59, s47, s31
	v_lshl_add_u64 v[216:217], s[60:61], 0, v[134:135]
	s_mov_b32 m0, s59
	ds_read_b128 v[184:187], v150 offset:16384
	ds_read_b128 v[188:191], v150 offset:17408
	ds_read_b128 v[192:195], v150 offset:18432
	ds_read_b128 v[196:199], v150 offset:19456
	ds_read_b128 v[200:203], v150 offset:20480
	ds_read_b128 v[204:207], v150 offset:21504
	ds_read_b128 v[208:211], v150 offset:22528
	ds_read_b128 v[212:215], v150 offset:23552
	global_load_lds_dwordx4 v[216:217], off
	s_add_i32 m0, s59, 0x2000
	v_lshl_add_u64 v[218:219], s[60:61], 0, v[130:131]
	s_add_u32 s60, s60, s8
	s_addc_u32 s61, s61, s9
	s_add_i32 s59, s48, s31
	global_load_lds_dwordx4 v[218:219], off
	v_lshl_add_u64 v[220:221], s[60:61], 0, v[134:135]
	s_mov_b32 m0, s59
	v_lshl_add_u64 v[222:223], s[60:61], 0, v[130:131]
	global_load_lds_dwordx4 v[220:221], off
	s_add_i32 m0, s59, 0x2000
	v_lshl_add_u64 v[224:225], s[26:27], 0, v[136:137]
	global_load_lds_dwordx4 v[222:223], off
	s_mov_b32 m0, s36
	v_lshl_add_u64 v[226:227], s[26:27], 0, v[132:133]
	global_load_lds_dwordx4 v[224:225], off
	s_mov_b32 m0, s37
	s_nop 0
	global_load_lds_dwordx4 v[226:227], off
	s_waitcnt vmcnt(8) lgkmcnt(0)
	s_barrier
; #define PG8_STAGE(bufoff, gbase, voff) do { _Pragma("unroll") for (int _i = 0; _i < 2; ++_i) \
;         __builtin_amdgcn_global_load_lds((const unsigned*)((const char*)(gbase) + (voff)[_i]), (PG8_LAS unsigned*)(lds + (bufoff) + ldsw + _i * 8192), 16, 0, 0); } while (0)
; #define PG8_LDA(dst, b, h) do { _Pragma("unroll") for (int m = 0; m < 4; ++m) _Pragma("unroll") for (int k = 0; k < 2; ++k) dst[m][k] = *(const PG8_LAS bf16x8*)(lds + PG8_SA(b, h) + aoff + m * 2048 + k * 1024); } while (0)
; #define PG8_LDB(dst, b, h) do { _Pragma("unroll") for (int n = 0; n < 2; ++n) _Pragma("unroll") for (int k = 0; k < 2; ++k) dst[n][k] = *(const PG8_LAS bf16x8*)(lds + PG8_SB(b, h) + boff + n * 2048 + k * 1024); } while (0)
; #define PG8_MMA(ai, bj, At, Bt) do { __builtin_amdgcn_s_setprio(1); _Pragma("unroll") for (int m = 0; m < 4; ++m) _Pragma("unroll") for (int n = 0; n < 2; ++n) _Pragma("unroll") for (int k = 0; k < 2; ++k) \
;         acc[ai][bj][m][n] = __builtin_amdgcn_mfma_f32_16x16x32_bf16(Bt[n][k], At[m][k], acc[ai][bj][m][n], 0, 0, 0); __builtin_amdgcn_s_setprio(0); } while (0)
; #define PG8_WAIT_V(n) asm volatile("s_waitcnt vmcnt(" #n ")" ::: "memory")
; #define PG8_WAIT_L(n) asm volatile("s_waitcnt lgkmcnt(" #n ")" ::: "memory")
; #define PG8_BAR __builtin_amdgcn_s_barrier()
; #define PG8_SCHED __builtin_amdgcn_sched_barrier(0)
; template <class Epi, class Sched, bool ALIGN_EPI = false, bool SP2 = false>
; __device__ __forceinline__ void gemm_phase(PG8_LAS unsigned char* lds, const Gemm g, const Sched& S, const Epi& E) {
;     ...
;             PG8_WAIT_V(8); PG8_WAIT_L(0); PG8_BAR; PG8_MMA(1, 0, At, B0); PG8_MMA(1, 1, At, B1); PG8_BAR; PG8_SCHED;
;             PG8_LDB(B0, 1, 0); PG8_LDB(B1, 1, 1); PG8_SCHED; PG8_LDA(At, 1, 0); PG8_STAGE(PG8_SA(0, 1), a2 + hstep, voffA);
;             PG8_WAIT_V(8); PG8_WAIT_L(0); PG8_BAR; PG8_MMA(0, 0, At, B0); PG8_MMA(0, 1, At, B1); PG8_BAR; PG8_SCHED;
	s_setprio 1
	v_mfma_f32_16x16x32_bf16 v[62:65], v[152:155], v[184:187], v[62:65]
	v_mfma_f32_16x16x32_bf16 v[54:57], v[160:163], v[184:187], v[54:57]
	v_mfma_f32_16x16x32_bf16 v[46:49], v[152:155], v[192:195], v[46:49]
	v_mfma_f32_16x16x32_bf16 v[38:41], v[160:163], v[192:195], v[38:41]
	v_mfma_f32_16x16x32_bf16 v[30:33], v[152:155], v[200:203], v[30:33]
	v_mfma_f32_16x16x32_bf16 v[22:25], v[160:163], v[200:203], v[22:25]
	v_mfma_f32_16x16x32_bf16 v[14:17], v[152:155], v[208:211], v[14:17]
	v_mfma_f32_16x16x32_bf16 v[6:9], v[160:163], v[208:211], v[6:9]
	v_mfma_f32_16x16x32_bf16 v[62:65], v[156:159], v[188:191], v[62:65]
	v_mfma_f32_16x16x32_bf16 v[54:57], v[164:167], v[188:191], v[54:57]
	v_mfma_f32_16x16x32_bf16 v[46:49], v[156:159], v[196:199], v[46:49]
	v_mfma_f32_16x16x32_bf16 v[38:41], v[164:167], v[196:199], v[38:41]
	v_mfma_f32_16x16x32_bf16 v[30:33], v[156:159], v[204:207], v[30:33]
	v_mfma_f32_16x16x32_bf16 v[22:25], v[164:167], v[204:207], v[22:25]
	v_mfma_f32_16x16x32_bf16 v[14:17], v[156:159], v[212:215], v[14:17]
	v_mfma_f32_16x16x32_bf16 v[6:9], v[164:167], v[212:215], v[6:9]
	v_mfma_f32_16x16x32_bf16 v[58:61], v[168:171], v[184:187], v[58:61]
	v_mfma_f32_16x16x32_bf16 v[50:53], v[176:179], v[184:187], v[50:53]
	v_mfma_f32_16x16x32_bf16 v[42:45], v[168:171], v[192:195], v[42:45]
	v_mfma_f32_16x16x32_bf16 v[34:37], v[176:179], v[192:195], v[34:37]
	v_mfma_f32_16x16x32_bf16 v[26:29], v[168:171], v[200:203], v[26:29]
	v_mfma_f32_16x16x32_bf16 v[18:21], v[176:179], v[200:203], v[18:21]
	v_mfma_f32_16x16x32_bf16 v[10:13], v[168:171], v[208:211], v[10:13]
	v_mfma_f32_16x16x32_bf16 v[2:5], v[176:179], v[208:211], v[2:5]
	v_mfma_f32_16x16x32_bf16 v[58:61], v[172:175], v[188:191], v[58:61]
	v_mfma_f32_16x16x32_bf16 v[50:53], v[180:183], v[188:191], v[50:53]
	v_mfma_f32_16x16x32_bf16 v[42:45], v[172:175], v[196:199], v[42:45]
	v_mfma_f32_16x16x32_bf16 v[34:37], v[180:183], v[196:199], v[34:37]
	v_mfma_f32_16x16x32_bf16 v[26:29], v[172:175], v[204:207], v[26:29]
	v_mfma_f32_16x16x32_bf16 v[18:21], v[180:183], v[204:207], v[18:21]
	v_mfma_f32_16x16x32_bf16 v[10:13], v[172:175], v[212:215], v[10:13]
	v_mfma_f32_16x16x32_bf16 v[2:5], v[180:183], v[212:215], v[2:5]
	s_setprio 0
	s_barrier
	s_add_i32 s59, 0, 0x18000
	v_add_u32_e32 v151, s59, v146
	s_add_i32 s60, 0, 0x1c000
	ds_read_b128 v[152:155], v151
	ds_read_b128 v[156:159], v151 offset:1024
	ds_read_b128 v[160:163], v151 offset:2048
	ds_read_b128 v[164:167], v151 offset:3072
	v_add_u32_e32 v151, s60, v146
	ds_read_b128 v[168:171], v151
	ds_read_b128 v[172:175], v151 offset:1024
	ds_read_b128 v[176:179], v151 offset:2048
	ds_read_b128 v[180:183], v151 offset:3072
	s_add_u32 s26, s26, s8
	s_addc_u32 s27, s27, s9
	s_mov_b32 m0, s38
	v_lshl_add_u64 v[228:229], s[26:27], 0, v[136:137]
	ds_read_b128 v[184:187], v150 offset:32768
	ds_read_b128 v[188:191], v150 offset:33792
	ds_read_b128 v[192:195], v150 offset:34816
	ds_read_b128 v[196:199], v150 offset:35840
	ds_read_b128 v[200:203], v150 offset:36864
	ds_read_b128 v[204:207], v150 offset:37888
	ds_read_b128 v[208:211], v150 offset:38912
	ds_read_b128 v[212:215], v150 offset:39936
	global_load_lds_dwordx4 v[228:229], off
	s_mov_b32 m0, s39
	v_lshl_add_u64 v[228:229], s[26:27], 0, v[132:133]
	global_load_lds_dwordx4 v[228:229], off
	s_waitcnt vmcnt(8) lgkmcnt(0)
	s_barrier
	s_setprio 1
	v_mfma_f32_16x16x32_bf16 v[122:125], v[152:155], v[184:187], v[122:125]
	v_mfma_f32_16x16x32_bf16 v[118:121], v[160:163], v[184:187], v[118:121]
	v_mfma_f32_16x16x32_bf16 v[110:113], v[152:155], v[192:195], v[110:113]
	v_mfma_f32_16x16x32_bf16 v[102:105], v[160:163], v[192:195], v[102:105]
	v_mfma_f32_16x16x32_bf16 v[94:97], v[152:155], v[200:203], v[94:97]
	v_mfma_f32_16x16x32_bf16 v[86:89], v[160:163], v[200:203], v[86:89]
	v_mfma_f32_16x16x32_bf16 v[78:81], v[152:155], v[208:211], v[78:81]
	v_mfma_f32_16x16x32_bf16 v[70:73], v[160:163], v[208:211], v[70:73]
	v_mfma_f32_16x16x32_bf16 v[122:125], v[156:159], v[188:191], v[122:125]
	v_mfma_f32_16x16x32_bf16 v[118:121], v[164:167], v[188:191], v[118:121]
	v_mfma_f32_16x16x32_bf16 v[110:113], v[156:159], v[196:199], v[110:113]
	v_mfma_f32_16x16x32_bf16 v[102:105], v[164:167], v[196:199], v[102:105]
	v_mfma_f32_16x16x32_bf16 v[94:97], v[156:159], v[204:207], v[94:97]
	v_mfma_f32_16x16x32_bf16 v[86:89], v[164:167], v[204:207], v[86:89]
	v_mfma_f32_16x16x32_bf16 v[78:81], v[156:159], v[212:215], v[78:81]
	v_mfma_f32_16x16x32_bf16 v[70:73], v[164:167], v[212:215], v[70:73]
	v_mfma_f32_16x16x32_bf16 v[126:129], v[168:171], v[184:187], v[126:129]
	v_mfma_f32_16x16x32_bf16 v[114:117], v[176:179], v[184:187], v[114:117]
	v_mfma_f32_16x16x32_bf16 v[106:109], v[168:171], v[192:195], v[106:109]
	v_mfma_f32_16x16x32_bf16 v[98:101], v[176:179], v[192:195], v[98:101]
	v_mfma_f32_16x16x32_bf16 v[90:93], v[168:171], v[200:203], v[90:93]
	v_mfma_f32_16x16x32_bf16 v[82:85], v[176:179], v[200:203], v[82:85]
	v_mfma_f32_16x16x32_bf16 v[74:77], v[168:171], v[208:211], v[74:77]
	v_mfma_f32_16x16x32_bf16 v[66:69], v[176:179], v[208:211], v[66:69]
	v_mfma_f32_16x16x32_bf16 v[126:129], v[172:175], v[188:191], v[126:129]
	v_mfma_f32_16x16x32_bf16 v[114:117], v[180:183], v[188:191], v[114:117]
	v_mfma_f32_16x16x32_bf16 v[106:109], v[172:175], v[196:199], v[106:109]
	v_mfma_f32_16x16x32_bf16 v[98:101], v[180:183], v[196:199], v[98:101]
	v_mfma_f32_16x16x32_bf16 v[90:93], v[172:175], v[204:207], v[90:93]
	v_mfma_f32_16x16x32_bf16 v[82:85], v[180:183], v[204:207], v[82:85]
	v_mfma_f32_16x16x32_bf16 v[74:77], v[172:175], v[212:215], v[74:77]
	v_mfma_f32_16x16x32_bf16 v[66:69], v[180:183], v[212:215], v[66:69]
	s_setprio 0
	s_barrier
; #define PG8_STAGE(bufoff, gbase, voff) do { _Pragma("unroll") for (int _i = 0; _i < 2; ++_i) \
;         __builtin_amdgcn_global_load_lds((const unsigned*)((const char*)(gbase) + (voff)[_i]), (PG8_LAS unsigned*)(lds + (bufoff) + ldsw + _i * 8192), 16, 0, 0); } while (0)
; #define PG8_LDA(dst, b, h) do { _Pragma("unroll") for (int m = 0; m < 4; ++m) _Pragma("unroll") for (int k = 0; k < 2; ++k) dst[m][k] = *(const PG8_LAS bf16x8*)(lds + PG8_SA(b, h) + aoff + m * 2048 + k * 1024); } while (0)
; #define PG8_MMA(ai, bj, At, Bt) do { __builtin_amdgcn_s_setprio(1); _Pragma("unroll") for (int m = 0; m < 4; ++m) _Pragma("unroll") for (int n = 0; n < 2; ++n) _Pragma("unroll") for (int k = 0; k < 2; ++k) \
;         acc[ai][bj][m][n] = __builtin_amdgcn_mfma_f32_16x16x32_bf16(Bt[n][k], At[m][k], acc[ai][bj][m][n], 0, 0, 0); __builtin_amdgcn_s_setprio(0); } while (0)
; #define PG8_WAIT_V(n) asm volatile("s_waitcnt vmcnt(" #n ")" ::: "memory")
; #define PG8_WAIT_L(n) asm volatile("s_waitcnt lgkmcnt(" #n ")" ::: "memory")
; #define PG8_BAR __builtin_amdgcn_s_barrier()
; #define PG8_SCHED __builtin_amdgcn_sched_barrier(0)
; template <class Epi, class Sched, bool ALIGN_EPI = false, bool SP2 = false>
; __device__ __forceinline__ void gemm_phase(PG8_LAS unsigned char* lds, const Gemm g, const Sched& S, const Epi& E) {
;     ...
;             PG8_LDA(At, 1, 1); PG8_STAGE(PG8_SB(1, 0), b3, voffB); PG8_STAGE(PG8_SB(1, 1), b3 + hstep, voffB); PG8_STAGE(PG8_SA(1, 0), a3, voffA);
;             PG8_WAIT_V(8); PG8_WAIT_L(0); PG8_BAR; PG8_MMA(1, 0, At, B0); PG8_MMA(1, 1, At, B1); PG8_BAR; PG8_SCHED;
	s_add_i32 s26, s59, s31
	v_lshl_add_u64 v[216:217], v[216:217], 0, s[16:17]
	s_mov_b32 m0, s26
	ds_read_b128 v[184:187], v150 offset:49152
	ds_read_b128 v[188:191], v150 offset:50176
	ds_read_b128 v[192:195], v150 offset:51200
	ds_read_b128 v[196:199], v150 offset:52224
	ds_read_b128 v[200:203], v150 offset:53248
	ds_read_b128 v[204:207], v150 offset:54272
	ds_read_b128 v[208:211], v150 offset:55296
	ds_read_b128 v[212:215], v150 offset:56320
	global_load_lds_dwordx4 v[216:217], off
	v_lshl_add_u64 v[216:217], v[218:219], 0, s[16:17]
	s_add_i32 m0, s26, 0x2000
	s_add_i32 s26, s60, s31
	global_load_lds_dwordx4 v[216:217], off
	s_mov_b32 m0, s26
	v_lshl_add_u64 v[216:217], v[220:221], 0, s[16:17]
	global_load_lds_dwordx4 v[216:217], off
	s_add_i32 m0, s26, 0x2000
	v_lshl_add_u64 v[216:217], v[222:223], 0, s[16:17]
	global_load_lds_dwordx4 v[216:217], off
	s_mov_b32 m0, s41
	v_lshl_add_u64 v[216:217], v[224:225], 0, s[16:17]
	global_load_lds_dwordx4 v[216:217], off
	s_mov_b32 m0, s42
	v_lshl_add_u64 v[216:217], v[226:227], 0, s[16:17]
	global_load_lds_dwordx4 v[216:217], off
	s_waitcnt vmcnt(8) lgkmcnt(0)
	s_barrier
	s_setprio 1
	v_mfma_f32_16x16x32_bf16 v[62:65], v[152:155], v[184:187], v[62:65]
	v_mfma_f32_16x16x32_bf16 v[54:57], v[160:163], v[184:187], v[54:57]
	v_mfma_f32_16x16x32_bf16 v[46:49], v[152:155], v[192:195], v[46:49]
	v_mfma_f32_16x16x32_bf16 v[38:41], v[160:163], v[192:195], v[38:41]
	v_mfma_f32_16x16x32_bf16 v[30:33], v[152:155], v[200:203], v[30:33]
	v_mfma_f32_16x16x32_bf16 v[22:25], v[160:163], v[200:203], v[22:25]
	v_mfma_f32_16x16x32_bf16 v[14:17], v[152:155], v[208:211], v[14:17]
	v_mfma_f32_16x16x32_bf16 v[6:9], v[160:163], v[208:211], v[6:9]
	v_mfma_f32_16x16x32_bf16 v[62:65], v[156:159], v[188:191], v[62:65]
	v_mfma_f32_16x16x32_bf16 v[54:57], v[164:167], v[188:191], v[54:57]
	v_mfma_f32_16x16x32_bf16 v[46:49], v[156:159], v[196:199], v[46:49]
	v_mfma_f32_16x16x32_bf16 v[38:41], v[164:167], v[196:199], v[38:41]
	v_mfma_f32_16x16x32_bf16 v[30:33], v[156:159], v[204:207], v[30:33]
	v_mfma_f32_16x16x32_bf16 v[22:25], v[164:167], v[204:207], v[22:25]
	v_mfma_f32_16x16x32_bf16 v[14:17], v[156:159], v[212:215], v[14:17]
	v_mfma_f32_16x16x32_bf16 v[6:9], v[164:167], v[212:215], v[6:9]
	v_mfma_f32_16x16x32_bf16 v[58:61], v[168:171], v[184:187], v[58:61]
	v_mfma_f32_16x16x32_bf16 v[50:53], v[176:179], v[184:187], v[50:53]
	v_mfma_f32_16x16x32_bf16 v[42:45], v[168:171], v[192:195], v[42:45]
	v_mfma_f32_16x16x32_bf16 v[34:37], v[176:179], v[192:195], v[34:37]
	v_mfma_f32_16x16x32_bf16 v[26:29], v[168:171], v[200:203], v[26:29]
	v_mfma_f32_16x16x32_bf16 v[18:21], v[176:179], v[200:203], v[18:21]
	v_mfma_f32_16x16x32_bf16 v[10:13], v[168:171], v[208:211], v[10:13]
	v_mfma_f32_16x16x32_bf16 v[2:5], v[176:179], v[208:211], v[2:5]
	v_mfma_f32_16x16x32_bf16 v[58:61], v[172:175], v[188:191], v[58:61]
	v_mfma_f32_16x16x32_bf16 v[50:53], v[180:183], v[188:191], v[50:53]
	v_mfma_f32_16x16x32_bf16 v[42:45], v[172:175], v[196:199], v[42:45]
	v_mfma_f32_16x16x32_bf16 v[34:37], v[180:183], v[196:199], v[34:37]
	v_mfma_f32_16x16x32_bf16 v[26:29], v[172:175], v[204:207], v[26:29]
	v_mfma_f32_16x16x32_bf16 v[18:21], v[180:183], v[204:207], v[18:21]
	v_mfma_f32_16x16x32_bf16 v[10:13], v[172:175], v[212:215], v[10:13]
	v_mfma_f32_16x16x32_bf16 v[2:5], v[180:183], v[212:215], v[2:5]
	s_setprio 0
	s_barrier
	s_add_u32 s56, s56, 0x100
	s_addc_u32 s57, s57, 0
	s_add_u32 s24, s24, 0x100
	s_addc_u32 s25, s25, 0
	s_cmp_ge_i32 s58, s43
	s_mov_b32 s26, s58
	s_cbranch_scc0 .LBB0_1976
